# v17 + blocks that own a split-K sample-row tile run it before their residual GEMM tile (its work overlaps the partner block's main loop; residual epilogues de-phase)
# speedup vs baseline: 1.0260x; 1.0127x over previous
; DEVI void run_phase(const Params& p, int ph, char* smem) {
;   if (ph == 0) { prologue_phase(p, smem); return; }
;   const int l = (ph - 1) / 13, s = (ph - 1) % 13;
; __global__ void __launch_bounds__(256, 2) mega_kernel(Params p) {
;     ...
;   for (int ph = 0; ph < NPHASE; ph++) {
;     run_phase(p, ph, smem);
.LBB0_9:
	v_writelane_b32 v255, 0, 41
	v_writelane_b32 v254, s0, 61
	s_cmp_lg_u32 s0, 0
	s_mov_b64 s[2:3], -1
	s_cbranch_scc1 .LBB0_10
	s_getpc_b64 s[98:99]

;     ...
;   for (int kt = 0; kt < nk; kt++) {
;     if (kt + 1 < nk) asm volatile("s_waitcnt vmcnt(6)" ::: "memory");
;     else asm volatile("s_waitcnt vmcnt(0)" ::: "memory");
;     __builtin_amdgcn_s_barrier();
;     asm volatile("" ::: "memory");
;     if (kt + 2 < nk) G2_STAGE(kt + 2);
;     const char* cS = smem + (kt % 3) * 24576;
;     bf16x8 xa[8], wb[4];
; #pragma unroll
;     for (int f = 0; f < 8; f++) xa[f] = *(const bf16x8*)(cS + aoff + f * 1024);
; #pragma unroll
;     for (int f = 0; f < 4; f++) wb[f] = *(const bf16x8*)(cS + boff + f * 1024);
; #pragma unroll
;     for (int nf = 0; nf < 4; nf++)
; #pragma unroll
;       for (int mf = 0; mf < 8; mf++)
;         acc[nf][mf] = __builtin_amdgcn_mfma_f32_16x16x32_bf16(wb[nf], xa[mf], acc[nf][mf], 0, 0, 0);
.Lta11_loop:
	.p2align 3
	s_waitcnt vmcnt(6) lgkmcnt(0)
	s_barrier
	s_setprio 1
	v_add_u32_e32 v144, s40, v136
	v_mfma_f32_16x16x32_bf16 v[126:129], v[184:187], v[146:149], v[126:129]
	ds_read_b128 v[200:203], v144 offset:0
	v_mfma_f32_16x16x32_bf16 v[122:125], v[184:187], v[152:155], v[122:125]
	ds_read_b128 v[204:207], v144 offset:1024
	v_mfma_f32_16x16x32_bf16 v[118:121], v[184:187], v[156:159], v[118:121]
	ds_read_b128 v[208:211], v144 offset:2048
	v_mfma_f32_16x16x32_bf16 v[114:117], v[184:187], v[162:165], v[114:117]
	ds_read_b128 v[212:215], v144 offset:3072
	v_mfma_f32_16x16x32_bf16 v[110:113], v[184:187], v[166:169], v[110:113]
	ds_read_b128 v[216:219], v144 offset:4096
	v_mfma_f32_16x16x32_bf16 v[106:109], v[184:187], v[170:173], v[106:109]
	ds_read_b128 v[220:223], v144 offset:5120
	v_mfma_f32_16x16x32_bf16 v[102:105], v[184:187], v[176:179], v[102:105]
	ds_read_b128 v[224:227], v144 offset:6144
	v_mfma_f32_16x16x32_bf16 v[98:101], v[184:187], v[180:183], v[98:101]
	ds_read_b128 v[228:231], v144 offset:7168
	v_mfma_f32_16x16x32_bf16 v[94:97], v[188:191], v[146:149], v[94:97]
	v_add_u32_e64 v144, s40, v137
	v_mfma_f32_16x16x32_bf16 v[90:93], v[188:191], v[152:155], v[90:93]
	v_mfma_f32_16x16x32_bf16 v[86:89], v[188:191], v[156:159], v[86:89]
	ds_read_b128 v[232:235], v144 offset:16384
	v_mfma_f32_16x16x32_bf16 v[82:85], v[188:191], v[162:165], v[82:85]
	ds_read_b128 v[236:239], v144 offset:17408
	v_mfma_f32_16x16x32_bf16 v[78:81], v[188:191], v[166:169], v[78:81]
	ds_read_b128 v[240:243], v144 offset:18432
	v_mfma_f32_16x16x32_bf16 v[74:77], v[188:191], v[170:173], v[74:77]
	ds_read_b128 v[244:247], v144 offset:19456
	v_mfma_f32_16x16x32_bf16 v[70:73], v[188:191], v[176:179], v[70:73]
	s_add_i32 s42, s46, s41
	s_mov_b32 m0, s42
	v_lshl_add_u64 v[142:143], v[132:133], 0, s[2:3]
	v_mfma_f32_16x16x32_bf16 v[66:69], v[188:191], v[180:183], v[66:69]
	global_load_lds_dwordx4 v[132:133], off
	s_add_i32 m0, m0, 0x1000
	v_mfma_f32_16x16x32_bf16 v[62:65], v[192:195], v[146:149], v[62:65]
	v_mfma_f32_16x16x32_bf16 v[58:61], v[192:195], v[152:155], v[58:61]
	v_mfma_f32_16x16x32_bf16 v[54:57], v[192:195], v[156:159], v[54:57]
	global_load_lds_dwordx4 v[142:143], off
	v_lshl_add_u64 v[142:143], v[142:143], 0, s[2:3]
	s_add_i32 m0, m0, 0x1000
	v_mfma_f32_16x16x32_bf16 v[50:53], v[192:195], v[162:165], v[50:53]
	v_mfma_f32_16x16x32_bf16 v[46:49], v[192:195], v[166:169], v[46:49]
	v_mfma_f32_16x16x32_bf16 v[42:45], v[192:195], v[170:173], v[42:45]
	global_load_lds_dwordx4 v[142:143], off
	v_lshl_add_u64 v[142:143], v[142:143], 0, s[2:3]
	s_add_i32 m0, m0, 0x1000
	v_mfma_f32_16x16x32_bf16 v[38:41], v[192:195], v[176:179], v[38:41]
	v_mfma_f32_16x16x32_bf16 v[34:37], v[192:195], v[180:183], v[34:37]
	v_mfma_f32_16x16x32_bf16 v[30:33], v[196:199], v[146:149], v[30:33]
	global_load_lds_dwordx4 v[142:143], off
	s_add_i32 m0, m0, 0x1000
	v_lshl_add_u64 v[142:143], v[134:135], 0, s[2:3]
	v_mfma_f32_16x16x32_bf16 v[26:29], v[196:199], v[152:155], v[26:29]
	v_mfma_f32_16x16x32_bf16 v[22:25], v[196:199], v[156:159], v[22:25]
	v_mfma_f32_16x16x32_bf16 v[18:21], v[196:199], v[162:165], v[18:21]
	global_load_lds_dwordx4 v[134:135], off
	s_add_i32 m0, m0, 0x1000
	v_lshl_add_u64 v[132:133], v[132:133], 0, s[12:13]
	v_mfma_f32_16x16x32_bf16 v[14:17], v[196:199], v[166:169], v[14:17]
	v_mfma_f32_16x16x32_bf16 v[10:13], v[196:199], v[170:173], v[10:13]
	v_mfma_f32_16x16x32_bf16 v[6:9], v[196:199], v[176:179], v[6:9]
	global_load_lds_dwordx4 v[142:143], off
	v_lshl_add_u64 v[134:135], v[134:135], 0, s[4:5]
	v_mfma_f32_16x16x32_bf16 v[2:5], v[196:199], v[180:183], v[2:5]
	s_setprio 0
	s_mov_b32 s41, s40
	s_add_i32 s40, s40, 0x6000
	s_cmp_eq_u32 s40, 0x12000
	s_cselect_b32 s40, 0, s40
	s_nop 0
	.p2align 3
	s_waitcnt vmcnt(6) lgkmcnt(0)
	s_barrier
	s_setprio 1
	v_add_u32_e32 v144, s40, v136
	v_mfma_f32_16x16x32_bf16 v[126:129], v[232:235], v[200:203], v[126:129]
	ds_read_b128 v[146:149], v144 offset:0
	v_mfma_f32_16x16x32_bf16 v[122:125], v[232:235], v[204:207], v[122:125]
	ds_read_b128 v[152:155], v144 offset:1024
	v_mfma_f32_16x16x32_bf16 v[118:121], v[232:235], v[208:211], v[118:121]
	ds_read_b128 v[156:159], v144 offset:2048
	v_mfma_f32_16x16x32_bf16 v[114:117], v[232:235], v[212:215], v[114:117]
	ds_read_b128 v[162:165], v144 offset:3072
	v_mfma_f32_16x16x32_bf16 v[110:113], v[232:235], v[216:219], v[110:113]
	ds_read_b128 v[166:169], v144 offset:4096
	v_mfma_f32_16x16x32_bf16 v[106:109], v[232:235], v[220:223], v[106:109]
	ds_read_b128 v[170:173], v144 offset:5120
	v_mfma_f32_16x16x32_bf16 v[102:105], v[232:235], v[224:227], v[102:105]
	ds_read_b128 v[176:179], v144 offset:6144
	v_mfma_f32_16x16x32_bf16 v[98:101], v[232:235], v[228:231], v[98:101]
	ds_read_b128 v[180:183], v144 offset:7168
	v_mfma_f32_16x16x32_bf16 v[94:97], v[236:239], v[200:203], v[94:97]
	v_add_u32_e64 v144, s40, v137
	v_mfma_f32_16x16x32_bf16 v[90:93], v[236:239], v[204:207], v[90:93]
	v_mfma_f32_16x16x32_bf16 v[86:89], v[236:239], v[208:211], v[86:89]
	ds_read_b128 v[184:187], v144 offset:16384
	v_mfma_f32_16x16x32_bf16 v[82:85], v[236:239], v[212:215], v[82:85]
	ds_read_b128 v[188:191], v144 offset:17408
	v_mfma_f32_16x16x32_bf16 v[78:81], v[236:239], v[216:219], v[78:81]
	ds_read_b128 v[192:195], v144 offset:18432
	v_mfma_f32_16x16x32_bf16 v[74:77], v[236:239], v[220:223], v[74:77]
	ds_read_b128 v[196:199], v144 offset:19456
	v_mfma_f32_16x16x32_bf16 v[70:73], v[236:239], v[224:227], v[70:73]
	s_add_i32 s42, s46, s41
	s_mov_b32 m0, s42
	v_lshl_add_u64 v[142:143], v[132:133], 0, s[2:3]
	v_mfma_f32_16x16x32_bf16 v[66:69], v[236:239], v[228:231], v[66:69]
	global_load_lds_dwordx4 v[132:133], off
;     ...
;   for (int kt = 0; kt < nk; kt++) {
;     if (kt + 1 < nk) asm volatile("s_waitcnt vmcnt(6)" ::: "memory");
;     else asm volatile("s_waitcnt vmcnt(0)" ::: "memory");
;     __builtin_amdgcn_s_barrier();
;     asm volatile("" ::: "memory");
;     if (kt + 2 < nk) G2_STAGE(kt + 2);
;     const char* cS = smem + (kt % 3) * 24576;
;     bf16x8 xa[8], wb[4];
; #pragma unroll
;     for (int f = 0; f < 8; f++) xa[f] = *(const bf16x8*)(cS + aoff + f * 1024);
; #pragma unroll
;     for (int f = 0; f < 4; f++) wb[f] = *(const bf16x8*)(cS + boff + f * 1024);
; #pragma unroll
;     for (int nf = 0; nf < 4; nf++)
; #pragma unroll
;       for (int mf = 0; mf < 8; mf++)
;         acc[nf][mf] = __builtin_amdgcn_mfma_f32_16x16x32_bf16(wb[nf], xa[mf], acc[nf][mf], 0, 0, 0);
	s_add_i32 m0, m0, 0x1000
	v_mfma_f32_16x16x32_bf16 v[62:65], v[240:243], v[200:203], v[62:65]
	v_mfma_f32_16x16x32_bf16 v[58:61], v[240:243], v[204:207], v[58:61]
	v_mfma_f32_16x16x32_bf16 v[54:57], v[240:243], v[208:211], v[54:57]
	global_load_lds_dwordx4 v[142:143], off
	v_lshl_add_u64 v[142:143], v[142:143], 0, s[2:3]
	s_add_i32 m0, m0, 0x1000
	v_mfma_f32_16x16x32_bf16 v[50:53], v[240:243], v[212:215], v[50:53]
	v_mfma_f32_16x16x32_bf16 v[46:49], v[240:243], v[216:219], v[46:49]
	v_mfma_f32_16x16x32_bf16 v[42:45], v[240:243], v[220:223], v[42:45]
	global_load_lds_dwordx4 v[142:143], off
	v_lshl_add_u64 v[142:143], v[142:143], 0, s[2:3]
	s_add_i32 m0, m0, 0x1000
	v_mfma_f32_16x16x32_bf16 v[38:41], v[240:243], v[224:227], v[38:41]
	v_mfma_f32_16x16x32_bf16 v[34:37], v[240:243], v[228:231], v[34:37]
	v_mfma_f32_16x16x32_bf16 v[30:33], v[244:247], v[200:203], v[30:33]
	global_load_lds_dwordx4 v[142:143], off
	s_add_i32 m0, m0, 0x1000
	v_lshl_add_u64 v[142:143], v[134:135], 0, s[2:3]
	v_mfma_f32_16x16x32_bf16 v[26:29], v[244:247], v[204:207], v[26:29]
	v_mfma_f32_16x16x32_bf16 v[22:25], v[244:247], v[208:211], v[22:25]
	v_mfma_f32_16x16x32_bf16 v[18:21], v[244:247], v[212:215], v[18:21]
	global_load_lds_dwordx4 v[134:135], off
	s_add_i32 m0, m0, 0x1000
	v_lshl_add_u64 v[132:133], v[132:133], 0, s[12:13]
	v_mfma_f32_16x16x32_bf16 v[14:17], v[244:247], v[216:219], v[14:17]
	v_mfma_f32_16x16x32_bf16 v[10:13], v[244:247], v[220:223], v[10:13]
	v_mfma_f32_16x16x32_bf16 v[6:9], v[244:247], v[224:227], v[6:9]
	global_load_lds_dwordx4 v[142:143], off
	v_lshl_add_u64 v[134:135], v[134:135], 0, s[4:5]
	v_mfma_f32_16x16x32_bf16 v[2:5], v[244:247], v[228:231], v[2:5]
	s_setprio 0
	s_mov_b32 s41, s40
	s_add_i32 s40, s40, 0x6000
	s_cmp_eq_u32 s40, 0x12000
	s_cselect_b32 s40, 0, s40
	s_nop 0
	s_sub_i32 s39, s39, 1
	s_cmp_lg_u32 s39, 0
	s_cbranch_scc1 .Lta11_loop
	.p2align 3
	s_waitcnt vmcnt(6) lgkmcnt(0)
	s_barrier
	s_setprio 1
	v_add_u32_e32 v144, s40, v136
	v_mfma_f32_16x16x32_bf16 v[126:129], v[184:187], v[146:149], v[126:129]
	ds_read_b128 v[200:203], v144 offset:0
	v_mfma_f32_16x16x32_bf16 v[122:125], v[184:187], v[152:155], v[122:125]
	ds_read_b128 v[204:207], v144 offset:1024
	v_mfma_f32_16x16x32_bf16 v[118:121], v[184:187], v[156:159], v[118:121]
	ds_read_b128 v[208:211], v144 offset:2048
	v_mfma_f32_16x16x32_bf16 v[114:117], v[184:187], v[162:165], v[114:117]
	ds_read_b128 v[212:215], v144 offset:3072
	v_mfma_f32_16x16x32_bf16 v[110:113], v[184:187], v[166:169], v[110:113]
	ds_read_b128 v[216:219], v144 offset:4096
	v_mfma_f32_16x16x32_bf16 v[106:109], v[184:187], v[170:173], v[106:109]
	ds_read_b128 v[220:223], v144 offset:5120
	v_mfma_f32_16x16x32_bf16 v[102:105], v[184:187], v[176:179], v[102:105]
	ds_read_b128 v[224:227], v144 offset:6144
	v_mfma_f32_16x16x32_bf16 v[98:101], v[184:187], v[180:183], v[98:101]
	ds_read_b128 v[228:231], v144 offset:7168
	v_mfma_f32_16x16x32_bf16 v[94:97], v[188:191], v[146:149], v[94:97]
	v_add_u32_e64 v144, s40, v137
	v_mfma_f32_16x16x32_bf16 v[90:93], v[188:191], v[152:155], v[90:93]
	v_mfma_f32_16x16x32_bf16 v[86:89], v[188:191], v[156:159], v[86:89]
	ds_read_b128 v[232:235], v144 offset:16384
	v_mfma_f32_16x16x32_bf16 v[82:85], v[188:191], v[162:165], v[82:85]
	ds_read_b128 v[236:239], v144 offset:17408
	v_mfma_f32_16x16x32_bf16 v[78:81], v[188:191], v[166:169], v[78:81]
	ds_read_b128 v[240:243], v144 offset:18432
	v_mfma_f32_16x16x32_bf16 v[74:77], v[188:191], v[170:173], v[74:77]
	ds_read_b128 v[244:247], v144 offset:19456
	v_mfma_f32_16x16x32_bf16 v[70:73], v[188:191], v[176:179], v[70:73]
	s_add_i32 s42, s46, s41
	s_mov_b32 m0, s42
	v_lshl_add_u64 v[142:143], v[132:133], 0, s[2:3]
	v_mfma_f32_16x16x32_bf16 v[66:69], v[188:191], v[180:183], v[66:69]
	global_load_lds_dwordx4 v[132:133], off
	s_add_i32 m0, m0, 0x1000
	v_mfma_f32_16x16x32_bf16 v[62:65], v[192:195], v[146:149], v[62:65]
	v_mfma_f32_16x16x32_bf16 v[58:61], v[192:195], v[152:155], v[58:61]
	v_mfma_f32_16x16x32_bf16 v[54:57], v[192:195], v[156:159], v[54:57]
	global_load_lds_dwordx4 v[142:143], off
	v_lshl_add_u64 v[142:143], v[142:143], 0, s[2:3]
	s_add_i32 m0, m0, 0x1000
	v_mfma_f32_16x16x32_bf16 v[50:53], v[192:195], v[162:165], v[50:53]
	v_mfma_f32_16x16x32_bf16 v[46:49], v[192:195], v[166:169], v[46:49]
	v_mfma_f32_16x16x32_bf16 v[42:45], v[192:195], v[170:173], v[42:45]
	global_load_lds_dwordx4 v[142:143], off
	v_lshl_add_u64 v[142:143], v[142:143], 0, s[2:3]
	s_add_i32 m0, m0, 0x1000
	v_mfma_f32_16x16x32_bf16 v[38:41], v[192:195], v[176:179], v[38:41]
	v_mfma_f32_16x16x32_bf16 v[34:37], v[192:195], v[180:183], v[34:37]
	v_mfma_f32_16x16x32_bf16 v[30:33], v[196:199], v[146:149], v[30:33]
	global_load_lds_dwordx4 v[142:143], off
	s_add_i32 m0, m0, 0x1000
	v_lshl_add_u64 v[142:143], v[134:135], 0, s[2:3]
	v_mfma_f32_16x16x32_bf16 v[26:29], v[196:199], v[152:155], v[26:29]
	v_mfma_f32_16x16x32_bf16 v[22:25], v[196:199], v[156:159], v[22:25]
	v_mfma_f32_16x16x32_bf16 v[18:21], v[196:199], v[162:165], v[18:21]
	global_load_lds_dwordx4 v[134:135], off
	s_add_i32 m0, m0, 0x1000
	v_lshl_add_u64 v[132:133], v[132:133], 0, s[12:13]
	v_mfma_f32_16x16x32_bf16 v[14:17], v[196:199], v[166:169], v[14:17]
	v_mfma_f32_16x16x32_bf16 v[10:13], v[196:199], v[170:173], v[10:13]
	v_mfma_f32_16x16x32_bf16 v[6:9], v[196:199], v[176:179], v[6:9]
	global_load_lds_dwordx4 v[142:143], off
	v_lshl_add_u64 v[134:135], v[134:135], 0, s[4:5]
	v_mfma_f32_16x16x32_bf16 v[2:5], v[196:199], v[180:183], v[2:5]
	s_setprio 0
	s_mov_b32 s41, s40
	s_add_i32 s40, s40, 0x6000
	s_cmp_eq_u32 s40, 0x12000
	s_cselect_b32 s40, 0, s40
	s_nop 0
	.p2align 3
	s_waitcnt vmcnt(6) lgkmcnt(0)
	s_barrier
;     ...
;   for (int kt = 0; kt < nk; kt++) {
;     if (kt + 1 < nk) asm volatile("s_waitcnt vmcnt(6)" ::: "memory");
;     else asm volatile("s_waitcnt vmcnt(0)" ::: "memory");
;     __builtin_amdgcn_s_barrier();
;     asm volatile("" ::: "memory");
;     if (kt + 2 < nk) G2_STAGE(kt + 2);
;     const char* cS = smem + (kt % 3) * 24576;
;     bf16x8 xa[8], wb[4];
; #pragma unroll
;     for (int f = 0; f < 8; f++) xa[f] = *(const bf16x8*)(cS + aoff + f * 1024);
; #pragma unroll
;     for (int f = 0; f < 4; f++) wb[f] = *(const bf16x8*)(cS + boff + f * 1024);
; #pragma unroll
;     for (int nf = 0; nf < 4; nf++)
; #pragma unroll
;       for (int mf = 0; mf < 8; mf++)
;         acc[nf][mf] = __builtin_amdgcn_mfma_f32_16x16x32_bf16(wb[nf], xa[mf], acc[nf][mf], 0, 0, 0);
	s_setprio 1
	v_add_u32_e32 v144, s40, v136
	v_mfma_f32_16x16x32_bf16 v[126:129], v[232:235], v[200:203], v[126:129]
	ds_read_b128 v[146:149], v144 offset:0
	v_mfma_f32_16x16x32_bf16 v[122:125], v[232:235], v[204:207], v[122:125]
	ds_read_b128 v[152:155], v144 offset:1024
	v_mfma_f32_16x16x32_bf16 v[118:121], v[232:235], v[208:211], v[118:121]
	ds_read_b128 v[156:159], v144 offset:2048
	v_mfma_f32_16x16x32_bf16 v[114:117], v[232:235], v[212:215], v[114:117]
	ds_read_b128 v[162:165], v144 offset:3072
	v_mfma_f32_16x16x32_bf16 v[110:113], v[232:235], v[216:219], v[110:113]
	ds_read_b128 v[166:169], v144 offset:4096
	v_mfma_f32_16x16x32_bf16 v[106:109], v[232:235], v[220:223], v[106:109]
	ds_read_b128 v[170:173], v144 offset:5120
	v_mfma_f32_16x16x32_bf16 v[102:105], v[232:235], v[224:227], v[102:105]
	ds_read_b128 v[176:179], v144 offset:6144
	v_mfma_f32_16x16x32_bf16 v[98:101], v[232:235], v[228:231], v[98:101]
	ds_read_b128 v[180:183], v144 offset:7168
	v_mfma_f32_16x16x32_bf16 v[94:97], v[236:239], v[200:203], v[94:97]
	v_add_u32_e64 v144, s40, v137
	v_mfma_f32_16x16x32_bf16 v[90:93], v[236:239], v[204:207], v[90:93]
	v_mfma_f32_16x16x32_bf16 v[86:89], v[236:239], v[208:211], v[86:89]
	ds_read_b128 v[184:187], v144 offset:16384
	v_mfma_f32_16x16x32_bf16 v[82:85], v[236:239], v[212:215], v[82:85]
	ds_read_b128 v[188:191], v144 offset:17408
	v_mfma_f32_16x16x32_bf16 v[78:81], v[236:239], v[216:219], v[78:81]
	ds_read_b128 v[192:195], v144 offset:18432
	v_mfma_f32_16x16x32_bf16 v[74:77], v[236:239], v[220:223], v[74:77]
	ds_read_b128 v[196:199], v144 offset:19456
	v_mfma_f32_16x16x32_bf16 v[70:73], v[236:239], v[224:227], v[70:73]
	v_mfma_f32_16x16x32_bf16 v[66:69], v[236:239], v[228:231], v[66:69]
	v_mfma_f32_16x16x32_bf16 v[62:65], v[240:243], v[200:203], v[62:65]
	v_mfma_f32_16x16x32_bf16 v[58:61], v[240:243], v[204:207], v[58:61]
	v_mfma_f32_16x16x32_bf16 v[54:57], v[240:243], v[208:211], v[54:57]
	v_mfma_f32_16x16x32_bf16 v[50:53], v[240:243], v[212:215], v[50:53]
	v_mfma_f32_16x16x32_bf16 v[46:49], v[240:243], v[216:219], v[46:49]
	v_mfma_f32_16x16x32_bf16 v[42:45], v[240:243], v[220:223], v[42:45]
	v_mfma_f32_16x16x32_bf16 v[38:41], v[240:243], v[224:227], v[38:41]
	v_mfma_f32_16x16x32_bf16 v[34:37], v[240:243], v[228:231], v[34:37]
	v_mfma_f32_16x16x32_bf16 v[30:33], v[244:247], v[200:203], v[30:33]
	v_mfma_f32_16x16x32_bf16 v[26:29], v[244:247], v[204:207], v[26:29]
	v_mfma_f32_16x16x32_bf16 v[22:25], v[244:247], v[208:211], v[22:25]
	v_mfma_f32_16x16x32_bf16 v[18:21], v[244:247], v[212:215], v[18:21]
	v_mfma_f32_16x16x32_bf16 v[14:17], v[244:247], v[216:219], v[14:17]
	v_mfma_f32_16x16x32_bf16 v[10:13], v[244:247], v[220:223], v[10:13]
	v_mfma_f32_16x16x32_bf16 v[6:9], v[244:247], v[224:227], v[6:9]
	v_mfma_f32_16x16x32_bf16 v[2:5], v[244:247], v[228:231], v[2:5]
	s_setprio 0
	s_mov_b32 s41, s40
	s_add_i32 s40, s40, 0x6000
	s_cmp_eq_u32 s40, 0x12000
	s_cselect_b32 s40, 0, s40
	s_nop 0
	.p2align 3
	s_waitcnt vmcnt(0) lgkmcnt(0)
	s_barrier
	s_setprio 1
	v_add_u32_e32 v144, s40, v136
	v_mfma_f32_16x16x32_bf16 v[126:129], v[184:187], v[146:149], v[126:129]
	ds_read_b128 v[200:203], v144 offset:0
	v_mfma_f32_16x16x32_bf16 v[122:125], v[184:187], v[152:155], v[122:125]
	ds_read_b128 v[204:207], v144 offset:1024
	v_mfma_f32_16x16x32_bf16 v[118:121], v[184:187], v[156:159], v[118:121]
	ds_read_b128 v[208:211], v144 offset:2048
	v_mfma_f32_16x16x32_bf16 v[114:117], v[184:187], v[162:165], v[114:117]
	ds_read_b128 v[212:215], v144 offset:3072
	v_mfma_f32_16x16x32_bf16 v[110:113], v[184:187], v[166:169], v[110:113]
	ds_read_b128 v[216:219], v144 offset:4096
	v_mfma_f32_16x16x32_bf16 v[106:109], v[184:187], v[170:173], v[106:109]
	ds_read_b128 v[220:223], v144 offset:5120
	v_mfma_f32_16x16x32_bf16 v[102:105], v[184:187], v[176:179], v[102:105]
	ds_read_b128 v[224:227], v144 offset:6144
	v_mfma_f32_16x16x32_bf16 v[98:101], v[184:187], v[180:183], v[98:101]
	ds_read_b128 v[228:231], v144 offset:7168
	v_mfma_f32_16x16x32_bf16 v[94:97], v[188:191], v[146:149], v[94:97]
	v_add_u32_e64 v144, s40, v137
	v_mfma_f32_16x16x32_bf16 v[90:93], v[188:191], v[152:155], v[90:93]
	v_mfma_f32_16x16x32_bf16 v[86:89], v[188:191], v[156:159], v[86:89]
	ds_read_b128 v[232:235], v144 offset:16384
	v_mfma_f32_16x16x32_bf16 v[82:85], v[188:191], v[162:165], v[82:85]
	ds_read_b128 v[236:239], v144 offset:17408
	v_mfma_f32_16x16x32_bf16 v[78:81], v[188:191], v[166:169], v[78:81]
	ds_read_b128 v[240:243], v144 offset:18432
	v_mfma_f32_16x16x32_bf16 v[74:77], v[188:191], v[170:173], v[74:77]
	ds_read_b128 v[244:247], v144 offset:19456
	v_mfma_f32_16x16x32_bf16 v[70:73], v[188:191], v[176:179], v[70:73]
	v_mfma_f32_16x16x32_bf16 v[66:69], v[188:191], v[180:183], v[66:69]
	v_mfma_f32_16x16x32_bf16 v[62:65], v[192:195], v[146:149], v[62:65]
	v_mfma_f32_16x16x32_bf16 v[58:61], v[192:195], v[152:155], v[58:61]
	v_mfma_f32_16x16x32_bf16 v[54:57], v[192:195], v[156:159], v[54:57]
	v_mfma_f32_16x16x32_bf16 v[50:53], v[192:195], v[162:165], v[50:53]
	v_mfma_f32_16x16x32_bf16 v[46:49], v[192:195], v[166:169], v[46:49]
	v_mfma_f32_16x16x32_bf16 v[42:45], v[192:195], v[170:173], v[42:45]
	v_mfma_f32_16x16x32_bf16 v[38:41], v[192:195], v[176:179], v[38:41]
	v_mfma_f32_16x16x32_bf16 v[34:37], v[192:195], v[180:183], v[34:37]
	v_mfma_f32_16x16x32_bf16 v[30:33], v[196:199], v[146:149], v[30:33]
	v_mfma_f32_16x16x32_bf16 v[26:29], v[196:199], v[152:155], v[26:29]
	v_mfma_f32_16x16x32_bf16 v[22:25], v[196:199], v[156:159], v[22:25]
	v_mfma_f32_16x16x32_bf16 v[18:21], v[196:199], v[162:165], v[18:21]
	v_mfma_f32_16x16x32_bf16 v[14:17], v[196:199], v[166:169], v[14:17]
	v_mfma_f32_16x16x32_bf16 v[10:13], v[196:199], v[170:173], v[10:13]
	v_mfma_f32_16x16x32_bf16 v[6:9], v[196:199], v[176:179], v[6:9]
	v_mfma_f32_16x16x32_bf16 v[2:5], v[196:199], v[180:183], v[2:5]
	s_setprio 0
	s_mov_b32 s41, s40
	s_add_i32 s40, s40, 0x6000
	s_cmp_eq_u32 s40, 0x12000
	s_cselect_b32 s40, 0, s40
	s_nop 0
	s_mov_b32 s4, 0x8000
	s_mov_b32 s5, 0
	s_mov_b32 s10, 0x10000
	s_mov_b32 s11, 0
	s_mov_b32 s44, 0x3fd744fd
	.p2align 3
	s_waitcnt lgkmcnt(0)
; DEVI float blo(unsigned u) { return __uint_as_float(u << 16); }
; DEVI float bhi(unsigned u) { return __uint_as_float(u & 0xffff0000u); }
; DEVI int xcd_first_tile() { return (blockIdx.x & 7) * (gridDim.x >> 3) + (blockIdx.x >> 3); }
;     ...
;         if (EPI == EPI_RESID || EPI == EPI_RESID_ATOMIC) {
;           f32x4 x = a;
;           if (EPI == EPI_RESID || kpart == 0) {
;             const u32x2 xr = *(const u32x2*)((const u16*)(p.ws + WS_XB) + (size_t)row * 1024 + col);
;             x[0] += ALPHA * blo(xr[0]); x[1] += ALPHA * bhi(xr[0]); x[2] += ALPHA * blo(xr[1]); x[3] += ALPHA * bhi(xr[1]);
;           }
;           if (EPI == EPI_RESID) *(f32x4*)((float*)(p.ws + WS_XF) + (size_t)row * 1024 + col) = x;
;           else *(f32x4*)((float*)(p.ws + WS_SLAB) + ((size_t)kpart * 512 + (row - T_P)) * 1024 + col) = x;
; DEVI void run_phase(const Params& p, int ph, char* smem) {
;     ...
;       for (int t = xcd_first_tile(); t < 512 + 16 * 11; t += xcd_tile_step()) {
;         if (t < 512) {
;           int mt_, nt_; tile_coords(t, 64, 8, mt_, nt_);
;           gemm_tile256<EPI_RESID>(p, hb, DFF, Bt, DFF, mt_ * 256, nt_ * 128, nullptr, 0, smem);
;         } else {
;           const int u_ = t - 512, tl_ = u_ / 11, q_ = u_ - tl_ * 11;
;           gemm_tile256<EPI_RESID_ATOMIC>(p, hb, DFF, Bt, DFF, (64 + (tl_ & 1)) * 256, (tl_ >> 1) * 128, nullptr, 0, smem, q_ * 256, 8, q_);
;         }
	s_nop 0
	v_mfma_f32_16x16x32_bf16 v[126:129], v[232:235], v[200:203], v[126:129]
	v_mfma_f32_16x16x32_bf16 v[122:125], v[232:235], v[204:207], v[122:125]
	v_mfma_f32_16x16x32_bf16 v[118:121], v[232:235], v[208:211], v[118:121]
	v_mfma_f32_16x16x32_bf16 v[114:117], v[232:235], v[212:215], v[114:117]
	v_mfma_f32_16x16x32_bf16 v[110:113], v[232:235], v[216:219], v[110:113]
	v_mfma_f32_16x16x32_bf16 v[106:109], v[232:235], v[220:223], v[106:109]
	v_mfma_f32_16x16x32_bf16 v[102:105], v[232:235], v[224:227], v[102:105]
	v_mfma_f32_16x16x32_bf16 v[98:101], v[232:235], v[228:231], v[98:101]
	v_mfma_f32_16x16x32_bf16 v[94:97], v[236:239], v[200:203], v[94:97]
	v_mfma_f32_16x16x32_bf16 v[90:93], v[236:239], v[204:207], v[90:93]
	v_mfma_f32_16x16x32_bf16 v[86:89], v[236:239], v[208:211], v[86:89]
	v_mfma_f32_16x16x32_bf16 v[82:85], v[236:239], v[212:215], v[82:85]
	v_mfma_f32_16x16x32_bf16 v[78:81], v[236:239], v[216:219], v[78:81]
	v_mfma_f32_16x16x32_bf16 v[74:77], v[236:239], v[220:223], v[74:77]
	v_mfma_f32_16x16x32_bf16 v[70:73], v[236:239], v[224:227], v[70:73]
	v_mfma_f32_16x16x32_bf16 v[66:69], v[236:239], v[228:231], v[66:69]
	v_mfma_f32_16x16x32_bf16 v[62:65], v[240:243], v[200:203], v[62:65]
	v_mfma_f32_16x16x32_bf16 v[58:61], v[240:243], v[204:207], v[58:61]
	v_mfma_f32_16x16x32_bf16 v[54:57], v[240:243], v[208:211], v[54:57]
	v_mfma_f32_16x16x32_bf16 v[50:53], v[240:243], v[212:215], v[50:53]
	v_mfma_f32_16x16x32_bf16 v[46:49], v[240:243], v[216:219], v[46:49]
	v_mfma_f32_16x16x32_bf16 v[42:45], v[240:243], v[220:223], v[42:45]
	v_mfma_f32_16x16x32_bf16 v[38:41], v[240:243], v[224:227], v[38:41]
	v_mfma_f32_16x16x32_bf16 v[34:37], v[240:243], v[228:231], v[34:37]
	v_mfma_f32_16x16x32_bf16 v[30:33], v[244:247], v[200:203], v[30:33]
	v_mfma_f32_16x16x32_bf16 v[26:29], v[244:247], v[204:207], v[26:29]
	v_mfma_f32_16x16x32_bf16 v[22:25], v[244:247], v[208:211], v[22:25]
	v_mfma_f32_16x16x32_bf16 v[18:21], v[244:247], v[212:215], v[18:21]
	v_mfma_f32_16x16x32_bf16 v[14:17], v[244:247], v[216:219], v[14:17]
	v_mfma_f32_16x16x32_bf16 v[10:13], v[244:247], v[220:223], v[10:13]
	v_mfma_f32_16x16x32_bf16 v[6:9], v[244:247], v[224:227], v[6:9]
	v_mfma_f32_16x16x32_bf16 v[2:5], v[244:247], v[228:231], v[2:5]
	s_mov_b32 m0, s43
	s_cmp_eq_u32 s47, 0
	s_cbranch_scc1 .Lta11_first
	s_nop 7
	global_store_dwordx4 v[140:141], v[126:129], off offset:0
	global_store_dwordx4 v[140:141], v[94:97], off offset:64
	global_store_dwordx4 v[140:141], v[62:65], off offset:128
	global_store_dwordx4 v[140:141], v[30:33], off offset:192
	v_lshl_add_u64 v[140:141], v[140:141], 0, s[10:11]
	global_store_dwordx4 v[140:141], v[122:125], off offset:0
	global_store_dwordx4 v[140:141], v[90:93], off offset:64
	global_store_dwordx4 v[140:141], v[58:61], off offset:128
	global_store_dwordx4 v[140:141], v[26:29], off offset:192
	v_lshl_add_u64 v[140:141], v[140:141], 0, s[10:11]
	global_store_dwordx4 v[140:141], v[118:121], off offset:0
	global_store_dwordx4 v[140:141], v[86:89], off offset:64
	global_store_dwordx4 v[140:141], v[54:57], off offset:128
	global_store_dwordx4 v[140:141], v[22:25], off offset:192
	v_lshl_add_u64 v[140:141], v[140:141], 0, s[10:11]
	global_store_dwordx4 v[140:141], v[114:117], off offset:0
	global_store_dwordx4 v[140:141], v[82:85], off offset:64
	global_store_dwordx4 v[140:141], v[50:53], off offset:128
	global_store_dwordx4 v[140:141], v[18:21], off offset:192
	v_lshl_add_u64 v[140:141], v[140:141], 0, s[10:11]
	global_store_dwordx4 v[140:141], v[110:113], off offset:0
	global_store_dwordx4 v[140:141], v[78:81], off offset:64
	global_store_dwordx4 v[140:141], v[46:49], off offset:128
	global_store_dwordx4 v[140:141], v[14:17], off offset:192
	v_lshl_add_u64 v[140:141], v[140:141], 0, s[10:11]
	global_store_dwordx4 v[140:141], v[106:109], off offset:0
	global_store_dwordx4 v[140:141], v[74:77], off offset:64
	global_store_dwordx4 v[140:141], v[42:45], off offset:128
	global_store_dwordx4 v[140:141], v[10:13], off offset:192
	v_lshl_add_u64 v[140:141], v[140:141], 0, s[10:11]
	global_store_dwordx4 v[140:141], v[102:105], off offset:0
	global_store_dwordx4 v[140:141], v[70:73], off offset:64
	global_store_dwordx4 v[140:141], v[38:41], off offset:128
	global_store_dwordx4 v[140:141], v[6:9], off offset:192
	v_lshl_add_u64 v[140:141], v[140:141], 0, s[10:11]
	global_store_dwordx4 v[140:141], v[98:101], off offset:0
	global_store_dwordx4 v[140:141], v[66:69], off offset:64
	global_store_dwordx4 v[140:141], v[34:37], off offset:128
	global_store_dwordx4 v[140:141], v[2:5], off offset:192
	v_readlane_b32 s39, v250, 7
	s_cmpk_lg_u32 s39, 0x200
	s_cbranch_scc1 .Lta11_ar1
	s_mov_b32 s39, 1
	v_writelane_b32 v255, s39, 41
	v_readlane_b32 s40, v250, 0
	s_lshr_b32 s41, s40, 3
	s_and_b32 s40, s40, 7
	s_lshl_b32 s40, s40, 6
	s_add_i32 s40, s40, s41
	s_sub_i32 s38, s40, 0x200

; DEVI float blo(unsigned u) { return __uint_as_float(u << 16); }
; DEVI float bhi(unsigned u) { return __uint_as_float(u & 0xffff0000u); }
;     ...
;         if (EPI == EPI_RESID || EPI == EPI_RESID_ATOMIC) {
;           f32x4 x = a;
;           if (EPI == EPI_RESID || kpart == 0) {
;             const u32x2 xr = *(const u32x2*)((const u16*)(p.ws + WS_XB) + (size_t)row * 1024 + col);
;             x[0] += ALPHA * blo(xr[0]); x[1] += ALPHA * bhi(xr[0]); x[2] += ALPHA * blo(xr[1]); x[3] += ALPHA * bhi(xr[1]);
;           }
;           if (EPI == EPI_RESID) *(f32x4*)((float*)(p.ws + WS_XF) + (size_t)row * 1024 + col) = x;
.Lta11_first:
	global_load_dwordx4 v[146:149], v[138:139], off offset:0
	global_load_dwordx4 v[152:155], v[138:139], off offset:64
	v_lshl_add_u64 v[138:139], v[138:139], 0, s[4:5]
	global_load_dwordx4 v[156:159], v[138:139], off offset:0
	global_load_dwordx4 v[162:165], v[138:139], off offset:64
	v_lshl_add_u64 v[138:139], v[138:139], 0, s[4:5]
	global_load_dwordx4 v[166:169], v[138:139], off offset:0
	global_load_dwordx4 v[170:173], v[138:139], off offset:64
	v_lshl_add_u64 v[138:139], v[138:139], 0, s[4:5]
	global_load_dwordx4 v[176:179], v[138:139], off offset:0
	global_load_dwordx4 v[180:183], v[138:139], off offset:64
	v_lshl_add_u64 v[138:139], v[138:139], 0, s[4:5]
	global_load_dwordx4 v[184:187], v[138:139], off offset:0
	global_load_dwordx4 v[188:191], v[138:139], off offset:64
	v_lshl_add_u64 v[138:139], v[138:139], 0, s[4:5]
	global_load_dwordx4 v[192:195], v[138:139], off offset:0
	global_load_dwordx4 v[196:199], v[138:139], off offset:64
	v_lshl_add_u64 v[138:139], v[138:139], 0, s[4:5]
	global_load_dwordx4 v[200:203], v[138:139], off offset:0
	global_load_dwordx4 v[204:207], v[138:139], off offset:64
	v_lshl_add_u64 v[138:139], v[138:139], 0, s[4:5]
	global_load_dwordx4 v[208:211], v[138:139], off offset:0
	global_load_dwordx4 v[212:215], v[138:139], off offset:64
	v_lshl_add_u64 v[138:139], v[138:139], 0, s[4:5]
	s_nop 7
	s_waitcnt vmcnt(15)
	v_permlane16_swap_b32_e32 v146, v148
	v_permlane16_swap_b32_e32 v147, v149
	v_lshlrev_b32_e32 v216, 16, v146
	v_and_b32_e32 v146, 0xffff0000, v146
	v_lshlrev_b32_e32 v217, 16, v147
	v_and_b32_e32 v147, 0xffff0000, v147
	v_fmac_f32_e32 v126, s44, v216
	v_fmac_f32_e32 v127, s44, v146
	v_fmac_f32_e32 v128, s44, v217
	v_fmac_f32_e32 v129, s44, v147
	global_store_dwordx4 v[140:141], v[126:129], off offset:0
	v_lshlrev_b32_e32 v216, 16, v148
	v_and_b32_e32 v148, 0xffff0000, v148
	v_lshlrev_b32_e32 v217, 16, v149
	v_and_b32_e32 v149, 0xffff0000, v149
	v_fmac_f32_e32 v94, s44, v216
	v_fmac_f32_e32 v95, s44, v148
	v_fmac_f32_e32 v96, s44, v217
	v_fmac_f32_e32 v97, s44, v149
	global_store_dwordx4 v[140:141], v[94:97], off offset:64
	s_waitcnt vmcnt(16)
	v_permlane16_swap_b32_e32 v152, v154
	v_permlane16_swap_b32_e32 v153, v155
	v_lshlrev_b32_e32 v216, 16, v152
	v_and_b32_e32 v152, 0xffff0000, v152
	v_lshlrev_b32_e32 v217, 16, v153
	v_and_b32_e32 v153, 0xffff0000, v153
	v_fmac_f32_e32 v62, s44, v216
	v_fmac_f32_e32 v63, s44, v152
	v_fmac_f32_e32 v64, s44, v217
	v_fmac_f32_e32 v65, s44, v153
	global_store_dwordx4 v[140:141], v[62:65], off offset:128
	v_lshlrev_b32_e32 v216, 16, v154
	v_and_b32_e32 v154, 0xffff0000, v154
	v_lshlrev_b32_e32 v217, 16, v155
	v_and_b32_e32 v155, 0xffff0000, v155
	v_fmac_f32_e32 v30, s44, v216
	v_fmac_f32_e32 v31, s44, v154
	v_fmac_f32_e32 v32, s44, v217
	v_fmac_f32_e32 v33, s44, v155
	global_store_dwordx4 v[140:141], v[30:33], off offset:192
	v_lshl_add_u64 v[140:141], v[140:141], 0, s[10:11]
	s_waitcnt vmcnt(17)
	v_permlane16_swap_b32_e32 v156, v158
	v_permlane16_swap_b32_e32 v157, v159
	v_lshlrev_b32_e32 v216, 16, v156
	v_and_b32_e32 v156, 0xffff0000, v156
	v_lshlrev_b32_e32 v217, 16, v157
	v_and_b32_e32 v157, 0xffff0000, v157
	v_fmac_f32_e32 v122, s44, v216
	v_fmac_f32_e32 v123, s44, v156
	v_fmac_f32_e32 v124, s44, v217
	v_fmac_f32_e32 v125, s44, v157
	global_store_dwordx4 v[140:141], v[122:125], off offset:0
	v_lshlrev_b32_e32 v216, 16, v158
	v_and_b32_e32 v158, 0xffff0000, v158
	v_lshlrev_b32_e32 v217, 16, v159
	v_and_b32_e32 v159, 0xffff0000, v159
	v_fmac_f32_e32 v90, s44, v216
	v_fmac_f32_e32 v91, s44, v158
	v_fmac_f32_e32 v92, s44, v217
	v_fmac_f32_e32 v93, s44, v159
	global_store_dwordx4 v[140:141], v[90:93], off offset:64
	s_waitcnt vmcnt(18)
	v_permlane16_swap_b32_e32 v162, v164
	v_permlane16_swap_b32_e32 v163, v165
	v_lshlrev_b32_e32 v216, 16, v162
	v_and_b32_e32 v162, 0xffff0000, v162
	v_lshlrev_b32_e32 v217, 16, v163
	v_and_b32_e32 v163, 0xffff0000, v163
	v_fmac_f32_e32 v58, s44, v216
	v_fmac_f32_e32 v59, s44, v162
	v_fmac_f32_e32 v60, s44, v217
	v_fmac_f32_e32 v61, s44, v163
	global_store_dwordx4 v[140:141], v[58:61], off offset:128
	v_lshlrev_b32_e32 v216, 16, v164
	v_and_b32_e32 v164, 0xffff0000, v164
	v_lshlrev_b32_e32 v217, 16, v165
	v_and_b32_e32 v165, 0xffff0000, v165
	v_fmac_f32_e32 v26, s44, v216
	v_fmac_f32_e32 v27, s44, v164
	v_fmac_f32_e32 v28, s44, v217
	v_fmac_f32_e32 v29, s44, v165
	global_store_dwordx4 v[140:141], v[26:29], off offset:192
	v_lshl_add_u64 v[140:141], v[140:141], 0, s[10:11]
	s_waitcnt vmcnt(19)
	v_permlane16_swap_b32_e32 v166, v168
	v_permlane16_swap_b32_e32 v167, v169
	v_lshlrev_b32_e32 v216, 16, v166
	v_and_b32_e32 v166, 0xffff0000, v166
	v_lshlrev_b32_e32 v217, 16, v167
	v_and_b32_e32 v167, 0xffff0000, v167
	v_fmac_f32_e32 v118, s44, v216
	v_fmac_f32_e32 v119, s44, v166
	v_fmac_f32_e32 v120, s44, v217
	v_fmac_f32_e32 v121, s44, v167
	global_store_dwordx4 v[140:141], v[118:121], off offset:0
	v_lshlrev_b32_e32 v216, 16, v168
	v_and_b32_e32 v168, 0xffff0000, v168
	v_lshlrev_b32_e32 v217, 16, v169
	v_and_b32_e32 v169, 0xffff0000, v169
	v_fmac_f32_e32 v86, s44, v216
	v_fmac_f32_e32 v87, s44, v168
	v_fmac_f32_e32 v88, s44, v217
	v_fmac_f32_e32 v89, s44, v169
	global_store_dwordx4 v[140:141], v[86:89], off offset:64
	s_waitcnt vmcnt(20)
; DEVI float blo(unsigned u) { return __uint_as_float(u << 16); }
; DEVI float bhi(unsigned u) { return __uint_as_float(u & 0xffff0000u); }
;     ...
;         if (EPI == EPI_RESID || EPI == EPI_RESID_ATOMIC) {
;           f32x4 x = a;
;           if (EPI == EPI_RESID || kpart == 0) {
;             const u32x2 xr = *(const u32x2*)((const u16*)(p.ws + WS_XB) + (size_t)row * 1024 + col);
;             x[0] += ALPHA * blo(xr[0]); x[1] += ALPHA * bhi(xr[0]); x[2] += ALPHA * blo(xr[1]); x[3] += ALPHA * bhi(xr[1]);
;           }
;           if (EPI == EPI_RESID) *(f32x4*)((float*)(p.ws + WS_XF) + (size_t)row * 1024 + col) = x;
	v_permlane16_swap_b32_e32 v170, v172
	v_permlane16_swap_b32_e32 v171, v173
	v_lshlrev_b32_e32 v216, 16, v170
	v_and_b32_e32 v170, 0xffff0000, v170
	v_lshlrev_b32_e32 v217, 16, v171
	v_and_b32_e32 v171, 0xffff0000, v171
	v_fmac_f32_e32 v54, s44, v216
	v_fmac_f32_e32 v55, s44, v170
	v_fmac_f32_e32 v56, s44, v217
	v_fmac_f32_e32 v57, s44, v171
	global_store_dwordx4 v[140:141], v[54:57], off offset:128
	v_lshlrev_b32_e32 v216, 16, v172
	v_and_b32_e32 v172, 0xffff0000, v172
	v_lshlrev_b32_e32 v217, 16, v173
	v_and_b32_e32 v173, 0xffff0000, v173
	v_fmac_f32_e32 v22, s44, v216
	v_fmac_f32_e32 v23, s44, v172
	v_fmac_f32_e32 v24, s44, v217
	v_fmac_f32_e32 v25, s44, v173
	global_store_dwordx4 v[140:141], v[22:25], off offset:192
	v_lshl_add_u64 v[140:141], v[140:141], 0, s[10:11]
	s_waitcnt vmcnt(21)
	v_permlane16_swap_b32_e32 v176, v178
	v_permlane16_swap_b32_e32 v177, v179
	v_lshlrev_b32_e32 v216, 16, v176
	v_and_b32_e32 v176, 0xffff0000, v176
	v_lshlrev_b32_e32 v217, 16, v177
	v_and_b32_e32 v177, 0xffff0000, v177
	v_fmac_f32_e32 v114, s44, v216
	v_fmac_f32_e32 v115, s44, v176
	v_fmac_f32_e32 v116, s44, v217
	v_fmac_f32_e32 v117, s44, v177
	global_store_dwordx4 v[140:141], v[114:117], off offset:0
	v_lshlrev_b32_e32 v216, 16, v178
	v_and_b32_e32 v178, 0xffff0000, v178
	v_lshlrev_b32_e32 v217, 16, v179
	v_and_b32_e32 v179, 0xffff0000, v179
	v_fmac_f32_e32 v82, s44, v216
	v_fmac_f32_e32 v83, s44, v178
	v_fmac_f32_e32 v84, s44, v217
	v_fmac_f32_e32 v85, s44, v179
	global_store_dwordx4 v[140:141], v[82:85], off offset:64
	s_waitcnt vmcnt(22)
	v_permlane16_swap_b32_e32 v180, v182
	v_permlane16_swap_b32_e32 v181, v183
	v_lshlrev_b32_e32 v216, 16, v180
	v_and_b32_e32 v180, 0xffff0000, v180
	v_lshlrev_b32_e32 v217, 16, v181
	v_and_b32_e32 v181, 0xffff0000, v181
	v_fmac_f32_e32 v50, s44, v216
	v_fmac_f32_e32 v51, s44, v180
	v_fmac_f32_e32 v52, s44, v217
	v_fmac_f32_e32 v53, s44, v181
	global_store_dwordx4 v[140:141], v[50:53], off offset:128
	v_lshlrev_b32_e32 v216, 16, v182
	v_and_b32_e32 v182, 0xffff0000, v182
	v_lshlrev_b32_e32 v217, 16, v183
	v_and_b32_e32 v183, 0xffff0000, v183
	v_fmac_f32_e32 v18, s44, v216
	v_fmac_f32_e32 v19, s44, v182
	v_fmac_f32_e32 v20, s44, v217
	v_fmac_f32_e32 v21, s44, v183
	global_store_dwordx4 v[140:141], v[18:21], off offset:192
	v_lshl_add_u64 v[140:141], v[140:141], 0, s[10:11]
	s_waitcnt vmcnt(23)
	v_permlane16_swap_b32_e32 v184, v186
	v_permlane16_swap_b32_e32 v185, v187
	v_lshlrev_b32_e32 v216, 16, v184
	v_and_b32_e32 v184, 0xffff0000, v184
	v_lshlrev_b32_e32 v217, 16, v185
	v_and_b32_e32 v185, 0xffff0000, v185
	v_fmac_f32_e32 v110, s44, v216
	v_fmac_f32_e32 v111, s44, v184
	v_fmac_f32_e32 v112, s44, v217
	v_fmac_f32_e32 v113, s44, v185
	global_store_dwordx4 v[140:141], v[110:113], off offset:0
	v_lshlrev_b32_e32 v216, 16, v186
	v_and_b32_e32 v186, 0xffff0000, v186
	v_lshlrev_b32_e32 v217, 16, v187
	v_and_b32_e32 v187, 0xffff0000, v187
	v_fmac_f32_e32 v78, s44, v216
	v_fmac_f32_e32 v79, s44, v186
	v_fmac_f32_e32 v80, s44, v217
	v_fmac_f32_e32 v81, s44, v187
	global_store_dwordx4 v[140:141], v[78:81], off offset:64
	s_waitcnt vmcnt(24)
	v_permlane16_swap_b32_e32 v188, v190
	v_permlane16_swap_b32_e32 v189, v191
	v_lshlrev_b32_e32 v216, 16, v188
	v_and_b32_e32 v188, 0xffff0000, v188
	v_lshlrev_b32_e32 v217, 16, v189
	v_and_b32_e32 v189, 0xffff0000, v189
	v_fmac_f32_e32 v46, s44, v216
	v_fmac_f32_e32 v47, s44, v188
	v_fmac_f32_e32 v48, s44, v217
	v_fmac_f32_e32 v49, s44, v189
	global_store_dwordx4 v[140:141], v[46:49], off offset:128
	v_lshlrev_b32_e32 v216, 16, v190
	v_and_b32_e32 v190, 0xffff0000, v190
	v_lshlrev_b32_e32 v217, 16, v191
	v_and_b32_e32 v191, 0xffff0000, v191
	v_fmac_f32_e32 v14, s44, v216
	v_fmac_f32_e32 v15, s44, v190
	v_fmac_f32_e32 v16, s44, v217
	v_fmac_f32_e32 v17, s44, v191
	global_store_dwordx4 v[140:141], v[14:17], off offset:192
	v_lshl_add_u64 v[140:141], v[140:141], 0, s[10:11]
	s_waitcnt vmcnt(25)
	v_permlane16_swap_b32_e32 v192, v194
	v_permlane16_swap_b32_e32 v193, v195
	v_lshlrev_b32_e32 v216, 16, v192
	v_and_b32_e32 v192, 0xffff0000, v192
	v_lshlrev_b32_e32 v217, 16, v193
	v_and_b32_e32 v193, 0xffff0000, v193
	v_fmac_f32_e32 v106, s44, v216
	v_fmac_f32_e32 v107, s44, v192
	v_fmac_f32_e32 v108, s44, v217
	v_fmac_f32_e32 v109, s44, v193
	global_store_dwordx4 v[140:141], v[106:109], off offset:0
	v_lshlrev_b32_e32 v216, 16, v194
	v_and_b32_e32 v194, 0xffff0000, v194
	v_lshlrev_b32_e32 v217, 16, v195
	v_and_b32_e32 v195, 0xffff0000, v195
	v_fmac_f32_e32 v74, s44, v216
	v_fmac_f32_e32 v75, s44, v194
	v_fmac_f32_e32 v76, s44, v217
	v_fmac_f32_e32 v77, s44, v195
	global_store_dwordx4 v[140:141], v[74:77], off offset:64
	s_waitcnt vmcnt(26)
; DEVI float blo(unsigned u) { return __uint_as_float(u << 16); }
; DEVI float bhi(unsigned u) { return __uint_as_float(u & 0xffff0000u); }
; DEVI int xcd_first_tile() { return (blockIdx.x & 7) * (gridDim.x >> 3) + (blockIdx.x >> 3); }
;     ...
;         if (EPI == EPI_RESID || EPI == EPI_RESID_ATOMIC) {
;           f32x4 x = a;
;           if (EPI == EPI_RESID || kpart == 0) {
;             const u32x2 xr = *(const u32x2*)((const u16*)(p.ws + WS_XB) + (size_t)row * 1024 + col);
;             x[0] += ALPHA * blo(xr[0]); x[1] += ALPHA * bhi(xr[0]); x[2] += ALPHA * blo(xr[1]); x[3] += ALPHA * bhi(xr[1]);
;           }
;           if (EPI == EPI_RESID) *(f32x4*)((float*)(p.ws + WS_XF) + (size_t)row * 1024 + col) = x;
;           else *(f32x4*)((float*)(p.ws + WS_SLAB) + ((size_t)kpart * 512 + (row - T_P)) * 1024 + col) = x;
; DEVI void run_phase(const Params& p, int ph, char* smem) {
;     ...
;       for (int t = xcd_first_tile(); t < 512 + 16 * 11; t += xcd_tile_step()) {
;         if (t < 512) {
;           int mt_, nt_; tile_coords(t, 64, 8, mt_, nt_);
;           gemm_tile256<EPI_RESID>(p, hb, DFF, Bt, DFF, mt_ * 256, nt_ * 128, nullptr, 0, smem);
;         } else {
;           const int u_ = t - 512, tl_ = u_ / 11, q_ = u_ - tl_ * 11;
;           gemm_tile256<EPI_RESID_ATOMIC>(p, hb, DFF, Bt, DFF, (64 + (tl_ & 1)) * 256, (tl_ >> 1) * 128, nullptr, 0, smem, q_ * 256, 8, q_);
;         }
	v_permlane16_swap_b32_e32 v196, v198
	v_permlane16_swap_b32_e32 v197, v199
	v_lshlrev_b32_e32 v216, 16, v196
	v_and_b32_e32 v196, 0xffff0000, v196
	v_lshlrev_b32_e32 v217, 16, v197
	v_and_b32_e32 v197, 0xffff0000, v197
	v_fmac_f32_e32 v42, s44, v216
	v_fmac_f32_e32 v43, s44, v196
	v_fmac_f32_e32 v44, s44, v217
	v_fmac_f32_e32 v45, s44, v197
	global_store_dwordx4 v[140:141], v[42:45], off offset:128
	v_lshlrev_b32_e32 v216, 16, v198
	v_and_b32_e32 v198, 0xffff0000, v198
	v_lshlrev_b32_e32 v217, 16, v199
	v_and_b32_e32 v199, 0xffff0000, v199
	v_fmac_f32_e32 v10, s44, v216
	v_fmac_f32_e32 v11, s44, v198
	v_fmac_f32_e32 v12, s44, v217
	v_fmac_f32_e32 v13, s44, v199
	global_store_dwordx4 v[140:141], v[10:13], off offset:192
	v_lshl_add_u64 v[140:141], v[140:141], 0, s[10:11]
	s_waitcnt vmcnt(27)
	v_permlane16_swap_b32_e32 v200, v202
	v_permlane16_swap_b32_e32 v201, v203
	v_lshlrev_b32_e32 v216, 16, v200
	v_and_b32_e32 v200, 0xffff0000, v200
	v_lshlrev_b32_e32 v217, 16, v201
	v_and_b32_e32 v201, 0xffff0000, v201
	v_fmac_f32_e32 v102, s44, v216
	v_fmac_f32_e32 v103, s44, v200
	v_fmac_f32_e32 v104, s44, v217
	v_fmac_f32_e32 v105, s44, v201
	global_store_dwordx4 v[140:141], v[102:105], off offset:0
	v_lshlrev_b32_e32 v216, 16, v202
	v_and_b32_e32 v202, 0xffff0000, v202
	v_lshlrev_b32_e32 v217, 16, v203
	v_and_b32_e32 v203, 0xffff0000, v203
	v_fmac_f32_e32 v70, s44, v216
	v_fmac_f32_e32 v71, s44, v202
	v_fmac_f32_e32 v72, s44, v217
	v_fmac_f32_e32 v73, s44, v203
	global_store_dwordx4 v[140:141], v[70:73], off offset:64
	s_waitcnt vmcnt(28)
	v_permlane16_swap_b32_e32 v204, v206
	v_permlane16_swap_b32_e32 v205, v207
	v_lshlrev_b32_e32 v216, 16, v204
	v_and_b32_e32 v204, 0xffff0000, v204
	v_lshlrev_b32_e32 v217, 16, v205
	v_and_b32_e32 v205, 0xffff0000, v205
	v_fmac_f32_e32 v38, s44, v216
	v_fmac_f32_e32 v39, s44, v204
	v_fmac_f32_e32 v40, s44, v217
	v_fmac_f32_e32 v41, s44, v205
	global_store_dwordx4 v[140:141], v[38:41], off offset:128
	v_lshlrev_b32_e32 v216, 16, v206
	v_and_b32_e32 v206, 0xffff0000, v206
	v_lshlrev_b32_e32 v217, 16, v207
	v_and_b32_e32 v207, 0xffff0000, v207
	v_fmac_f32_e32 v6, s44, v216
	v_fmac_f32_e32 v7, s44, v206
	v_fmac_f32_e32 v8, s44, v217
	v_fmac_f32_e32 v9, s44, v207
	global_store_dwordx4 v[140:141], v[6:9], off offset:192
	v_lshl_add_u64 v[140:141], v[140:141], 0, s[10:11]
	s_waitcnt vmcnt(29)
	v_permlane16_swap_b32_e32 v208, v210
	v_permlane16_swap_b32_e32 v209, v211
	v_lshlrev_b32_e32 v216, 16, v208
	v_and_b32_e32 v208, 0xffff0000, v208
	v_lshlrev_b32_e32 v217, 16, v209
	v_and_b32_e32 v209, 0xffff0000, v209
	v_fmac_f32_e32 v98, s44, v216
	v_fmac_f32_e32 v99, s44, v208
	v_fmac_f32_e32 v100, s44, v217
	v_fmac_f32_e32 v101, s44, v209
	global_store_dwordx4 v[140:141], v[98:101], off offset:0
	v_lshlrev_b32_e32 v216, 16, v210
	v_and_b32_e32 v210, 0xffff0000, v210
	v_lshlrev_b32_e32 v217, 16, v211
	v_and_b32_e32 v211, 0xffff0000, v211
	v_fmac_f32_e32 v66, s44, v216
	v_fmac_f32_e32 v67, s44, v210
	v_fmac_f32_e32 v68, s44, v217
	v_fmac_f32_e32 v69, s44, v211
	global_store_dwordx4 v[140:141], v[66:69], off offset:64
	s_waitcnt vmcnt(30)
	v_permlane16_swap_b32_e32 v212, v214
	v_permlane16_swap_b32_e32 v213, v215
	v_lshlrev_b32_e32 v216, 16, v212
	v_and_b32_e32 v212, 0xffff0000, v212
	v_lshlrev_b32_e32 v217, 16, v213
	v_and_b32_e32 v213, 0xffff0000, v213
	v_fmac_f32_e32 v34, s44, v216
	v_fmac_f32_e32 v35, s44, v212
	v_fmac_f32_e32 v36, s44, v217
	v_fmac_f32_e32 v37, s44, v213
	global_store_dwordx4 v[140:141], v[34:37], off offset:128
	v_lshlrev_b32_e32 v216, 16, v214
	v_and_b32_e32 v214, 0xffff0000, v214
	v_lshlrev_b32_e32 v217, 16, v215
	v_and_b32_e32 v215, 0xffff0000, v215
	v_fmac_f32_e32 v2, s44, v216
	v_fmac_f32_e32 v3, s44, v214
	v_fmac_f32_e32 v4, s44, v217
	v_fmac_f32_e32 v5, s44, v215
	global_store_dwordx4 v[140:141], v[2:5], off offset:192
	v_readlane_b32 s39, v250, 7
	s_cmpk_lg_u32 s39, 0x200
	s_cbranch_scc1 .Lta11_ar2
	s_mov_b32 s39, 1
	v_writelane_b32 v255, s39, 41
	v_readlane_b32 s40, v250, 0
	s_lshr_b32 s41, s40, 3
	s_and_b32 s40, s40, 7
	s_lshl_b32 s40, s40, 6
	s_add_i32 s40, s40, s41
	s_sub_i32 s38, s40, 0x200

; #define LAS __attribute__((address_space(3)))
; DEVI int xcd_first_tile() { return (blockIdx.x & 7) * (gridDim.x >> 3) + (blockIdx.x >> 3); }
;     ...
;   const int nk = (nk_part < 0) ? (K >> 5) : nk_part;
;   const int lrow = tid >> 2, lpc = tid & 3;
;   const int lch = lpc ^ ((0x78 >> (((lrow >> 2) & 3) * 2)) & 3);
;   const u16* ga = A + (size_t)(m0 + lrow) * lda + kbeg + lch * 8;
;   const u16* gb = Bt + (size_t)(n0 + lrow) * K + kbeg + lch * 8;
;   const size_t ga1 = (size_t)64 * lda, gb1 = (size_t)64 * K;
;   const unsigned lds0 = (unsigned)(uintptr_t)(LAS char*)smem + (unsigned)__builtin_amdgcn_readfirstlane(wid) * 1024u;
;     ...
;   __syncthreads();
;   G2_STAGE(0); G2_STAGE(1);
;   const int fsw = (0x78 >> (((r16 >> 2) & 3) * 2)) & 3;
;   const int aoff = (wm * 128 + r16) * 64 + ((quad ^ fsw) << 4);
;   const int boff = 16384 + (wn * 64 + r16) * 64 + ((quad ^ fsw) << 4);
; DEVI void run_phase(const Params& p, int ph, char* smem) {
;     ...
;       for (int t = xcd_first_tile(); t < 512 + 16 * 11; t += xcd_tile_step()) {
;         if (t < 512) {
;           int mt_, nt_; tile_coords(t, 64, 8, mt_, nt_);
;           gemm_tile256<EPI_RESID>(p, hb, DFF, Bt, DFF, mt_ * 256, nt_ * 128, nullptr, 0, smem);
;         } else {
;           const int u_ = t - 512, tl_ = u_ / 11, q_ = u_ - tl_ * 11;
;           gemm_tile256<EPI_RESID_ATOMIC>(p, hb, DFF, Bt, DFF, (64 + (tl_ & 1)) * 256, (tl_ >> 1) * 128, nullptr, 0, smem, q_ * 256, 8, q_);
.LBB0_116:
	s_and_b64 vcc, exec, s[2:3]
	s_cbranch_vccz .LBB0_41
	v_readlane_b32 s39, v250, 7
	s_cmpk_lg_u32 s39, 0x200
	s_cbranch_scc1 .Lt11_go
	v_readlane_b32 s40, v255, 41
	s_cmp_lg_u32 s40, 0
	s_cbranch_scc1 .Lt11_go
	v_readlane_b32 s40, v250, 0
	s_lshr_b32 s41, s40, 3
	s_cmp_lt_u32 s41, 22
	s_cbranch_scc0 .Lt11_go
	s_and_b32 s40, s40, 7
	s_mul_i32 s40, s40, 22
	s_add_i32 s38, s40, s41
	s_branch .LBB0_41
.Lt11_go:
	s_lshr_b32 s45, s38, 6
	s_and_b32 s46, s38, 63
	s_lshr_b32 s42, s46, 3
	s_and_b32 s46, s46, 7
	s_lshl_b32 s45, s45, 3
	s_add_i32 s45, s45, s46
	s_cmp_lt_u32 s45, 64
	s_cselect_b32 s44, 1, 0
	v_readlane_b32 s2, v250, 5
	v_readlane_b32 s3, v250, 6
	v_readlane_b32 s46, v254, 62
	s_mul_i32 s40, s45, 0x160000
	s_add_u32 s4, s2, s40
	s_addc_u32 s5, s3, 0
	s_add_u32 s4, s4, 0xef40000
	s_addc_u32 s5, s5, 0
	s_mul_i32 s40, s46, 0x580000
	s_mul_i32 s41, s42, 0xb0000
	s_add_i32 s40, s40, s41
	s_add_u32 s10, s2, s40
	s_addc_u32 s11, s3, 0
	s_add_u32 s10, s10, 0x19a00000
	s_addc_u32 s11, s11, 0
	s_movk_i32 s39, 0x78
	v_lshrrev_b32_e32 v0, 2, v145
	v_and_b32_e32 v131, 3, v145
	v_bfe_u32 v136, v145, 4, 2
	v_lshlrev_b32_e32 v136, 1, v136
	v_lshrrev_b32_e64 v136, v136, s39
	v_and_b32_e32 v136, 3, v136
	v_xor_b32_e32 v131, v131, v136
	v_lshlrev_b32_e32 v131, 4, v131
	s_movk_i32 s41, 0x1600
	v_mad_u32_u24 v0, v0, s41, v131
	v_bfe_u32 v137, v145, 2, 1
	s_movk_i32 s41, 0x15c0
	v_mul_u32_u24_e32 v136, s41, v137
	v_sub_u32_e32 v136, v0, v136
	v_mov_b32_e32 v137, 0
	v_lshl_add_u64 v[134:135], s[10:11], 0, v[136:137]
	v_bfe_u32 v137, v145, 2, 1
	s_mul_i32 s41, s44, 0x15c0
	v_mul_u32_u24_e32 v136, s41, v137
	v_sub_u32_e32 v0, v0, v136
	s_lshl_b32 s12, s44, 6
	s_add_i32 s12, s12, 64
	s_mov_b32 s13, 0
	v_lshl_add_u64 v[132:133], s[4:5], 0, v[0:1]
	v_bfe_u32 v136, v145, 2, 2
	v_lshlrev_b32_e32 v136, 1, v136
	v_lshrrev_b32_e64 v136, v136, s39
	v_and_b32_e32 v136, 3, v136
	v_bfe_u32 v137, v145, 4, 2
	v_xor_b32_e32 v136, v136, v137
	v_lshlrev_b32_e32 v136, 4, v136
	v_and_b32_e32 v131, 15, v145
	v_lshl_or_b32 v136, v131, 6, v136
	v_bfe_u32 v137, v145, 6, 1
	v_lshl_or_b32 v137, v137, 12, v136
	v_lshrrev_b32_e32 v0, 7, v145
	v_lshl_or_b32 v136, v0, 13, v136
	v_and_b32_e32 v140, 1, v131
	v_lshl_or_b32 v131, v0, 7, v131
	v_bfe_u32 v0, v145, 4, 2
	v_lshlrev_b32_e32 v0, 3, v0
	v_bfe_u32 v141, v145, 6, 1
	s_lshl_b32 s40, s45, 19
	s_lshl_b32 s41, s42, 9
	s_add_i32 s40, s40, s41
	s_add_u32 s4, s2, s40
	s_addc_u32 s5, s3, 0
	s_add_u32 s4, s4, 0x4200000
	s_addc_u32 s5, s5, 0
	v_lshlrev_b32_e32 v138, 11, v131
	v_lshl_add_u32 v138, v141, 8, v138
	v_bfe_u32 v139, v145, 4, 1
	v_lshl_add_u32 v138, v139, 5, v138
	v_bfe_u32 v139, v145, 5, 1
	v_lshl_add_u32 v138, v139, 4, v138
	s_movk_i32 s41, 1984
	v_mul_u32_u24_e32 v139, s41, v140
	v_sub_u32_e32 v138, v138, v139
	v_mov_b32_e32 v139, 0
	v_lshl_add_u64 v[138:139], s[4:5], 0, v[138:139]
	s_lshl_b32 s40, s45, 20
	s_lshl_b32 s41, s42, 9
	s_add_i32 s40, s40, s41
	s_add_u32 s10, s2, s40
	s_addc_u32 s11, s3, 0
	v_lshlrev_b32_e32 v140, 12, v131
	v_lshl_add_u32 v140, v141, 8, v140
	v_lshl_add_u32 v140, v0, 1, v140
	v_mov_b32_e32 v141, 0
	v_lshl_add_u64 v[140:141], s[10:11], 0, v[140:141]
	s_mov_b32 s2, 0x58000
	s_mov_b32 s3, 0
	v_lshrrev_b32_e32 v0, 6, v145
	v_lshlrev_b32_e32 v0, 10, v0
	s_nop 0
	v_readfirstlane_b32 s46, v0
	s_mov_b32 s43, m0
	s_mov_b32 s4, 128
	s_mov_b32 s5, 0
	s_barrier
	s_add_i32 s42, s46, 0x0
	s_mov_b32 m0, s42
	v_lshl_add_u64 v[142:143], v[132:133], 0, s[2:3]
	global_load_lds_dwordx4 v[132:133], off
	s_add_i32 m0, m0, 0x1000
	s_nop 0
	global_load_lds_dwordx4 v[142:143], off
	v_lshl_add_u64 v[142:143], v[142:143], 0, s[2:3]
	s_add_i32 m0, m0, 0x1000
	s_nop 0
	global_load_lds_dwordx4 v[142:143], off
	v_lshl_add_u64 v[142:143], v[142:143], 0, s[2:3]
	s_add_i32 m0, m0, 0x1000
	s_nop 0
	global_load_lds_dwordx4 v[142:143], off
	s_add_i32 m0, m0, 0x1000
	v_lshl_add_u64 v[142:143], v[134:135], 0, s[2:3]
	s_nop 0
	global_load_lds_dwordx4 v[134:135], off
	s_add_i32 m0, m0, 0x1000
	v_lshl_add_u64 v[132:133], v[132:133], 0, s[12:13]
	s_nop 0
	global_load_lds_dwordx4 v[142:143], off
	v_lshl_add_u64 v[134:135], v[134:135], 0, s[4:5]
	s_nop 0
	s_add_i32 s42, s46, 0x6000
	s_mov_b32 m0, s42
	v_lshl_add_u64 v[142:143], v[132:133], 0, s[2:3]
	global_load_lds_dwordx4 v[132:133], off
	s_add_i32 m0, m0, 0x1000
	s_nop 0
	global_load_lds_dwordx4 v[142:143], off
	v_lshl_add_u64 v[142:143], v[142:143], 0, s[2:3]
	s_add_i32 m0, m0, 0x1000
	s_nop 0
	global_load_lds_dwordx4 v[142:143], off
	v_lshl_add_u64 v[142:143], v[142:143], 0, s[2:3]
	s_add_i32 m0, m0, 0x1000
	s_nop 0
	global_load_lds_dwordx4 v[142:143], off
	s_add_i32 m0, m0, 0x1000
	v_lshl_add_u64 v[142:143], v[134:135], 0, s[2:3]
	s_nop 0
	global_load_lds_dwordx4 v[134:135], off
	s_add_i32 m0, m0, 0x1000
	v_lshl_add_u64 v[132:133], v[132:133], 0, s[12:13]
	s_nop 0
	global_load_lds_dwordx4 v[142:143], off
	v_lshl_add_u64 v[134:135], v[134:135], 0, s[4:5]
	s_nop 0
	s_add_i32 s42, s46, 0xc000
	s_mov_b32 m0, s42
	v_lshl_add_u64 v[142:143], v[132:133], 0, s[2:3]
	global_load_lds_dwordx4 v[132:133], off
	s_add_i32 m0, m0, 0x1000
	s_nop 0
	global_load_lds_dwordx4 v[142:143], off
	v_lshl_add_u64 v[142:143], v[142:143], 0, s[2:3]
	s_add_i32 m0, m0, 0x1000
	s_nop 0
	global_load_lds_dwordx4 v[142:143], off
	v_lshl_add_u64 v[142:143], v[142:143], 0, s[2:3]
	s_add_i32 m0, m0, 0x1000
	s_nop 0
	global_load_lds_dwordx4 v[142:143], off
	s_add_i32 m0, m0, 0x1000
	v_lshl_add_u64 v[142:143], v[134:135], 0, s[2:3]
	s_nop 0
	global_load_lds_dwordx4 v[134:135], off
	s_add_i32 m0, m0, 0x1000
	v_lshl_add_u64 v[132:133], v[132:133], 0, s[12:13]
	s_nop 0
	global_load_lds_dwordx4 v[142:143], off
; #define LAS __attribute__((address_space(3)))
;     ...
;   f32x4 acc[4][8];
; #pragma unroll
;   for (int i = 0; i < 4; i++)
; #pragma unroll
;     for (int j = 0; j < 8; j++) acc[i][j] = (f32x4){0.f, 0.f, 0.f, 0.f};
;   const int nk = (nk_part < 0) ? (K >> 5) : nk_part;
;   const int lrow = tid >> 2, lpc = tid & 3;
;   const int lch = lpc ^ ((0x78 >> (((lrow >> 2) & 3) * 2)) & 3);
;   const u16* ga = A + (size_t)(m0 + lrow) * lda + kbeg + lch * 8;
;   const u16* gb = Bt + (size_t)(n0 + lrow) * K + kbeg + lch * 8;
;   const size_t ga1 = (size_t)64 * lda, gb1 = (size_t)64 * K;
;   const unsigned lds0 = (unsigned)(uintptr_t)(LAS char*)smem + (unsigned)__builtin_amdgcn_readfirstlane(wid) * 1024u;
;     ...
;   __syncthreads();
;   G2_STAGE(0); G2_STAGE(1);
;   const int fsw = (0x78 >> (((r16 >> 2) & 3) * 2)) & 3;
;   const int aoff = (wm * 128 + r16) * 64 + ((quad ^ fsw) << 4);
;   const int boff = 16384 + (wn * 64 + r16) * 64 + ((quad ^ fsw) << 4);
;   for (int kt = 0; kt < nk; kt++) {
;     if (kt + 1 < nk) asm volatile("s_waitcnt vmcnt(6)" ::: "memory");
;     else asm volatile("s_waitcnt vmcnt(0)" ::: "memory");
;     __builtin_amdgcn_s_barrier();
;     asm volatile("" ::: "memory");
;     if (kt + 2 < nk) G2_STAGE(kt + 2);
;     const char* cS = smem + (kt % 3) * 24576;
;     bf16x8 xa[8], wb[4];
; #pragma unroll
;     for (int f = 0; f < 8; f++) xa[f] = *(const bf16x8*)(cS + aoff + f * 1024);
; #pragma unroll
;     for (int f = 0; f < 4; f++) wb[f] = *(const bf16x8*)(cS + boff + f * 1024);
; #pragma unroll
;     for (int nf = 0; nf < 4; nf++)
; #pragma unroll
;       for (int mf = 0; mf < 8; mf++)
;         acc[nf][mf] = __builtin_amdgcn_mfma_f32_16x16x32_bf16(wb[nf], xa[mf], acc[nf][mf], 0, 0, 0);
	v_lshl_add_u64 v[134:135], v[134:135], 0, s[4:5]
	s_nop 0
	v_mov_b32_e32 v2, 0
	v_mov_b32_e32 v3, 0
	v_mov_b32_e32 v4, 0
	v_mov_b32_e32 v5, 0
	v_mov_b32_e32 v6, 0
	v_mov_b32_e32 v7, 0
	v_mov_b32_e32 v8, 0
	v_mov_b32_e32 v9, 0
	v_mov_b32_e32 v10, 0
	v_mov_b32_e32 v11, 0
	v_mov_b32_e32 v12, 0
	v_mov_b32_e32 v13, 0
	v_mov_b32_e32 v14, 0
	v_mov_b32_e32 v15, 0
	v_mov_b32_e32 v16, 0
	v_mov_b32_e32 v17, 0
	v_mov_b32_e32 v18, 0
	v_mov_b32_e32 v19, 0
	v_mov_b32_e32 v20, 0
	v_mov_b32_e32 v21, 0
	v_mov_b32_e32 v22, 0
	v_mov_b32_e32 v23, 0
	v_mov_b32_e32 v24, 0
	v_mov_b32_e32 v25, 0
	v_mov_b32_e32 v26, 0
	v_mov_b32_e32 v27, 0
	v_mov_b32_e32 v28, 0
	v_mov_b32_e32 v29, 0
	v_mov_b32_e32 v30, 0
	v_mov_b32_e32 v31, 0
	v_mov_b32_e32 v32, 0
	v_mov_b32_e32 v33, 0
	v_mov_b32_e32 v34, 0
	v_mov_b32_e32 v35, 0
	v_mov_b32_e32 v36, 0
	v_mov_b32_e32 v37, 0
	v_mov_b32_e32 v38, 0
	v_mov_b32_e32 v39, 0
	v_mov_b32_e32 v40, 0
	v_mov_b32_e32 v41, 0
	v_mov_b32_e32 v42, 0
	v_mov_b32_e32 v43, 0
	v_mov_b32_e32 v44, 0
	v_mov_b32_e32 v45, 0
	v_mov_b32_e32 v46, 0
	v_mov_b32_e32 v47, 0
	v_mov_b32_e32 v48, 0
	v_mov_b32_e32 v49, 0
	v_mov_b32_e32 v50, 0
	v_mov_b32_e32 v51, 0
	v_mov_b32_e32 v52, 0
	v_mov_b32_e32 v53, 0
	v_mov_b32_e32 v54, 0
	v_mov_b32_e32 v55, 0
	v_mov_b32_e32 v56, 0
	v_mov_b32_e32 v57, 0
	v_mov_b32_e32 v58, 0
	v_mov_b32_e32 v59, 0
	v_mov_b32_e32 v60, 0
	v_mov_b32_e32 v61, 0
	v_mov_b32_e32 v62, 0
	v_mov_b32_e32 v63, 0
	v_mov_b32_e32 v64, 0
	v_mov_b32_e32 v65, 0
	v_mov_b32_e32 v66, 0
	v_mov_b32_e32 v67, 0
	v_mov_b32_e32 v68, 0
	v_mov_b32_e32 v69, 0
	v_mov_b32_e32 v70, 0
	v_mov_b32_e32 v71, 0
	v_mov_b32_e32 v72, 0
	v_mov_b32_e32 v73, 0
	v_mov_b32_e32 v74, 0
	v_mov_b32_e32 v75, 0
	v_mov_b32_e32 v76, 0
	v_mov_b32_e32 v77, 0
	v_mov_b32_e32 v78, 0
	v_mov_b32_e32 v79, 0
	v_mov_b32_e32 v80, 0
	v_mov_b32_e32 v81, 0
	v_mov_b32_e32 v82, 0
	v_mov_b32_e32 v83, 0
	v_mov_b32_e32 v84, 0
	v_mov_b32_e32 v85, 0
	v_mov_b32_e32 v86, 0
	v_mov_b32_e32 v87, 0
	v_mov_b32_e32 v88, 0
	v_mov_b32_e32 v89, 0
	v_mov_b32_e32 v90, 0
	v_mov_b32_e32 v91, 0
	v_mov_b32_e32 v92, 0
	v_mov_b32_e32 v93, 0
	v_mov_b32_e32 v94, 0
	v_mov_b32_e32 v95, 0
	v_mov_b32_e32 v96, 0
	v_mov_b32_e32 v97, 0
	v_mov_b32_e32 v98, 0
	v_mov_b32_e32 v99, 0
	v_mov_b32_e32 v100, 0
	v_mov_b32_e32 v101, 0
	v_mov_b32_e32 v102, 0
	v_mov_b32_e32 v103, 0
	v_mov_b32_e32 v104, 0
	v_mov_b32_e32 v105, 0
	v_mov_b32_e32 v106, 0
	v_mov_b32_e32 v107, 0
	v_mov_b32_e32 v108, 0
	v_mov_b32_e32 v109, 0
	v_mov_b32_e32 v110, 0
	v_mov_b32_e32 v111, 0
	v_mov_b32_e32 v112, 0
	v_mov_b32_e32 v113, 0
	v_mov_b32_e32 v114, 0
	v_mov_b32_e32 v115, 0
	v_mov_b32_e32 v116, 0
	v_mov_b32_e32 v117, 0
	v_mov_b32_e32 v118, 0
	v_mov_b32_e32 v119, 0
	v_mov_b32_e32 v120, 0
	v_mov_b32_e32 v121, 0
	v_mov_b32_e32 v122, 0
	v_mov_b32_e32 v123, 0
	v_mov_b32_e32 v124, 0
	v_mov_b32_e32 v125, 0
	v_mov_b32_e32 v126, 0
	v_mov_b32_e32 v127, 0
	v_mov_b32_e32 v128, 0
	v_mov_b32_e32 v129, 0
	s_waitcnt vmcnt(12)
	s_barrier
	ds_read_b128 v[146:149], v136 offset:0
	ds_read_b128 v[152:155], v136 offset:1024
	ds_read_b128 v[156:159], v136 offset:2048
	ds_read_b128 v[162:165], v136 offset:3072
	ds_read_b128 v[166:169], v136 offset:4096
	ds_read_b128 v[170:173], v136 offset:5120
	ds_read_b128 v[176:179], v136 offset:6144
	ds_read_b128 v[180:183], v136 offset:7168
	ds_read_b128 v[184:187], v137 offset:16384
	ds_read_b128 v[188:191], v137 offset:17408
	ds_read_b128 v[192:195], v137 offset:18432
	ds_read_b128 v[196:199], v137 offset:19456
	s_movk_i32 s40, 0x6000
	s_mov_b32 s41, 0
	s_movk_i32 s39, 42
	.p2align 6
.Lt11_loop:
	.p2align 3
	s_waitcnt vmcnt(6) lgkmcnt(0)
	s_barrier
	s_setprio 1
	v_add_u32_e32 v144, s40, v136
	v_mfma_f32_16x16x32_bf16 v[126:129], v[184:187], v[146:149], v[126:129]
	ds_read_b128 v[200:203], v144 offset:0
	v_mfma_f32_16x16x32_bf16 v[122:125], v[184:187], v[152:155], v[122:125]
	ds_read_b128 v[204:207], v144 offset:1024
	v_mfma_f32_16x16x32_bf16 v[118:121], v[184:187], v[156:159], v[118:121]
	ds_read_b128 v[208:211], v144 offset:2048
	v_mfma_f32_16x16x32_bf16 v[114:117], v[184:187], v[162:165], v[114:117]
	ds_read_b128 v[212:215], v144 offset:3072
	v_mfma_f32_16x16x32_bf16 v[110:113], v[184:187], v[166:169], v[110:113]
	ds_read_b128 v[216:219], v144 offset:4096
	v_mfma_f32_16x16x32_bf16 v[106:109], v[184:187], v[170:173], v[106:109]
	ds_read_b128 v[220:223], v144 offset:5120
	v_mfma_f32_16x16x32_bf16 v[102:105], v[184:187], v[176:179], v[102:105]
	ds_read_b128 v[224:227], v144 offset:6144
	v_mfma_f32_16x16x32_bf16 v[98:101], v[184:187], v[180:183], v[98:101]
	ds_read_b128 v[228:231], v144 offset:7168
	v_mfma_f32_16x16x32_bf16 v[94:97], v[188:191], v[146:149], v[94:97]
	v_add_u32_e64 v144, s40, v137
	v_mfma_f32_16x16x32_bf16 v[90:93], v[188:191], v[152:155], v[90:93]
	v_mfma_f32_16x16x32_bf16 v[86:89], v[188:191], v[156:159], v[86:89]
	ds_read_b128 v[232:235], v144 offset:16384
	v_mfma_f32_16x16x32_bf16 v[82:85], v[188:191], v[162:165], v[82:85]
	ds_read_b128 v[236:239], v144 offset:17408
	v_mfma_f32_16x16x32_bf16 v[78:81], v[188:191], v[166:169], v[78:81]
	ds_read_b128 v[240:243], v144 offset:18432
	v_mfma_f32_16x16x32_bf16 v[74:77], v[188:191], v[170:173], v[74:77]
	ds_read_b128 v[244:247], v144 offset:19456
	v_mfma_f32_16x16x32_bf16 v[70:73], v[188:191], v[176:179], v[70:73]
	s_add_i32 s42, s46, s41
	s_mov_b32 m0, s42
	v_lshl_add_u64 v[142:143], v[132:133], 0, s[2:3]
	v_mfma_f32_16x16x32_bf16 v[66:69], v[188:191], v[180:183], v[66:69]
	global_load_lds_dwordx4 v[132:133], off
	s_add_i32 m0, m0, 0x1000
	v_mfma_f32_16x16x32_bf16 v[62:65], v[192:195], v[146:149], v[62:65]
	v_mfma_f32_16x16x32_bf16 v[58:61], v[192:195], v[152:155], v[58:61]
;     ...
;   for (int kt = 0; kt < nk; kt++) {
;     if (kt + 1 < nk) asm volatile("s_waitcnt vmcnt(6)" ::: "memory");
;     else asm volatile("s_waitcnt vmcnt(0)" ::: "memory");
;     __builtin_amdgcn_s_barrier();
;     asm volatile("" ::: "memory");
;     if (kt + 2 < nk) G2_STAGE(kt + 2);
;     const char* cS = smem + (kt % 3) * 24576;
;     bf16x8 xa[8], wb[4];
; #pragma unroll
;     for (int f = 0; f < 8; f++) xa[f] = *(const bf16x8*)(cS + aoff + f * 1024);
; #pragma unroll
;     for (int f = 0; f < 4; f++) wb[f] = *(const bf16x8*)(cS + boff + f * 1024);
; #pragma unroll
;     for (int nf = 0; nf < 4; nf++)
; #pragma unroll
;       for (int mf = 0; mf < 8; mf++)
;         acc[nf][mf] = __builtin_amdgcn_mfma_f32_16x16x32_bf16(wb[nf], xa[mf], acc[nf][mf], 0, 0, 0);
	v_mfma_f32_16x16x32_bf16 v[54:57], v[192:195], v[156:159], v[54:57]
	global_load_lds_dwordx4 v[142:143], off
	v_lshl_add_u64 v[142:143], v[142:143], 0, s[2:3]
	s_add_i32 m0, m0, 0x1000
	v_mfma_f32_16x16x32_bf16 v[50:53], v[192:195], v[162:165], v[50:53]
	v_mfma_f32_16x16x32_bf16 v[46:49], v[192:195], v[166:169], v[46:49]
	v_mfma_f32_16x16x32_bf16 v[42:45], v[192:195], v[170:173], v[42:45]
	global_load_lds_dwordx4 v[142:143], off
	v_lshl_add_u64 v[142:143], v[142:143], 0, s[2:3]
	s_add_i32 m0, m0, 0x1000
	v_mfma_f32_16x16x32_bf16 v[38:41], v[192:195], v[176:179], v[38:41]
	v_mfma_f32_16x16x32_bf16 v[34:37], v[192:195], v[180:183], v[34:37]
	v_mfma_f32_16x16x32_bf16 v[30:33], v[196:199], v[146:149], v[30:33]
	global_load_lds_dwordx4 v[142:143], off
	s_add_i32 m0, m0, 0x1000
	v_lshl_add_u64 v[142:143], v[134:135], 0, s[2:3]
	v_mfma_f32_16x16x32_bf16 v[26:29], v[196:199], v[152:155], v[26:29]
	v_mfma_f32_16x16x32_bf16 v[22:25], v[196:199], v[156:159], v[22:25]
	v_mfma_f32_16x16x32_bf16 v[18:21], v[196:199], v[162:165], v[18:21]
	global_load_lds_dwordx4 v[134:135], off
	s_add_i32 m0, m0, 0x1000
	v_lshl_add_u64 v[132:133], v[132:133], 0, s[12:13]
	v_mfma_f32_16x16x32_bf16 v[14:17], v[196:199], v[166:169], v[14:17]
	v_mfma_f32_16x16x32_bf16 v[10:13], v[196:199], v[170:173], v[10:13]
	v_mfma_f32_16x16x32_bf16 v[6:9], v[196:199], v[176:179], v[6:9]
	global_load_lds_dwordx4 v[142:143], off
	v_lshl_add_u64 v[134:135], v[134:135], 0, s[4:5]
	v_mfma_f32_16x16x32_bf16 v[2:5], v[196:199], v[180:183], v[2:5]
	s_setprio 0
	s_mov_b32 s41, s40
	s_add_i32 s40, s40, 0x6000
	s_cmp_eq_u32 s40, 0x12000
	s_cselect_b32 s40, 0, s40
	s_nop 0
	.p2align 3
	s_waitcnt vmcnt(6) lgkmcnt(0)
	s_barrier
	s_setprio 1
	v_add_u32_e32 v144, s40, v136
	v_mfma_f32_16x16x32_bf16 v[126:129], v[232:235], v[200:203], v[126:129]
	ds_read_b128 v[146:149], v144 offset:0
	v_mfma_f32_16x16x32_bf16 v[122:125], v[232:235], v[204:207], v[122:125]
	ds_read_b128 v[152:155], v144 offset:1024
	v_mfma_f32_16x16x32_bf16 v[118:121], v[232:235], v[208:211], v[118:121]
	ds_read_b128 v[156:159], v144 offset:2048
	v_mfma_f32_16x16x32_bf16 v[114:117], v[232:235], v[212:215], v[114:117]
	ds_read_b128 v[162:165], v144 offset:3072
	v_mfma_f32_16x16x32_bf16 v[110:113], v[232:235], v[216:219], v[110:113]
	ds_read_b128 v[166:169], v144 offset:4096
	v_mfma_f32_16x16x32_bf16 v[106:109], v[232:235], v[220:223], v[106:109]
	ds_read_b128 v[170:173], v144 offset:5120
	v_mfma_f32_16x16x32_bf16 v[102:105], v[232:235], v[224:227], v[102:105]
	ds_read_b128 v[176:179], v144 offset:6144
	v_mfma_f32_16x16x32_bf16 v[98:101], v[232:235], v[228:231], v[98:101]
	ds_read_b128 v[180:183], v144 offset:7168
	v_mfma_f32_16x16x32_bf16 v[94:97], v[236:239], v[200:203], v[94:97]
	v_add_u32_e64 v144, s40, v137
	v_mfma_f32_16x16x32_bf16 v[90:93], v[236:239], v[204:207], v[90:93]
	v_mfma_f32_16x16x32_bf16 v[86:89], v[236:239], v[208:211], v[86:89]
	ds_read_b128 v[184:187], v144 offset:16384
	v_mfma_f32_16x16x32_bf16 v[82:85], v[236:239], v[212:215], v[82:85]
	ds_read_b128 v[188:191], v144 offset:17408
	v_mfma_f32_16x16x32_bf16 v[78:81], v[236:239], v[216:219], v[78:81]
	ds_read_b128 v[192:195], v144 offset:18432
	v_mfma_f32_16x16x32_bf16 v[74:77], v[236:239], v[220:223], v[74:77]
	ds_read_b128 v[196:199], v144 offset:19456
	v_mfma_f32_16x16x32_bf16 v[70:73], v[236:239], v[224:227], v[70:73]
	s_add_i32 s42, s46, s41
	s_mov_b32 m0, s42
	v_lshl_add_u64 v[142:143], v[132:133], 0, s[2:3]
	v_mfma_f32_16x16x32_bf16 v[66:69], v[236:239], v[228:231], v[66:69]
	global_load_lds_dwordx4 v[132:133], off
	s_add_i32 m0, m0, 0x1000
	v_mfma_f32_16x16x32_bf16 v[62:65], v[240:243], v[200:203], v[62:65]
	v_mfma_f32_16x16x32_bf16 v[58:61], v[240:243], v[204:207], v[58:61]
	v_mfma_f32_16x16x32_bf16 v[54:57], v[240:243], v[208:211], v[54:57]
	global_load_lds_dwordx4 v[142:143], off
	v_lshl_add_u64 v[142:143], v[142:143], 0, s[2:3]
	s_add_i32 m0, m0, 0x1000
	v_mfma_f32_16x16x32_bf16 v[50:53], v[240:243], v[212:215], v[50:53]
	v_mfma_f32_16x16x32_bf16 v[46:49], v[240:243], v[216:219], v[46:49]
	v_mfma_f32_16x16x32_bf16 v[42:45], v[240:243], v[220:223], v[42:45]
	global_load_lds_dwordx4 v[142:143], off
	v_lshl_add_u64 v[142:143], v[142:143], 0, s[2:3]
	s_add_i32 m0, m0, 0x1000
	v_mfma_f32_16x16x32_bf16 v[38:41], v[240:243], v[224:227], v[38:41]
	v_mfma_f32_16x16x32_bf16 v[34:37], v[240:243], v[228:231], v[34:37]
	v_mfma_f32_16x16x32_bf16 v[30:33], v[244:247], v[200:203], v[30:33]
	global_load_lds_dwordx4 v[142:143], off
	s_add_i32 m0, m0, 0x1000
	v_lshl_add_u64 v[142:143], v[134:135], 0, s[2:3]
	v_mfma_f32_16x16x32_bf16 v[26:29], v[244:247], v[204:207], v[26:29]
	v_mfma_f32_16x16x32_bf16 v[22:25], v[244:247], v[208:211], v[22:25]
	v_mfma_f32_16x16x32_bf16 v[18:21], v[244:247], v[212:215], v[18:21]
	global_load_lds_dwordx4 v[134:135], off
	s_add_i32 m0, m0, 0x1000
	v_lshl_add_u64 v[132:133], v[132:133], 0, s[12:13]
	v_mfma_f32_16x16x32_bf16 v[14:17], v[244:247], v[216:219], v[14:17]
	v_mfma_f32_16x16x32_bf16 v[10:13], v[244:247], v[220:223], v[10:13]
	v_mfma_f32_16x16x32_bf16 v[6:9], v[244:247], v[224:227], v[6:9]
	global_load_lds_dwordx4 v[142:143], off
	v_lshl_add_u64 v[134:135], v[134:135], 0, s[4:5]
	v_mfma_f32_16x16x32_bf16 v[2:5], v[244:247], v[228:231], v[2:5]
	s_setprio 0
	s_mov_b32 s41, s40
	s_add_i32 s40, s40, 0x6000
	s_cmp_eq_u32 s40, 0x12000
	s_cselect_b32 s40, 0, s40
	s_nop 0
	s_sub_i32 s39, s39, 1
	s_cmp_lg_u32 s39, 0
	s_cbranch_scc1 .Lt11_loop
	.p2align 3
	s_waitcnt vmcnt(6) lgkmcnt(0)
	s_barrier
;     ...
;   for (int kt = 0; kt < nk; kt++) {
;     if (kt + 1 < nk) asm volatile("s_waitcnt vmcnt(6)" ::: "memory");
;     else asm volatile("s_waitcnt vmcnt(0)" ::: "memory");
;     __builtin_amdgcn_s_barrier();
;     asm volatile("" ::: "memory");
;     if (kt + 2 < nk) G2_STAGE(kt + 2);
;     const char* cS = smem + (kt % 3) * 24576;
;     bf16x8 xa[8], wb[4];
; #pragma unroll
;     for (int f = 0; f < 8; f++) xa[f] = *(const bf16x8*)(cS + aoff + f * 1024);
; #pragma unroll
;     for (int f = 0; f < 4; f++) wb[f] = *(const bf16x8*)(cS + boff + f * 1024);
; #pragma unroll
;     for (int nf = 0; nf < 4; nf++)
; #pragma unroll
;       for (int mf = 0; mf < 8; mf++)
;         acc[nf][mf] = __builtin_amdgcn_mfma_f32_16x16x32_bf16(wb[nf], xa[mf], acc[nf][mf], 0, 0, 0);
	s_setprio 1
	v_add_u32_e32 v144, s40, v136
	v_mfma_f32_16x16x32_bf16 v[126:129], v[184:187], v[146:149], v[126:129]
	ds_read_b128 v[200:203], v144 offset:0
	v_mfma_f32_16x16x32_bf16 v[122:125], v[184:187], v[152:155], v[122:125]
	ds_read_b128 v[204:207], v144 offset:1024
	v_mfma_f32_16x16x32_bf16 v[118:121], v[184:187], v[156:159], v[118:121]
	ds_read_b128 v[208:211], v144 offset:2048
	v_mfma_f32_16x16x32_bf16 v[114:117], v[184:187], v[162:165], v[114:117]
	ds_read_b128 v[212:215], v144 offset:3072
	v_mfma_f32_16x16x32_bf16 v[110:113], v[184:187], v[166:169], v[110:113]
	ds_read_b128 v[216:219], v144 offset:4096
	v_mfma_f32_16x16x32_bf16 v[106:109], v[184:187], v[170:173], v[106:109]
	ds_read_b128 v[220:223], v144 offset:5120
	v_mfma_f32_16x16x32_bf16 v[102:105], v[184:187], v[176:179], v[102:105]
	ds_read_b128 v[224:227], v144 offset:6144
	v_mfma_f32_16x16x32_bf16 v[98:101], v[184:187], v[180:183], v[98:101]
	ds_read_b128 v[228:231], v144 offset:7168
	v_mfma_f32_16x16x32_bf16 v[94:97], v[188:191], v[146:149], v[94:97]
	v_add_u32_e64 v144, s40, v137
	v_mfma_f32_16x16x32_bf16 v[90:93], v[188:191], v[152:155], v[90:93]
	v_mfma_f32_16x16x32_bf16 v[86:89], v[188:191], v[156:159], v[86:89]
	ds_read_b128 v[232:235], v144 offset:16384
	v_mfma_f32_16x16x32_bf16 v[82:85], v[188:191], v[162:165], v[82:85]
	ds_read_b128 v[236:239], v144 offset:17408
	v_mfma_f32_16x16x32_bf16 v[78:81], v[188:191], v[166:169], v[78:81]
	ds_read_b128 v[240:243], v144 offset:18432
	v_mfma_f32_16x16x32_bf16 v[74:77], v[188:191], v[170:173], v[74:77]
	ds_read_b128 v[244:247], v144 offset:19456
	v_mfma_f32_16x16x32_bf16 v[70:73], v[188:191], v[176:179], v[70:73]
	s_add_i32 s42, s46, s41
	s_mov_b32 m0, s42
	v_lshl_add_u64 v[142:143], v[132:133], 0, s[2:3]
	v_mfma_f32_16x16x32_bf16 v[66:69], v[188:191], v[180:183], v[66:69]
	global_load_lds_dwordx4 v[132:133], off
	s_add_i32 m0, m0, 0x1000
	v_mfma_f32_16x16x32_bf16 v[62:65], v[192:195], v[146:149], v[62:65]
	v_mfma_f32_16x16x32_bf16 v[58:61], v[192:195], v[152:155], v[58:61]
	v_mfma_f32_16x16x32_bf16 v[54:57], v[192:195], v[156:159], v[54:57]
	global_load_lds_dwordx4 v[142:143], off
	v_lshl_add_u64 v[142:143], v[142:143], 0, s[2:3]
	s_add_i32 m0, m0, 0x1000
	v_mfma_f32_16x16x32_bf16 v[50:53], v[192:195], v[162:165], v[50:53]
	v_mfma_f32_16x16x32_bf16 v[46:49], v[192:195], v[166:169], v[46:49]
	v_mfma_f32_16x16x32_bf16 v[42:45], v[192:195], v[170:173], v[42:45]
	global_load_lds_dwordx4 v[142:143], off
	v_lshl_add_u64 v[142:143], v[142:143], 0, s[2:3]
	s_add_i32 m0, m0, 0x1000
	v_mfma_f32_16x16x32_bf16 v[38:41], v[192:195], v[176:179], v[38:41]
	v_mfma_f32_16x16x32_bf16 v[34:37], v[192:195], v[180:183], v[34:37]
	v_mfma_f32_16x16x32_bf16 v[30:33], v[196:199], v[146:149], v[30:33]
	global_load_lds_dwordx4 v[142:143], off
	s_add_i32 m0, m0, 0x1000
	v_lshl_add_u64 v[142:143], v[134:135], 0, s[2:3]
	v_mfma_f32_16x16x32_bf16 v[26:29], v[196:199], v[152:155], v[26:29]
	v_mfma_f32_16x16x32_bf16 v[22:25], v[196:199], v[156:159], v[22:25]
	v_mfma_f32_16x16x32_bf16 v[18:21], v[196:199], v[162:165], v[18:21]
	global_load_lds_dwordx4 v[134:135], off
	s_add_i32 m0, m0, 0x1000
	v_lshl_add_u64 v[132:133], v[132:133], 0, s[12:13]
	v_mfma_f32_16x16x32_bf16 v[14:17], v[196:199], v[166:169], v[14:17]
	v_mfma_f32_16x16x32_bf16 v[10:13], v[196:199], v[170:173], v[10:13]
	v_mfma_f32_16x16x32_bf16 v[6:9], v[196:199], v[176:179], v[6:9]
	global_load_lds_dwordx4 v[142:143], off
	v_lshl_add_u64 v[134:135], v[134:135], 0, s[4:5]
	v_mfma_f32_16x16x32_bf16 v[2:5], v[196:199], v[180:183], v[2:5]
	s_setprio 0
	s_mov_b32 s41, s40
	s_add_i32 s40, s40, 0x6000
	s_cmp_eq_u32 s40, 0x12000
	s_cselect_b32 s40, 0, s40
	s_nop 0
	.p2align 3
	s_waitcnt vmcnt(6) lgkmcnt(0)
	s_barrier
	s_setprio 1
	v_add_u32_e32 v144, s40, v136
	v_mfma_f32_16x16x32_bf16 v[126:129], v[232:235], v[200:203], v[126:129]
	ds_read_b128 v[146:149], v144 offset:0
	v_mfma_f32_16x16x32_bf16 v[122:125], v[232:235], v[204:207], v[122:125]
	ds_read_b128 v[152:155], v144 offset:1024
	v_mfma_f32_16x16x32_bf16 v[118:121], v[232:235], v[208:211], v[118:121]
	ds_read_b128 v[156:159], v144 offset:2048
	v_mfma_f32_16x16x32_bf16 v[114:117], v[232:235], v[212:215], v[114:117]
	ds_read_b128 v[162:165], v144 offset:3072
	v_mfma_f32_16x16x32_bf16 v[110:113], v[232:235], v[216:219], v[110:113]
	ds_read_b128 v[166:169], v144 offset:4096
	v_mfma_f32_16x16x32_bf16 v[106:109], v[232:235], v[220:223], v[106:109]
	ds_read_b128 v[170:173], v144 offset:5120
	v_mfma_f32_16x16x32_bf16 v[102:105], v[232:235], v[224:227], v[102:105]
	ds_read_b128 v[176:179], v144 offset:6144
	v_mfma_f32_16x16x32_bf16 v[98:101], v[232:235], v[228:231], v[98:101]
	ds_read_b128 v[180:183], v144 offset:7168
	v_mfma_f32_16x16x32_bf16 v[94:97], v[236:239], v[200:203], v[94:97]
	v_add_u32_e64 v144, s40, v137
	v_mfma_f32_16x16x32_bf16 v[90:93], v[236:239], v[204:207], v[90:93]
	v_mfma_f32_16x16x32_bf16 v[86:89], v[236:239], v[208:211], v[86:89]
	ds_read_b128 v[184:187], v144 offset:16384
	v_mfma_f32_16x16x32_bf16 v[82:85], v[236:239], v[212:215], v[82:85]
	ds_read_b128 v[188:191], v144 offset:17408
	v_mfma_f32_16x16x32_bf16 v[78:81], v[236:239], v[216:219], v[78:81]
	ds_read_b128 v[192:195], v144 offset:18432
	v_mfma_f32_16x16x32_bf16 v[74:77], v[236:239], v[220:223], v[74:77]
	ds_read_b128 v[196:199], v144 offset:19456
	v_mfma_f32_16x16x32_bf16 v[70:73], v[236:239], v[224:227], v[70:73]
	v_mfma_f32_16x16x32_bf16 v[66:69], v[236:239], v[228:231], v[66:69]
	v_mfma_f32_16x16x32_bf16 v[62:65], v[240:243], v[200:203], v[62:65]
	v_mfma_f32_16x16x32_bf16 v[58:61], v[240:243], v[204:207], v[58:61]
	v_mfma_f32_16x16x32_bf16 v[54:57], v[240:243], v[208:211], v[54:57]
	v_mfma_f32_16x16x32_bf16 v[50:53], v[240:243], v[212:215], v[50:53]
	v_mfma_f32_16x16x32_bf16 v[46:49], v[240:243], v[216:219], v[46:49]
	v_mfma_f32_16x16x32_bf16 v[42:45], v[240:243], v[220:223], v[42:45]
	v_mfma_f32_16x16x32_bf16 v[38:41], v[240:243], v[224:227], v[38:41]
	v_mfma_f32_16x16x32_bf16 v[34:37], v[240:243], v[228:231], v[34:37]
	v_mfma_f32_16x16x32_bf16 v[30:33], v[244:247], v[200:203], v[30:33]
	v_mfma_f32_16x16x32_bf16 v[26:29], v[244:247], v[204:207], v[26:29]
	v_mfma_f32_16x16x32_bf16 v[22:25], v[244:247], v[208:211], v[22:25]
	v_mfma_f32_16x16x32_bf16 v[18:21], v[244:247], v[212:215], v[18:21]
	v_mfma_f32_16x16x32_bf16 v[14:17], v[244:247], v[216:219], v[14:17]
	v_mfma_f32_16x16x32_bf16 v[10:13], v[244:247], v[220:223], v[10:13]
	v_mfma_f32_16x16x32_bf16 v[6:9], v[244:247], v[224:227], v[6:9]
	v_mfma_f32_16x16x32_bf16 v[2:5], v[244:247], v[228:231], v[2:5]
	s_setprio 0
	s_mov_b32 s41, s40
	s_add_i32 s40, s40, 0x6000
	s_cmp_eq_u32 s40, 0x12000
	s_cselect_b32 s40, 0, s40
	s_nop 0
	.p2align 3
	s_waitcnt vmcnt(0) lgkmcnt(0)
	s_barrier
; DEVI float blo(unsigned u) { return __uint_as_float(u << 16); }
; DEVI float bhi(unsigned u) { return __uint_as_float(u & 0xffff0000u); }
;     ...
;   for (int kt = 0; kt < nk; kt++) {
;     if (kt + 1 < nk) asm volatile("s_waitcnt vmcnt(6)" ::: "memory");
;     else asm volatile("s_waitcnt vmcnt(0)" ::: "memory");
;     __builtin_amdgcn_s_barrier();
;     asm volatile("" ::: "memory");
;     if (kt + 2 < nk) G2_STAGE(kt + 2);
;     const char* cS = smem + (kt % 3) * 24576;
;     bf16x8 xa[8], wb[4];
; #pragma unroll
;     for (int f = 0; f < 8; f++) xa[f] = *(const bf16x8*)(cS + aoff + f * 1024);
; #pragma unroll
;     for (int f = 0; f < 4; f++) wb[f] = *(const bf16x8*)(cS + boff + f * 1024);
; #pragma unroll
;     for (int nf = 0; nf < 4; nf++)
; #pragma unroll
;       for (int mf = 0; mf < 8; mf++)
;         acc[nf][mf] = __builtin_amdgcn_mfma_f32_16x16x32_bf16(wb[nf], xa[mf], acc[nf][mf], 0, 0, 0);
;     ...
;         if (EPI == EPI_RESID || EPI == EPI_RESID_ATOMIC) {
;           f32x4 x = a;
;           if (EPI == EPI_RESID || kpart == 0) {
;             const u32x2 xr = *(const u32x2*)((const u16*)(p.ws + WS_XB) + (size_t)row * 1024 + col);
;             x[0] += ALPHA * blo(xr[0]); x[1] += ALPHA * bhi(xr[0]); x[2] += ALPHA * blo(xr[1]); x[3] += ALPHA * bhi(xr[1]);
;           }
;           if (EPI == EPI_RESID) *(f32x4*)((float*)(p.ws + WS_XF) + (size_t)row * 1024 + col) = x;
	s_setprio 1
	v_add_u32_e32 v144, s40, v136
	v_mfma_f32_16x16x32_bf16 v[126:129], v[184:187], v[146:149], v[126:129]
	ds_read_b128 v[200:203], v144 offset:0
	v_mfma_f32_16x16x32_bf16 v[122:125], v[184:187], v[152:155], v[122:125]
	ds_read_b128 v[204:207], v144 offset:1024
	v_mfma_f32_16x16x32_bf16 v[118:121], v[184:187], v[156:159], v[118:121]
	ds_read_b128 v[208:211], v144 offset:2048
	v_mfma_f32_16x16x32_bf16 v[114:117], v[184:187], v[162:165], v[114:117]
	ds_read_b128 v[212:215], v144 offset:3072
	v_mfma_f32_16x16x32_bf16 v[110:113], v[184:187], v[166:169], v[110:113]
	ds_read_b128 v[216:219], v144 offset:4096
	v_mfma_f32_16x16x32_bf16 v[106:109], v[184:187], v[170:173], v[106:109]
	ds_read_b128 v[220:223], v144 offset:5120
	v_mfma_f32_16x16x32_bf16 v[102:105], v[184:187], v[176:179], v[102:105]
	ds_read_b128 v[224:227], v144 offset:6144
	v_mfma_f32_16x16x32_bf16 v[98:101], v[184:187], v[180:183], v[98:101]
	ds_read_b128 v[228:231], v144 offset:7168
	v_mfma_f32_16x16x32_bf16 v[94:97], v[188:191], v[146:149], v[94:97]
	v_add_u32_e64 v144, s40, v137
	v_mfma_f32_16x16x32_bf16 v[90:93], v[188:191], v[152:155], v[90:93]
	v_mfma_f32_16x16x32_bf16 v[86:89], v[188:191], v[156:159], v[86:89]
	ds_read_b128 v[232:235], v144 offset:16384
	v_mfma_f32_16x16x32_bf16 v[82:85], v[188:191], v[162:165], v[82:85]
	ds_read_b128 v[236:239], v144 offset:17408
	v_mfma_f32_16x16x32_bf16 v[78:81], v[188:191], v[166:169], v[78:81]
	ds_read_b128 v[240:243], v144 offset:18432
	v_mfma_f32_16x16x32_bf16 v[74:77], v[188:191], v[170:173], v[74:77]
	ds_read_b128 v[244:247], v144 offset:19456
	v_mfma_f32_16x16x32_bf16 v[70:73], v[188:191], v[176:179], v[70:73]
	v_mfma_f32_16x16x32_bf16 v[66:69], v[188:191], v[180:183], v[66:69]
	v_mfma_f32_16x16x32_bf16 v[62:65], v[192:195], v[146:149], v[62:65]
	v_mfma_f32_16x16x32_bf16 v[58:61], v[192:195], v[152:155], v[58:61]
	v_mfma_f32_16x16x32_bf16 v[54:57], v[192:195], v[156:159], v[54:57]
	v_mfma_f32_16x16x32_bf16 v[50:53], v[192:195], v[162:165], v[50:53]
	v_mfma_f32_16x16x32_bf16 v[46:49], v[192:195], v[166:169], v[46:49]
	v_mfma_f32_16x16x32_bf16 v[42:45], v[192:195], v[170:173], v[42:45]
	v_mfma_f32_16x16x32_bf16 v[38:41], v[192:195], v[176:179], v[38:41]
	v_mfma_f32_16x16x32_bf16 v[34:37], v[192:195], v[180:183], v[34:37]
	v_mfma_f32_16x16x32_bf16 v[30:33], v[196:199], v[146:149], v[30:33]
	v_mfma_f32_16x16x32_bf16 v[26:29], v[196:199], v[152:155], v[26:29]
	v_mfma_f32_16x16x32_bf16 v[22:25], v[196:199], v[156:159], v[22:25]
	v_mfma_f32_16x16x32_bf16 v[18:21], v[196:199], v[162:165], v[18:21]
	v_mfma_f32_16x16x32_bf16 v[14:17], v[196:199], v[166:169], v[14:17]
	v_mfma_f32_16x16x32_bf16 v[10:13], v[196:199], v[170:173], v[10:13]
	v_mfma_f32_16x16x32_bf16 v[6:9], v[196:199], v[176:179], v[6:9]
	v_mfma_f32_16x16x32_bf16 v[2:5], v[196:199], v[180:183], v[2:5]
	s_setprio 0
	s_mov_b32 s41, s40
	s_add_i32 s40, s40, 0x6000
	s_cmp_eq_u32 s40, 0x12000
	s_cselect_b32 s40, 0, s40
	s_nop 0
	s_mov_b32 s4, 0x8000
	s_mov_b32 s5, 0
	s_mov_b32 s10, 0x10000
	s_mov_b32 s11, 0
	s_mov_b32 s44, 0x3fd744fd
	.p2align 3
	s_waitcnt lgkmcnt(0)
	s_nop 0
	v_mfma_f32_16x16x32_bf16 v[126:129], v[232:235], v[200:203], v[126:129]
	v_mfma_f32_16x16x32_bf16 v[122:125], v[232:235], v[204:207], v[122:125]
	v_mfma_f32_16x16x32_bf16 v[118:121], v[232:235], v[208:211], v[118:121]
	v_mfma_f32_16x16x32_bf16 v[114:117], v[232:235], v[212:215], v[114:117]
	v_mfma_f32_16x16x32_bf16 v[110:113], v[232:235], v[216:219], v[110:113]
	global_load_dwordx4 v[146:149], v[138:139], off offset:0
	v_mfma_f32_16x16x32_bf16 v[106:109], v[232:235], v[220:223], v[106:109]
	v_mfma_f32_16x16x32_bf16 v[102:105], v[232:235], v[224:227], v[102:105]
	global_load_dwordx4 v[152:155], v[138:139], off offset:128
	v_mfma_f32_16x16x32_bf16 v[98:101], v[232:235], v[228:231], v[98:101]
	v_lshl_add_u64 v[138:139], v[138:139], 0, s[4:5]
	v_mfma_f32_16x16x32_bf16 v[94:97], v[236:239], v[200:203], v[94:97]
	global_load_dwordx4 v[156:159], v[138:139], off offset:0
	v_mfma_f32_16x16x32_bf16 v[90:93], v[236:239], v[204:207], v[90:93]
	v_mfma_f32_16x16x32_bf16 v[86:89], v[236:239], v[208:211], v[86:89]
	global_load_dwordx4 v[162:165], v[138:139], off offset:128
	v_mfma_f32_16x16x32_bf16 v[82:85], v[236:239], v[212:215], v[82:85]
	v_lshl_add_u64 v[138:139], v[138:139], 0, s[4:5]
	v_mfma_f32_16x16x32_bf16 v[78:81], v[236:239], v[216:219], v[78:81]
	global_load_dwordx4 v[166:169], v[138:139], off offset:0
	v_mfma_f32_16x16x32_bf16 v[74:77], v[236:239], v[220:223], v[74:77]
	v_mfma_f32_16x16x32_bf16 v[70:73], v[236:239], v[224:227], v[70:73]
	global_load_dwordx4 v[170:173], v[138:139], off offset:128
	v_mfma_f32_16x16x32_bf16 v[66:69], v[236:239], v[228:231], v[66:69]
	v_lshl_add_u64 v[138:139], v[138:139], 0, s[4:5]
	v_mfma_f32_16x16x32_bf16 v[62:65], v[240:243], v[200:203], v[62:65]
	global_load_dwordx4 v[176:179], v[138:139], off offset:0
	v_mfma_f32_16x16x32_bf16 v[58:61], v[240:243], v[204:207], v[58:61]
	v_mfma_f32_16x16x32_bf16 v[54:57], v[240:243], v[208:211], v[54:57]
	global_load_dwordx4 v[180:183], v[138:139], off offset:128
	v_mfma_f32_16x16x32_bf16 v[50:53], v[240:243], v[212:215], v[50:53]
	v_lshl_add_u64 v[138:139], v[138:139], 0, s[4:5]
	v_mfma_f32_16x16x32_bf16 v[46:49], v[240:243], v[216:219], v[46:49]
	global_load_dwordx4 v[184:187], v[138:139], off offset:0
	v_mfma_f32_16x16x32_bf16 v[42:45], v[240:243], v[220:223], v[42:45]
	v_mfma_f32_16x16x32_bf16 v[38:41], v[240:243], v[224:227], v[38:41]
	global_load_dwordx4 v[188:191], v[138:139], off offset:128
	v_mfma_f32_16x16x32_bf16 v[34:37], v[240:243], v[228:231], v[34:37]
	v_lshl_add_u64 v[138:139], v[138:139], 0, s[4:5]
	v_mfma_f32_16x16x32_bf16 v[30:33], v[244:247], v[200:203], v[30:33]
	global_load_dwordx4 v[192:195], v[138:139], off offset:0
	v_mfma_f32_16x16x32_bf16 v[26:29], v[244:247], v[204:207], v[26:29]
	v_mfma_f32_16x16x32_bf16 v[22:25], v[244:247], v[208:211], v[22:25]
	global_load_dwordx4 v[196:199], v[138:139], off offset:128
	v_mfma_f32_16x16x32_bf16 v[18:21], v[244:247], v[212:215], v[18:21]
	v_lshl_add_u64 v[138:139], v[138:139], 0, s[4:5]
	v_mfma_f32_16x16x32_bf16 v[14:17], v[244:247], v[216:219], v[14:17]
	v_mfma_f32_16x16x32_bf16 v[10:13], v[244:247], v[220:223], v[10:13]
	v_mfma_f32_16x16x32_bf16 v[6:9], v[244:247], v[224:227], v[6:9]
	v_mfma_f32_16x16x32_bf16 v[2:5], v[244:247], v[228:231], v[2:5]
	s_mov_b32 m0, s43
	global_load_dwordx4 v[200:203], v[138:139], off offset:0
	global_load_dwordx4 v[204:207], v[138:139], off offset:128
	v_lshl_add_u64 v[138:139], v[138:139], 0, s[4:5]
	global_load_dwordx4 v[208:211], v[138:139], off offset:0
	global_load_dwordx4 v[212:215], v[138:139], off offset:128
	v_lshl_add_u64 v[138:139], v[138:139], 0, s[4:5]
	s_nop 7
	s_waitcnt vmcnt(15)
; DEVI float blo(unsigned u) { return __uint_as_float(u << 16); }
; DEVI float bhi(unsigned u) { return __uint_as_float(u & 0xffff0000u); }
;     ...
; #pragma unroll
;       for (int nf = 0; nf < 4; nf++) {
;         const int col = n0 + wn * 64 + nf * 16 + quad * 4;
;         f32x4 a = acc[nf][mf];
;         if (EPI == EPI_RESID || EPI == EPI_RESID_ATOMIC) {
;           f32x4 x = a;
;           if (EPI == EPI_RESID || kpart == 0) {
;             const u32x2 xr = *(const u32x2*)((const u16*)(p.ws + WS_XB) + (size_t)row * 1024 + col);
;             x[0] += ALPHA * blo(xr[0]); x[1] += ALPHA * bhi(xr[0]); x[2] += ALPHA * blo(xr[1]); x[3] += ALPHA * bhi(xr[1]);
;           }
;           if (EPI == EPI_RESID) *(f32x4*)((float*)(p.ws + WS_XF) + (size_t)row * 1024 + col) = x;
;           else *(f32x4*)((float*)(p.ws + WS_SLAB) + ((size_t)kpart * 512 + (row - T_P)) * 1024 + col) = x;
	v_permlane16_swap_b32_e32 v146, v148
	v_permlane16_swap_b32_e32 v147, v149
	v_lshlrev_b32_e32 v216, 16, v146
	v_and_b32_e32 v146, 0xffff0000, v146
	v_lshlrev_b32_e32 v217, 16, v147
	v_and_b32_e32 v147, 0xffff0000, v147
	v_fmac_f32_e32 v126, s44, v216
	v_fmac_f32_e32 v127, s44, v146
	v_fmac_f32_e32 v128, s44, v217
	v_fmac_f32_e32 v129, s44, v147
	global_store_dwordx4 v[140:141], v[126:129], off offset:0
	v_lshlrev_b32_e32 v216, 16, v148
	v_and_b32_e32 v148, 0xffff0000, v148
	v_lshlrev_b32_e32 v217, 16, v149
	v_and_b32_e32 v149, 0xffff0000, v149
	v_fmac_f32_e32 v94, s44, v216
	v_fmac_f32_e32 v95, s44, v148
	v_fmac_f32_e32 v96, s44, v217
	v_fmac_f32_e32 v97, s44, v149
	global_store_dwordx4 v[140:141], v[94:97], off offset:64
	s_waitcnt vmcnt(16)
	v_permlane16_swap_b32_e32 v152, v154
	v_permlane16_swap_b32_e32 v153, v155
	v_lshlrev_b32_e32 v216, 16, v152
	v_and_b32_e32 v152, 0xffff0000, v152
	v_lshlrev_b32_e32 v217, 16, v153
	v_and_b32_e32 v153, 0xffff0000, v153
	v_fmac_f32_e32 v62, s44, v216
	v_fmac_f32_e32 v63, s44, v152
	v_fmac_f32_e32 v64, s44, v217
	v_fmac_f32_e32 v65, s44, v153
	global_store_dwordx4 v[140:141], v[62:65], off offset:128
	v_lshlrev_b32_e32 v216, 16, v154
	v_and_b32_e32 v154, 0xffff0000, v154
	v_lshlrev_b32_e32 v217, 16, v155
	v_and_b32_e32 v155, 0xffff0000, v155
	v_fmac_f32_e32 v30, s44, v216
	v_fmac_f32_e32 v31, s44, v154
	v_fmac_f32_e32 v32, s44, v217
	v_fmac_f32_e32 v33, s44, v155
	global_store_dwordx4 v[140:141], v[30:33], off offset:192
	v_lshl_add_u64 v[140:141], v[140:141], 0, s[10:11]
	s_waitcnt vmcnt(17)
	v_permlane16_swap_b32_e32 v156, v158
	v_permlane16_swap_b32_e32 v157, v159
	v_lshlrev_b32_e32 v216, 16, v156
	v_and_b32_e32 v156, 0xffff0000, v156
	v_lshlrev_b32_e32 v217, 16, v157
	v_and_b32_e32 v157, 0xffff0000, v157
	v_fmac_f32_e32 v122, s44, v216
	v_fmac_f32_e32 v123, s44, v156
	v_fmac_f32_e32 v124, s44, v217
	v_fmac_f32_e32 v125, s44, v157
	global_store_dwordx4 v[140:141], v[122:125], off offset:0
	v_lshlrev_b32_e32 v216, 16, v158
	v_and_b32_e32 v158, 0xffff0000, v158
	v_lshlrev_b32_e32 v217, 16, v159
	v_and_b32_e32 v159, 0xffff0000, v159
	v_fmac_f32_e32 v90, s44, v216
	v_fmac_f32_e32 v91, s44, v158
	v_fmac_f32_e32 v92, s44, v217
	v_fmac_f32_e32 v93, s44, v159
	global_store_dwordx4 v[140:141], v[90:93], off offset:64
	s_waitcnt vmcnt(18)
	v_permlane16_swap_b32_e32 v162, v164
	v_permlane16_swap_b32_e32 v163, v165
	v_lshlrev_b32_e32 v216, 16, v162
	v_and_b32_e32 v162, 0xffff0000, v162
	v_lshlrev_b32_e32 v217, 16, v163
	v_and_b32_e32 v163, 0xffff0000, v163
	v_fmac_f32_e32 v58, s44, v216
	v_fmac_f32_e32 v59, s44, v162
	v_fmac_f32_e32 v60, s44, v217
	v_fmac_f32_e32 v61, s44, v163
	global_store_dwordx4 v[140:141], v[58:61], off offset:128
	v_lshlrev_b32_e32 v216, 16, v164
	v_and_b32_e32 v164, 0xffff0000, v164
	v_lshlrev_b32_e32 v217, 16, v165
	v_and_b32_e32 v165, 0xffff0000, v165
	v_fmac_f32_e32 v26, s44, v216
	v_fmac_f32_e32 v27, s44, v164
	v_fmac_f32_e32 v28, s44, v217
	v_fmac_f32_e32 v29, s44, v165
	global_store_dwordx4 v[140:141], v[26:29], off offset:192
	v_lshl_add_u64 v[140:141], v[140:141], 0, s[10:11]
	s_waitcnt vmcnt(19)
	v_permlane16_swap_b32_e32 v166, v168
	v_permlane16_swap_b32_e32 v167, v169
	v_lshlrev_b32_e32 v216, 16, v166
	v_and_b32_e32 v166, 0xffff0000, v166
	v_lshlrev_b32_e32 v217, 16, v167
	v_and_b32_e32 v167, 0xffff0000, v167
	v_fmac_f32_e32 v118, s44, v216
	v_fmac_f32_e32 v119, s44, v166
	v_fmac_f32_e32 v120, s44, v217
	v_fmac_f32_e32 v121, s44, v167
	global_store_dwordx4 v[140:141], v[118:121], off offset:0
	v_lshlrev_b32_e32 v216, 16, v168
	v_and_b32_e32 v168, 0xffff0000, v168
	v_lshlrev_b32_e32 v217, 16, v169
	v_and_b32_e32 v169, 0xffff0000, v169
	v_fmac_f32_e32 v86, s44, v216
	v_fmac_f32_e32 v87, s44, v168
	v_fmac_f32_e32 v88, s44, v217
	v_fmac_f32_e32 v89, s44, v169
	global_store_dwordx4 v[140:141], v[86:89], off offset:64
	s_waitcnt vmcnt(20)
	v_permlane16_swap_b32_e32 v170, v172
	v_permlane16_swap_b32_e32 v171, v173
	v_lshlrev_b32_e32 v216, 16, v170
	v_and_b32_e32 v170, 0xffff0000, v170
	v_lshlrev_b32_e32 v217, 16, v171
	v_and_b32_e32 v171, 0xffff0000, v171
	v_fmac_f32_e32 v54, s44, v216
	v_fmac_f32_e32 v55, s44, v170
	v_fmac_f32_e32 v56, s44, v217
	v_fmac_f32_e32 v57, s44, v171
	global_store_dwordx4 v[140:141], v[54:57], off offset:128
	v_lshlrev_b32_e32 v216, 16, v172
	v_and_b32_e32 v172, 0xffff0000, v172
	v_lshlrev_b32_e32 v217, 16, v173
	v_and_b32_e32 v173, 0xffff0000, v173
	v_fmac_f32_e32 v22, s44, v216
	v_fmac_f32_e32 v23, s44, v172
	v_fmac_f32_e32 v24, s44, v217
	v_fmac_f32_e32 v25, s44, v173
	global_store_dwordx4 v[140:141], v[22:25], off offset:192
	v_lshl_add_u64 v[140:141], v[140:141], 0, s[10:11]
	s_waitcnt vmcnt(21)
	v_permlane16_swap_b32_e32 v176, v178
	v_permlane16_swap_b32_e32 v177, v179
	v_lshlrev_b32_e32 v216, 16, v176
	v_and_b32_e32 v176, 0xffff0000, v176
	v_lshlrev_b32_e32 v217, 16, v177
	v_and_b32_e32 v177, 0xffff0000, v177
	v_fmac_f32_e32 v114, s44, v216
	v_fmac_f32_e32 v115, s44, v176
	v_fmac_f32_e32 v116, s44, v217
	v_fmac_f32_e32 v117, s44, v177
	global_store_dwordx4 v[140:141], v[114:117], off offset:0
	v_lshlrev_b32_e32 v216, 16, v178
	v_and_b32_e32 v178, 0xffff0000, v178
	v_lshlrev_b32_e32 v217, 16, v179
	v_and_b32_e32 v179, 0xffff0000, v179
	v_fmac_f32_e32 v82, s44, v216
	v_fmac_f32_e32 v83, s44, v178
	v_fmac_f32_e32 v84, s44, v217
	v_fmac_f32_e32 v85, s44, v179
	global_store_dwordx4 v[140:141], v[82:85], off offset:64
	s_waitcnt vmcnt(22)
; DEVI float blo(unsigned u) { return __uint_as_float(u << 16); }
; DEVI float bhi(unsigned u) { return __uint_as_float(u & 0xffff0000u); }
;     ...
; #pragma unroll
;       for (int nf = 0; nf < 4; nf++) {
;         const int col = n0 + wn * 64 + nf * 16 + quad * 4;
;         f32x4 a = acc[nf][mf];
;         if (EPI == EPI_RESID || EPI == EPI_RESID_ATOMIC) {
;           f32x4 x = a;
;           if (EPI == EPI_RESID || kpart == 0) {
;             const u32x2 xr = *(const u32x2*)((const u16*)(p.ws + WS_XB) + (size_t)row * 1024 + col);
;             x[0] += ALPHA * blo(xr[0]); x[1] += ALPHA * bhi(xr[0]); x[2] += ALPHA * blo(xr[1]); x[3] += ALPHA * bhi(xr[1]);
;           }
;           if (EPI == EPI_RESID) *(f32x4*)((float*)(p.ws + WS_XF) + (size_t)row * 1024 + col) = x;
;           else *(f32x4*)((float*)(p.ws + WS_SLAB) + ((size_t)kpart * 512 + (row - T_P)) * 1024 + col) = x;
	v_permlane16_swap_b32_e32 v180, v182
	v_permlane16_swap_b32_e32 v181, v183
	v_lshlrev_b32_e32 v216, 16, v180
	v_and_b32_e32 v180, 0xffff0000, v180
	v_lshlrev_b32_e32 v217, 16, v181
	v_and_b32_e32 v181, 0xffff0000, v181
	v_fmac_f32_e32 v50, s44, v216
	v_fmac_f32_e32 v51, s44, v180
	v_fmac_f32_e32 v52, s44, v217
	v_fmac_f32_e32 v53, s44, v181
	global_store_dwordx4 v[140:141], v[50:53], off offset:128
	v_lshlrev_b32_e32 v216, 16, v182
	v_and_b32_e32 v182, 0xffff0000, v182
	v_lshlrev_b32_e32 v217, 16, v183
	v_and_b32_e32 v183, 0xffff0000, v183
	v_fmac_f32_e32 v18, s44, v216
	v_fmac_f32_e32 v19, s44, v182
	v_fmac_f32_e32 v20, s44, v217
	v_fmac_f32_e32 v21, s44, v183
	global_store_dwordx4 v[140:141], v[18:21], off offset:192
	v_lshl_add_u64 v[140:141], v[140:141], 0, s[10:11]
	s_waitcnt vmcnt(23)
	v_permlane16_swap_b32_e32 v184, v186
	v_permlane16_swap_b32_e32 v185, v187
	v_lshlrev_b32_e32 v216, 16, v184
	v_and_b32_e32 v184, 0xffff0000, v184
	v_lshlrev_b32_e32 v217, 16, v185
	v_and_b32_e32 v185, 0xffff0000, v185
	v_fmac_f32_e32 v110, s44, v216
	v_fmac_f32_e32 v111, s44, v184
	v_fmac_f32_e32 v112, s44, v217
	v_fmac_f32_e32 v113, s44, v185
	global_store_dwordx4 v[140:141], v[110:113], off offset:0
	v_lshlrev_b32_e32 v216, 16, v186
	v_and_b32_e32 v186, 0xffff0000, v186
	v_lshlrev_b32_e32 v217, 16, v187
	v_and_b32_e32 v187, 0xffff0000, v187
	v_fmac_f32_e32 v78, s44, v216
	v_fmac_f32_e32 v79, s44, v186
	v_fmac_f32_e32 v80, s44, v217
	v_fmac_f32_e32 v81, s44, v187
	global_store_dwordx4 v[140:141], v[78:81], off offset:64
	s_waitcnt vmcnt(24)
	v_permlane16_swap_b32_e32 v188, v190
	v_permlane16_swap_b32_e32 v189, v191
	v_lshlrev_b32_e32 v216, 16, v188
	v_and_b32_e32 v188, 0xffff0000, v188
	v_lshlrev_b32_e32 v217, 16, v189
	v_and_b32_e32 v189, 0xffff0000, v189
	v_fmac_f32_e32 v46, s44, v216
	v_fmac_f32_e32 v47, s44, v188
	v_fmac_f32_e32 v48, s44, v217
	v_fmac_f32_e32 v49, s44, v189
	global_store_dwordx4 v[140:141], v[46:49], off offset:128
	v_lshlrev_b32_e32 v216, 16, v190
	v_and_b32_e32 v190, 0xffff0000, v190
	v_lshlrev_b32_e32 v217, 16, v191
	v_and_b32_e32 v191, 0xffff0000, v191
	v_fmac_f32_e32 v14, s44, v216
	v_fmac_f32_e32 v15, s44, v190
	v_fmac_f32_e32 v16, s44, v217
	v_fmac_f32_e32 v17, s44, v191
	global_store_dwordx4 v[140:141], v[14:17], off offset:192
	v_lshl_add_u64 v[140:141], v[140:141], 0, s[10:11]
	s_waitcnt vmcnt(25)
	v_permlane16_swap_b32_e32 v192, v194
	v_permlane16_swap_b32_e32 v193, v195
	v_lshlrev_b32_e32 v216, 16, v192
	v_and_b32_e32 v192, 0xffff0000, v192
	v_lshlrev_b32_e32 v217, 16, v193
	v_and_b32_e32 v193, 0xffff0000, v193
	v_fmac_f32_e32 v106, s44, v216
	v_fmac_f32_e32 v107, s44, v192
	v_fmac_f32_e32 v108, s44, v217
	v_fmac_f32_e32 v109, s44, v193
	global_store_dwordx4 v[140:141], v[106:109], off offset:0
	v_lshlrev_b32_e32 v216, 16, v194
	v_and_b32_e32 v194, 0xffff0000, v194
	v_lshlrev_b32_e32 v217, 16, v195
	v_and_b32_e32 v195, 0xffff0000, v195
	v_fmac_f32_e32 v74, s44, v216
	v_fmac_f32_e32 v75, s44, v194
	v_fmac_f32_e32 v76, s44, v217
	v_fmac_f32_e32 v77, s44, v195
	global_store_dwordx4 v[140:141], v[74:77], off offset:64
	s_waitcnt vmcnt(26)
	v_permlane16_swap_b32_e32 v196, v198
	v_permlane16_swap_b32_e32 v197, v199
	v_lshlrev_b32_e32 v216, 16, v196
	v_and_b32_e32 v196, 0xffff0000, v196
	v_lshlrev_b32_e32 v217, 16, v197
	v_and_b32_e32 v197, 0xffff0000, v197
	v_fmac_f32_e32 v42, s44, v216
	v_fmac_f32_e32 v43, s44, v196
	v_fmac_f32_e32 v44, s44, v217
	v_fmac_f32_e32 v45, s44, v197
	global_store_dwordx4 v[140:141], v[42:45], off offset:128
	v_lshlrev_b32_e32 v216, 16, v198
	v_and_b32_e32 v198, 0xffff0000, v198
	v_lshlrev_b32_e32 v217, 16, v199
	v_and_b32_e32 v199, 0xffff0000, v199
	v_fmac_f32_e32 v10, s44, v216
	v_fmac_f32_e32 v11, s44, v198
	v_fmac_f32_e32 v12, s44, v217
	v_fmac_f32_e32 v13, s44, v199
	global_store_dwordx4 v[140:141], v[10:13], off offset:192
	v_lshl_add_u64 v[140:141], v[140:141], 0, s[10:11]
	s_waitcnt vmcnt(27)
	v_permlane16_swap_b32_e32 v200, v202
	v_permlane16_swap_b32_e32 v201, v203
	v_lshlrev_b32_e32 v216, 16, v200
	v_and_b32_e32 v200, 0xffff0000, v200
	v_lshlrev_b32_e32 v217, 16, v201
	v_and_b32_e32 v201, 0xffff0000, v201
	v_fmac_f32_e32 v102, s44, v216
	v_fmac_f32_e32 v103, s44, v200
	v_fmac_f32_e32 v104, s44, v217
	v_fmac_f32_e32 v105, s44, v201
	global_store_dwordx4 v[140:141], v[102:105], off offset:0
	v_lshlrev_b32_e32 v216, 16, v202
	v_and_b32_e32 v202, 0xffff0000, v202
	v_lshlrev_b32_e32 v217, 16, v203
	v_and_b32_e32 v203, 0xffff0000, v203
	v_fmac_f32_e32 v70, s44, v216
	v_fmac_f32_e32 v71, s44, v202
	v_fmac_f32_e32 v72, s44, v217
	v_fmac_f32_e32 v73, s44, v203
	global_store_dwordx4 v[140:141], v[70:73], off offset:64
	s_waitcnt vmcnt(28)
	v_permlane16_swap_b32_e32 v204, v206
	v_permlane16_swap_b32_e32 v205, v207
	v_lshlrev_b32_e32 v216, 16, v204
	v_and_b32_e32 v204, 0xffff0000, v204
	v_lshlrev_b32_e32 v217, 16, v205
	v_and_b32_e32 v205, 0xffff0000, v205
	v_fmac_f32_e32 v38, s44, v216
	v_fmac_f32_e32 v39, s44, v204
	v_fmac_f32_e32 v40, s44, v217
	v_fmac_f32_e32 v41, s44, v205
	global_store_dwordx4 v[140:141], v[38:41], off offset:128
	v_lshlrev_b32_e32 v216, 16, v206
	v_and_b32_e32 v206, 0xffff0000, v206
	v_lshlrev_b32_e32 v217, 16, v207
	v_and_b32_e32 v207, 0xffff0000, v207
	v_fmac_f32_e32 v6, s44, v216
	v_fmac_f32_e32 v7, s44, v206
	v_fmac_f32_e32 v8, s44, v217
	v_fmac_f32_e32 v9, s44, v207
	global_store_dwordx4 v[140:141], v[6:9], off offset:192
	v_lshl_add_u64 v[140:141], v[140:141], 0, s[10:11]
	s_waitcnt vmcnt(29)
	v_permlane16_swap_b32_e32 v208, v210
	v_permlane16_swap_b32_e32 v209, v211
	v_lshlrev_b32_e32 v216, 16, v208
	v_and_b32_e32 v208, 0xffff0000, v208
	v_lshlrev_b32_e32 v217, 16, v209
	v_and_b32_e32 v209, 0xffff0000, v209
	v_fmac_f32_e32 v98, s44, v216
	v_fmac_f32_e32 v99, s44, v208
	v_fmac_f32_e32 v100, s44, v217
	v_fmac_f32_e32 v101, s44, v209
	global_store_dwordx4 v[140:141], v[98:101], off offset:0
	v_lshlrev_b32_e32 v216, 16, v210
	v_and_b32_e32 v210, 0xffff0000, v210
	v_lshlrev_b32_e32 v217, 16, v211
	v_and_b32_e32 v211, 0xffff0000, v211
	v_fmac_f32_e32 v66, s44, v216
	v_fmac_f32_e32 v67, s44, v210
	v_fmac_f32_e32 v68, s44, v217
	v_fmac_f32_e32 v69, s44, v211
	global_store_dwordx4 v[140:141], v[66:69], off offset:64
	s_waitcnt vmcnt(30)
	v_permlane16_swap_b32_e32 v212, v214
	v_permlane16_swap_b32_e32 v213, v215
	v_lshlrev_b32_e32 v216, 16, v212
	v_and_b32_e32 v212, 0xffff0000, v212
	v_lshlrev_b32_e32 v217, 16, v213
	v_and_b32_e32 v213, 0xffff0000, v213
	v_fmac_f32_e32 v34, s44, v216
	v_fmac_f32_e32 v35, s44, v212
	v_fmac_f32_e32 v36, s44, v217
	v_fmac_f32_e32 v37, s44, v213
	global_store_dwordx4 v[140:141], v[34:37], off offset:128
	v_lshlrev_b32_e32 v216, 16, v214
	v_and_b32_e32 v214, 0xffff0000, v214
	v_lshlrev_b32_e32 v217, 16, v215
	v_and_b32_e32 v215, 0xffff0000, v215
	v_fmac_f32_e32 v2, s44, v216
	v_fmac_f32_e32 v3, s44, v214
	v_fmac_f32_e32 v4, s44, v217
	v_fmac_f32_e32 v5, s44, v215
	global_store_dwordx4 v[140:141], v[2:5], off offset:192
	v_readlane_b32 s39, v250, 7
	s_cmpk_lg_u32 s39, 0x200
	s_cbranch_scc1 .LBB0_41
; DEVI int xcd_first_tile() { return (blockIdx.x & 7) * (gridDim.x >> 3) + (blockIdx.x >> 3); }
; DEVI void run_phase(const Params& p, int ph, char* smem) {
;     ...
;       for (int t = xcd_first_tile(); t < 512 + 16 * 11; t += xcd_tile_step()) {
;         if (t < 512) {
;           int mt_, nt_; tile_coords(t, 64, 8, mt_, nt_);
;           gemm_tile256<EPI_RESID>(p, hb, DFF, Bt, DFF, mt_ * 256, nt_ * 128, nullptr, 0, smem);
;         } else {
;           const int u_ = t - 512, tl_ = u_ / 11, q_ = u_ - tl_ * 11;
;           gemm_tile256<EPI_RESID_ATOMIC>(p, hb, DFF, Bt, DFF, (64 + (tl_ & 1)) * 256, (tl_ >> 1) * 128, nullptr, 0, smem, q_ * 256, 8, q_);
	v_readlane_b32 s40, v250, 0
	s_lshr_b32 s41, s40, 3
	s_and_b32 s40, s40, 7
	s_mul_i32 s40, s40, 22
	s_add_i32 s40, s40, s41
	s_cmp_lt_u32 s41, 22
	s_movk_i32 s38, 0x4000
	s_branch .LBB0_41

; #define LAS __attribute__((address_space(3)))
;     ...
;   const int nk = (nk_part < 0) ? (K >> 5) : nk_part;
;   const int lrow = tid >> 2, lpc = tid & 3;
;   const int lch = lpc ^ ((0x78 >> (((lrow >> 2) & 3) * 2)) & 3);
;   const u16* ga = A + (size_t)(m0 + lrow) * lda + kbeg + lch * 8;
;   const u16* gb = Bt + (size_t)(n0 + lrow) * K + kbeg + lch * 8;
;   const size_t ga1 = (size_t)64 * lda, gb1 = (size_t)64 * K;
;   const unsigned lds0 = (unsigned)(uintptr_t)(LAS char*)smem + (unsigned)__builtin_amdgcn_readfirstlane(wid) * 1024u;
;     ...
;   __syncthreads();
;   G2_STAGE(0); G2_STAGE(1);
; DEVI void run_phase(const Params& p, int ph, char* smem) {
;     ...
;           const int u_ = t - 512, tl_ = u_ / 2, q_ = u_ - tl_ * 2;
;           gemm_tile256<EPI_RESID_ATOMIC>(p, ox, 256, Bt, 256, (64 + (tl_ & 1)) * 256, (tl_ >> 1) * 128, nullptr, 0, smem, q_ * 128, 4, q_);
.LBB0_147:
	s_cmpk_gt_i32 s38, 0x1ff
	s_mov_b64 s[2:3], -1
	s_cbranch_scc0 .LBB0_208
	s_sub_i32 s98, s38, 512
	s_lshr_b32 s41, s98, 1
	s_and_b32 s99, s98, 1
	s_lshr_b32 s13, s41, 1
	s_and_b32 s41, s41, 1
	s_add_i32 s41, s41, 64
	v_readlane_b32 s2, v250, 5
	v_readlane_b32 s3, v250, 6
	v_readlane_b32 s98, v254, 62
	s_mul_i32 s1, s41, 0x20000
	s_add_u32 s4, s2, s1
	s_addc_u32 s5, s3, 0
	s_add_u32 s4, s4, 0xe700000
	s_addc_u32 s5, s5, 0
	s_mul_i32 s1, s98, 0x80000
	s_mul_i32 s12, s13, 0x10000
	s_add_i32 s1, s1, s12
	s_add_u32 s8, s2, s1
	s_addc_u32 s9, s3, 0
	s_add_u32 s8, s8, 0x16c00000
	s_addc_u32 s9, s9, 0
	s_mul_i32 s1, s99, 256
	s_add_u32 s4, s4, s1
	s_addc_u32 s5, s5, 0
	s_mul_i32 s1, s99, 512
	s_add_u32 s8, s8, s1
	s_addc_u32 s9, s9, 0
	s_movk_i32 s0, 0x78
	v_lshrrev_b32_e32 v0, 2, v145
	v_and_b32_e32 v131, 3, v145
	v_bfe_u32 v136, v145, 4, 2
	v_lshlrev_b32_e32 v136, 1, v136
	v_lshrrev_b32_e64 v136, v136, s0
	v_and_b32_e32 v136, 3, v136
	v_xor_b32_e32 v131, v131, v136
	v_lshlrev_b32_e32 v131, 4, v131
	s_movk_i32 s12, 0x200
	v_mad_u32_u24 v0, v0, s12, v131
	v_bfe_u32 v137, v145, 2, 1
	s_movk_i32 s12, 0x1c0
	v_mul_u32_u24_e32 v136, s12, v137
	v_sub_u32_e32 v136, v0, v136
	v_mov_b32_e32 v137, 0
	v_lshl_add_u64 v[134:135], s[8:9], 0, v[136:137]
	v_bfe_u32 v137, v145, 2, 1
	s_mov_b32 s10, 64
	s_mov_b32 s11, 0
	v_lshl_add_u64 v[132:133], s[4:5], 0, v[0:1]
	v_bfe_u32 v136, v145, 2, 2
	v_lshlrev_b32_e32 v136, 1, v136
	v_lshrrev_b32_e64 v136, v136, s0
	v_and_b32_e32 v136, 3, v136
	v_bfe_u32 v137, v145, 4, 2
	v_xor_b32_e32 v136, v136, v137
	v_lshlrev_b32_e32 v136, 4, v136
	v_and_b32_e32 v131, 15, v145
	v_lshl_or_b32 v136, v131, 6, v136
	v_bfe_u32 v137, v145, 6, 1
	v_lshl_or_b32 v137, v137, 12, v136
	v_lshrrev_b32_e32 v0, 7, v145
	v_lshl_or_b32 v136, v0, 13, v136
	v_and_b32_e32 v140, 1, v131
	v_lshl_or_b32 v131, v0, 7, v131
	v_bfe_u32 v0, v145, 4, 2
	v_lshlrev_b32_e32 v0, 3, v0
	v_bfe_u32 v141, v145, 6, 1
	s_lshl_b32 s1, s41, 19
	s_lshl_b32 s12, s13, 8
	s_add_i32 s1, s1, s12
	s_add_u32 s4, s2, s1
	s_addc_u32 s5, s3, 0
	s_add_u32 s4, s4, 0x4200000
	s_addc_u32 s5, s5, 0
	v_lshlrev_b32_e32 v138, 11, v131
	v_lshl_add_u32 v138, v141, 7, v138
	v_bfe_u32 v139, v145, 4, 1
	v_lshl_add_u32 v138, v139, 5, v138
	v_bfe_u32 v139, v145, 5, 1
	v_lshl_add_u32 v138, v139, 4, v138
	v_mov_b32_e32 v139, 0
	v_lshl_add_u64 v[138:139], s[4:5], 0, v[138:139]
	s_and_b32 s1, s41, 1
	s_lshl_b32 s1, s1, 20
	s_lshl_b32 s12, s99, 21
	s_add_i32 s1, s1, s12
	s_lshl_b32 s12, s13, 9
	s_add_i32 s1, s1, s12
	s_add_u32 s8, s2, s1
	s_addc_u32 s9, s3, 0
	s_add_u32 s8, s8, 0x1dcc0000
	s_addc_u32 s9, s9, 0
	v_lshlrev_b32_e32 v140, 12, v131
	v_lshl_add_u32 v140, v141, 8, v140
	v_lshl_add_u32 v140, v0, 1, v140
	v_mov_b32_e32 v141, 0
	v_lshl_add_u64 v[140:141], s[8:9], 0, v[140:141]
	s_mov_b32 s2, 0x8000
	s_mov_b32 s3, 0
	v_lshrrev_b32_e32 v0, 6, v145
	v_lshlrev_b32_e32 v0, 10, v0
	s_nop 0
	v_readfirstlane_b32 s98, v0
	s_mov_b32 s39, m0
	s_mov_b32 s4, 128
	s_mov_b32 s5, 0
	s_barrier
	s_add_i32 s13, s98, 0x0
	s_mov_b32 m0, s13
	v_lshl_add_u64 v[142:143], v[132:133], 0, s[2:3]
	global_load_lds_dwordx4 v[132:133], off
	s_add_i32 m0, m0, 0x1000
	s_nop 0
	global_load_lds_dwordx4 v[142:143], off
	v_lshl_add_u64 v[142:143], v[142:143], 0, s[2:3]
	s_add_i32 m0, m0, 0x1000
	s_nop 0
	global_load_lds_dwordx4 v[142:143], off
	v_lshl_add_u64 v[142:143], v[142:143], 0, s[2:3]
	s_add_i32 m0, m0, 0x1000
	s_nop 0
	global_load_lds_dwordx4 v[142:143], off
	s_add_i32 m0, m0, 0x1000
	v_lshl_add_u64 v[142:143], v[134:135], 0, s[2:3]
	s_nop 0
	global_load_lds_dwordx4 v[134:135], off
	s_add_i32 m0, m0, 0x1000
	v_lshl_add_u64 v[132:133], v[132:133], 0, s[10:11]
	s_nop 0
	global_load_lds_dwordx4 v[142:143], off
	v_lshl_add_u64 v[134:135], v[134:135], 0, s[4:5]
	s_nop 0
	s_add_i32 s13, s98, 0x6000
	s_mov_b32 m0, s13
	v_lshl_add_u64 v[142:143], v[132:133], 0, s[2:3]
	global_load_lds_dwordx4 v[132:133], off
	s_add_i32 m0, m0, 0x1000
	s_nop 0
	global_load_lds_dwordx4 v[142:143], off
	v_lshl_add_u64 v[142:143], v[142:143], 0, s[2:3]
	s_add_i32 m0, m0, 0x1000
	s_nop 0
	global_load_lds_dwordx4 v[142:143], off
	v_lshl_add_u64 v[142:143], v[142:143], 0, s[2:3]
	s_add_i32 m0, m0, 0x1000
	s_nop 0
	global_load_lds_dwordx4 v[142:143], off
	s_add_i32 m0, m0, 0x1000
	v_lshl_add_u64 v[142:143], v[134:135], 0, s[2:3]
	s_nop 0
	global_load_lds_dwordx4 v[134:135], off
	s_add_i32 m0, m0, 0x1000
	v_lshl_add_u64 v[132:133], v[132:133], 0, s[10:11]
	s_nop 0
	global_load_lds_dwordx4 v[142:143], off
	v_lshl_add_u64 v[134:135], v[134:135], 0, s[4:5]
	s_nop 0
	s_add_i32 s13, s98, 0xc000
	s_mov_b32 m0, s13
	v_lshl_add_u64 v[142:143], v[132:133], 0, s[2:3]
	global_load_lds_dwordx4 v[132:133], off
	s_add_i32 m0, m0, 0x1000
	s_nop 0
	global_load_lds_dwordx4 v[142:143], off
	v_lshl_add_u64 v[142:143], v[142:143], 0, s[2:3]
	s_add_i32 m0, m0, 0x1000
	s_nop 0
	global_load_lds_dwordx4 v[142:143], off
	v_lshl_add_u64 v[142:143], v[142:143], 0, s[2:3]
	s_add_i32 m0, m0, 0x1000
	s_nop 0
	global_load_lds_dwordx4 v[142:143], off
	s_add_i32 m0, m0, 0x1000
	v_lshl_add_u64 v[142:143], v[134:135], 0, s[2:3]
	s_nop 0
	global_load_lds_dwordx4 v[134:135], off
	s_add_i32 m0, m0, 0x1000
	v_lshl_add_u64 v[132:133], v[132:133], 0, s[10:11]
	s_nop 0
	global_load_lds_dwordx4 v[142:143], off
	v_lshl_add_u64 v[134:135], v[134:135], 0, s[4:5]
	s_nop 0
	v_mov_b32_e32 v2, 0
	v_mov_b32_e32 v3, 0
	v_mov_b32_e32 v4, 0
	v_mov_b32_e32 v5, 0
	v_mov_b32_e32 v6, 0
	v_mov_b32_e32 v7, 0
	v_mov_b32_e32 v8, 0
	v_mov_b32_e32 v9, 0
	v_mov_b32_e32 v10, 0
	v_mov_b32_e32 v11, 0
	v_mov_b32_e32 v12, 0
	v_mov_b32_e32 v13, 0
	v_mov_b32_e32 v14, 0
	v_mov_b32_e32 v15, 0
	v_mov_b32_e32 v16, 0
; #define LAS __attribute__((address_space(3)))
;     ...
;   f32x4 acc[4][8];
; #pragma unroll
;   for (int i = 0; i < 4; i++)
; #pragma unroll
;     for (int j = 0; j < 8; j++) acc[i][j] = (f32x4){0.f, 0.f, 0.f, 0.f};
;   const int nk = (nk_part < 0) ? (K >> 5) : nk_part;
;   const int lrow = tid >> 2, lpc = tid & 3;
;   const int lch = lpc ^ ((0x78 >> (((lrow >> 2) & 3) * 2)) & 3);
;   const u16* ga = A + (size_t)(m0 + lrow) * lda + kbeg + lch * 8;
;   const u16* gb = Bt + (size_t)(n0 + lrow) * K + kbeg + lch * 8;
;   const size_t ga1 = (size_t)64 * lda, gb1 = (size_t)64 * K;
;   const unsigned lds0 = (unsigned)(uintptr_t)(LAS char*)smem + (unsigned)__builtin_amdgcn_readfirstlane(wid) * 1024u;
;     ...
;   __syncthreads();
;   G2_STAGE(0); G2_STAGE(1);
;   const int fsw = (0x78 >> (((r16 >> 2) & 3) * 2)) & 3;
;   const int aoff = (wm * 128 + r16) * 64 + ((quad ^ fsw) << 4);
;   const int boff = 16384 + (wn * 64 + r16) * 64 + ((quad ^ fsw) << 4);
;   for (int kt = 0; kt < nk; kt++) {
;     if (kt + 1 < nk) asm volatile("s_waitcnt vmcnt(6)" ::: "memory");
;     else asm volatile("s_waitcnt vmcnt(0)" ::: "memory");
;     __builtin_amdgcn_s_barrier();
;     asm volatile("" ::: "memory");
;     if (kt + 2 < nk) G2_STAGE(kt + 2);
;     const char* cS = smem + (kt % 3) * 24576;
;     bf16x8 xa[8], wb[4];
; #pragma unroll
;     for (int f = 0; f < 8; f++) xa[f] = *(const bf16x8*)(cS + aoff + f * 1024);
; #pragma unroll
;     for (int f = 0; f < 4; f++) wb[f] = *(const bf16x8*)(cS + boff + f * 1024);
; #pragma unroll
;     for (int nf = 0; nf < 4; nf++)
; #pragma unroll
;       for (int mf = 0; mf < 8; mf++)
;         acc[nf][mf] = __builtin_amdgcn_mfma_f32_16x16x32_bf16(wb[nf], xa[mf], acc[nf][mf], 0, 0, 0);
	v_mov_b32_e32 v17, 0
	v_mov_b32_e32 v18, 0
	v_mov_b32_e32 v19, 0
	v_mov_b32_e32 v20, 0
	v_mov_b32_e32 v21, 0
	v_mov_b32_e32 v22, 0
	v_mov_b32_e32 v23, 0
	v_mov_b32_e32 v24, 0
	v_mov_b32_e32 v25, 0
	v_mov_b32_e32 v26, 0
	v_mov_b32_e32 v27, 0
	v_mov_b32_e32 v28, 0
	v_mov_b32_e32 v29, 0
	v_mov_b32_e32 v30, 0
	v_mov_b32_e32 v31, 0
	v_mov_b32_e32 v32, 0
	v_mov_b32_e32 v33, 0
	v_mov_b32_e32 v34, 0
	v_mov_b32_e32 v35, 0
	v_mov_b32_e32 v36, 0
	v_mov_b32_e32 v37, 0
	v_mov_b32_e32 v38, 0
	v_mov_b32_e32 v39, 0
	v_mov_b32_e32 v40, 0
	v_mov_b32_e32 v41, 0
	v_mov_b32_e32 v42, 0
	v_mov_b32_e32 v43, 0
	v_mov_b32_e32 v44, 0
	v_mov_b32_e32 v45, 0
	v_mov_b32_e32 v46, 0
	v_mov_b32_e32 v47, 0
	v_mov_b32_e32 v48, 0
	v_mov_b32_e32 v49, 0
	v_mov_b32_e32 v50, 0
	v_mov_b32_e32 v51, 0
	v_mov_b32_e32 v52, 0
	v_mov_b32_e32 v53, 0
	v_mov_b32_e32 v54, 0
	v_mov_b32_e32 v55, 0
	v_mov_b32_e32 v56, 0
	v_mov_b32_e32 v57, 0
	v_mov_b32_e32 v58, 0
	v_mov_b32_e32 v59, 0
	v_mov_b32_e32 v60, 0
	v_mov_b32_e32 v61, 0
	v_mov_b32_e32 v62, 0
	v_mov_b32_e32 v63, 0
	v_mov_b32_e32 v64, 0
	v_mov_b32_e32 v65, 0
	v_mov_b32_e32 v66, 0
	v_mov_b32_e32 v67, 0
	v_mov_b32_e32 v68, 0
	v_mov_b32_e32 v69, 0
	v_mov_b32_e32 v70, 0
	v_mov_b32_e32 v71, 0
	v_mov_b32_e32 v72, 0
	v_mov_b32_e32 v73, 0
	v_mov_b32_e32 v74, 0
	v_mov_b32_e32 v75, 0
	v_mov_b32_e32 v76, 0
	v_mov_b32_e32 v77, 0
	v_mov_b32_e32 v78, 0
	v_mov_b32_e32 v79, 0
	v_mov_b32_e32 v80, 0
	v_mov_b32_e32 v81, 0
	v_mov_b32_e32 v82, 0
	v_mov_b32_e32 v83, 0
	v_mov_b32_e32 v84, 0
	v_mov_b32_e32 v85, 0
	v_mov_b32_e32 v86, 0
	v_mov_b32_e32 v87, 0
	v_mov_b32_e32 v88, 0
	v_mov_b32_e32 v89, 0
	v_mov_b32_e32 v90, 0
	v_mov_b32_e32 v91, 0
	v_mov_b32_e32 v92, 0
	v_mov_b32_e32 v93, 0
	v_mov_b32_e32 v94, 0
	v_mov_b32_e32 v95, 0
	v_mov_b32_e32 v96, 0
	v_mov_b32_e32 v97, 0
	v_mov_b32_e32 v98, 0
	v_mov_b32_e32 v99, 0
	v_mov_b32_e32 v100, 0
	v_mov_b32_e32 v101, 0
	v_mov_b32_e32 v102, 0
	v_mov_b32_e32 v103, 0
	v_mov_b32_e32 v104, 0
	v_mov_b32_e32 v105, 0
	v_mov_b32_e32 v106, 0
	v_mov_b32_e32 v107, 0
	v_mov_b32_e32 v108, 0
	v_mov_b32_e32 v109, 0
	v_mov_b32_e32 v110, 0
	v_mov_b32_e32 v111, 0
	v_mov_b32_e32 v112, 0
	v_mov_b32_e32 v113, 0
	v_mov_b32_e32 v114, 0
	v_mov_b32_e32 v115, 0
	v_mov_b32_e32 v116, 0
	v_mov_b32_e32 v117, 0
	v_mov_b32_e32 v118, 0
	v_mov_b32_e32 v119, 0
	v_mov_b32_e32 v120, 0
	v_mov_b32_e32 v121, 0
	v_mov_b32_e32 v122, 0
	v_mov_b32_e32 v123, 0
	v_mov_b32_e32 v124, 0
	v_mov_b32_e32 v125, 0
	v_mov_b32_e32 v126, 0
	v_mov_b32_e32 v127, 0
	v_mov_b32_e32 v128, 0
	v_mov_b32_e32 v129, 0
	s_waitcnt vmcnt(12)
	s_barrier
	ds_read_b128 v[146:149], v136 offset:0
	ds_read_b128 v[152:155], v136 offset:1024
	ds_read_b128 v[156:159], v136 offset:2048
	ds_read_b128 v[162:165], v136 offset:3072
	ds_read_b128 v[166:169], v136 offset:4096
	ds_read_b128 v[170:173], v136 offset:5120
	ds_read_b128 v[176:179], v136 offset:6144
	ds_read_b128 v[180:183], v136 offset:7168
	ds_read_b128 v[184:187], v137 offset:16384
	ds_read_b128 v[188:191], v137 offset:17408
	ds_read_b128 v[192:195], v137 offset:18432
	ds_read_b128 v[196:199], v137 offset:19456
	s_movk_i32 s1, 0x6000
	s_mov_b32 s12, 0
	.p2align 3
	s_waitcnt vmcnt(6) lgkmcnt(0)
	s_barrier
	s_setprio 1
	v_add_u32_e32 v144, s1, v136
	v_mfma_f32_16x16x32_bf16 v[126:129], v[184:187], v[146:149], v[126:129]
	ds_read_b128 v[200:203], v144 offset:0
	v_mfma_f32_16x16x32_bf16 v[122:125], v[184:187], v[152:155], v[122:125]
	ds_read_b128 v[204:207], v144 offset:1024
	v_mfma_f32_16x16x32_bf16 v[118:121], v[184:187], v[156:159], v[118:121]
	ds_read_b128 v[208:211], v144 offset:2048
	v_mfma_f32_16x16x32_bf16 v[114:117], v[184:187], v[162:165], v[114:117]
	ds_read_b128 v[212:215], v144 offset:3072
	v_mfma_f32_16x16x32_bf16 v[110:113], v[184:187], v[166:169], v[110:113]
	ds_read_b128 v[216:219], v144 offset:4096
	v_mfma_f32_16x16x32_bf16 v[106:109], v[184:187], v[170:173], v[106:109]
	ds_read_b128 v[220:223], v144 offset:5120
	v_mfma_f32_16x16x32_bf16 v[102:105], v[184:187], v[176:179], v[102:105]
	ds_read_b128 v[224:227], v144 offset:6144
	v_mfma_f32_16x16x32_bf16 v[98:101], v[184:187], v[180:183], v[98:101]
	ds_read_b128 v[228:231], v144 offset:7168
	v_mfma_f32_16x16x32_bf16 v[94:97], v[188:191], v[146:149], v[94:97]
	v_add_u32_e64 v144, s1, v137
	v_mfma_f32_16x16x32_bf16 v[90:93], v[188:191], v[152:155], v[90:93]
	v_mfma_f32_16x16x32_bf16 v[86:89], v[188:191], v[156:159], v[86:89]
	ds_read_b128 v[232:235], v144 offset:16384
	v_mfma_f32_16x16x32_bf16 v[82:85], v[188:191], v[162:165], v[82:85]
	ds_read_b128 v[236:239], v144 offset:17408
	v_mfma_f32_16x16x32_bf16 v[78:81], v[188:191], v[166:169], v[78:81]
	ds_read_b128 v[240:243], v144 offset:18432
	v_mfma_f32_16x16x32_bf16 v[74:77], v[188:191], v[170:173], v[74:77]
	ds_read_b128 v[244:247], v144 offset:19456
	v_mfma_f32_16x16x32_bf16 v[70:73], v[188:191], v[176:179], v[70:73]
	s_add_i32 s13, s98, s12
	s_mov_b32 m0, s13
	v_lshl_add_u64 v[142:143], v[132:133], 0, s[2:3]
	v_mfma_f32_16x16x32_bf16 v[66:69], v[188:191], v[180:183], v[66:69]
	global_load_lds_dwordx4 v[132:133], off
	s_add_i32 m0, m0, 0x1000
	v_mfma_f32_16x16x32_bf16 v[62:65], v[192:195], v[146:149], v[62:65]
	v_mfma_f32_16x16x32_bf16 v[58:61], v[192:195], v[152:155], v[58:61]
	v_mfma_f32_16x16x32_bf16 v[54:57], v[192:195], v[156:159], v[54:57]
	global_load_lds_dwordx4 v[142:143], off
	v_lshl_add_u64 v[142:143], v[142:143], 0, s[2:3]
	s_add_i32 m0, m0, 0x1000
	v_mfma_f32_16x16x32_bf16 v[50:53], v[192:195], v[162:165], v[50:53]
	v_mfma_f32_16x16x32_bf16 v[46:49], v[192:195], v[166:169], v[46:49]
	v_mfma_f32_16x16x32_bf16 v[42:45], v[192:195], v[170:173], v[42:45]
	global_load_lds_dwordx4 v[142:143], off
	v_lshl_add_u64 v[142:143], v[142:143], 0, s[2:3]
	s_add_i32 m0, m0, 0x1000
	v_mfma_f32_16x16x32_bf16 v[38:41], v[192:195], v[176:179], v[38:41]
	v_mfma_f32_16x16x32_bf16 v[34:37], v[192:195], v[180:183], v[34:37]
	v_mfma_f32_16x16x32_bf16 v[30:33], v[196:199], v[146:149], v[30:33]
	global_load_lds_dwordx4 v[142:143], off
	s_add_i32 m0, m0, 0x1000
	v_lshl_add_u64 v[142:143], v[134:135], 0, s[2:3]
	v_mfma_f32_16x16x32_bf16 v[26:29], v[196:199], v[152:155], v[26:29]
	v_mfma_f32_16x16x32_bf16 v[22:25], v[196:199], v[156:159], v[22:25]
	v_mfma_f32_16x16x32_bf16 v[18:21], v[196:199], v[162:165], v[18:21]
	global_load_lds_dwordx4 v[134:135], off
	s_add_i32 m0, m0, 0x1000
	v_lshl_add_u64 v[132:133], v[132:133], 0, s[10:11]
	v_mfma_f32_16x16x32_bf16 v[14:17], v[196:199], v[166:169], v[14:17]
	v_mfma_f32_16x16x32_bf16 v[10:13], v[196:199], v[170:173], v[10:13]
	v_mfma_f32_16x16x32_bf16 v[6:9], v[196:199], v[176:179], v[6:9]
	global_load_lds_dwordx4 v[142:143], off
	v_lshl_add_u64 v[134:135], v[134:135], 0, s[4:5]
	v_mfma_f32_16x16x32_bf16 v[2:5], v[196:199], v[180:183], v[2:5]
	s_setprio 0
	s_mov_b32 s12, s1
	s_add_i32 s1, s1, 0x6000
	s_cmp_eq_u32 s1, 0x12000
	s_cselect_b32 s1, 0, s1
	s_nop 0
	.p2align 3
	s_waitcnt vmcnt(6) lgkmcnt(0)
	s_barrier
;     ...
;   for (int kt = 0; kt < nk; kt++) {
;     if (kt + 1 < nk) asm volatile("s_waitcnt vmcnt(6)" ::: "memory");
;     else asm volatile("s_waitcnt vmcnt(0)" ::: "memory");
;     __builtin_amdgcn_s_barrier();
;     asm volatile("" ::: "memory");
;     if (kt + 2 < nk) G2_STAGE(kt + 2);
;     const char* cS = smem + (kt % 3) * 24576;
;     bf16x8 xa[8], wb[4];
; #pragma unroll
;     for (int f = 0; f < 8; f++) xa[f] = *(const bf16x8*)(cS + aoff + f * 1024);
; #pragma unroll
;     for (int f = 0; f < 4; f++) wb[f] = *(const bf16x8*)(cS + boff + f * 1024);
; #pragma unroll
;     for (int nf = 0; nf < 4; nf++)
; #pragma unroll
;       for (int mf = 0; mf < 8; mf++)
;         acc[nf][mf] = __builtin_amdgcn_mfma_f32_16x16x32_bf16(wb[nf], xa[mf], acc[nf][mf], 0, 0, 0);
	s_setprio 1
	v_add_u32_e32 v144, s1, v136
	v_mfma_f32_16x16x32_bf16 v[126:129], v[232:235], v[200:203], v[126:129]
	ds_read_b128 v[146:149], v144 offset:0
	v_mfma_f32_16x16x32_bf16 v[122:125], v[232:235], v[204:207], v[122:125]
	ds_read_b128 v[152:155], v144 offset:1024
	v_mfma_f32_16x16x32_bf16 v[118:121], v[232:235], v[208:211], v[118:121]
	ds_read_b128 v[156:159], v144 offset:2048
	v_mfma_f32_16x16x32_bf16 v[114:117], v[232:235], v[212:215], v[114:117]
	ds_read_b128 v[162:165], v144 offset:3072
	v_mfma_f32_16x16x32_bf16 v[110:113], v[232:235], v[216:219], v[110:113]
	ds_read_b128 v[166:169], v144 offset:4096
	v_mfma_f32_16x16x32_bf16 v[106:109], v[232:235], v[220:223], v[106:109]
	ds_read_b128 v[170:173], v144 offset:5120
	v_mfma_f32_16x16x32_bf16 v[102:105], v[232:235], v[224:227], v[102:105]
	ds_read_b128 v[176:179], v144 offset:6144
	v_mfma_f32_16x16x32_bf16 v[98:101], v[232:235], v[228:231], v[98:101]
	ds_read_b128 v[180:183], v144 offset:7168
	v_mfma_f32_16x16x32_bf16 v[94:97], v[236:239], v[200:203], v[94:97]
	v_add_u32_e64 v144, s1, v137
	v_mfma_f32_16x16x32_bf16 v[90:93], v[236:239], v[204:207], v[90:93]
	v_mfma_f32_16x16x32_bf16 v[86:89], v[236:239], v[208:211], v[86:89]
	ds_read_b128 v[184:187], v144 offset:16384
	v_mfma_f32_16x16x32_bf16 v[82:85], v[236:239], v[212:215], v[82:85]
	ds_read_b128 v[188:191], v144 offset:17408
	v_mfma_f32_16x16x32_bf16 v[78:81], v[236:239], v[216:219], v[78:81]
	ds_read_b128 v[192:195], v144 offset:18432
	v_mfma_f32_16x16x32_bf16 v[74:77], v[236:239], v[220:223], v[74:77]
	ds_read_b128 v[196:199], v144 offset:19456
	v_mfma_f32_16x16x32_bf16 v[70:73], v[236:239], v[224:227], v[70:73]
	v_mfma_f32_16x16x32_bf16 v[66:69], v[236:239], v[228:231], v[66:69]
	v_mfma_f32_16x16x32_bf16 v[62:65], v[240:243], v[200:203], v[62:65]
	v_mfma_f32_16x16x32_bf16 v[58:61], v[240:243], v[204:207], v[58:61]
	v_mfma_f32_16x16x32_bf16 v[54:57], v[240:243], v[208:211], v[54:57]
	v_mfma_f32_16x16x32_bf16 v[50:53], v[240:243], v[212:215], v[50:53]
	v_mfma_f32_16x16x32_bf16 v[46:49], v[240:243], v[216:219], v[46:49]
	v_mfma_f32_16x16x32_bf16 v[42:45], v[240:243], v[220:223], v[42:45]
	v_mfma_f32_16x16x32_bf16 v[38:41], v[240:243], v[224:227], v[38:41]
	v_mfma_f32_16x16x32_bf16 v[34:37], v[240:243], v[228:231], v[34:37]
	v_mfma_f32_16x16x32_bf16 v[30:33], v[244:247], v[200:203], v[30:33]
	v_mfma_f32_16x16x32_bf16 v[26:29], v[244:247], v[204:207], v[26:29]
	v_mfma_f32_16x16x32_bf16 v[22:25], v[244:247], v[208:211], v[22:25]
	v_mfma_f32_16x16x32_bf16 v[18:21], v[244:247], v[212:215], v[18:21]
	v_mfma_f32_16x16x32_bf16 v[14:17], v[244:247], v[216:219], v[14:17]
	v_mfma_f32_16x16x32_bf16 v[10:13], v[244:247], v[220:223], v[10:13]
	v_mfma_f32_16x16x32_bf16 v[6:9], v[244:247], v[224:227], v[6:9]
	v_mfma_f32_16x16x32_bf16 v[2:5], v[244:247], v[228:231], v[2:5]
	s_setprio 0
	s_mov_b32 s12, s1
	s_add_i32 s1, s1, 0x6000
	s_cmp_eq_u32 s1, 0x12000
	s_cselect_b32 s1, 0, s1
	s_nop 0
	.p2align 3
	s_waitcnt vmcnt(0) lgkmcnt(0)
	s_barrier
	s_setprio 1
	v_add_u32_e32 v144, s1, v136
	v_mfma_f32_16x16x32_bf16 v[126:129], v[184:187], v[146:149], v[126:129]
	ds_read_b128 v[200:203], v144 offset:0
	v_mfma_f32_16x16x32_bf16 v[122:125], v[184:187], v[152:155], v[122:125]
	ds_read_b128 v[204:207], v144 offset:1024
	v_mfma_f32_16x16x32_bf16 v[118:121], v[184:187], v[156:159], v[118:121]
	ds_read_b128 v[208:211], v144 offset:2048
	v_mfma_f32_16x16x32_bf16 v[114:117], v[184:187], v[162:165], v[114:117]
	ds_read_b128 v[212:215], v144 offset:3072
	v_mfma_f32_16x16x32_bf16 v[110:113], v[184:187], v[166:169], v[110:113]
	ds_read_b128 v[216:219], v144 offset:4096
	v_mfma_f32_16x16x32_bf16 v[106:109], v[184:187], v[170:173], v[106:109]
	ds_read_b128 v[220:223], v144 offset:5120
	v_mfma_f32_16x16x32_bf16 v[102:105], v[184:187], v[176:179], v[102:105]
	ds_read_b128 v[224:227], v144 offset:6144
	v_mfma_f32_16x16x32_bf16 v[98:101], v[184:187], v[180:183], v[98:101]
	ds_read_b128 v[228:231], v144 offset:7168
	v_mfma_f32_16x16x32_bf16 v[94:97], v[188:191], v[146:149], v[94:97]
	v_add_u32_e64 v144, s1, v137
	v_mfma_f32_16x16x32_bf16 v[90:93], v[188:191], v[152:155], v[90:93]
	v_mfma_f32_16x16x32_bf16 v[86:89], v[188:191], v[156:159], v[86:89]
	ds_read_b128 v[232:235], v144 offset:16384
	v_mfma_f32_16x16x32_bf16 v[82:85], v[188:191], v[162:165], v[82:85]
	ds_read_b128 v[236:239], v144 offset:17408
	v_mfma_f32_16x16x32_bf16 v[78:81], v[188:191], v[166:169], v[78:81]
	ds_read_b128 v[240:243], v144 offset:18432
	v_mfma_f32_16x16x32_bf16 v[74:77], v[188:191], v[170:173], v[74:77]
	ds_read_b128 v[244:247], v144 offset:19456
	v_mfma_f32_16x16x32_bf16 v[70:73], v[188:191], v[176:179], v[70:73]
	v_mfma_f32_16x16x32_bf16 v[66:69], v[188:191], v[180:183], v[66:69]
	v_mfma_f32_16x16x32_bf16 v[62:65], v[192:195], v[146:149], v[62:65]
	v_mfma_f32_16x16x32_bf16 v[58:61], v[192:195], v[152:155], v[58:61]
	v_mfma_f32_16x16x32_bf16 v[54:57], v[192:195], v[156:159], v[54:57]
	v_mfma_f32_16x16x32_bf16 v[50:53], v[192:195], v[162:165], v[50:53]
	v_mfma_f32_16x16x32_bf16 v[46:49], v[192:195], v[166:169], v[46:49]
	v_mfma_f32_16x16x32_bf16 v[42:45], v[192:195], v[170:173], v[42:45]
	v_mfma_f32_16x16x32_bf16 v[38:41], v[192:195], v[176:179], v[38:41]
	v_mfma_f32_16x16x32_bf16 v[34:37], v[192:195], v[180:183], v[34:37]
	v_mfma_f32_16x16x32_bf16 v[30:33], v[196:199], v[146:149], v[30:33]
	v_mfma_f32_16x16x32_bf16 v[26:29], v[196:199], v[152:155], v[26:29]
	v_mfma_f32_16x16x32_bf16 v[22:25], v[196:199], v[156:159], v[22:25]
	v_mfma_f32_16x16x32_bf16 v[18:21], v[196:199], v[162:165], v[18:21]
	v_mfma_f32_16x16x32_bf16 v[14:17], v[196:199], v[166:169], v[14:17]
	v_mfma_f32_16x16x32_bf16 v[10:13], v[196:199], v[170:173], v[10:13]
	v_mfma_f32_16x16x32_bf16 v[6:9], v[196:199], v[176:179], v[6:9]
	v_mfma_f32_16x16x32_bf16 v[2:5], v[196:199], v[180:183], v[2:5]
	s_setprio 0
	s_mov_b32 s12, s1
	s_add_i32 s1, s1, 0x6000
	s_cmp_eq_u32 s1, 0x12000
	s_cselect_b32 s1, 0, s1
	s_nop 0
	s_mov_b32 s4, 0x8000
	s_mov_b32 s5, 0
	s_mov_b32 s8, 0x10000
	s_mov_b32 s9, 0
	s_mov_b32 s40, 0x3fd744fd
	.p2align 3
	s_waitcnt lgkmcnt(0)
; DEVI float blo(unsigned u) { return __uint_as_float(u << 16); }
; DEVI float bhi(unsigned u) { return __uint_as_float(u & 0xffff0000u); }
;     ...
;   for (int kt = 0; kt < nk; kt++) {
;     if (kt + 1 < nk) asm volatile("s_waitcnt vmcnt(6)" ::: "memory");
;     else asm volatile("s_waitcnt vmcnt(0)" ::: "memory");
;     __builtin_amdgcn_s_barrier();
;     asm volatile("" ::: "memory");
;     if (kt + 2 < nk) G2_STAGE(kt + 2);
;     const char* cS = smem + (kt % 3) * 24576;
;     bf16x8 xa[8], wb[4];
; #pragma unroll
;     for (int f = 0; f < 8; f++) xa[f] = *(const bf16x8*)(cS + aoff + f * 1024);
; #pragma unroll
;     for (int f = 0; f < 4; f++) wb[f] = *(const bf16x8*)(cS + boff + f * 1024);
; #pragma unroll
;     for (int nf = 0; nf < 4; nf++)
; #pragma unroll
;       for (int mf = 0; mf < 8; mf++)
;         acc[nf][mf] = __builtin_amdgcn_mfma_f32_16x16x32_bf16(wb[nf], xa[mf], acc[nf][mf], 0, 0, 0);
;     ...
;         if (EPI == EPI_RESID || EPI == EPI_RESID_ATOMIC) {
;           f32x4 x = a;
;           if (EPI == EPI_RESID || kpart == 0) {
;             const u32x2 xr = *(const u32x2*)((const u16*)(p.ws + WS_XB) + (size_t)row * 1024 + col);
;             x[0] += ALPHA * blo(xr[0]); x[1] += ALPHA * bhi(xr[0]); x[2] += ALPHA * blo(xr[1]); x[3] += ALPHA * bhi(xr[1]);
;           }
;           if (EPI == EPI_RESID) *(f32x4*)((float*)(p.ws + WS_XF) + (size_t)row * 1024 + col) = x;
;           else *(f32x4*)((float*)(p.ws + WS_SLAB) + ((size_t)kpart * 512 + (row - T_P)) * 1024 + col) = x;
	s_nop 0
	v_mfma_f32_16x16x32_bf16 v[126:129], v[232:235], v[200:203], v[126:129]
	v_mfma_f32_16x16x32_bf16 v[122:125], v[232:235], v[204:207], v[122:125]
	v_mfma_f32_16x16x32_bf16 v[118:121], v[232:235], v[208:211], v[118:121]
	v_mfma_f32_16x16x32_bf16 v[114:117], v[232:235], v[212:215], v[114:117]
	v_mfma_f32_16x16x32_bf16 v[110:113], v[232:235], v[216:219], v[110:113]
	v_mfma_f32_16x16x32_bf16 v[106:109], v[232:235], v[220:223], v[106:109]
	v_mfma_f32_16x16x32_bf16 v[102:105], v[232:235], v[224:227], v[102:105]
	v_mfma_f32_16x16x32_bf16 v[98:101], v[232:235], v[228:231], v[98:101]
	v_mfma_f32_16x16x32_bf16 v[94:97], v[236:239], v[200:203], v[94:97]
	v_mfma_f32_16x16x32_bf16 v[90:93], v[236:239], v[204:207], v[90:93]
	v_mfma_f32_16x16x32_bf16 v[86:89], v[236:239], v[208:211], v[86:89]
	v_mfma_f32_16x16x32_bf16 v[82:85], v[236:239], v[212:215], v[82:85]
	v_mfma_f32_16x16x32_bf16 v[78:81], v[236:239], v[216:219], v[78:81]
	v_mfma_f32_16x16x32_bf16 v[74:77], v[236:239], v[220:223], v[74:77]
	v_mfma_f32_16x16x32_bf16 v[70:73], v[236:239], v[224:227], v[70:73]
	v_mfma_f32_16x16x32_bf16 v[66:69], v[236:239], v[228:231], v[66:69]
	v_mfma_f32_16x16x32_bf16 v[62:65], v[240:243], v[200:203], v[62:65]
	v_mfma_f32_16x16x32_bf16 v[58:61], v[240:243], v[204:207], v[58:61]
	v_mfma_f32_16x16x32_bf16 v[54:57], v[240:243], v[208:211], v[54:57]
	v_mfma_f32_16x16x32_bf16 v[50:53], v[240:243], v[212:215], v[50:53]
	v_mfma_f32_16x16x32_bf16 v[46:49], v[240:243], v[216:219], v[46:49]
	v_mfma_f32_16x16x32_bf16 v[42:45], v[240:243], v[220:223], v[42:45]
	v_mfma_f32_16x16x32_bf16 v[38:41], v[240:243], v[224:227], v[38:41]
	v_mfma_f32_16x16x32_bf16 v[34:37], v[240:243], v[228:231], v[34:37]
	v_mfma_f32_16x16x32_bf16 v[30:33], v[244:247], v[200:203], v[30:33]
	v_mfma_f32_16x16x32_bf16 v[26:29], v[244:247], v[204:207], v[26:29]
	v_mfma_f32_16x16x32_bf16 v[22:25], v[244:247], v[208:211], v[22:25]
	v_mfma_f32_16x16x32_bf16 v[18:21], v[244:247], v[212:215], v[18:21]
	v_mfma_f32_16x16x32_bf16 v[14:17], v[244:247], v[216:219], v[14:17]
	v_mfma_f32_16x16x32_bf16 v[10:13], v[244:247], v[220:223], v[10:13]
	v_mfma_f32_16x16x32_bf16 v[6:9], v[244:247], v[224:227], v[6:9]
	v_mfma_f32_16x16x32_bf16 v[2:5], v[244:247], v[228:231], v[2:5]
	s_mov_b32 m0, s39
	s_cmp_eq_u32 s99, 0
	s_cbranch_scc1 .Lta8_first
	s_nop 7
	global_store_dwordx4 v[140:141], v[126:129], off offset:0
	global_store_dwordx4 v[140:141], v[94:97], off offset:64
	global_store_dwordx4 v[140:141], v[62:65], off offset:128
	global_store_dwordx4 v[140:141], v[30:33], off offset:192
	v_lshl_add_u64 v[140:141], v[140:141], 0, s[8:9]
	global_store_dwordx4 v[140:141], v[122:125], off offset:0
	global_store_dwordx4 v[140:141], v[90:93], off offset:64
	global_store_dwordx4 v[140:141], v[58:61], off offset:128
	global_store_dwordx4 v[140:141], v[26:29], off offset:192
	v_lshl_add_u64 v[140:141], v[140:141], 0, s[8:9]
	global_store_dwordx4 v[140:141], v[118:121], off offset:0
	global_store_dwordx4 v[140:141], v[86:89], off offset:64
	global_store_dwordx4 v[140:141], v[54:57], off offset:128
	global_store_dwordx4 v[140:141], v[22:25], off offset:192
	v_lshl_add_u64 v[140:141], v[140:141], 0, s[8:9]
	global_store_dwordx4 v[140:141], v[114:117], off offset:0
	global_store_dwordx4 v[140:141], v[82:85], off offset:64
	global_store_dwordx4 v[140:141], v[50:53], off offset:128
	global_store_dwordx4 v[140:141], v[18:21], off offset:192
	v_lshl_add_u64 v[140:141], v[140:141], 0, s[8:9]
	global_store_dwordx4 v[140:141], v[110:113], off offset:0
	global_store_dwordx4 v[140:141], v[78:81], off offset:64
	global_store_dwordx4 v[140:141], v[46:49], off offset:128
	global_store_dwordx4 v[140:141], v[14:17], off offset:192
	v_lshl_add_u64 v[140:141], v[140:141], 0, s[8:9]
	global_store_dwordx4 v[140:141], v[106:109], off offset:0
	global_store_dwordx4 v[140:141], v[74:77], off offset:64
	global_store_dwordx4 v[140:141], v[42:45], off offset:128
	global_store_dwordx4 v[140:141], v[10:13], off offset:192
	v_lshl_add_u64 v[140:141], v[140:141], 0, s[8:9]
	global_store_dwordx4 v[140:141], v[102:105], off offset:0
	global_store_dwordx4 v[140:141], v[70:73], off offset:64
	global_store_dwordx4 v[140:141], v[38:41], off offset:128
	global_store_dwordx4 v[140:141], v[6:9], off offset:192
	v_lshl_add_u64 v[140:141], v[140:141], 0, s[8:9]
	global_store_dwordx4 v[140:141], v[98:101], off offset:0
	global_store_dwordx4 v[140:141], v[66:69], off offset:64
	global_store_dwordx4 v[140:141], v[34:37], off offset:128
	global_store_dwordx4 v[140:141], v[2:5], off offset:192
	v_readlane_b32 s0, v250, 7
	s_cmpk_lg_u32 s0, 0x200
	s_cbranch_scc1 .Lta8_ar1
	s_mov_b32 s0, 1
	v_writelane_b32 v255, s0, 41
	v_readlane_b32 s1, v250, 0
	s_lshr_b32 s12, s1, 3
	s_and_b32 s1, s1, 7
	s_lshl_b32 s1, s1, 6
	s_add_i32 s1, s1, s12
	s_sub_i32 s38, s1, 0x200

; DEVI float blo(unsigned u) { return __uint_as_float(u << 16); }
; DEVI float bhi(unsigned u) { return __uint_as_float(u & 0xffff0000u); }
;     ...
;         if (EPI == EPI_RESID || EPI == EPI_RESID_ATOMIC) {
;           f32x4 x = a;
;           if (EPI == EPI_RESID || kpart == 0) {
;             const u32x2 xr = *(const u32x2*)((const u16*)(p.ws + WS_XB) + (size_t)row * 1024 + col);
;             x[0] += ALPHA * blo(xr[0]); x[1] += ALPHA * bhi(xr[0]); x[2] += ALPHA * blo(xr[1]); x[3] += ALPHA * bhi(xr[1]);
;           }
;           if (EPI == EPI_RESID) *(f32x4*)((float*)(p.ws + WS_XF) + (size_t)row * 1024 + col) = x;
;           else *(f32x4*)((float*)(p.ws + WS_SLAB) + ((size_t)kpart * 512 + (row - T_P)) * 1024 + col) = x;
.Lta8_first:
	global_load_dwordx4 v[146:149], v[138:139], off offset:0
	global_load_dwordx4 v[152:155], v[138:139], off offset:64
	v_lshl_add_u64 v[138:139], v[138:139], 0, s[4:5]
	global_load_dwordx4 v[156:159], v[138:139], off offset:0
	global_load_dwordx4 v[162:165], v[138:139], off offset:64
	v_lshl_add_u64 v[138:139], v[138:139], 0, s[4:5]
	global_load_dwordx4 v[166:169], v[138:139], off offset:0
	global_load_dwordx4 v[170:173], v[138:139], off offset:64
	v_lshl_add_u64 v[138:139], v[138:139], 0, s[4:5]
	global_load_dwordx4 v[176:179], v[138:139], off offset:0
	global_load_dwordx4 v[180:183], v[138:139], off offset:64
	v_lshl_add_u64 v[138:139], v[138:139], 0, s[4:5]
	global_load_dwordx4 v[184:187], v[138:139], off offset:0
	global_load_dwordx4 v[188:191], v[138:139], off offset:64
	v_lshl_add_u64 v[138:139], v[138:139], 0, s[4:5]
	global_load_dwordx4 v[192:195], v[138:139], off offset:0
	global_load_dwordx4 v[196:199], v[138:139], off offset:64
	v_lshl_add_u64 v[138:139], v[138:139], 0, s[4:5]
	global_load_dwordx4 v[200:203], v[138:139], off offset:0
	global_load_dwordx4 v[204:207], v[138:139], off offset:64
	v_lshl_add_u64 v[138:139], v[138:139], 0, s[4:5]
	global_load_dwordx4 v[208:211], v[138:139], off offset:0
	global_load_dwordx4 v[212:215], v[138:139], off offset:64
	v_lshl_add_u64 v[138:139], v[138:139], 0, s[4:5]
	s_nop 7
	s_waitcnt vmcnt(15)
	v_permlane16_swap_b32_e32 v146, v148
	v_permlane16_swap_b32_e32 v147, v149
	v_lshlrev_b32_e32 v216, 16, v146
	v_and_b32_e32 v146, 0xffff0000, v146
	v_lshlrev_b32_e32 v217, 16, v147
	v_and_b32_e32 v147, 0xffff0000, v147
	v_fmac_f32_e32 v126, s40, v216
	v_fmac_f32_e32 v127, s40, v146
	v_fmac_f32_e32 v128, s40, v217
	v_fmac_f32_e32 v129, s40, v147
	global_store_dwordx4 v[140:141], v[126:129], off offset:0
	v_lshlrev_b32_e32 v216, 16, v148
	v_and_b32_e32 v148, 0xffff0000, v148
	v_lshlrev_b32_e32 v217, 16, v149
	v_and_b32_e32 v149, 0xffff0000, v149
	v_fmac_f32_e32 v94, s40, v216
	v_fmac_f32_e32 v95, s40, v148
	v_fmac_f32_e32 v96, s40, v217
	v_fmac_f32_e32 v97, s40, v149
	global_store_dwordx4 v[140:141], v[94:97], off offset:64
	s_waitcnt vmcnt(16)
	v_permlane16_swap_b32_e32 v152, v154
	v_permlane16_swap_b32_e32 v153, v155
	v_lshlrev_b32_e32 v216, 16, v152
	v_and_b32_e32 v152, 0xffff0000, v152
	v_lshlrev_b32_e32 v217, 16, v153
	v_and_b32_e32 v153, 0xffff0000, v153
	v_fmac_f32_e32 v62, s40, v216
	v_fmac_f32_e32 v63, s40, v152
	v_fmac_f32_e32 v64, s40, v217
	v_fmac_f32_e32 v65, s40, v153
	global_store_dwordx4 v[140:141], v[62:65], off offset:128
	v_lshlrev_b32_e32 v216, 16, v154
	v_and_b32_e32 v154, 0xffff0000, v154
	v_lshlrev_b32_e32 v217, 16, v155
	v_and_b32_e32 v155, 0xffff0000, v155
	v_fmac_f32_e32 v30, s40, v216
	v_fmac_f32_e32 v31, s40, v154
	v_fmac_f32_e32 v32, s40, v217
	v_fmac_f32_e32 v33, s40, v155
	global_store_dwordx4 v[140:141], v[30:33], off offset:192
	v_lshl_add_u64 v[140:141], v[140:141], 0, s[8:9]
	s_waitcnt vmcnt(17)
	v_permlane16_swap_b32_e32 v156, v158
	v_permlane16_swap_b32_e32 v157, v159
	v_lshlrev_b32_e32 v216, 16, v156
	v_and_b32_e32 v156, 0xffff0000, v156
	v_lshlrev_b32_e32 v217, 16, v157
	v_and_b32_e32 v157, 0xffff0000, v157
	v_fmac_f32_e32 v122, s40, v216
	v_fmac_f32_e32 v123, s40, v156
	v_fmac_f32_e32 v124, s40, v217
	v_fmac_f32_e32 v125, s40, v157
	global_store_dwordx4 v[140:141], v[122:125], off offset:0
	v_lshlrev_b32_e32 v216, 16, v158
	v_and_b32_e32 v158, 0xffff0000, v158
	v_lshlrev_b32_e32 v217, 16, v159
	v_and_b32_e32 v159, 0xffff0000, v159
	v_fmac_f32_e32 v90, s40, v216
	v_fmac_f32_e32 v91, s40, v158
	v_fmac_f32_e32 v92, s40, v217
	v_fmac_f32_e32 v93, s40, v159
	global_store_dwordx4 v[140:141], v[90:93], off offset:64
	s_waitcnt vmcnt(18)
	v_permlane16_swap_b32_e32 v162, v164
	v_permlane16_swap_b32_e32 v163, v165
	v_lshlrev_b32_e32 v216, 16, v162
	v_and_b32_e32 v162, 0xffff0000, v162
	v_lshlrev_b32_e32 v217, 16, v163
	v_and_b32_e32 v163, 0xffff0000, v163
	v_fmac_f32_e32 v58, s40, v216
	v_fmac_f32_e32 v59, s40, v162
	v_fmac_f32_e32 v60, s40, v217
	v_fmac_f32_e32 v61, s40, v163
	global_store_dwordx4 v[140:141], v[58:61], off offset:128
	v_lshlrev_b32_e32 v216, 16, v164
	v_and_b32_e32 v164, 0xffff0000, v164
	v_lshlrev_b32_e32 v217, 16, v165
	v_and_b32_e32 v165, 0xffff0000, v165
	v_fmac_f32_e32 v26, s40, v216
	v_fmac_f32_e32 v27, s40, v164
	v_fmac_f32_e32 v28, s40, v217
	v_fmac_f32_e32 v29, s40, v165
	global_store_dwordx4 v[140:141], v[26:29], off offset:192
	v_lshl_add_u64 v[140:141], v[140:141], 0, s[8:9]
	s_waitcnt vmcnt(19)
	v_permlane16_swap_b32_e32 v166, v168
	v_permlane16_swap_b32_e32 v167, v169
	v_lshlrev_b32_e32 v216, 16, v166
	v_and_b32_e32 v166, 0xffff0000, v166
	v_lshlrev_b32_e32 v217, 16, v167
	v_and_b32_e32 v167, 0xffff0000, v167
	v_fmac_f32_e32 v118, s40, v216
	v_fmac_f32_e32 v119, s40, v166
	v_fmac_f32_e32 v120, s40, v217
	v_fmac_f32_e32 v121, s40, v167
	global_store_dwordx4 v[140:141], v[118:121], off offset:0
	v_lshlrev_b32_e32 v216, 16, v168
	v_and_b32_e32 v168, 0xffff0000, v168
	v_lshlrev_b32_e32 v217, 16, v169
	v_and_b32_e32 v169, 0xffff0000, v169
	v_fmac_f32_e32 v86, s40, v216
	v_fmac_f32_e32 v87, s40, v168
	v_fmac_f32_e32 v88, s40, v217
	v_fmac_f32_e32 v89, s40, v169
	global_store_dwordx4 v[140:141], v[86:89], off offset:64
	s_waitcnt vmcnt(20)
; DEVI float blo(unsigned u) { return __uint_as_float(u << 16); }
; DEVI float bhi(unsigned u) { return __uint_as_float(u & 0xffff0000u); }
;     ...
;         if (EPI == EPI_RESID || EPI == EPI_RESID_ATOMIC) {
;           f32x4 x = a;
;           if (EPI == EPI_RESID || kpart == 0) {
;             const u32x2 xr = *(const u32x2*)((const u16*)(p.ws + WS_XB) + (size_t)row * 1024 + col);
;             x[0] += ALPHA * blo(xr[0]); x[1] += ALPHA * bhi(xr[0]); x[2] += ALPHA * blo(xr[1]); x[3] += ALPHA * bhi(xr[1]);
;           }
;           if (EPI == EPI_RESID) *(f32x4*)((float*)(p.ws + WS_XF) + (size_t)row * 1024 + col) = x;
;           else *(f32x4*)((float*)(p.ws + WS_SLAB) + ((size_t)kpart * 512 + (row - T_P)) * 1024 + col) = x;
	v_permlane16_swap_b32_e32 v170, v172
	v_permlane16_swap_b32_e32 v171, v173
	v_lshlrev_b32_e32 v216, 16, v170
	v_and_b32_e32 v170, 0xffff0000, v170
	v_lshlrev_b32_e32 v217, 16, v171
	v_and_b32_e32 v171, 0xffff0000, v171
	v_fmac_f32_e32 v54, s40, v216
	v_fmac_f32_e32 v55, s40, v170
	v_fmac_f32_e32 v56, s40, v217
	v_fmac_f32_e32 v57, s40, v171
	global_store_dwordx4 v[140:141], v[54:57], off offset:128
	v_lshlrev_b32_e32 v216, 16, v172
	v_and_b32_e32 v172, 0xffff0000, v172
	v_lshlrev_b32_e32 v217, 16, v173
	v_and_b32_e32 v173, 0xffff0000, v173
	v_fmac_f32_e32 v22, s40, v216
	v_fmac_f32_e32 v23, s40, v172
	v_fmac_f32_e32 v24, s40, v217
	v_fmac_f32_e32 v25, s40, v173
	global_store_dwordx4 v[140:141], v[22:25], off offset:192
	v_lshl_add_u64 v[140:141], v[140:141], 0, s[8:9]
	s_waitcnt vmcnt(21)
	v_permlane16_swap_b32_e32 v176, v178
	v_permlane16_swap_b32_e32 v177, v179
	v_lshlrev_b32_e32 v216, 16, v176
	v_and_b32_e32 v176, 0xffff0000, v176
	v_lshlrev_b32_e32 v217, 16, v177
	v_and_b32_e32 v177, 0xffff0000, v177
	v_fmac_f32_e32 v114, s40, v216
	v_fmac_f32_e32 v115, s40, v176
	v_fmac_f32_e32 v116, s40, v217
	v_fmac_f32_e32 v117, s40, v177
	global_store_dwordx4 v[140:141], v[114:117], off offset:0
	v_lshlrev_b32_e32 v216, 16, v178
	v_and_b32_e32 v178, 0xffff0000, v178
	v_lshlrev_b32_e32 v217, 16, v179
	v_and_b32_e32 v179, 0xffff0000, v179
	v_fmac_f32_e32 v82, s40, v216
	v_fmac_f32_e32 v83, s40, v178
	v_fmac_f32_e32 v84, s40, v217
	v_fmac_f32_e32 v85, s40, v179
	global_store_dwordx4 v[140:141], v[82:85], off offset:64
	s_waitcnt vmcnt(22)
	v_permlane16_swap_b32_e32 v180, v182
	v_permlane16_swap_b32_e32 v181, v183
	v_lshlrev_b32_e32 v216, 16, v180
	v_and_b32_e32 v180, 0xffff0000, v180
	v_lshlrev_b32_e32 v217, 16, v181
	v_and_b32_e32 v181, 0xffff0000, v181
	v_fmac_f32_e32 v50, s40, v216
	v_fmac_f32_e32 v51, s40, v180
	v_fmac_f32_e32 v52, s40, v217
	v_fmac_f32_e32 v53, s40, v181
	global_store_dwordx4 v[140:141], v[50:53], off offset:128
	v_lshlrev_b32_e32 v216, 16, v182
	v_and_b32_e32 v182, 0xffff0000, v182
	v_lshlrev_b32_e32 v217, 16, v183
	v_and_b32_e32 v183, 0xffff0000, v183
	v_fmac_f32_e32 v18, s40, v216
	v_fmac_f32_e32 v19, s40, v182
	v_fmac_f32_e32 v20, s40, v217
	v_fmac_f32_e32 v21, s40, v183
	global_store_dwordx4 v[140:141], v[18:21], off offset:192
	v_lshl_add_u64 v[140:141], v[140:141], 0, s[8:9]
	s_waitcnt vmcnt(23)
	v_permlane16_swap_b32_e32 v184, v186
	v_permlane16_swap_b32_e32 v185, v187
	v_lshlrev_b32_e32 v216, 16, v184
	v_and_b32_e32 v184, 0xffff0000, v184
	v_lshlrev_b32_e32 v217, 16, v185
	v_and_b32_e32 v185, 0xffff0000, v185
	v_fmac_f32_e32 v110, s40, v216
	v_fmac_f32_e32 v111, s40, v184
	v_fmac_f32_e32 v112, s40, v217
	v_fmac_f32_e32 v113, s40, v185
	global_store_dwordx4 v[140:141], v[110:113], off offset:0
	v_lshlrev_b32_e32 v216, 16, v186
	v_and_b32_e32 v186, 0xffff0000, v186
	v_lshlrev_b32_e32 v217, 16, v187
	v_and_b32_e32 v187, 0xffff0000, v187
	v_fmac_f32_e32 v78, s40, v216
	v_fmac_f32_e32 v79, s40, v186
	v_fmac_f32_e32 v80, s40, v217
	v_fmac_f32_e32 v81, s40, v187
	global_store_dwordx4 v[140:141], v[78:81], off offset:64
	s_waitcnt vmcnt(24)
	v_permlane16_swap_b32_e32 v188, v190
	v_permlane16_swap_b32_e32 v189, v191
	v_lshlrev_b32_e32 v216, 16, v188
	v_and_b32_e32 v188, 0xffff0000, v188
	v_lshlrev_b32_e32 v217, 16, v189
	v_and_b32_e32 v189, 0xffff0000, v189
	v_fmac_f32_e32 v46, s40, v216
	v_fmac_f32_e32 v47, s40, v188
	v_fmac_f32_e32 v48, s40, v217
	v_fmac_f32_e32 v49, s40, v189
	global_store_dwordx4 v[140:141], v[46:49], off offset:128
	v_lshlrev_b32_e32 v216, 16, v190
	v_and_b32_e32 v190, 0xffff0000, v190
	v_lshlrev_b32_e32 v217, 16, v191
	v_and_b32_e32 v191, 0xffff0000, v191
	v_fmac_f32_e32 v14, s40, v216
	v_fmac_f32_e32 v15, s40, v190
	v_fmac_f32_e32 v16, s40, v217
	v_fmac_f32_e32 v17, s40, v191
	global_store_dwordx4 v[140:141], v[14:17], off offset:192
	v_lshl_add_u64 v[140:141], v[140:141], 0, s[8:9]
	s_waitcnt vmcnt(25)
	v_permlane16_swap_b32_e32 v192, v194
	v_permlane16_swap_b32_e32 v193, v195
	v_lshlrev_b32_e32 v216, 16, v192
	v_and_b32_e32 v192, 0xffff0000, v192
	v_lshlrev_b32_e32 v217, 16, v193
	v_and_b32_e32 v193, 0xffff0000, v193
	v_fmac_f32_e32 v106, s40, v216
	v_fmac_f32_e32 v107, s40, v192
	v_fmac_f32_e32 v108, s40, v217
	v_fmac_f32_e32 v109, s40, v193
	global_store_dwordx4 v[140:141], v[106:109], off offset:0
	v_lshlrev_b32_e32 v216, 16, v194
	v_and_b32_e32 v194, 0xffff0000, v194
	v_lshlrev_b32_e32 v217, 16, v195
	v_and_b32_e32 v195, 0xffff0000, v195
	v_fmac_f32_e32 v74, s40, v216
	v_fmac_f32_e32 v75, s40, v194
	v_fmac_f32_e32 v76, s40, v217
	v_fmac_f32_e32 v77, s40, v195
	global_store_dwordx4 v[140:141], v[74:77], off offset:64
	s_waitcnt vmcnt(26)
; DEVI float blo(unsigned u) { return __uint_as_float(u << 16); }
; DEVI float bhi(unsigned u) { return __uint_as_float(u & 0xffff0000u); }
;     ...
;         if (EPI == EPI_RESID || EPI == EPI_RESID_ATOMIC) {
;           f32x4 x = a;
;           if (EPI == EPI_RESID || kpart == 0) {
;             const u32x2 xr = *(const u32x2*)((const u16*)(p.ws + WS_XB) + (size_t)row * 1024 + col);
;             x[0] += ALPHA * blo(xr[0]); x[1] += ALPHA * bhi(xr[0]); x[2] += ALPHA * blo(xr[1]); x[3] += ALPHA * bhi(xr[1]);
;           }
;           if (EPI == EPI_RESID) *(f32x4*)((float*)(p.ws + WS_XF) + (size_t)row * 1024 + col) = x;
;           else *(f32x4*)((float*)(p.ws + WS_SLAB) + ((size_t)kpart * 512 + (row - T_P)) * 1024 + col) = x;
	v_permlane16_swap_b32_e32 v196, v198
	v_permlane16_swap_b32_e32 v197, v199
	v_lshlrev_b32_e32 v216, 16, v196
	v_and_b32_e32 v196, 0xffff0000, v196
	v_lshlrev_b32_e32 v217, 16, v197
	v_and_b32_e32 v197, 0xffff0000, v197
	v_fmac_f32_e32 v42, s40, v216
	v_fmac_f32_e32 v43, s40, v196
	v_fmac_f32_e32 v44, s40, v217
	v_fmac_f32_e32 v45, s40, v197
	global_store_dwordx4 v[140:141], v[42:45], off offset:128
	v_lshlrev_b32_e32 v216, 16, v198
	v_and_b32_e32 v198, 0xffff0000, v198
	v_lshlrev_b32_e32 v217, 16, v199
	v_and_b32_e32 v199, 0xffff0000, v199
	v_fmac_f32_e32 v10, s40, v216
	v_fmac_f32_e32 v11, s40, v198
	v_fmac_f32_e32 v12, s40, v217
	v_fmac_f32_e32 v13, s40, v199
	global_store_dwordx4 v[140:141], v[10:13], off offset:192
	v_lshl_add_u64 v[140:141], v[140:141], 0, s[8:9]
	s_waitcnt vmcnt(27)
	v_permlane16_swap_b32_e32 v200, v202
	v_permlane16_swap_b32_e32 v201, v203
	v_lshlrev_b32_e32 v216, 16, v200
	v_and_b32_e32 v200, 0xffff0000, v200
	v_lshlrev_b32_e32 v217, 16, v201
	v_and_b32_e32 v201, 0xffff0000, v201
	v_fmac_f32_e32 v102, s40, v216
	v_fmac_f32_e32 v103, s40, v200
	v_fmac_f32_e32 v104, s40, v217
	v_fmac_f32_e32 v105, s40, v201
	global_store_dwordx4 v[140:141], v[102:105], off offset:0
	v_lshlrev_b32_e32 v216, 16, v202
	v_and_b32_e32 v202, 0xffff0000, v202
	v_lshlrev_b32_e32 v217, 16, v203
	v_and_b32_e32 v203, 0xffff0000, v203
	v_fmac_f32_e32 v70, s40, v216
	v_fmac_f32_e32 v71, s40, v202
	v_fmac_f32_e32 v72, s40, v217
	v_fmac_f32_e32 v73, s40, v203
	global_store_dwordx4 v[140:141], v[70:73], off offset:64
	s_waitcnt vmcnt(28)
	v_permlane16_swap_b32_e32 v204, v206
	v_permlane16_swap_b32_e32 v205, v207
	v_lshlrev_b32_e32 v216, 16, v204
	v_and_b32_e32 v204, 0xffff0000, v204
	v_lshlrev_b32_e32 v217, 16, v205
	v_and_b32_e32 v205, 0xffff0000, v205
	v_fmac_f32_e32 v38, s40, v216
	v_fmac_f32_e32 v39, s40, v204
	v_fmac_f32_e32 v40, s40, v217
	v_fmac_f32_e32 v41, s40, v205
	global_store_dwordx4 v[140:141], v[38:41], off offset:128
	v_lshlrev_b32_e32 v216, 16, v206
	v_and_b32_e32 v206, 0xffff0000, v206
	v_lshlrev_b32_e32 v217, 16, v207
	v_and_b32_e32 v207, 0xffff0000, v207
	v_fmac_f32_e32 v6, s40, v216
	v_fmac_f32_e32 v7, s40, v206
	v_fmac_f32_e32 v8, s40, v217
	v_fmac_f32_e32 v9, s40, v207
	global_store_dwordx4 v[140:141], v[6:9], off offset:192
	v_lshl_add_u64 v[140:141], v[140:141], 0, s[8:9]
	s_waitcnt vmcnt(29)
	v_permlane16_swap_b32_e32 v208, v210
	v_permlane16_swap_b32_e32 v209, v211
	v_lshlrev_b32_e32 v216, 16, v208
	v_and_b32_e32 v208, 0xffff0000, v208
	v_lshlrev_b32_e32 v217, 16, v209
	v_and_b32_e32 v209, 0xffff0000, v209
	v_fmac_f32_e32 v98, s40, v216
	v_fmac_f32_e32 v99, s40, v208
	v_fmac_f32_e32 v100, s40, v217
	v_fmac_f32_e32 v101, s40, v209
	global_store_dwordx4 v[140:141], v[98:101], off offset:0
	v_lshlrev_b32_e32 v216, 16, v210
	v_and_b32_e32 v210, 0xffff0000, v210
	v_lshlrev_b32_e32 v217, 16, v211
	v_and_b32_e32 v211, 0xffff0000, v211
	v_fmac_f32_e32 v66, s40, v216
	v_fmac_f32_e32 v67, s40, v210
	v_fmac_f32_e32 v68, s40, v217
	v_fmac_f32_e32 v69, s40, v211
	global_store_dwordx4 v[140:141], v[66:69], off offset:64
	s_waitcnt vmcnt(30)
	v_permlane16_swap_b32_e32 v212, v214
	v_permlane16_swap_b32_e32 v213, v215
	v_lshlrev_b32_e32 v216, 16, v212
	v_and_b32_e32 v212, 0xffff0000, v212
	v_lshlrev_b32_e32 v217, 16, v213
	v_and_b32_e32 v213, 0xffff0000, v213
	v_fmac_f32_e32 v34, s40, v216
	v_fmac_f32_e32 v35, s40, v212
	v_fmac_f32_e32 v36, s40, v217
	v_fmac_f32_e32 v37, s40, v213
	global_store_dwordx4 v[140:141], v[34:37], off offset:128
	v_lshlrev_b32_e32 v216, 16, v214
	v_and_b32_e32 v214, 0xffff0000, v214
	v_lshlrev_b32_e32 v217, 16, v215
	v_and_b32_e32 v215, 0xffff0000, v215
	v_fmac_f32_e32 v2, s40, v216
	v_fmac_f32_e32 v3, s40, v214
	v_fmac_f32_e32 v4, s40, v217
	v_fmac_f32_e32 v5, s40, v215
	global_store_dwordx4 v[140:141], v[2:5], off offset:192
	v_readlane_b32 s0, v250, 7
	s_cmpk_lg_u32 s0, 0x200
	s_cbranch_scc1 .Lta8_ar2
	s_mov_b32 s0, 1
	v_writelane_b32 v255, s0, 41
	v_readlane_b32 s1, v250, 0
	s_lshr_b32 s12, s1, 3
	s_and_b32 s1, s1, 7
	s_lshl_b32 s1, s1, 6
	s_add_i32 s1, s1, s12
	s_sub_i32 s38, s1, 0x200

; #define LAS __attribute__((address_space(3)))
; DEVI int xcd_first_tile() { return (blockIdx.x & 7) * (gridDim.x >> 3) + (blockIdx.x >> 3); }
;     ...
;   const int nk = (nk_part < 0) ? (K >> 5) : nk_part;
;   const int lrow = tid >> 2, lpc = tid & 3;
;   const int lch = lpc ^ ((0x78 >> (((lrow >> 2) & 3) * 2)) & 3);
;   const u16* ga = A + (size_t)(m0 + lrow) * lda + kbeg + lch * 8;
;   const u16* gb = Bt + (size_t)(n0 + lrow) * K + kbeg + lch * 8;
;   const size_t ga1 = (size_t)64 * lda, gb1 = (size_t)64 * K;
;   const unsigned lds0 = (unsigned)(uintptr_t)(LAS char*)smem + (unsigned)__builtin_amdgcn_readfirstlane(wid) * 1024u;
;     ...
;   __syncthreads();
;   G2_STAGE(0); G2_STAGE(1);
;   const int fsw = (0x78 >> (((r16 >> 2) & 3) * 2)) & 3;
;   const int aoff = (wm * 128 + r16) * 64 + ((quad ^ fsw) << 4);
;   const int boff = 16384 + (wn * 64 + r16) * 64 + ((quad ^ fsw) << 4);
; DEVI void run_phase(const Params& p, int ph, char* smem) {
;     ...
;       for (int t = xcd_first_tile(); t < 512 + 16 * 2; t += xcd_tile_step()) {
;         if (t < 512) {
;           int mt_, nt_; tile_coords(t, 64, 8, mt_, nt_);
;           gemm_tile256<EPI_RESID>(p, ox, 256, Bt, 256, mt_ * 256, nt_ * 128, nullptr, 0, smem);
;         } else {
;           const int u_ = t - 512, tl_ = u_ / 2, q_ = u_ - tl_ * 2;
;           gemm_tile256<EPI_RESID_ATOMIC>(p, ox, 256, Bt, 256, (64 + (tl_ & 1)) * 256, (tl_ >> 1) * 128, nullptr, 0, smem, q_ * 128, 4, q_);
;         }
.LBB0_208:
	s_and_b64 vcc, exec, s[2:3]
	s_cbranch_vccz .LBB0_146
	v_readlane_b32 s39, v250, 7
	s_cmpk_lg_u32 s39, 0x200
	s_cbranch_scc1 .Lt8_go
	v_readlane_b32 s40, v255, 41
	s_cmp_lg_u32 s40, 0
	s_cbranch_scc1 .Lt8_go
	v_readlane_b32 s40, v250, 0
	s_lshr_b32 s41, s40, 3
	s_cmp_lt_u32 s41, 4
	s_cbranch_scc0 .Lt8_go
	s_and_b32 s40, s40, 7
	s_mul_i32 s40, s40, 4
	s_add_i32 s38, s40, s41
	s_branch .LBB0_146
.Lt8_go:
	s_lshr_b32 s45, s38, 6
	s_and_b32 s46, s38, 63
	s_lshr_b32 s42, s46, 3
	s_and_b32 s46, s46, 7
	s_lshl_b32 s45, s45, 3
	s_add_i32 s45, s45, s46
	v_readlane_b32 s2, v250, 5
	v_readlane_b32 s3, v250, 6
	v_readlane_b32 s46, v254, 62
	s_mul_i32 s40, s45, 0x20000
	s_add_u32 s4, s2, s40
	s_addc_u32 s5, s3, 0
	s_add_u32 s4, s4, 0xe700000
	s_addc_u32 s5, s5, 0
	s_mul_i32 s40, s46, 0x80000
	s_mul_i32 s41, s42, 0x10000
	s_add_i32 s40, s40, s41
	s_add_u32 s10, s2, s40
	s_addc_u32 s11, s3, 0
	s_add_u32 s10, s10, 0x16c00000
	s_addc_u32 s11, s11, 0
	s_movk_i32 s39, 0x78
	v_lshrrev_b32_e32 v0, 2, v145
	v_and_b32_e32 v131, 3, v145
	v_bfe_u32 v136, v145, 4, 2
	v_lshlrev_b32_e32 v136, 1, v136
	v_lshrrev_b32_e64 v136, v136, s39
	v_and_b32_e32 v136, 3, v136
	v_xor_b32_e32 v131, v131, v136
	v_lshlrev_b32_e32 v131, 4, v131
	s_movk_i32 s41, 0x200
	v_mad_u32_u24 v0, v0, s41, v131
	v_bfe_u32 v137, v145, 2, 1
	s_movk_i32 s41, 0x1c0
	v_mul_u32_u24_e32 v136, s41, v137
	v_sub_u32_e32 v136, v0, v136
	v_mov_b32_e32 v137, 0
	v_lshl_add_u64 v[134:135], s[10:11], 0, v[136:137]
	v_bfe_u32 v137, v145, 2, 1
	s_mov_b32 s12, 64
	s_mov_b32 s13, 0
	v_lshl_add_u64 v[132:133], s[4:5], 0, v[0:1]
	v_bfe_u32 v136, v145, 2, 2
	v_lshlrev_b32_e32 v136, 1, v136
	v_lshrrev_b32_e64 v136, v136, s39
	v_and_b32_e32 v136, 3, v136
	v_bfe_u32 v137, v145, 4, 2
	v_xor_b32_e32 v136, v136, v137
	v_lshlrev_b32_e32 v136, 4, v136
	v_and_b32_e32 v131, 15, v145
	v_lshl_or_b32 v136, v131, 6, v136
	v_bfe_u32 v137, v145, 6, 1
	v_lshl_or_b32 v137, v137, 12, v136
	v_lshrrev_b32_e32 v0, 7, v145
	v_lshl_or_b32 v136, v0, 13, v136
	v_and_b32_e32 v140, 1, v131
	v_lshl_or_b32 v131, v0, 7, v131
	v_bfe_u32 v0, v145, 4, 2
	v_lshlrev_b32_e32 v0, 3, v0
	v_bfe_u32 v141, v145, 6, 1
	s_lshl_b32 s40, s45, 19
	s_lshl_b32 s41, s42, 8
	s_add_i32 s40, s40, s41
	s_add_u32 s4, s2, s40
	s_addc_u32 s5, s3, 0
	s_add_u32 s4, s4, 0x4200000
	s_addc_u32 s5, s5, 0
	v_lshlrev_b32_e32 v138, 11, v131
	v_lshl_add_u32 v138, v141, 7, v138
	v_bfe_u32 v139, v145, 4, 1
	v_lshl_add_u32 v138, v139, 5, v138
	v_bfe_u32 v139, v145, 5, 1
	v_lshl_add_u32 v138, v139, 4, v138
	v_mov_b32_e32 v139, 0
	v_lshl_add_u64 v[138:139], s[4:5], 0, v[138:139]
	s_lshl_b32 s40, s45, 20
	s_lshl_b32 s41, s42, 9
	s_add_i32 s40, s40, s41
	s_add_u32 s10, s2, s40
	s_addc_u32 s11, s3, 0
	v_lshlrev_b32_e32 v140, 12, v131
	v_lshl_add_u32 v140, v141, 8, v140
	v_lshl_add_u32 v140, v0, 1, v140
	v_mov_b32_e32 v141, 0
	v_lshl_add_u64 v[140:141], s[10:11], 0, v[140:141]
	s_mov_b32 s2, 0x8000
	s_mov_b32 s3, 0
	v_lshrrev_b32_e32 v0, 6, v145
	v_lshlrev_b32_e32 v0, 10, v0
	s_nop 0
	v_readfirstlane_b32 s46, v0
	s_mov_b32 s43, m0
	s_mov_b32 s4, 128
	s_mov_b32 s5, 0
	s_barrier
	s_add_i32 s42, s46, 0x0
	s_mov_b32 m0, s42
	v_lshl_add_u64 v[142:143], v[132:133], 0, s[2:3]
	global_load_lds_dwordx4 v[132:133], off
	s_add_i32 m0, m0, 0x1000
	s_nop 0
	global_load_lds_dwordx4 v[142:143], off
	v_lshl_add_u64 v[142:143], v[142:143], 0, s[2:3]
	s_add_i32 m0, m0, 0x1000
	s_nop 0
	global_load_lds_dwordx4 v[142:143], off
	v_lshl_add_u64 v[142:143], v[142:143], 0, s[2:3]
	s_add_i32 m0, m0, 0x1000
	s_nop 0
	global_load_lds_dwordx4 v[142:143], off
	s_add_i32 m0, m0, 0x1000
	v_lshl_add_u64 v[142:143], v[134:135], 0, s[2:3]
	s_nop 0
	global_load_lds_dwordx4 v[134:135], off
	s_add_i32 m0, m0, 0x1000
	v_lshl_add_u64 v[132:133], v[132:133], 0, s[12:13]
	s_nop 0
	global_load_lds_dwordx4 v[142:143], off
	v_lshl_add_u64 v[134:135], v[134:135], 0, s[4:5]
	s_nop 0
	s_add_i32 s42, s46, 0x6000
	s_mov_b32 m0, s42
	v_lshl_add_u64 v[142:143], v[132:133], 0, s[2:3]
	global_load_lds_dwordx4 v[132:133], off
	s_add_i32 m0, m0, 0x1000
	s_nop 0
	global_load_lds_dwordx4 v[142:143], off
	v_lshl_add_u64 v[142:143], v[142:143], 0, s[2:3]
	s_add_i32 m0, m0, 0x1000
	s_nop 0
	global_load_lds_dwordx4 v[142:143], off
	v_lshl_add_u64 v[142:143], v[142:143], 0, s[2:3]
	s_add_i32 m0, m0, 0x1000
	s_nop 0
	global_load_lds_dwordx4 v[142:143], off
	s_add_i32 m0, m0, 0x1000
	v_lshl_add_u64 v[142:143], v[134:135], 0, s[2:3]
	s_nop 0
	global_load_lds_dwordx4 v[134:135], off
	s_add_i32 m0, m0, 0x1000
	v_lshl_add_u64 v[132:133], v[132:133], 0, s[12:13]
	s_nop 0
	global_load_lds_dwordx4 v[142:143], off
	v_lshl_add_u64 v[134:135], v[134:135], 0, s[4:5]
	s_nop 0
	s_add_i32 s42, s46, 0xc000
	s_mov_b32 m0, s42
	v_lshl_add_u64 v[142:143], v[132:133], 0, s[2:3]
	global_load_lds_dwordx4 v[132:133], off
	s_add_i32 m0, m0, 0x1000
	s_nop 0
	global_load_lds_dwordx4 v[142:143], off
	v_lshl_add_u64 v[142:143], v[142:143], 0, s[2:3]
	s_add_i32 m0, m0, 0x1000
	s_nop 0
	global_load_lds_dwordx4 v[142:143], off
	v_lshl_add_u64 v[142:143], v[142:143], 0, s[2:3]
	s_add_i32 m0, m0, 0x1000
	s_nop 0
	global_load_lds_dwordx4 v[142:143], off
	s_add_i32 m0, m0, 0x1000
	v_lshl_add_u64 v[142:143], v[134:135], 0, s[2:3]
	s_nop 0
	global_load_lds_dwordx4 v[134:135], off
	s_add_i32 m0, m0, 0x1000
	v_lshl_add_u64 v[132:133], v[132:133], 0, s[12:13]
	s_nop 0
	global_load_lds_dwordx4 v[142:143], off
	v_lshl_add_u64 v[134:135], v[134:135], 0, s[4:5]
	s_nop 0
	v_mov_b32_e32 v2, 0
	v_mov_b32_e32 v3, 0
	v_mov_b32_e32 v4, 0
	v_mov_b32_e32 v5, 0
	v_mov_b32_e32 v6, 0
	v_mov_b32_e32 v7, 0
	v_mov_b32_e32 v8, 0
	v_mov_b32_e32 v9, 0
	v_mov_b32_e32 v10, 0
	v_mov_b32_e32 v11, 0
; #define LAS __attribute__((address_space(3)))
;     ...
;   f32x4 acc[4][8];
; #pragma unroll
;   for (int i = 0; i < 4; i++)
; #pragma unroll
;     for (int j = 0; j < 8; j++) acc[i][j] = (f32x4){0.f, 0.f, 0.f, 0.f};
;   const int nk = (nk_part < 0) ? (K >> 5) : nk_part;
;   const int lrow = tid >> 2, lpc = tid & 3;
;   const int lch = lpc ^ ((0x78 >> (((lrow >> 2) & 3) * 2)) & 3);
;   const u16* ga = A + (size_t)(m0 + lrow) * lda + kbeg + lch * 8;
;   const u16* gb = Bt + (size_t)(n0 + lrow) * K + kbeg + lch * 8;
;   const size_t ga1 = (size_t)64 * lda, gb1 = (size_t)64 * K;
;   const unsigned lds0 = (unsigned)(uintptr_t)(LAS char*)smem + (unsigned)__builtin_amdgcn_readfirstlane(wid) * 1024u;
;     ...
;   __syncthreads();
;   G2_STAGE(0); G2_STAGE(1);
;   const int fsw = (0x78 >> (((r16 >> 2) & 3) * 2)) & 3;
;   const int aoff = (wm * 128 + r16) * 64 + ((quad ^ fsw) << 4);
;   const int boff = 16384 + (wn * 64 + r16) * 64 + ((quad ^ fsw) << 4);
;   for (int kt = 0; kt < nk; kt++) {
;     if (kt + 1 < nk) asm volatile("s_waitcnt vmcnt(6)" ::: "memory");
;     else asm volatile("s_waitcnt vmcnt(0)" ::: "memory");
;     __builtin_amdgcn_s_barrier();
;     asm volatile("" ::: "memory");
;     if (kt + 2 < nk) G2_STAGE(kt + 2);
;     const char* cS = smem + (kt % 3) * 24576;
;     bf16x8 xa[8], wb[4];
; #pragma unroll
;     for (int f = 0; f < 8; f++) xa[f] = *(const bf16x8*)(cS + aoff + f * 1024);
; #pragma unroll
;     for (int f = 0; f < 4; f++) wb[f] = *(const bf16x8*)(cS + boff + f * 1024);
; #pragma unroll
;     for (int nf = 0; nf < 4; nf++)
; #pragma unroll
;       for (int mf = 0; mf < 8; mf++)
;         acc[nf][mf] = __builtin_amdgcn_mfma_f32_16x16x32_bf16(wb[nf], xa[mf], acc[nf][mf], 0, 0, 0);
	v_mov_b32_e32 v12, 0
	v_mov_b32_e32 v13, 0
	v_mov_b32_e32 v14, 0
	v_mov_b32_e32 v15, 0
	v_mov_b32_e32 v16, 0
	v_mov_b32_e32 v17, 0
	v_mov_b32_e32 v18, 0
	v_mov_b32_e32 v19, 0
	v_mov_b32_e32 v20, 0
	v_mov_b32_e32 v21, 0
	v_mov_b32_e32 v22, 0
	v_mov_b32_e32 v23, 0
	v_mov_b32_e32 v24, 0
	v_mov_b32_e32 v25, 0
	v_mov_b32_e32 v26, 0
	v_mov_b32_e32 v27, 0
	v_mov_b32_e32 v28, 0
	v_mov_b32_e32 v29, 0
	v_mov_b32_e32 v30, 0
	v_mov_b32_e32 v31, 0
	v_mov_b32_e32 v32, 0
	v_mov_b32_e32 v33, 0
	v_mov_b32_e32 v34, 0
	v_mov_b32_e32 v35, 0
	v_mov_b32_e32 v36, 0
	v_mov_b32_e32 v37, 0
	v_mov_b32_e32 v38, 0
	v_mov_b32_e32 v39, 0
	v_mov_b32_e32 v40, 0
	v_mov_b32_e32 v41, 0
	v_mov_b32_e32 v42, 0
	v_mov_b32_e32 v43, 0
	v_mov_b32_e32 v44, 0
	v_mov_b32_e32 v45, 0
	v_mov_b32_e32 v46, 0
	v_mov_b32_e32 v47, 0
	v_mov_b32_e32 v48, 0
	v_mov_b32_e32 v49, 0
	v_mov_b32_e32 v50, 0
	v_mov_b32_e32 v51, 0
	v_mov_b32_e32 v52, 0
	v_mov_b32_e32 v53, 0
	v_mov_b32_e32 v54, 0
	v_mov_b32_e32 v55, 0
	v_mov_b32_e32 v56, 0
	v_mov_b32_e32 v57, 0
	v_mov_b32_e32 v58, 0
	v_mov_b32_e32 v59, 0
	v_mov_b32_e32 v60, 0
	v_mov_b32_e32 v61, 0
	v_mov_b32_e32 v62, 0
	v_mov_b32_e32 v63, 0
	v_mov_b32_e32 v64, 0
	v_mov_b32_e32 v65, 0
	v_mov_b32_e32 v66, 0
	v_mov_b32_e32 v67, 0
	v_mov_b32_e32 v68, 0
	v_mov_b32_e32 v69, 0
	v_mov_b32_e32 v70, 0
	v_mov_b32_e32 v71, 0
	v_mov_b32_e32 v72, 0
	v_mov_b32_e32 v73, 0
	v_mov_b32_e32 v74, 0
	v_mov_b32_e32 v75, 0
	v_mov_b32_e32 v76, 0
	v_mov_b32_e32 v77, 0
	v_mov_b32_e32 v78, 0
	v_mov_b32_e32 v79, 0
	v_mov_b32_e32 v80, 0
	v_mov_b32_e32 v81, 0
	v_mov_b32_e32 v82, 0
	v_mov_b32_e32 v83, 0
	v_mov_b32_e32 v84, 0
	v_mov_b32_e32 v85, 0
	v_mov_b32_e32 v86, 0
	v_mov_b32_e32 v87, 0
	v_mov_b32_e32 v88, 0
	v_mov_b32_e32 v89, 0
	v_mov_b32_e32 v90, 0
	v_mov_b32_e32 v91, 0
	v_mov_b32_e32 v92, 0
	v_mov_b32_e32 v93, 0
	v_mov_b32_e32 v94, 0
	v_mov_b32_e32 v95, 0
	v_mov_b32_e32 v96, 0
	v_mov_b32_e32 v97, 0
	v_mov_b32_e32 v98, 0
	v_mov_b32_e32 v99, 0
	v_mov_b32_e32 v100, 0
	v_mov_b32_e32 v101, 0
	v_mov_b32_e32 v102, 0
	v_mov_b32_e32 v103, 0
	v_mov_b32_e32 v104, 0
	v_mov_b32_e32 v105, 0
	v_mov_b32_e32 v106, 0
	v_mov_b32_e32 v107, 0
	v_mov_b32_e32 v108, 0
	v_mov_b32_e32 v109, 0
	v_mov_b32_e32 v110, 0
	v_mov_b32_e32 v111, 0
	v_mov_b32_e32 v112, 0
	v_mov_b32_e32 v113, 0
	v_mov_b32_e32 v114, 0
	v_mov_b32_e32 v115, 0
	v_mov_b32_e32 v116, 0
	v_mov_b32_e32 v117, 0
	v_mov_b32_e32 v118, 0
	v_mov_b32_e32 v119, 0
	v_mov_b32_e32 v120, 0
	v_mov_b32_e32 v121, 0
	v_mov_b32_e32 v122, 0
	v_mov_b32_e32 v123, 0
	v_mov_b32_e32 v124, 0
	v_mov_b32_e32 v125, 0
	v_mov_b32_e32 v126, 0
	v_mov_b32_e32 v127, 0
	v_mov_b32_e32 v128, 0
	v_mov_b32_e32 v129, 0
	s_waitcnt vmcnt(12)
	s_barrier
	ds_read_b128 v[146:149], v136 offset:0
	ds_read_b128 v[152:155], v136 offset:1024
	ds_read_b128 v[156:159], v136 offset:2048
	ds_read_b128 v[162:165], v136 offset:3072
	ds_read_b128 v[166:169], v136 offset:4096
	ds_read_b128 v[170:173], v136 offset:5120
	ds_read_b128 v[176:179], v136 offset:6144
	ds_read_b128 v[180:183], v136 offset:7168
	ds_read_b128 v[184:187], v137 offset:16384
	ds_read_b128 v[188:191], v137 offset:17408
	ds_read_b128 v[192:195], v137 offset:18432
	ds_read_b128 v[196:199], v137 offset:19456
	s_movk_i32 s40, 0x6000
	s_mov_b32 s41, 0
	s_movk_i32 s39, 2
	.p2align 6
.Lt8_loop:
	.p2align 3
	s_waitcnt vmcnt(6) lgkmcnt(0)
	s_barrier
	s_setprio 1
	v_add_u32_e32 v144, s40, v136
	v_mfma_f32_16x16x32_bf16 v[126:129], v[184:187], v[146:149], v[126:129]
	ds_read_b128 v[200:203], v144 offset:0
	v_mfma_f32_16x16x32_bf16 v[122:125], v[184:187], v[152:155], v[122:125]
	ds_read_b128 v[204:207], v144 offset:1024
	v_mfma_f32_16x16x32_bf16 v[118:121], v[184:187], v[156:159], v[118:121]
	ds_read_b128 v[208:211], v144 offset:2048
	v_mfma_f32_16x16x32_bf16 v[114:117], v[184:187], v[162:165], v[114:117]
	ds_read_b128 v[212:215], v144 offset:3072
	v_mfma_f32_16x16x32_bf16 v[110:113], v[184:187], v[166:169], v[110:113]
	ds_read_b128 v[216:219], v144 offset:4096
	v_mfma_f32_16x16x32_bf16 v[106:109], v[184:187], v[170:173], v[106:109]
	ds_read_b128 v[220:223], v144 offset:5120
	v_mfma_f32_16x16x32_bf16 v[102:105], v[184:187], v[176:179], v[102:105]
	ds_read_b128 v[224:227], v144 offset:6144
	v_mfma_f32_16x16x32_bf16 v[98:101], v[184:187], v[180:183], v[98:101]
	ds_read_b128 v[228:231], v144 offset:7168
	v_mfma_f32_16x16x32_bf16 v[94:97], v[188:191], v[146:149], v[94:97]
	v_add_u32_e64 v144, s40, v137
	v_mfma_f32_16x16x32_bf16 v[90:93], v[188:191], v[152:155], v[90:93]
	v_mfma_f32_16x16x32_bf16 v[86:89], v[188:191], v[156:159], v[86:89]
	ds_read_b128 v[232:235], v144 offset:16384
	v_mfma_f32_16x16x32_bf16 v[82:85], v[188:191], v[162:165], v[82:85]
	ds_read_b128 v[236:239], v144 offset:17408
	v_mfma_f32_16x16x32_bf16 v[78:81], v[188:191], v[166:169], v[78:81]
	ds_read_b128 v[240:243], v144 offset:18432
	v_mfma_f32_16x16x32_bf16 v[74:77], v[188:191], v[170:173], v[74:77]
	ds_read_b128 v[244:247], v144 offset:19456
	v_mfma_f32_16x16x32_bf16 v[70:73], v[188:191], v[176:179], v[70:73]
	s_add_i32 s42, s46, s41
	s_mov_b32 m0, s42
	v_lshl_add_u64 v[142:143], v[132:133], 0, s[2:3]
	v_mfma_f32_16x16x32_bf16 v[66:69], v[188:191], v[180:183], v[66:69]
	global_load_lds_dwordx4 v[132:133], off
	s_add_i32 m0, m0, 0x1000
	v_mfma_f32_16x16x32_bf16 v[62:65], v[192:195], v[146:149], v[62:65]
	v_mfma_f32_16x16x32_bf16 v[58:61], v[192:195], v[152:155], v[58:61]
	v_mfma_f32_16x16x32_bf16 v[54:57], v[192:195], v[156:159], v[54:57]
	global_load_lds_dwordx4 v[142:143], off
	v_lshl_add_u64 v[142:143], v[142:143], 0, s[2:3]
	s_add_i32 m0, m0, 0x1000
	v_mfma_f32_16x16x32_bf16 v[50:53], v[192:195], v[162:165], v[50:53]
	v_mfma_f32_16x16x32_bf16 v[46:49], v[192:195], v[166:169], v[46:49]
	v_mfma_f32_16x16x32_bf16 v[42:45], v[192:195], v[170:173], v[42:45]
	global_load_lds_dwordx4 v[142:143], off
	v_lshl_add_u64 v[142:143], v[142:143], 0, s[2:3]
	s_add_i32 m0, m0, 0x1000
	v_mfma_f32_16x16x32_bf16 v[38:41], v[192:195], v[176:179], v[38:41]
	v_mfma_f32_16x16x32_bf16 v[34:37], v[192:195], v[180:183], v[34:37]
	v_mfma_f32_16x16x32_bf16 v[30:33], v[196:199], v[146:149], v[30:33]
	global_load_lds_dwordx4 v[142:143], off
	s_add_i32 m0, m0, 0x1000
	v_lshl_add_u64 v[142:143], v[134:135], 0, s[2:3]
	v_mfma_f32_16x16x32_bf16 v[26:29], v[196:199], v[152:155], v[26:29]
	v_mfma_f32_16x16x32_bf16 v[22:25], v[196:199], v[156:159], v[22:25]
	v_mfma_f32_16x16x32_bf16 v[18:21], v[196:199], v[162:165], v[18:21]
	global_load_lds_dwordx4 v[134:135], off
	s_add_i32 m0, m0, 0x1000
	v_lshl_add_u64 v[132:133], v[132:133], 0, s[12:13]
	v_mfma_f32_16x16x32_bf16 v[14:17], v[196:199], v[166:169], v[14:17]
	v_mfma_f32_16x16x32_bf16 v[10:13], v[196:199], v[170:173], v[10:13]
	v_mfma_f32_16x16x32_bf16 v[6:9], v[196:199], v[176:179], v[6:9]
	global_load_lds_dwordx4 v[142:143], off
	v_lshl_add_u64 v[134:135], v[134:135], 0, s[4:5]
	v_mfma_f32_16x16x32_bf16 v[2:5], v[196:199], v[180:183], v[2:5]
	s_setprio 0
	s_mov_b32 s41, s40
	s_add_i32 s40, s40, 0x6000
	s_cmp_eq_u32 s40, 0x12000
	s_cselect_b32 s40, 0, s40
	s_nop 0
	.p2align 3
	s_waitcnt vmcnt(6) lgkmcnt(0)
	s_barrier
;     ...
;   for (int kt = 0; kt < nk; kt++) {
;     if (kt + 1 < nk) asm volatile("s_waitcnt vmcnt(6)" ::: "memory");
;     else asm volatile("s_waitcnt vmcnt(0)" ::: "memory");
;     __builtin_amdgcn_s_barrier();
;     asm volatile("" ::: "memory");
;     if (kt + 2 < nk) G2_STAGE(kt + 2);
;     const char* cS = smem + (kt % 3) * 24576;
;     bf16x8 xa[8], wb[4];
; #pragma unroll
;     for (int f = 0; f < 8; f++) xa[f] = *(const bf16x8*)(cS + aoff + f * 1024);
; #pragma unroll
;     for (int f = 0; f < 4; f++) wb[f] = *(const bf16x8*)(cS + boff + f * 1024);
; #pragma unroll
;     for (int nf = 0; nf < 4; nf++)
; #pragma unroll
;       for (int mf = 0; mf < 8; mf++)
;         acc[nf][mf] = __builtin_amdgcn_mfma_f32_16x16x32_bf16(wb[nf], xa[mf], acc[nf][mf], 0, 0, 0);
	s_setprio 1
	v_add_u32_e32 v144, s40, v136
	v_mfma_f32_16x16x32_bf16 v[126:129], v[232:235], v[200:203], v[126:129]
	ds_read_b128 v[146:149], v144 offset:0
	v_mfma_f32_16x16x32_bf16 v[122:125], v[232:235], v[204:207], v[122:125]
	ds_read_b128 v[152:155], v144 offset:1024
	v_mfma_f32_16x16x32_bf16 v[118:121], v[232:235], v[208:211], v[118:121]
	ds_read_b128 v[156:159], v144 offset:2048
	v_mfma_f32_16x16x32_bf16 v[114:117], v[232:235], v[212:215], v[114:117]
	ds_read_b128 v[162:165], v144 offset:3072
	v_mfma_f32_16x16x32_bf16 v[110:113], v[232:235], v[216:219], v[110:113]
	ds_read_b128 v[166:169], v144 offset:4096
	v_mfma_f32_16x16x32_bf16 v[106:109], v[232:235], v[220:223], v[106:109]
	ds_read_b128 v[170:173], v144 offset:5120
	v_mfma_f32_16x16x32_bf16 v[102:105], v[232:235], v[224:227], v[102:105]
	ds_read_b128 v[176:179], v144 offset:6144
	v_mfma_f32_16x16x32_bf16 v[98:101], v[232:235], v[228:231], v[98:101]
	ds_read_b128 v[180:183], v144 offset:7168
	v_mfma_f32_16x16x32_bf16 v[94:97], v[236:239], v[200:203], v[94:97]
	v_add_u32_e64 v144, s40, v137
	v_mfma_f32_16x16x32_bf16 v[90:93], v[236:239], v[204:207], v[90:93]
	v_mfma_f32_16x16x32_bf16 v[86:89], v[236:239], v[208:211], v[86:89]
	ds_read_b128 v[184:187], v144 offset:16384
	v_mfma_f32_16x16x32_bf16 v[82:85], v[236:239], v[212:215], v[82:85]
	ds_read_b128 v[188:191], v144 offset:17408
	v_mfma_f32_16x16x32_bf16 v[78:81], v[236:239], v[216:219], v[78:81]
	ds_read_b128 v[192:195], v144 offset:18432
	v_mfma_f32_16x16x32_bf16 v[74:77], v[236:239], v[220:223], v[74:77]
	ds_read_b128 v[196:199], v144 offset:19456
	v_mfma_f32_16x16x32_bf16 v[70:73], v[236:239], v[224:227], v[70:73]
	s_add_i32 s42, s46, s41
	s_mov_b32 m0, s42
	v_lshl_add_u64 v[142:143], v[132:133], 0, s[2:3]
	v_mfma_f32_16x16x32_bf16 v[66:69], v[236:239], v[228:231], v[66:69]
	global_load_lds_dwordx4 v[132:133], off
	s_add_i32 m0, m0, 0x1000
	v_mfma_f32_16x16x32_bf16 v[62:65], v[240:243], v[200:203], v[62:65]
	v_mfma_f32_16x16x32_bf16 v[58:61], v[240:243], v[204:207], v[58:61]
	v_mfma_f32_16x16x32_bf16 v[54:57], v[240:243], v[208:211], v[54:57]
	global_load_lds_dwordx4 v[142:143], off
	v_lshl_add_u64 v[142:143], v[142:143], 0, s[2:3]
	s_add_i32 m0, m0, 0x1000
	v_mfma_f32_16x16x32_bf16 v[50:53], v[240:243], v[212:215], v[50:53]
	v_mfma_f32_16x16x32_bf16 v[46:49], v[240:243], v[216:219], v[46:49]
	v_mfma_f32_16x16x32_bf16 v[42:45], v[240:243], v[220:223], v[42:45]
	global_load_lds_dwordx4 v[142:143], off
	v_lshl_add_u64 v[142:143], v[142:143], 0, s[2:3]
	s_add_i32 m0, m0, 0x1000
	v_mfma_f32_16x16x32_bf16 v[38:41], v[240:243], v[224:227], v[38:41]
	v_mfma_f32_16x16x32_bf16 v[34:37], v[240:243], v[228:231], v[34:37]
	v_mfma_f32_16x16x32_bf16 v[30:33], v[244:247], v[200:203], v[30:33]
	global_load_lds_dwordx4 v[142:143], off
	s_add_i32 m0, m0, 0x1000
	v_lshl_add_u64 v[142:143], v[134:135], 0, s[2:3]
	v_mfma_f32_16x16x32_bf16 v[26:29], v[244:247], v[204:207], v[26:29]
	v_mfma_f32_16x16x32_bf16 v[22:25], v[244:247], v[208:211], v[22:25]
	v_mfma_f32_16x16x32_bf16 v[18:21], v[244:247], v[212:215], v[18:21]
	global_load_lds_dwordx4 v[134:135], off
	s_add_i32 m0, m0, 0x1000
	v_lshl_add_u64 v[132:133], v[132:133], 0, s[12:13]
	v_mfma_f32_16x16x32_bf16 v[14:17], v[244:247], v[216:219], v[14:17]
	v_mfma_f32_16x16x32_bf16 v[10:13], v[244:247], v[220:223], v[10:13]
	v_mfma_f32_16x16x32_bf16 v[6:9], v[244:247], v[224:227], v[6:9]
	global_load_lds_dwordx4 v[142:143], off
	v_lshl_add_u64 v[134:135], v[134:135], 0, s[4:5]
	v_mfma_f32_16x16x32_bf16 v[2:5], v[244:247], v[228:231], v[2:5]
	s_setprio 0
	s_mov_b32 s41, s40
	s_add_i32 s40, s40, 0x6000
	s_cmp_eq_u32 s40, 0x12000
	s_cselect_b32 s40, 0, s40
	s_nop 0
	s_sub_i32 s39, s39, 1
	s_cmp_lg_u32 s39, 0
	s_cbranch_scc1 .Lt8_loop
	.p2align 3
	s_waitcnt vmcnt(6) lgkmcnt(0)
	s_barrier
	s_setprio 1
	v_add_u32_e32 v144, s40, v136
	v_mfma_f32_16x16x32_bf16 v[126:129], v[184:187], v[146:149], v[126:129]
	ds_read_b128 v[200:203], v144 offset:0
	v_mfma_f32_16x16x32_bf16 v[122:125], v[184:187], v[152:155], v[122:125]
	ds_read_b128 v[204:207], v144 offset:1024
	v_mfma_f32_16x16x32_bf16 v[118:121], v[184:187], v[156:159], v[118:121]
	ds_read_b128 v[208:211], v144 offset:2048
	v_mfma_f32_16x16x32_bf16 v[114:117], v[184:187], v[162:165], v[114:117]
	ds_read_b128 v[212:215], v144 offset:3072
	v_mfma_f32_16x16x32_bf16 v[110:113], v[184:187], v[166:169], v[110:113]
	ds_read_b128 v[216:219], v144 offset:4096
	v_mfma_f32_16x16x32_bf16 v[106:109], v[184:187], v[170:173], v[106:109]
	ds_read_b128 v[220:223], v144 offset:5120
	v_mfma_f32_16x16x32_bf16 v[102:105], v[184:187], v[176:179], v[102:105]
	ds_read_b128 v[224:227], v144 offset:6144
	v_mfma_f32_16x16x32_bf16 v[98:101], v[184:187], v[180:183], v[98:101]
	ds_read_b128 v[228:231], v144 offset:7168
	v_mfma_f32_16x16x32_bf16 v[94:97], v[188:191], v[146:149], v[94:97]
	v_add_u32_e64 v144, s40, v137
	v_mfma_f32_16x16x32_bf16 v[90:93], v[188:191], v[152:155], v[90:93]
	v_mfma_f32_16x16x32_bf16 v[86:89], v[188:191], v[156:159], v[86:89]
	ds_read_b128 v[232:235], v144 offset:16384
	v_mfma_f32_16x16x32_bf16 v[82:85], v[188:191], v[162:165], v[82:85]
	ds_read_b128 v[236:239], v144 offset:17408
	v_mfma_f32_16x16x32_bf16 v[78:81], v[188:191], v[166:169], v[78:81]
	ds_read_b128 v[240:243], v144 offset:18432
	v_mfma_f32_16x16x32_bf16 v[74:77], v[188:191], v[170:173], v[74:77]
	ds_read_b128 v[244:247], v144 offset:19456
	v_mfma_f32_16x16x32_bf16 v[70:73], v[188:191], v[176:179], v[70:73]
	s_add_i32 s42, s46, s41
	s_mov_b32 m0, s42
	v_lshl_add_u64 v[142:143], v[132:133], 0, s[2:3]
	v_mfma_f32_16x16x32_bf16 v[66:69], v[188:191], v[180:183], v[66:69]
	global_load_lds_dwordx4 v[132:133], off
;     ...
;   for (int kt = 0; kt < nk; kt++) {
;     if (kt + 1 < nk) asm volatile("s_waitcnt vmcnt(6)" ::: "memory");
;     else asm volatile("s_waitcnt vmcnt(0)" ::: "memory");
;     __builtin_amdgcn_s_barrier();
;     asm volatile("" ::: "memory");
;     if (kt + 2 < nk) G2_STAGE(kt + 2);
;     const char* cS = smem + (kt % 3) * 24576;
;     bf16x8 xa[8], wb[4];
; #pragma unroll
;     for (int f = 0; f < 8; f++) xa[f] = *(const bf16x8*)(cS + aoff + f * 1024);
; #pragma unroll
;     for (int f = 0; f < 4; f++) wb[f] = *(const bf16x8*)(cS + boff + f * 1024);
; #pragma unroll
;     for (int nf = 0; nf < 4; nf++)
; #pragma unroll
;       for (int mf = 0; mf < 8; mf++)
;         acc[nf][mf] = __builtin_amdgcn_mfma_f32_16x16x32_bf16(wb[nf], xa[mf], acc[nf][mf], 0, 0, 0);
	s_add_i32 m0, m0, 0x1000
	v_mfma_f32_16x16x32_bf16 v[62:65], v[192:195], v[146:149], v[62:65]
	v_mfma_f32_16x16x32_bf16 v[58:61], v[192:195], v[152:155], v[58:61]
	v_mfma_f32_16x16x32_bf16 v[54:57], v[192:195], v[156:159], v[54:57]
	global_load_lds_dwordx4 v[142:143], off
	v_lshl_add_u64 v[142:143], v[142:143], 0, s[2:3]
	s_add_i32 m0, m0, 0x1000
	v_mfma_f32_16x16x32_bf16 v[50:53], v[192:195], v[162:165], v[50:53]
	v_mfma_f32_16x16x32_bf16 v[46:49], v[192:195], v[166:169], v[46:49]
	v_mfma_f32_16x16x32_bf16 v[42:45], v[192:195], v[170:173], v[42:45]
	global_load_lds_dwordx4 v[142:143], off
	v_lshl_add_u64 v[142:143], v[142:143], 0, s[2:3]
	s_add_i32 m0, m0, 0x1000
	v_mfma_f32_16x16x32_bf16 v[38:41], v[192:195], v[176:179], v[38:41]
	v_mfma_f32_16x16x32_bf16 v[34:37], v[192:195], v[180:183], v[34:37]
	v_mfma_f32_16x16x32_bf16 v[30:33], v[196:199], v[146:149], v[30:33]
	global_load_lds_dwordx4 v[142:143], off
	s_add_i32 m0, m0, 0x1000
	v_lshl_add_u64 v[142:143], v[134:135], 0, s[2:3]
	v_mfma_f32_16x16x32_bf16 v[26:29], v[196:199], v[152:155], v[26:29]
	v_mfma_f32_16x16x32_bf16 v[22:25], v[196:199], v[156:159], v[22:25]
	v_mfma_f32_16x16x32_bf16 v[18:21], v[196:199], v[162:165], v[18:21]
	global_load_lds_dwordx4 v[134:135], off
	s_add_i32 m0, m0, 0x1000
	v_lshl_add_u64 v[132:133], v[132:133], 0, s[12:13]
	v_mfma_f32_16x16x32_bf16 v[14:17], v[196:199], v[166:169], v[14:17]
	v_mfma_f32_16x16x32_bf16 v[10:13], v[196:199], v[170:173], v[10:13]
	v_mfma_f32_16x16x32_bf16 v[6:9], v[196:199], v[176:179], v[6:9]
	global_load_lds_dwordx4 v[142:143], off
	v_lshl_add_u64 v[134:135], v[134:135], 0, s[4:5]
	v_mfma_f32_16x16x32_bf16 v[2:5], v[196:199], v[180:183], v[2:5]
	s_setprio 0
	s_mov_b32 s41, s40
	s_add_i32 s40, s40, 0x6000
	s_cmp_eq_u32 s40, 0x12000
	s_cselect_b32 s40, 0, s40
	s_nop 0
	.p2align 3
	s_waitcnt vmcnt(6) lgkmcnt(0)
	s_barrier
	s_setprio 1
	v_add_u32_e32 v144, s40, v136
	v_mfma_f32_16x16x32_bf16 v[126:129], v[232:235], v[200:203], v[126:129]
	ds_read_b128 v[146:149], v144 offset:0
	v_mfma_f32_16x16x32_bf16 v[122:125], v[232:235], v[204:207], v[122:125]
	ds_read_b128 v[152:155], v144 offset:1024
	v_mfma_f32_16x16x32_bf16 v[118:121], v[232:235], v[208:211], v[118:121]
	ds_read_b128 v[156:159], v144 offset:2048
	v_mfma_f32_16x16x32_bf16 v[114:117], v[232:235], v[212:215], v[114:117]
	ds_read_b128 v[162:165], v144 offset:3072
	v_mfma_f32_16x16x32_bf16 v[110:113], v[232:235], v[216:219], v[110:113]
	ds_read_b128 v[166:169], v144 offset:4096
	v_mfma_f32_16x16x32_bf16 v[106:109], v[232:235], v[220:223], v[106:109]
	ds_read_b128 v[170:173], v144 offset:5120
	v_mfma_f32_16x16x32_bf16 v[102:105], v[232:235], v[224:227], v[102:105]
	ds_read_b128 v[176:179], v144 offset:6144
	v_mfma_f32_16x16x32_bf16 v[98:101], v[232:235], v[228:231], v[98:101]
	ds_read_b128 v[180:183], v144 offset:7168
	v_mfma_f32_16x16x32_bf16 v[94:97], v[236:239], v[200:203], v[94:97]
	v_add_u32_e64 v144, s40, v137
	v_mfma_f32_16x16x32_bf16 v[90:93], v[236:239], v[204:207], v[90:93]
	v_mfma_f32_16x16x32_bf16 v[86:89], v[236:239], v[208:211], v[86:89]
	ds_read_b128 v[184:187], v144 offset:16384
	v_mfma_f32_16x16x32_bf16 v[82:85], v[236:239], v[212:215], v[82:85]
	ds_read_b128 v[188:191], v144 offset:17408
	v_mfma_f32_16x16x32_bf16 v[78:81], v[236:239], v[216:219], v[78:81]
	ds_read_b128 v[192:195], v144 offset:18432
	v_mfma_f32_16x16x32_bf16 v[74:77], v[236:239], v[220:223], v[74:77]
	ds_read_b128 v[196:199], v144 offset:19456
	v_mfma_f32_16x16x32_bf16 v[70:73], v[236:239], v[224:227], v[70:73]
	v_mfma_f32_16x16x32_bf16 v[66:69], v[236:239], v[228:231], v[66:69]
	v_mfma_f32_16x16x32_bf16 v[62:65], v[240:243], v[200:203], v[62:65]
	v_mfma_f32_16x16x32_bf16 v[58:61], v[240:243], v[204:207], v[58:61]
	v_mfma_f32_16x16x32_bf16 v[54:57], v[240:243], v[208:211], v[54:57]
	v_mfma_f32_16x16x32_bf16 v[50:53], v[240:243], v[212:215], v[50:53]
	v_mfma_f32_16x16x32_bf16 v[46:49], v[240:243], v[216:219], v[46:49]
	v_mfma_f32_16x16x32_bf16 v[42:45], v[240:243], v[220:223], v[42:45]
	v_mfma_f32_16x16x32_bf16 v[38:41], v[240:243], v[224:227], v[38:41]
	v_mfma_f32_16x16x32_bf16 v[34:37], v[240:243], v[228:231], v[34:37]
	v_mfma_f32_16x16x32_bf16 v[30:33], v[244:247], v[200:203], v[30:33]
	v_mfma_f32_16x16x32_bf16 v[26:29], v[244:247], v[204:207], v[26:29]
	v_mfma_f32_16x16x32_bf16 v[22:25], v[244:247], v[208:211], v[22:25]
	v_mfma_f32_16x16x32_bf16 v[18:21], v[244:247], v[212:215], v[18:21]
	v_mfma_f32_16x16x32_bf16 v[14:17], v[244:247], v[216:219], v[14:17]
	v_mfma_f32_16x16x32_bf16 v[10:13], v[244:247], v[220:223], v[10:13]
	v_mfma_f32_16x16x32_bf16 v[6:9], v[244:247], v[224:227], v[6:9]
	v_mfma_f32_16x16x32_bf16 v[2:5], v[244:247], v[228:231], v[2:5]
	s_setprio 0
	s_mov_b32 s41, s40
	s_add_i32 s40, s40, 0x6000
	s_cmp_eq_u32 s40, 0x12000
	s_cselect_b32 s40, 0, s40
	s_nop 0
	.p2align 3
	s_waitcnt vmcnt(0) lgkmcnt(0)
	s_barrier
; DEVI float blo(unsigned u) { return __uint_as_float(u << 16); }
; DEVI float bhi(unsigned u) { return __uint_as_float(u & 0xffff0000u); }
;     ...
;   for (int kt = 0; kt < nk; kt++) {
;     if (kt + 1 < nk) asm volatile("s_waitcnt vmcnt(6)" ::: "memory");
;     else asm volatile("s_waitcnt vmcnt(0)" ::: "memory");
;     __builtin_amdgcn_s_barrier();
;     asm volatile("" ::: "memory");
;     if (kt + 2 < nk) G2_STAGE(kt + 2);
;     const char* cS = smem + (kt % 3) * 24576;
;     bf16x8 xa[8], wb[4];
; #pragma unroll
;     for (int f = 0; f < 8; f++) xa[f] = *(const bf16x8*)(cS + aoff + f * 1024);
; #pragma unroll
;     for (int f = 0; f < 4; f++) wb[f] = *(const bf16x8*)(cS + boff + f * 1024);
; #pragma unroll
;     for (int nf = 0; nf < 4; nf++)
; #pragma unroll
;       for (int mf = 0; mf < 8; mf++)
;         acc[nf][mf] = __builtin_amdgcn_mfma_f32_16x16x32_bf16(wb[nf], xa[mf], acc[nf][mf], 0, 0, 0);
;     ...
;         if (EPI == EPI_RESID || EPI == EPI_RESID_ATOMIC) {
;           f32x4 x = a;
;           if (EPI == EPI_RESID || kpart == 0) {
;             const u32x2 xr = *(const u32x2*)((const u16*)(p.ws + WS_XB) + (size_t)row * 1024 + col);
;             x[0] += ALPHA * blo(xr[0]); x[1] += ALPHA * bhi(xr[0]); x[2] += ALPHA * blo(xr[1]); x[3] += ALPHA * bhi(xr[1]);
;           }
;           if (EPI == EPI_RESID) *(f32x4*)((float*)(p.ws + WS_XF) + (size_t)row * 1024 + col) = x;
	s_setprio 1
	v_add_u32_e32 v144, s40, v136
	v_mfma_f32_16x16x32_bf16 v[126:129], v[184:187], v[146:149], v[126:129]
	ds_read_b128 v[200:203], v144 offset:0
	v_mfma_f32_16x16x32_bf16 v[122:125], v[184:187], v[152:155], v[122:125]
	ds_read_b128 v[204:207], v144 offset:1024
	v_mfma_f32_16x16x32_bf16 v[118:121], v[184:187], v[156:159], v[118:121]
	ds_read_b128 v[208:211], v144 offset:2048
	v_mfma_f32_16x16x32_bf16 v[114:117], v[184:187], v[162:165], v[114:117]
	ds_read_b128 v[212:215], v144 offset:3072
	v_mfma_f32_16x16x32_bf16 v[110:113], v[184:187], v[166:169], v[110:113]
	ds_read_b128 v[216:219], v144 offset:4096
	v_mfma_f32_16x16x32_bf16 v[106:109], v[184:187], v[170:173], v[106:109]
	ds_read_b128 v[220:223], v144 offset:5120
	v_mfma_f32_16x16x32_bf16 v[102:105], v[184:187], v[176:179], v[102:105]
	ds_read_b128 v[224:227], v144 offset:6144
	v_mfma_f32_16x16x32_bf16 v[98:101], v[184:187], v[180:183], v[98:101]
	ds_read_b128 v[228:231], v144 offset:7168
	v_mfma_f32_16x16x32_bf16 v[94:97], v[188:191], v[146:149], v[94:97]
	v_add_u32_e64 v144, s40, v137
	v_mfma_f32_16x16x32_bf16 v[90:93], v[188:191], v[152:155], v[90:93]
	v_mfma_f32_16x16x32_bf16 v[86:89], v[188:191], v[156:159], v[86:89]
	ds_read_b128 v[232:235], v144 offset:16384
	v_mfma_f32_16x16x32_bf16 v[82:85], v[188:191], v[162:165], v[82:85]
	ds_read_b128 v[236:239], v144 offset:17408
	v_mfma_f32_16x16x32_bf16 v[78:81], v[188:191], v[166:169], v[78:81]
	ds_read_b128 v[240:243], v144 offset:18432
	v_mfma_f32_16x16x32_bf16 v[74:77], v[188:191], v[170:173], v[74:77]
	ds_read_b128 v[244:247], v144 offset:19456
	v_mfma_f32_16x16x32_bf16 v[70:73], v[188:191], v[176:179], v[70:73]
	v_mfma_f32_16x16x32_bf16 v[66:69], v[188:191], v[180:183], v[66:69]
	v_mfma_f32_16x16x32_bf16 v[62:65], v[192:195], v[146:149], v[62:65]
	v_mfma_f32_16x16x32_bf16 v[58:61], v[192:195], v[152:155], v[58:61]
	v_mfma_f32_16x16x32_bf16 v[54:57], v[192:195], v[156:159], v[54:57]
	v_mfma_f32_16x16x32_bf16 v[50:53], v[192:195], v[162:165], v[50:53]
	v_mfma_f32_16x16x32_bf16 v[46:49], v[192:195], v[166:169], v[46:49]
	v_mfma_f32_16x16x32_bf16 v[42:45], v[192:195], v[170:173], v[42:45]
	v_mfma_f32_16x16x32_bf16 v[38:41], v[192:195], v[176:179], v[38:41]
	v_mfma_f32_16x16x32_bf16 v[34:37], v[192:195], v[180:183], v[34:37]
	v_mfma_f32_16x16x32_bf16 v[30:33], v[196:199], v[146:149], v[30:33]
	v_mfma_f32_16x16x32_bf16 v[26:29], v[196:199], v[152:155], v[26:29]
	v_mfma_f32_16x16x32_bf16 v[22:25], v[196:199], v[156:159], v[22:25]
	v_mfma_f32_16x16x32_bf16 v[18:21], v[196:199], v[162:165], v[18:21]
	v_mfma_f32_16x16x32_bf16 v[14:17], v[196:199], v[166:169], v[14:17]
	v_mfma_f32_16x16x32_bf16 v[10:13], v[196:199], v[170:173], v[10:13]
	v_mfma_f32_16x16x32_bf16 v[6:9], v[196:199], v[176:179], v[6:9]
	v_mfma_f32_16x16x32_bf16 v[2:5], v[196:199], v[180:183], v[2:5]
	s_setprio 0
	s_mov_b32 s41, s40
	s_add_i32 s40, s40, 0x6000
	s_cmp_eq_u32 s40, 0x12000
	s_cselect_b32 s40, 0, s40
	s_nop 0
	s_mov_b32 s4, 0x8000
	s_mov_b32 s5, 0
	s_mov_b32 s10, 0x10000
	s_mov_b32 s11, 0
	s_mov_b32 s44, 0x3fd744fd
	.p2align 3
	s_waitcnt lgkmcnt(0)
	s_nop 0
	v_mfma_f32_16x16x32_bf16 v[126:129], v[232:235], v[200:203], v[126:129]
	v_mfma_f32_16x16x32_bf16 v[122:125], v[232:235], v[204:207], v[122:125]
	v_mfma_f32_16x16x32_bf16 v[118:121], v[232:235], v[208:211], v[118:121]
	v_mfma_f32_16x16x32_bf16 v[114:117], v[232:235], v[212:215], v[114:117]
	v_mfma_f32_16x16x32_bf16 v[110:113], v[232:235], v[216:219], v[110:113]
	global_load_dwordx4 v[146:149], v[138:139], off offset:0
	v_mfma_f32_16x16x32_bf16 v[106:109], v[232:235], v[220:223], v[106:109]
	v_mfma_f32_16x16x32_bf16 v[102:105], v[232:235], v[224:227], v[102:105]
	global_load_dwordx4 v[152:155], v[138:139], off offset:64
	v_mfma_f32_16x16x32_bf16 v[98:101], v[232:235], v[228:231], v[98:101]
	v_lshl_add_u64 v[138:139], v[138:139], 0, s[4:5]
	v_mfma_f32_16x16x32_bf16 v[94:97], v[236:239], v[200:203], v[94:97]
	global_load_dwordx4 v[156:159], v[138:139], off offset:0
	v_mfma_f32_16x16x32_bf16 v[90:93], v[236:239], v[204:207], v[90:93]
	v_mfma_f32_16x16x32_bf16 v[86:89], v[236:239], v[208:211], v[86:89]
	global_load_dwordx4 v[162:165], v[138:139], off offset:64
	v_mfma_f32_16x16x32_bf16 v[82:85], v[236:239], v[212:215], v[82:85]
	v_lshl_add_u64 v[138:139], v[138:139], 0, s[4:5]
	v_mfma_f32_16x16x32_bf16 v[78:81], v[236:239], v[216:219], v[78:81]
	global_load_dwordx4 v[166:169], v[138:139], off offset:0
	v_mfma_f32_16x16x32_bf16 v[74:77], v[236:239], v[220:223], v[74:77]
	v_mfma_f32_16x16x32_bf16 v[70:73], v[236:239], v[224:227], v[70:73]
	global_load_dwordx4 v[170:173], v[138:139], off offset:64
	v_mfma_f32_16x16x32_bf16 v[66:69], v[236:239], v[228:231], v[66:69]
	v_lshl_add_u64 v[138:139], v[138:139], 0, s[4:5]
	v_mfma_f32_16x16x32_bf16 v[62:65], v[240:243], v[200:203], v[62:65]
	global_load_dwordx4 v[176:179], v[138:139], off offset:0
	v_mfma_f32_16x16x32_bf16 v[58:61], v[240:243], v[204:207], v[58:61]
	v_mfma_f32_16x16x32_bf16 v[54:57], v[240:243], v[208:211], v[54:57]
	global_load_dwordx4 v[180:183], v[138:139], off offset:64
	v_mfma_f32_16x16x32_bf16 v[50:53], v[240:243], v[212:215], v[50:53]
	v_lshl_add_u64 v[138:139], v[138:139], 0, s[4:5]
	v_mfma_f32_16x16x32_bf16 v[46:49], v[240:243], v[216:219], v[46:49]
	global_load_dwordx4 v[184:187], v[138:139], off offset:0
	v_mfma_f32_16x16x32_bf16 v[42:45], v[240:243], v[220:223], v[42:45]
	v_mfma_f32_16x16x32_bf16 v[38:41], v[240:243], v[224:227], v[38:41]
	global_load_dwordx4 v[188:191], v[138:139], off offset:64
	v_mfma_f32_16x16x32_bf16 v[34:37], v[240:243], v[228:231], v[34:37]
	v_lshl_add_u64 v[138:139], v[138:139], 0, s[4:5]
	v_mfma_f32_16x16x32_bf16 v[30:33], v[244:247], v[200:203], v[30:33]
	global_load_dwordx4 v[192:195], v[138:139], off offset:0
	v_mfma_f32_16x16x32_bf16 v[26:29], v[244:247], v[204:207], v[26:29]
	v_mfma_f32_16x16x32_bf16 v[22:25], v[244:247], v[208:211], v[22:25]
	global_load_dwordx4 v[196:199], v[138:139], off offset:64
	v_mfma_f32_16x16x32_bf16 v[18:21], v[244:247], v[212:215], v[18:21]
	v_lshl_add_u64 v[138:139], v[138:139], 0, s[4:5]
	v_mfma_f32_16x16x32_bf16 v[14:17], v[244:247], v[216:219], v[14:17]
	v_mfma_f32_16x16x32_bf16 v[10:13], v[244:247], v[220:223], v[10:13]
	v_mfma_f32_16x16x32_bf16 v[6:9], v[244:247], v[224:227], v[6:9]
	v_mfma_f32_16x16x32_bf16 v[2:5], v[244:247], v[228:231], v[2:5]
	s_mov_b32 m0, s43
	global_load_dwordx4 v[200:203], v[138:139], off offset:0
	global_load_dwordx4 v[204:207], v[138:139], off offset:64
	v_lshl_add_u64 v[138:139], v[138:139], 0, s[4:5]
	global_load_dwordx4 v[208:211], v[138:139], off offset:0
	global_load_dwordx4 v[212:215], v[138:139], off offset:64
	v_lshl_add_u64 v[138:139], v[138:139], 0, s[4:5]
	s_nop 7
	s_waitcnt vmcnt(15)
; DEVI float blo(unsigned u) { return __uint_as_float(u << 16); }
; DEVI float bhi(unsigned u) { return __uint_as_float(u & 0xffff0000u); }
;     ...
; #pragma unroll
;       for (int nf = 0; nf < 4; nf++) {
;         const int col = n0 + wn * 64 + nf * 16 + quad * 4;
;         f32x4 a = acc[nf][mf];
;         if (EPI == EPI_RESID || EPI == EPI_RESID_ATOMIC) {
;           f32x4 x = a;
;           if (EPI == EPI_RESID || kpart == 0) {
;             const u32x2 xr = *(const u32x2*)((const u16*)(p.ws + WS_XB) + (size_t)row * 1024 + col);
;             x[0] += ALPHA * blo(xr[0]); x[1] += ALPHA * bhi(xr[0]); x[2] += ALPHA * blo(xr[1]); x[3] += ALPHA * bhi(xr[1]);
;           }
;           if (EPI == EPI_RESID) *(f32x4*)((float*)(p.ws + WS_XF) + (size_t)row * 1024 + col) = x;
;           else *(f32x4*)((float*)(p.ws + WS_SLAB) + ((size_t)kpart * 512 + (row - T_P)) * 1024 + col) = x;
	v_permlane16_swap_b32_e32 v146, v148
	v_permlane16_swap_b32_e32 v147, v149
	v_lshlrev_b32_e32 v216, 16, v146
	v_and_b32_e32 v146, 0xffff0000, v146
	v_lshlrev_b32_e32 v217, 16, v147
	v_and_b32_e32 v147, 0xffff0000, v147
	v_fmac_f32_e32 v126, s44, v216
	v_fmac_f32_e32 v127, s44, v146
	v_fmac_f32_e32 v128, s44, v217
	v_fmac_f32_e32 v129, s44, v147
	global_store_dwordx4 v[140:141], v[126:129], off offset:0
	v_lshlrev_b32_e32 v216, 16, v148
	v_and_b32_e32 v148, 0xffff0000, v148
	v_lshlrev_b32_e32 v217, 16, v149
	v_and_b32_e32 v149, 0xffff0000, v149
	v_fmac_f32_e32 v94, s44, v216
	v_fmac_f32_e32 v95, s44, v148
	v_fmac_f32_e32 v96, s44, v217
	v_fmac_f32_e32 v97, s44, v149
	global_store_dwordx4 v[140:141], v[94:97], off offset:64
	s_waitcnt vmcnt(16)
	v_permlane16_swap_b32_e32 v152, v154
	v_permlane16_swap_b32_e32 v153, v155
	v_lshlrev_b32_e32 v216, 16, v152
	v_and_b32_e32 v152, 0xffff0000, v152
	v_lshlrev_b32_e32 v217, 16, v153
	v_and_b32_e32 v153, 0xffff0000, v153
	v_fmac_f32_e32 v62, s44, v216
	v_fmac_f32_e32 v63, s44, v152
	v_fmac_f32_e32 v64, s44, v217
	v_fmac_f32_e32 v65, s44, v153
	global_store_dwordx4 v[140:141], v[62:65], off offset:128
	v_lshlrev_b32_e32 v216, 16, v154
	v_and_b32_e32 v154, 0xffff0000, v154
	v_lshlrev_b32_e32 v217, 16, v155
	v_and_b32_e32 v155, 0xffff0000, v155
	v_fmac_f32_e32 v30, s44, v216
	v_fmac_f32_e32 v31, s44, v154
	v_fmac_f32_e32 v32, s44, v217
	v_fmac_f32_e32 v33, s44, v155
	global_store_dwordx4 v[140:141], v[30:33], off offset:192
	v_lshl_add_u64 v[140:141], v[140:141], 0, s[10:11]
	s_waitcnt vmcnt(17)
	v_permlane16_swap_b32_e32 v156, v158
	v_permlane16_swap_b32_e32 v157, v159
	v_lshlrev_b32_e32 v216, 16, v156
	v_and_b32_e32 v156, 0xffff0000, v156
	v_lshlrev_b32_e32 v217, 16, v157
	v_and_b32_e32 v157, 0xffff0000, v157
	v_fmac_f32_e32 v122, s44, v216
	v_fmac_f32_e32 v123, s44, v156
	v_fmac_f32_e32 v124, s44, v217
	v_fmac_f32_e32 v125, s44, v157
	global_store_dwordx4 v[140:141], v[122:125], off offset:0
	v_lshlrev_b32_e32 v216, 16, v158
	v_and_b32_e32 v158, 0xffff0000, v158
	v_lshlrev_b32_e32 v217, 16, v159
	v_and_b32_e32 v159, 0xffff0000, v159
	v_fmac_f32_e32 v90, s44, v216
	v_fmac_f32_e32 v91, s44, v158
	v_fmac_f32_e32 v92, s44, v217
	v_fmac_f32_e32 v93, s44, v159
	global_store_dwordx4 v[140:141], v[90:93], off offset:64
	s_waitcnt vmcnt(18)
	v_permlane16_swap_b32_e32 v162, v164
	v_permlane16_swap_b32_e32 v163, v165
	v_lshlrev_b32_e32 v216, 16, v162
	v_and_b32_e32 v162, 0xffff0000, v162
	v_lshlrev_b32_e32 v217, 16, v163
	v_and_b32_e32 v163, 0xffff0000, v163
	v_fmac_f32_e32 v58, s44, v216
	v_fmac_f32_e32 v59, s44, v162
	v_fmac_f32_e32 v60, s44, v217
	v_fmac_f32_e32 v61, s44, v163
	global_store_dwordx4 v[140:141], v[58:61], off offset:128
	v_lshlrev_b32_e32 v216, 16, v164
	v_and_b32_e32 v164, 0xffff0000, v164
	v_lshlrev_b32_e32 v217, 16, v165
	v_and_b32_e32 v165, 0xffff0000, v165
	v_fmac_f32_e32 v26, s44, v216
	v_fmac_f32_e32 v27, s44, v164
	v_fmac_f32_e32 v28, s44, v217
	v_fmac_f32_e32 v29, s44, v165
	global_store_dwordx4 v[140:141], v[26:29], off offset:192
	v_lshl_add_u64 v[140:141], v[140:141], 0, s[10:11]
	s_waitcnt vmcnt(19)
	v_permlane16_swap_b32_e32 v166, v168
	v_permlane16_swap_b32_e32 v167, v169
	v_lshlrev_b32_e32 v216, 16, v166
	v_and_b32_e32 v166, 0xffff0000, v166
	v_lshlrev_b32_e32 v217, 16, v167
	v_and_b32_e32 v167, 0xffff0000, v167
	v_fmac_f32_e32 v118, s44, v216
	v_fmac_f32_e32 v119, s44, v166
	v_fmac_f32_e32 v120, s44, v217
	v_fmac_f32_e32 v121, s44, v167
	global_store_dwordx4 v[140:141], v[118:121], off offset:0
	v_lshlrev_b32_e32 v216, 16, v168
	v_and_b32_e32 v168, 0xffff0000, v168
	v_lshlrev_b32_e32 v217, 16, v169
	v_and_b32_e32 v169, 0xffff0000, v169
	v_fmac_f32_e32 v86, s44, v216
	v_fmac_f32_e32 v87, s44, v168
	v_fmac_f32_e32 v88, s44, v217
	v_fmac_f32_e32 v89, s44, v169
	global_store_dwordx4 v[140:141], v[86:89], off offset:64
	s_waitcnt vmcnt(20)
	v_permlane16_swap_b32_e32 v170, v172
	v_permlane16_swap_b32_e32 v171, v173
	v_lshlrev_b32_e32 v216, 16, v170
	v_and_b32_e32 v170, 0xffff0000, v170
	v_lshlrev_b32_e32 v217, 16, v171
	v_and_b32_e32 v171, 0xffff0000, v171
	v_fmac_f32_e32 v54, s44, v216
	v_fmac_f32_e32 v55, s44, v170
	v_fmac_f32_e32 v56, s44, v217
	v_fmac_f32_e32 v57, s44, v171
	global_store_dwordx4 v[140:141], v[54:57], off offset:128
	v_lshlrev_b32_e32 v216, 16, v172
	v_and_b32_e32 v172, 0xffff0000, v172
	v_lshlrev_b32_e32 v217, 16, v173
	v_and_b32_e32 v173, 0xffff0000, v173
	v_fmac_f32_e32 v22, s44, v216
	v_fmac_f32_e32 v23, s44, v172
	v_fmac_f32_e32 v24, s44, v217
	v_fmac_f32_e32 v25, s44, v173
	global_store_dwordx4 v[140:141], v[22:25], off offset:192
	v_lshl_add_u64 v[140:141], v[140:141], 0, s[10:11]
	s_waitcnt vmcnt(21)
	v_permlane16_swap_b32_e32 v176, v178
	v_permlane16_swap_b32_e32 v177, v179
	v_lshlrev_b32_e32 v216, 16, v176
	v_and_b32_e32 v176, 0xffff0000, v176
	v_lshlrev_b32_e32 v217, 16, v177
	v_and_b32_e32 v177, 0xffff0000, v177
	v_fmac_f32_e32 v114, s44, v216
	v_fmac_f32_e32 v115, s44, v176
	v_fmac_f32_e32 v116, s44, v217
	v_fmac_f32_e32 v117, s44, v177
	global_store_dwordx4 v[140:141], v[114:117], off offset:0
	v_lshlrev_b32_e32 v216, 16, v178
	v_and_b32_e32 v178, 0xffff0000, v178
	v_lshlrev_b32_e32 v217, 16, v179
	v_and_b32_e32 v179, 0xffff0000, v179
	v_fmac_f32_e32 v82, s44, v216
	v_fmac_f32_e32 v83, s44, v178
	v_fmac_f32_e32 v84, s44, v217
	v_fmac_f32_e32 v85, s44, v179
	global_store_dwordx4 v[140:141], v[82:85], off offset:64
	s_waitcnt vmcnt(22)
; DEVI float blo(unsigned u) { return __uint_as_float(u << 16); }
; DEVI float bhi(unsigned u) { return __uint_as_float(u & 0xffff0000u); }
;     ...
; #pragma unroll
;       for (int nf = 0; nf < 4; nf++) {
;         const int col = n0 + wn * 64 + nf * 16 + quad * 4;
;         f32x4 a = acc[nf][mf];
;         if (EPI == EPI_RESID || EPI == EPI_RESID_ATOMIC) {
;           f32x4 x = a;
;           if (EPI == EPI_RESID || kpart == 0) {
;             const u32x2 xr = *(const u32x2*)((const u16*)(p.ws + WS_XB) + (size_t)row * 1024 + col);
;             x[0] += ALPHA * blo(xr[0]); x[1] += ALPHA * bhi(xr[0]); x[2] += ALPHA * blo(xr[1]); x[3] += ALPHA * bhi(xr[1]);
;           }
;           if (EPI == EPI_RESID) *(f32x4*)((float*)(p.ws + WS_XF) + (size_t)row * 1024 + col) = x;
;           else *(f32x4*)((float*)(p.ws + WS_SLAB) + ((size_t)kpart * 512 + (row - T_P)) * 1024 + col) = x;
	v_permlane16_swap_b32_e32 v180, v182
	v_permlane16_swap_b32_e32 v181, v183
	v_lshlrev_b32_e32 v216, 16, v180
	v_and_b32_e32 v180, 0xffff0000, v180
	v_lshlrev_b32_e32 v217, 16, v181
	v_and_b32_e32 v181, 0xffff0000, v181
	v_fmac_f32_e32 v50, s44, v216
	v_fmac_f32_e32 v51, s44, v180
	v_fmac_f32_e32 v52, s44, v217
	v_fmac_f32_e32 v53, s44, v181
	global_store_dwordx4 v[140:141], v[50:53], off offset:128
	v_lshlrev_b32_e32 v216, 16, v182
	v_and_b32_e32 v182, 0xffff0000, v182
	v_lshlrev_b32_e32 v217, 16, v183
	v_and_b32_e32 v183, 0xffff0000, v183
	v_fmac_f32_e32 v18, s44, v216
	v_fmac_f32_e32 v19, s44, v182
	v_fmac_f32_e32 v20, s44, v217
	v_fmac_f32_e32 v21, s44, v183
	global_store_dwordx4 v[140:141], v[18:21], off offset:192
	v_lshl_add_u64 v[140:141], v[140:141], 0, s[10:11]
	s_waitcnt vmcnt(23)
	v_permlane16_swap_b32_e32 v184, v186
	v_permlane16_swap_b32_e32 v185, v187
	v_lshlrev_b32_e32 v216, 16, v184
	v_and_b32_e32 v184, 0xffff0000, v184
	v_lshlrev_b32_e32 v217, 16, v185
	v_and_b32_e32 v185, 0xffff0000, v185
	v_fmac_f32_e32 v110, s44, v216
	v_fmac_f32_e32 v111, s44, v184
	v_fmac_f32_e32 v112, s44, v217
	v_fmac_f32_e32 v113, s44, v185
	global_store_dwordx4 v[140:141], v[110:113], off offset:0
	v_lshlrev_b32_e32 v216, 16, v186
	v_and_b32_e32 v186, 0xffff0000, v186
	v_lshlrev_b32_e32 v217, 16, v187
	v_and_b32_e32 v187, 0xffff0000, v187
	v_fmac_f32_e32 v78, s44, v216
	v_fmac_f32_e32 v79, s44, v186
	v_fmac_f32_e32 v80, s44, v217
	v_fmac_f32_e32 v81, s44, v187
	global_store_dwordx4 v[140:141], v[78:81], off offset:64
	s_waitcnt vmcnt(24)
	v_permlane16_swap_b32_e32 v188, v190
	v_permlane16_swap_b32_e32 v189, v191
	v_lshlrev_b32_e32 v216, 16, v188
	v_and_b32_e32 v188, 0xffff0000, v188
	v_lshlrev_b32_e32 v217, 16, v189
	v_and_b32_e32 v189, 0xffff0000, v189
	v_fmac_f32_e32 v46, s44, v216
	v_fmac_f32_e32 v47, s44, v188
	v_fmac_f32_e32 v48, s44, v217
	v_fmac_f32_e32 v49, s44, v189
	global_store_dwordx4 v[140:141], v[46:49], off offset:128
	v_lshlrev_b32_e32 v216, 16, v190
	v_and_b32_e32 v190, 0xffff0000, v190
	v_lshlrev_b32_e32 v217, 16, v191
	v_and_b32_e32 v191, 0xffff0000, v191
	v_fmac_f32_e32 v14, s44, v216
	v_fmac_f32_e32 v15, s44, v190
	v_fmac_f32_e32 v16, s44, v217
	v_fmac_f32_e32 v17, s44, v191
	global_store_dwordx4 v[140:141], v[14:17], off offset:192
	v_lshl_add_u64 v[140:141], v[140:141], 0, s[10:11]
	s_waitcnt vmcnt(25)
	v_permlane16_swap_b32_e32 v192, v194
	v_permlane16_swap_b32_e32 v193, v195
	v_lshlrev_b32_e32 v216, 16, v192
	v_and_b32_e32 v192, 0xffff0000, v192
	v_lshlrev_b32_e32 v217, 16, v193
	v_and_b32_e32 v193, 0xffff0000, v193
	v_fmac_f32_e32 v106, s44, v216
	v_fmac_f32_e32 v107, s44, v192
	v_fmac_f32_e32 v108, s44, v217
	v_fmac_f32_e32 v109, s44, v193
	global_store_dwordx4 v[140:141], v[106:109], off offset:0
	v_lshlrev_b32_e32 v216, 16, v194
	v_and_b32_e32 v194, 0xffff0000, v194
	v_lshlrev_b32_e32 v217, 16, v195
	v_and_b32_e32 v195, 0xffff0000, v195
	v_fmac_f32_e32 v74, s44, v216
	v_fmac_f32_e32 v75, s44, v194
	v_fmac_f32_e32 v76, s44, v217
	v_fmac_f32_e32 v77, s44, v195
	global_store_dwordx4 v[140:141], v[74:77], off offset:64
	s_waitcnt vmcnt(26)
	v_permlane16_swap_b32_e32 v196, v198
	v_permlane16_swap_b32_e32 v197, v199
	v_lshlrev_b32_e32 v216, 16, v196
	v_and_b32_e32 v196, 0xffff0000, v196
	v_lshlrev_b32_e32 v217, 16, v197
	v_and_b32_e32 v197, 0xffff0000, v197
	v_fmac_f32_e32 v42, s44, v216
	v_fmac_f32_e32 v43, s44, v196
	v_fmac_f32_e32 v44, s44, v217
	v_fmac_f32_e32 v45, s44, v197
	global_store_dwordx4 v[140:141], v[42:45], off offset:128
	v_lshlrev_b32_e32 v216, 16, v198
	v_and_b32_e32 v198, 0xffff0000, v198
	v_lshlrev_b32_e32 v217, 16, v199
	v_and_b32_e32 v199, 0xffff0000, v199
	v_fmac_f32_e32 v10, s44, v216
	v_fmac_f32_e32 v11, s44, v198
	v_fmac_f32_e32 v12, s44, v217
	v_fmac_f32_e32 v13, s44, v199
	global_store_dwordx4 v[140:141], v[10:13], off offset:192
	v_lshl_add_u64 v[140:141], v[140:141], 0, s[10:11]
	s_waitcnt vmcnt(27)
	v_permlane16_swap_b32_e32 v200, v202
	v_permlane16_swap_b32_e32 v201, v203
	v_lshlrev_b32_e32 v216, 16, v200
	v_and_b32_e32 v200, 0xffff0000, v200
	v_lshlrev_b32_e32 v217, 16, v201
	v_and_b32_e32 v201, 0xffff0000, v201
	v_fmac_f32_e32 v102, s44, v216
	v_fmac_f32_e32 v103, s44, v200
	v_fmac_f32_e32 v104, s44, v217
	v_fmac_f32_e32 v105, s44, v201
	global_store_dwordx4 v[140:141], v[102:105], off offset:0
	v_lshlrev_b32_e32 v216, 16, v202
	v_and_b32_e32 v202, 0xffff0000, v202
	v_lshlrev_b32_e32 v217, 16, v203
	v_and_b32_e32 v203, 0xffff0000, v203
	v_fmac_f32_e32 v70, s44, v216
	v_fmac_f32_e32 v71, s44, v202
	v_fmac_f32_e32 v72, s44, v217
	v_fmac_f32_e32 v73, s44, v203
	global_store_dwordx4 v[140:141], v[70:73], off offset:64
	s_waitcnt vmcnt(28)
	v_permlane16_swap_b32_e32 v204, v206
	v_permlane16_swap_b32_e32 v205, v207
	v_lshlrev_b32_e32 v216, 16, v204
	v_and_b32_e32 v204, 0xffff0000, v204
	v_lshlrev_b32_e32 v217, 16, v205
	v_and_b32_e32 v205, 0xffff0000, v205
	v_fmac_f32_e32 v38, s44, v216
	v_fmac_f32_e32 v39, s44, v204
	v_fmac_f32_e32 v40, s44, v217
	v_fmac_f32_e32 v41, s44, v205
	global_store_dwordx4 v[140:141], v[38:41], off offset:128
	v_lshlrev_b32_e32 v216, 16, v206
	v_and_b32_e32 v206, 0xffff0000, v206
	v_lshlrev_b32_e32 v217, 16, v207
	v_and_b32_e32 v207, 0xffff0000, v207
	v_fmac_f32_e32 v6, s44, v216
	v_fmac_f32_e32 v7, s44, v206
	v_fmac_f32_e32 v8, s44, v217
	v_fmac_f32_e32 v9, s44, v207
	global_store_dwordx4 v[140:141], v[6:9], off offset:192
	v_lshl_add_u64 v[140:141], v[140:141], 0, s[10:11]
	s_waitcnt vmcnt(29)
	v_permlane16_swap_b32_e32 v208, v210
	v_permlane16_swap_b32_e32 v209, v211
	v_lshlrev_b32_e32 v216, 16, v208
	v_and_b32_e32 v208, 0xffff0000, v208
	v_lshlrev_b32_e32 v217, 16, v209
	v_and_b32_e32 v209, 0xffff0000, v209
	v_fmac_f32_e32 v98, s44, v216
	v_fmac_f32_e32 v99, s44, v208
	v_fmac_f32_e32 v100, s44, v217
	v_fmac_f32_e32 v101, s44, v209
	global_store_dwordx4 v[140:141], v[98:101], off offset:0
	v_lshlrev_b32_e32 v216, 16, v210
	v_and_b32_e32 v210, 0xffff0000, v210
	v_lshlrev_b32_e32 v217, 16, v211
	v_and_b32_e32 v211, 0xffff0000, v211
	v_fmac_f32_e32 v66, s44, v216
	v_fmac_f32_e32 v67, s44, v210
	v_fmac_f32_e32 v68, s44, v217
	v_fmac_f32_e32 v69, s44, v211
	global_store_dwordx4 v[140:141], v[66:69], off offset:64
	s_waitcnt vmcnt(30)
	v_permlane16_swap_b32_e32 v212, v214
	v_permlane16_swap_b32_e32 v213, v215
	v_lshlrev_b32_e32 v216, 16, v212
	v_and_b32_e32 v212, 0xffff0000, v212
	v_lshlrev_b32_e32 v217, 16, v213
	v_and_b32_e32 v213, 0xffff0000, v213
	v_fmac_f32_e32 v34, s44, v216
	v_fmac_f32_e32 v35, s44, v212
	v_fmac_f32_e32 v36, s44, v217
	v_fmac_f32_e32 v37, s44, v213
	global_store_dwordx4 v[140:141], v[34:37], off offset:128
	v_lshlrev_b32_e32 v216, 16, v214
	v_and_b32_e32 v214, 0xffff0000, v214
	v_lshlrev_b32_e32 v217, 16, v215
	v_and_b32_e32 v215, 0xffff0000, v215
	v_fmac_f32_e32 v2, s44, v216
	v_fmac_f32_e32 v3, s44, v214
	v_fmac_f32_e32 v4, s44, v217
	v_fmac_f32_e32 v5, s44, v215
	global_store_dwordx4 v[140:141], v[2:5], off offset:192
	v_readlane_b32 s39, v250, 7
	s_cmpk_lg_u32 s39, 0x200
	s_cbranch_scc1 .LBB0_146
; DEVI int xcd_first_tile() { return (blockIdx.x & 7) * (gridDim.x >> 3) + (blockIdx.x >> 3); }
; DEVI void run_phase(const Params& p, int ph, char* smem) {
;     ...
;       for (int t = xcd_first_tile(); t < 512 + 16 * 2; t += xcd_tile_step()) {
;         if (t < 512) {
;           int mt_, nt_; tile_coords(t, 64, 8, mt_, nt_);
;           gemm_tile256<EPI_RESID>(p, ox, 256, Bt, 256, mt_ * 256, nt_ * 128, nullptr, 0, smem);
;         } else {
;           const int u_ = t - 512, tl_ = u_ / 2, q_ = u_ - tl_ * 2;
;           gemm_tile256<EPI_RESID_ATOMIC>(p, ox, 256, Bt, 256, (64 + (tl_ & 1)) * 256, (tl_ >> 1) * 128, nullptr, 0, smem, q_ * 128, 4, q_);
;         }
	v_readlane_b32 s40, v250, 0
	s_lshr_b32 s41, s40, 3
	s_and_b32 s40, s40, 7
	s_mul_i32 s40, s40, 4
	s_add_i32 s40, s40, s41
	s_cmp_lt_u32 s41, 4
	s_movk_i32 s38, 0x4000
	s_branch .LBB0_146

; #define LAS __attribute__((address_space(3)))
; DEVI int tidx() { int t = threadIdx.x; asm volatile("" : "+v"(t)); return t; }
;   const int tid = tidx(), lane = tid & 63, wid = tid >> 6;
;   const int wm = wid >> 1, wn = wid & 1, r16 = lane & 15, quad = lane >> 4;
;   f32x4 acc[4][8];
; #pragma unroll
;   for (int i = 0; i < 4; i++)
; #pragma unroll
;     for (int j = 0; j < 8; j++) acc[i][j] = (f32x4){0.f, 0.f, 0.f, 0.f};
;   const int nk = (nk_part < 0) ? (K >> 5) : nk_part;
;   const int lrow = tid >> 2, lpc = tid & 3;
;   const int lch = lpc ^ ((0x78 >> (((lrow >> 2) & 3) * 2)) & 3);
;   const u16* ga = A + (size_t)(m0 + lrow) * lda + kbeg + lch * 8;
;   const u16* gb = Bt + (size_t)(n0 + lrow) * K + kbeg + lch * 8;
;   const size_t ga1 = (size_t)64 * lda, gb1 = (size_t)64 * K;
;   const unsigned lds0 = (unsigned)(uintptr_t)(LAS char*)smem + (unsigned)__builtin_amdgcn_readfirstlane(wid) * 1024u;
;     ...
;   __syncthreads();
;   G2_STAGE(0); G2_STAGE(1);
; DEVI void run_phase(const Params& p, int ph, char* smem) {
;     ...
;           const int u_ = t - 512, tl_ = u_ / 8, q_ = u_ - tl_ * 8;
;           gemm_tile256<EPI_RESID_ATOMIC>(p, mix, 1024, Bt, 1024, (64 + (tl_ & 1)) * 256, (tl_ >> 1) * 128, nullptr, 0, smem, q_ * 128, 4, q_);
.LBB0_758:
	s_cmpk_gt_i32 s39, 0x1ff
	s_mov_b64 s[2:3], -1
	s_cbranch_scc0 .LBB0_812
	s_sub_i32 s43, s39, 512
	s_lshr_b32 s42, s43, 3
	s_and_b32 s98, s43, 7
	s_lshr_b32 s15, s42, 1
	s_and_b32 s42, s42, 1
	s_add_i32 s42, s42, 64
	v_readlane_b32 s2, v250, 5
	v_readlane_b32 s3, v250, 6
	v_readlane_b32 s43, v254, 62
	s_mul_i32 s1, s42, 0x80000
	s_add_u32 s4, s2, s1
	s_addc_u32 s5, s3, 0
	s_add_u32 s4, s4, 0xb580000
	s_addc_u32 s5, s5, 0
	s_mul_i32 s1, s43, 0x200000
	s_mul_i32 s14, s15, 0x40000
	s_add_i32 s1, s1, s14
	s_add_u32 s10, s2, s1
	s_addc_u32 s11, s3, 0
	s_add_u32 s10, s10, 0x15e00000
	s_addc_u32 s11, s11, 0
	s_mul_i32 s1, s98, 256
	s_add_u32 s4, s4, s1
	s_addc_u32 s5, s5, 0
	s_mul_i32 s1, s98, 512
	s_add_u32 s10, s10, s1
	s_addc_u32 s11, s11, 0
	s_movk_i32 s0, 0x78
	v_lshrrev_b32_e32 v0, 2, v145
	v_and_b32_e32 v131, 3, v145
	v_bfe_u32 v136, v145, 4, 2
	v_lshlrev_b32_e32 v136, 1, v136
	v_lshrrev_b32_e64 v136, v136, s0
	v_and_b32_e32 v136, 3, v136
	v_xor_b32_e32 v131, v131, v136
	v_lshlrev_b32_e32 v131, 4, v131
	s_movk_i32 s14, 0x800
	v_mad_u32_u24 v0, v0, s14, v131
	v_bfe_u32 v137, v145, 2, 1
	s_movk_i32 s14, 0x7c0
	v_mul_u32_u24_e32 v136, s14, v137
	v_sub_u32_e32 v136, v0, v136
	v_mov_b32_e32 v137, 0
	v_lshl_add_u64 v[134:135], s[10:11], 0, v[136:137]
	v_bfe_u32 v137, v145, 2, 1
	s_mov_b32 s12, 64
	s_mov_b32 s13, 0
	v_lshl_add_u64 v[132:133], s[4:5], 0, v[0:1]
	v_bfe_u32 v136, v145, 2, 2
	v_lshlrev_b32_e32 v136, 1, v136
	v_lshrrev_b32_e64 v136, v136, s0
	v_and_b32_e32 v136, 3, v136
	v_bfe_u32 v137, v145, 4, 2
	v_xor_b32_e32 v136, v136, v137
	v_lshlrev_b32_e32 v136, 4, v136
	v_and_b32_e32 v131, 15, v145
	v_lshl_or_b32 v136, v131, 6, v136
	v_bfe_u32 v137, v145, 6, 1
	v_lshl_or_b32 v137, v137, 12, v136
	v_lshrrev_b32_e32 v0, 7, v145
	v_lshl_or_b32 v136, v0, 13, v136
	v_and_b32_e32 v140, 1, v131
	v_lshl_or_b32 v131, v0, 7, v131
	v_bfe_u32 v0, v145, 4, 2
	v_lshlrev_b32_e32 v0, 3, v0
	v_bfe_u32 v141, v145, 6, 1
	s_lshl_b32 s1, s42, 19
	s_lshl_b32 s14, s15, 8
	s_add_i32 s1, s1, s14
	s_add_u32 s4, s2, s1
	s_addc_u32 s5, s3, 0
	s_add_u32 s4, s4, 0x4200000
	s_addc_u32 s5, s5, 0
	v_lshlrev_b32_e32 v138, 11, v131
	v_lshl_add_u32 v138, v141, 7, v138
	v_bfe_u32 v139, v145, 4, 1
	v_lshl_add_u32 v138, v139, 5, v138
	v_bfe_u32 v139, v145, 5, 1
	v_lshl_add_u32 v138, v139, 4, v138
	v_mov_b32_e32 v139, 0
	v_lshl_add_u64 v[138:139], s[4:5], 0, v[138:139]
	s_and_b32 s1, s42, 1
	s_lshl_b32 s1, s1, 20
	s_lshl_b32 s14, s98, 21
	s_add_i32 s1, s1, s14
	s_lshl_b32 s14, s15, 9
	s_add_i32 s1, s1, s14
	s_add_u32 s10, s2, s1
	s_addc_u32 s11, s3, 0
	s_add_u32 s10, s10, 0x1dcc0000
	s_addc_u32 s11, s11, 0
	v_lshlrev_b32_e32 v140, 12, v131
	v_lshl_add_u32 v140, v141, 8, v140
	v_lshl_add_u32 v140, v0, 1, v140
	v_mov_b32_e32 v141, 0
	v_lshl_add_u64 v[140:141], s[10:11], 0, v[140:141]
	s_mov_b32 s2, 0x20000
	s_mov_b32 s3, 0
	v_lshrrev_b32_e32 v0, 6, v145
	v_lshlrev_b32_e32 v0, 10, v0
	s_nop 0
	v_readfirstlane_b32 s43, v0
	s_mov_b32 s40, m0
	s_mov_b32 s4, 128
	s_mov_b32 s5, 0
	s_barrier
	s_add_i32 s15, s43, 0x0
	s_mov_b32 m0, s15
	v_lshl_add_u64 v[142:143], v[132:133], 0, s[2:3]
	global_load_lds_dwordx4 v[132:133], off
	s_add_i32 m0, m0, 0x1000
	s_nop 0
	global_load_lds_dwordx4 v[142:143], off
	v_lshl_add_u64 v[142:143], v[142:143], 0, s[2:3]
	s_add_i32 m0, m0, 0x1000
	s_nop 0
	global_load_lds_dwordx4 v[142:143], off
	v_lshl_add_u64 v[142:143], v[142:143], 0, s[2:3]
	s_add_i32 m0, m0, 0x1000
	s_nop 0
	global_load_lds_dwordx4 v[142:143], off
	s_add_i32 m0, m0, 0x1000
	v_lshl_add_u64 v[142:143], v[134:135], 0, s[2:3]
	s_nop 0
	global_load_lds_dwordx4 v[134:135], off
	s_add_i32 m0, m0, 0x1000
	v_lshl_add_u64 v[132:133], v[132:133], 0, s[12:13]
	s_nop 0
	global_load_lds_dwordx4 v[142:143], off
	v_lshl_add_u64 v[134:135], v[134:135], 0, s[4:5]
	s_nop 0
	s_add_i32 s15, s43, 0x6000
	s_mov_b32 m0, s15
	v_lshl_add_u64 v[142:143], v[132:133], 0, s[2:3]
	global_load_lds_dwordx4 v[132:133], off
	s_add_i32 m0, m0, 0x1000
	s_nop 0
	global_load_lds_dwordx4 v[142:143], off
	v_lshl_add_u64 v[142:143], v[142:143], 0, s[2:3]
	s_add_i32 m0, m0, 0x1000
	s_nop 0
	global_load_lds_dwordx4 v[142:143], off
	v_lshl_add_u64 v[142:143], v[142:143], 0, s[2:3]
	s_add_i32 m0, m0, 0x1000
	s_nop 0
	global_load_lds_dwordx4 v[142:143], off
	s_add_i32 m0, m0, 0x1000
	v_lshl_add_u64 v[142:143], v[134:135], 0, s[2:3]
	s_nop 0
	global_load_lds_dwordx4 v[134:135], off
	s_add_i32 m0, m0, 0x1000
	v_lshl_add_u64 v[132:133], v[132:133], 0, s[12:13]
	s_nop 0
	global_load_lds_dwordx4 v[142:143], off
	v_lshl_add_u64 v[134:135], v[134:135], 0, s[4:5]
	s_nop 0
	s_add_i32 s15, s43, 0xc000
	s_mov_b32 m0, s15
	v_lshl_add_u64 v[142:143], v[132:133], 0, s[2:3]
	global_load_lds_dwordx4 v[132:133], off
	s_add_i32 m0, m0, 0x1000
	s_nop 0
	global_load_lds_dwordx4 v[142:143], off
	v_lshl_add_u64 v[142:143], v[142:143], 0, s[2:3]
	s_add_i32 m0, m0, 0x1000
	s_nop 0
	global_load_lds_dwordx4 v[142:143], off
	v_lshl_add_u64 v[142:143], v[142:143], 0, s[2:3]
	s_add_i32 m0, m0, 0x1000
	s_nop 0
	global_load_lds_dwordx4 v[142:143], off
	s_add_i32 m0, m0, 0x1000
	v_lshl_add_u64 v[142:143], v[134:135], 0, s[2:3]
	s_nop 0
	global_load_lds_dwordx4 v[134:135], off
	s_add_i32 m0, m0, 0x1000
	v_lshl_add_u64 v[132:133], v[132:133], 0, s[12:13]
	s_nop 0
	global_load_lds_dwordx4 v[142:143], off
	v_lshl_add_u64 v[134:135], v[134:135], 0, s[4:5]
	s_nop 0
	v_mov_b32_e32 v2, 0
	v_mov_b32_e32 v3, 0
	v_mov_b32_e32 v4, 0
	v_mov_b32_e32 v5, 0
	v_mov_b32_e32 v6, 0
	v_mov_b32_e32 v7, 0
	v_mov_b32_e32 v8, 0
	v_mov_b32_e32 v9, 0
	v_mov_b32_e32 v10, 0
	v_mov_b32_e32 v11, 0
	v_mov_b32_e32 v12, 0
	v_mov_b32_e32 v13, 0
	v_mov_b32_e32 v14, 0
	v_mov_b32_e32 v15, 0
; #define LAS __attribute__((address_space(3)))
;     ...
;   f32x4 acc[4][8];
; #pragma unroll
;   for (int i = 0; i < 4; i++)
; #pragma unroll
;     for (int j = 0; j < 8; j++) acc[i][j] = (f32x4){0.f, 0.f, 0.f, 0.f};
;   const int nk = (nk_part < 0) ? (K >> 5) : nk_part;
;   const int lrow = tid >> 2, lpc = tid & 3;
;   const int lch = lpc ^ ((0x78 >> (((lrow >> 2) & 3) * 2)) & 3);
;   const u16* ga = A + (size_t)(m0 + lrow) * lda + kbeg + lch * 8;
;   const u16* gb = Bt + (size_t)(n0 + lrow) * K + kbeg + lch * 8;
;   const size_t ga1 = (size_t)64 * lda, gb1 = (size_t)64 * K;
;   const unsigned lds0 = (unsigned)(uintptr_t)(LAS char*)smem + (unsigned)__builtin_amdgcn_readfirstlane(wid) * 1024u;
;     ...
;   __syncthreads();
;   G2_STAGE(0); G2_STAGE(1);
;   const int fsw = (0x78 >> (((r16 >> 2) & 3) * 2)) & 3;
;   const int aoff = (wm * 128 + r16) * 64 + ((quad ^ fsw) << 4);
;   const int boff = 16384 + (wn * 64 + r16) * 64 + ((quad ^ fsw) << 4);
;   for (int kt = 0; kt < nk; kt++) {
;     if (kt + 1 < nk) asm volatile("s_waitcnt vmcnt(6)" ::: "memory");
;     else asm volatile("s_waitcnt vmcnt(0)" ::: "memory");
;     __builtin_amdgcn_s_barrier();
;     asm volatile("" ::: "memory");
;     if (kt + 2 < nk) G2_STAGE(kt + 2);
;     const char* cS = smem + (kt % 3) * 24576;
;     bf16x8 xa[8], wb[4];
; #pragma unroll
;     for (int f = 0; f < 8; f++) xa[f] = *(const bf16x8*)(cS + aoff + f * 1024);
; #pragma unroll
;     for (int f = 0; f < 4; f++) wb[f] = *(const bf16x8*)(cS + boff + f * 1024);
; #pragma unroll
;     for (int nf = 0; nf < 4; nf++)
; #pragma unroll
;       for (int mf = 0; mf < 8; mf++)
;         acc[nf][mf] = __builtin_amdgcn_mfma_f32_16x16x32_bf16(wb[nf], xa[mf], acc[nf][mf], 0, 0, 0);
	v_mov_b32_e32 v16, 0
	v_mov_b32_e32 v17, 0
	v_mov_b32_e32 v18, 0
	v_mov_b32_e32 v19, 0
	v_mov_b32_e32 v20, 0
	v_mov_b32_e32 v21, 0
	v_mov_b32_e32 v22, 0
	v_mov_b32_e32 v23, 0
	v_mov_b32_e32 v24, 0
	v_mov_b32_e32 v25, 0
	v_mov_b32_e32 v26, 0
	v_mov_b32_e32 v27, 0
	v_mov_b32_e32 v28, 0
	v_mov_b32_e32 v29, 0
	v_mov_b32_e32 v30, 0
	v_mov_b32_e32 v31, 0
	v_mov_b32_e32 v32, 0
	v_mov_b32_e32 v33, 0
	v_mov_b32_e32 v34, 0
	v_mov_b32_e32 v35, 0
	v_mov_b32_e32 v36, 0
	v_mov_b32_e32 v37, 0
	v_mov_b32_e32 v38, 0
	v_mov_b32_e32 v39, 0
	v_mov_b32_e32 v40, 0
	v_mov_b32_e32 v41, 0
	v_mov_b32_e32 v42, 0
	v_mov_b32_e32 v43, 0
	v_mov_b32_e32 v44, 0
	v_mov_b32_e32 v45, 0
	v_mov_b32_e32 v46, 0
	v_mov_b32_e32 v47, 0
	v_mov_b32_e32 v48, 0
	v_mov_b32_e32 v49, 0
	v_mov_b32_e32 v50, 0
	v_mov_b32_e32 v51, 0
	v_mov_b32_e32 v52, 0
	v_mov_b32_e32 v53, 0
	v_mov_b32_e32 v54, 0
	v_mov_b32_e32 v55, 0
	v_mov_b32_e32 v56, 0
	v_mov_b32_e32 v57, 0
	v_mov_b32_e32 v58, 0
	v_mov_b32_e32 v59, 0
	v_mov_b32_e32 v60, 0
	v_mov_b32_e32 v61, 0
	v_mov_b32_e32 v62, 0
	v_mov_b32_e32 v63, 0
	v_mov_b32_e32 v64, 0
	v_mov_b32_e32 v65, 0
	v_mov_b32_e32 v66, 0
	v_mov_b32_e32 v67, 0
	v_mov_b32_e32 v68, 0
	v_mov_b32_e32 v69, 0
	v_mov_b32_e32 v70, 0
	v_mov_b32_e32 v71, 0
	v_mov_b32_e32 v72, 0
	v_mov_b32_e32 v73, 0
	v_mov_b32_e32 v74, 0
	v_mov_b32_e32 v75, 0
	v_mov_b32_e32 v76, 0
	v_mov_b32_e32 v77, 0
	v_mov_b32_e32 v78, 0
	v_mov_b32_e32 v79, 0
	v_mov_b32_e32 v80, 0
	v_mov_b32_e32 v81, 0
	v_mov_b32_e32 v82, 0
	v_mov_b32_e32 v83, 0
	v_mov_b32_e32 v84, 0
	v_mov_b32_e32 v85, 0
	v_mov_b32_e32 v86, 0
	v_mov_b32_e32 v87, 0
	v_mov_b32_e32 v88, 0
	v_mov_b32_e32 v89, 0
	v_mov_b32_e32 v90, 0
	v_mov_b32_e32 v91, 0
	v_mov_b32_e32 v92, 0
	v_mov_b32_e32 v93, 0
	v_mov_b32_e32 v94, 0
	v_mov_b32_e32 v95, 0
	v_mov_b32_e32 v96, 0
	v_mov_b32_e32 v97, 0
	v_mov_b32_e32 v98, 0
	v_mov_b32_e32 v99, 0
	v_mov_b32_e32 v100, 0
	v_mov_b32_e32 v101, 0
	v_mov_b32_e32 v102, 0
	v_mov_b32_e32 v103, 0
	v_mov_b32_e32 v104, 0
	v_mov_b32_e32 v105, 0
	v_mov_b32_e32 v106, 0
	v_mov_b32_e32 v107, 0
	v_mov_b32_e32 v108, 0
	v_mov_b32_e32 v109, 0
	v_mov_b32_e32 v110, 0
	v_mov_b32_e32 v111, 0
	v_mov_b32_e32 v112, 0
	v_mov_b32_e32 v113, 0
	v_mov_b32_e32 v114, 0
	v_mov_b32_e32 v115, 0
	v_mov_b32_e32 v116, 0
	v_mov_b32_e32 v117, 0
	v_mov_b32_e32 v118, 0
	v_mov_b32_e32 v119, 0
	v_mov_b32_e32 v120, 0
	v_mov_b32_e32 v121, 0
	v_mov_b32_e32 v122, 0
	v_mov_b32_e32 v123, 0
	v_mov_b32_e32 v124, 0
	v_mov_b32_e32 v125, 0
	v_mov_b32_e32 v126, 0
	v_mov_b32_e32 v127, 0
	v_mov_b32_e32 v128, 0
	v_mov_b32_e32 v129, 0
	s_waitcnt vmcnt(12)
	s_barrier
	ds_read_b128 v[146:149], v136 offset:0
	ds_read_b128 v[152:155], v136 offset:1024
	ds_read_b128 v[156:159], v136 offset:2048
	ds_read_b128 v[162:165], v136 offset:3072
	ds_read_b128 v[166:169], v136 offset:4096
	ds_read_b128 v[170:173], v136 offset:5120
	ds_read_b128 v[176:179], v136 offset:6144
	ds_read_b128 v[180:183], v136 offset:7168
	ds_read_b128 v[184:187], v137 offset:16384
	ds_read_b128 v[188:191], v137 offset:17408
	ds_read_b128 v[192:195], v137 offset:18432
	ds_read_b128 v[196:199], v137 offset:19456
	s_movk_i32 s1, 0x6000
	s_mov_b32 s14, 0
	.p2align 3
	s_waitcnt vmcnt(6) lgkmcnt(0)
	s_barrier
	s_setprio 1
	v_add_u32_e32 v144, s1, v136
	v_mfma_f32_16x16x32_bf16 v[126:129], v[184:187], v[146:149], v[126:129]
	ds_read_b128 v[200:203], v144 offset:0
	v_mfma_f32_16x16x32_bf16 v[122:125], v[184:187], v[152:155], v[122:125]
	ds_read_b128 v[204:207], v144 offset:1024
	v_mfma_f32_16x16x32_bf16 v[118:121], v[184:187], v[156:159], v[118:121]
	ds_read_b128 v[208:211], v144 offset:2048
	v_mfma_f32_16x16x32_bf16 v[114:117], v[184:187], v[162:165], v[114:117]
	ds_read_b128 v[212:215], v144 offset:3072
	v_mfma_f32_16x16x32_bf16 v[110:113], v[184:187], v[166:169], v[110:113]
	ds_read_b128 v[216:219], v144 offset:4096
	v_mfma_f32_16x16x32_bf16 v[106:109], v[184:187], v[170:173], v[106:109]
	ds_read_b128 v[220:223], v144 offset:5120
	v_mfma_f32_16x16x32_bf16 v[102:105], v[184:187], v[176:179], v[102:105]
	ds_read_b128 v[224:227], v144 offset:6144
	v_mfma_f32_16x16x32_bf16 v[98:101], v[184:187], v[180:183], v[98:101]
	ds_read_b128 v[228:231], v144 offset:7168
	v_mfma_f32_16x16x32_bf16 v[94:97], v[188:191], v[146:149], v[94:97]
	v_add_u32_e64 v144, s1, v137
	v_mfma_f32_16x16x32_bf16 v[90:93], v[188:191], v[152:155], v[90:93]
	v_mfma_f32_16x16x32_bf16 v[86:89], v[188:191], v[156:159], v[86:89]
	ds_read_b128 v[232:235], v144 offset:16384
	v_mfma_f32_16x16x32_bf16 v[82:85], v[188:191], v[162:165], v[82:85]
	ds_read_b128 v[236:239], v144 offset:17408
	v_mfma_f32_16x16x32_bf16 v[78:81], v[188:191], v[166:169], v[78:81]
	ds_read_b128 v[240:243], v144 offset:18432
	v_mfma_f32_16x16x32_bf16 v[74:77], v[188:191], v[170:173], v[74:77]
	ds_read_b128 v[244:247], v144 offset:19456
	v_mfma_f32_16x16x32_bf16 v[70:73], v[188:191], v[176:179], v[70:73]
	s_add_i32 s15, s43, s14
	s_mov_b32 m0, s15
	v_lshl_add_u64 v[142:143], v[132:133], 0, s[2:3]
	v_mfma_f32_16x16x32_bf16 v[66:69], v[188:191], v[180:183], v[66:69]
	global_load_lds_dwordx4 v[132:133], off
	s_add_i32 m0, m0, 0x1000
	v_mfma_f32_16x16x32_bf16 v[62:65], v[192:195], v[146:149], v[62:65]
	v_mfma_f32_16x16x32_bf16 v[58:61], v[192:195], v[152:155], v[58:61]
	v_mfma_f32_16x16x32_bf16 v[54:57], v[192:195], v[156:159], v[54:57]
	global_load_lds_dwordx4 v[142:143], off
	v_lshl_add_u64 v[142:143], v[142:143], 0, s[2:3]
	s_add_i32 m0, m0, 0x1000
	v_mfma_f32_16x16x32_bf16 v[50:53], v[192:195], v[162:165], v[50:53]
	v_mfma_f32_16x16x32_bf16 v[46:49], v[192:195], v[166:169], v[46:49]
	v_mfma_f32_16x16x32_bf16 v[42:45], v[192:195], v[170:173], v[42:45]
	global_load_lds_dwordx4 v[142:143], off
	v_lshl_add_u64 v[142:143], v[142:143], 0, s[2:3]
	s_add_i32 m0, m0, 0x1000
	v_mfma_f32_16x16x32_bf16 v[38:41], v[192:195], v[176:179], v[38:41]
	v_mfma_f32_16x16x32_bf16 v[34:37], v[192:195], v[180:183], v[34:37]
	v_mfma_f32_16x16x32_bf16 v[30:33], v[196:199], v[146:149], v[30:33]
	global_load_lds_dwordx4 v[142:143], off
	s_add_i32 m0, m0, 0x1000
	v_lshl_add_u64 v[142:143], v[134:135], 0, s[2:3]
	v_mfma_f32_16x16x32_bf16 v[26:29], v[196:199], v[152:155], v[26:29]
	v_mfma_f32_16x16x32_bf16 v[22:25], v[196:199], v[156:159], v[22:25]
	v_mfma_f32_16x16x32_bf16 v[18:21], v[196:199], v[162:165], v[18:21]
	global_load_lds_dwordx4 v[134:135], off
	s_add_i32 m0, m0, 0x1000
	v_lshl_add_u64 v[132:133], v[132:133], 0, s[12:13]
	v_mfma_f32_16x16x32_bf16 v[14:17], v[196:199], v[166:169], v[14:17]
	v_mfma_f32_16x16x32_bf16 v[10:13], v[196:199], v[170:173], v[10:13]
	v_mfma_f32_16x16x32_bf16 v[6:9], v[196:199], v[176:179], v[6:9]
	global_load_lds_dwordx4 v[142:143], off
	v_lshl_add_u64 v[134:135], v[134:135], 0, s[4:5]
	v_mfma_f32_16x16x32_bf16 v[2:5], v[196:199], v[180:183], v[2:5]
	s_setprio 0
	s_mov_b32 s14, s1
	s_add_i32 s1, s1, 0x6000
	s_cmp_eq_u32 s1, 0x12000
	s_cselect_b32 s1, 0, s1
	s_nop 0
	.p2align 3
	s_waitcnt vmcnt(6) lgkmcnt(0)
	s_barrier
;     ...
;   for (int kt = 0; kt < nk; kt++) {
;     if (kt + 1 < nk) asm volatile("s_waitcnt vmcnt(6)" ::: "memory");
;     else asm volatile("s_waitcnt vmcnt(0)" ::: "memory");
;     __builtin_amdgcn_s_barrier();
;     asm volatile("" ::: "memory");
;     if (kt + 2 < nk) G2_STAGE(kt + 2);
;     const char* cS = smem + (kt % 3) * 24576;
;     bf16x8 xa[8], wb[4];
; #pragma unroll
;     for (int f = 0; f < 8; f++) xa[f] = *(const bf16x8*)(cS + aoff + f * 1024);
; #pragma unroll
;     for (int f = 0; f < 4; f++) wb[f] = *(const bf16x8*)(cS + boff + f * 1024);
; #pragma unroll
;     for (int nf = 0; nf < 4; nf++)
; #pragma unroll
;       for (int mf = 0; mf < 8; mf++)
;         acc[nf][mf] = __builtin_amdgcn_mfma_f32_16x16x32_bf16(wb[nf], xa[mf], acc[nf][mf], 0, 0, 0);
	s_setprio 1
	v_add_u32_e32 v144, s1, v136
	v_mfma_f32_16x16x32_bf16 v[126:129], v[232:235], v[200:203], v[126:129]
	ds_read_b128 v[146:149], v144 offset:0
	v_mfma_f32_16x16x32_bf16 v[122:125], v[232:235], v[204:207], v[122:125]
	ds_read_b128 v[152:155], v144 offset:1024
	v_mfma_f32_16x16x32_bf16 v[118:121], v[232:235], v[208:211], v[118:121]
	ds_read_b128 v[156:159], v144 offset:2048
	v_mfma_f32_16x16x32_bf16 v[114:117], v[232:235], v[212:215], v[114:117]
	ds_read_b128 v[162:165], v144 offset:3072
	v_mfma_f32_16x16x32_bf16 v[110:113], v[232:235], v[216:219], v[110:113]
	ds_read_b128 v[166:169], v144 offset:4096
	v_mfma_f32_16x16x32_bf16 v[106:109], v[232:235], v[220:223], v[106:109]
	ds_read_b128 v[170:173], v144 offset:5120
	v_mfma_f32_16x16x32_bf16 v[102:105], v[232:235], v[224:227], v[102:105]
	ds_read_b128 v[176:179], v144 offset:6144
	v_mfma_f32_16x16x32_bf16 v[98:101], v[232:235], v[228:231], v[98:101]
	ds_read_b128 v[180:183], v144 offset:7168
	v_mfma_f32_16x16x32_bf16 v[94:97], v[236:239], v[200:203], v[94:97]
	v_add_u32_e64 v144, s1, v137
	v_mfma_f32_16x16x32_bf16 v[90:93], v[236:239], v[204:207], v[90:93]
	v_mfma_f32_16x16x32_bf16 v[86:89], v[236:239], v[208:211], v[86:89]
	ds_read_b128 v[184:187], v144 offset:16384
	v_mfma_f32_16x16x32_bf16 v[82:85], v[236:239], v[212:215], v[82:85]
	ds_read_b128 v[188:191], v144 offset:17408
	v_mfma_f32_16x16x32_bf16 v[78:81], v[236:239], v[216:219], v[78:81]
	ds_read_b128 v[192:195], v144 offset:18432
	v_mfma_f32_16x16x32_bf16 v[74:77], v[236:239], v[220:223], v[74:77]
	ds_read_b128 v[196:199], v144 offset:19456
	v_mfma_f32_16x16x32_bf16 v[70:73], v[236:239], v[224:227], v[70:73]
	v_mfma_f32_16x16x32_bf16 v[66:69], v[236:239], v[228:231], v[66:69]
	v_mfma_f32_16x16x32_bf16 v[62:65], v[240:243], v[200:203], v[62:65]
	v_mfma_f32_16x16x32_bf16 v[58:61], v[240:243], v[204:207], v[58:61]
	v_mfma_f32_16x16x32_bf16 v[54:57], v[240:243], v[208:211], v[54:57]
	v_mfma_f32_16x16x32_bf16 v[50:53], v[240:243], v[212:215], v[50:53]
	v_mfma_f32_16x16x32_bf16 v[46:49], v[240:243], v[216:219], v[46:49]
	v_mfma_f32_16x16x32_bf16 v[42:45], v[240:243], v[220:223], v[42:45]
	v_mfma_f32_16x16x32_bf16 v[38:41], v[240:243], v[224:227], v[38:41]
	v_mfma_f32_16x16x32_bf16 v[34:37], v[240:243], v[228:231], v[34:37]
	v_mfma_f32_16x16x32_bf16 v[30:33], v[244:247], v[200:203], v[30:33]
	v_mfma_f32_16x16x32_bf16 v[26:29], v[244:247], v[204:207], v[26:29]
	v_mfma_f32_16x16x32_bf16 v[22:25], v[244:247], v[208:211], v[22:25]
	v_mfma_f32_16x16x32_bf16 v[18:21], v[244:247], v[212:215], v[18:21]
	v_mfma_f32_16x16x32_bf16 v[14:17], v[244:247], v[216:219], v[14:17]
	v_mfma_f32_16x16x32_bf16 v[10:13], v[244:247], v[220:223], v[10:13]
	v_mfma_f32_16x16x32_bf16 v[6:9], v[244:247], v[224:227], v[6:9]
	v_mfma_f32_16x16x32_bf16 v[2:5], v[244:247], v[228:231], v[2:5]
	s_setprio 0
	s_mov_b32 s14, s1
	s_add_i32 s1, s1, 0x6000
	s_cmp_eq_u32 s1, 0x12000
	s_cselect_b32 s1, 0, s1
	s_nop 0
	.p2align 3
	s_waitcnt vmcnt(0) lgkmcnt(0)
	s_barrier
	s_setprio 1
	v_add_u32_e32 v144, s1, v136
	v_mfma_f32_16x16x32_bf16 v[126:129], v[184:187], v[146:149], v[126:129]
	ds_read_b128 v[200:203], v144 offset:0
	v_mfma_f32_16x16x32_bf16 v[122:125], v[184:187], v[152:155], v[122:125]
	ds_read_b128 v[204:207], v144 offset:1024
	v_mfma_f32_16x16x32_bf16 v[118:121], v[184:187], v[156:159], v[118:121]
	ds_read_b128 v[208:211], v144 offset:2048
	v_mfma_f32_16x16x32_bf16 v[114:117], v[184:187], v[162:165], v[114:117]
	ds_read_b128 v[212:215], v144 offset:3072
	v_mfma_f32_16x16x32_bf16 v[110:113], v[184:187], v[166:169], v[110:113]
	ds_read_b128 v[216:219], v144 offset:4096
	v_mfma_f32_16x16x32_bf16 v[106:109], v[184:187], v[170:173], v[106:109]
	ds_read_b128 v[220:223], v144 offset:5120
	v_mfma_f32_16x16x32_bf16 v[102:105], v[184:187], v[176:179], v[102:105]
	ds_read_b128 v[224:227], v144 offset:6144
	v_mfma_f32_16x16x32_bf16 v[98:101], v[184:187], v[180:183], v[98:101]
	ds_read_b128 v[228:231], v144 offset:7168
	v_mfma_f32_16x16x32_bf16 v[94:97], v[188:191], v[146:149], v[94:97]
	v_add_u32_e64 v144, s1, v137
	v_mfma_f32_16x16x32_bf16 v[90:93], v[188:191], v[152:155], v[90:93]
	v_mfma_f32_16x16x32_bf16 v[86:89], v[188:191], v[156:159], v[86:89]
	ds_read_b128 v[232:235], v144 offset:16384
	v_mfma_f32_16x16x32_bf16 v[82:85], v[188:191], v[162:165], v[82:85]
	ds_read_b128 v[236:239], v144 offset:17408
	v_mfma_f32_16x16x32_bf16 v[78:81], v[188:191], v[166:169], v[78:81]
	ds_read_b128 v[240:243], v144 offset:18432
	v_mfma_f32_16x16x32_bf16 v[74:77], v[188:191], v[170:173], v[74:77]
	ds_read_b128 v[244:247], v144 offset:19456
	v_mfma_f32_16x16x32_bf16 v[70:73], v[188:191], v[176:179], v[70:73]
	v_mfma_f32_16x16x32_bf16 v[66:69], v[188:191], v[180:183], v[66:69]
	v_mfma_f32_16x16x32_bf16 v[62:65], v[192:195], v[146:149], v[62:65]
	v_mfma_f32_16x16x32_bf16 v[58:61], v[192:195], v[152:155], v[58:61]
	v_mfma_f32_16x16x32_bf16 v[54:57], v[192:195], v[156:159], v[54:57]
	v_mfma_f32_16x16x32_bf16 v[50:53], v[192:195], v[162:165], v[50:53]
	v_mfma_f32_16x16x32_bf16 v[46:49], v[192:195], v[166:169], v[46:49]
	v_mfma_f32_16x16x32_bf16 v[42:45], v[192:195], v[170:173], v[42:45]
	v_mfma_f32_16x16x32_bf16 v[38:41], v[192:195], v[176:179], v[38:41]
	v_mfma_f32_16x16x32_bf16 v[34:37], v[192:195], v[180:183], v[34:37]
	v_mfma_f32_16x16x32_bf16 v[30:33], v[196:199], v[146:149], v[30:33]
	v_mfma_f32_16x16x32_bf16 v[26:29], v[196:199], v[152:155], v[26:29]
	v_mfma_f32_16x16x32_bf16 v[22:25], v[196:199], v[156:159], v[22:25]
	v_mfma_f32_16x16x32_bf16 v[18:21], v[196:199], v[162:165], v[18:21]
	v_mfma_f32_16x16x32_bf16 v[14:17], v[196:199], v[166:169], v[14:17]
	v_mfma_f32_16x16x32_bf16 v[10:13], v[196:199], v[170:173], v[10:13]
	v_mfma_f32_16x16x32_bf16 v[6:9], v[196:199], v[176:179], v[6:9]
	v_mfma_f32_16x16x32_bf16 v[2:5], v[196:199], v[180:183], v[2:5]
	s_setprio 0
	s_mov_b32 s14, s1
	s_add_i32 s1, s1, 0x6000
	s_cmp_eq_u32 s1, 0x12000
	s_cselect_b32 s1, 0, s1
	s_nop 0
	s_mov_b32 s4, 0x8000
	s_mov_b32 s5, 0
	s_mov_b32 s10, 0x10000
	s_mov_b32 s11, 0
	s_mov_b32 s41, 0x3fd744fd
	.p2align 3
	s_waitcnt lgkmcnt(0)
; DEVI unsigned pack2(float a, float b) { return __builtin_bit_cast(unsigned, __builtin_convertvector((f32x2_t){a, b}, bf16x2_t)); }
; DEVI float blo(unsigned u) { return __uint_as_float(u << 16); }
; DEVI float bhi(unsigned u) { return __uint_as_float(u & 0xffff0000u); }
; DEVI float siluf_(float x) { return x * __builtin_amdgcn_rcpf(1.f + __expf(-x)); }
; DEVI int xcd_first_tile() { return (blockIdx.x & 7) * (gridDim.x >> 3) + (blockIdx.x >> 3); }
;     ...
;     for (int nf = 0; nf < 4; nf++)
; #pragma unroll
;       for (int mf = 0; mf < 8; mf++)
;         acc[nf][mf] = __builtin_amdgcn_mfma_f32_16x16x32_bf16(wb[nf], xa[mf], acc[nf][mf], 0, 0, 0);
;   }
;     ...
; #pragma unroll
;   for (int mf = 0; mf < 8; mf++) {
;     const int row = m0 + wm * 128 + mf * 16 + r16;
;     if (EPI == EPI_SWIGLU) {
; #pragma unroll
;       for (int nf = 0; nf < 2; nf++) {
;         const int hcol = (n0 >> 1) + wn * 32 + nf * 16 + quad * 4;
;         f32x4 g = acc[nf][mf], u = acc[nf + 2][mf];
;         u32x2 pk;
;         pk[0] = pack2(siluf_(g[0]) * u[0], siluf_(g[1]) * u[1]);
;         pk[1] = pack2(siluf_(g[2]) * u[2], siluf_(g[3]) * u[3]);
;         *(u32x2*)(outb + (size_t)row * DFF + hcol) = pk;
;       }
;     } else {
; #pragma unroll
;       for (int nf = 0; nf < 4; nf++) {
;         const int col = n0 + wn * 64 + nf * 16 + quad * 4;
;         f32x4 a = acc[nf][mf];
;         if (EPI == EPI_RESID || EPI == EPI_RESID_ATOMIC) {
;           f32x4 x = a;
;           if (EPI == EPI_RESID || kpart == 0) {
;             const u32x2 xr = *(const u32x2*)((const u16*)(p.ws + WS_XB) + (size_t)row * 1024 + col);
;             x[0] += ALPHA * blo(xr[0]); x[1] += ALPHA * bhi(xr[0]); x[2] += ALPHA * blo(xr[1]); x[3] += ALPHA * bhi(xr[1]);
;           }
;           if (EPI == EPI_RESID) *(f32x4*)((float*)(p.ws + WS_XF) + (size_t)row * 1024 + col) = x;
;           else *(f32x4*)((float*)(p.ws + WS_SLAB) + ((size_t)kpart * 512 + (row - T_P)) * 1024 + col) = x;
; DEVI void run_phase(const Params& p, int ph, char* smem) {
;     ...
;       for (int t = xcd_first_tile(); t < 512 + 16 * 8; t += xcd_tile_step()) {
	s_nop 0
	v_mfma_f32_16x16x32_bf16 v[126:129], v[232:235], v[200:203], v[126:129]
	v_mfma_f32_16x16x32_bf16 v[122:125], v[232:235], v[204:207], v[122:125]
	v_mfma_f32_16x16x32_bf16 v[118:121], v[232:235], v[208:211], v[118:121]
	v_mfma_f32_16x16x32_bf16 v[114:117], v[232:235], v[212:215], v[114:117]
	v_mfma_f32_16x16x32_bf16 v[110:113], v[232:235], v[216:219], v[110:113]
	v_mfma_f32_16x16x32_bf16 v[106:109], v[232:235], v[220:223], v[106:109]
	v_mfma_f32_16x16x32_bf16 v[102:105], v[232:235], v[224:227], v[102:105]
	v_mfma_f32_16x16x32_bf16 v[98:101], v[232:235], v[228:231], v[98:101]
	v_mfma_f32_16x16x32_bf16 v[94:97], v[236:239], v[200:203], v[94:97]
	v_mfma_f32_16x16x32_bf16 v[90:93], v[236:239], v[204:207], v[90:93]
	v_mfma_f32_16x16x32_bf16 v[86:89], v[236:239], v[208:211], v[86:89]
	v_mfma_f32_16x16x32_bf16 v[82:85], v[236:239], v[212:215], v[82:85]
	v_mfma_f32_16x16x32_bf16 v[78:81], v[236:239], v[216:219], v[78:81]
	v_mfma_f32_16x16x32_bf16 v[74:77], v[236:239], v[220:223], v[74:77]
	v_mfma_f32_16x16x32_bf16 v[70:73], v[236:239], v[224:227], v[70:73]
	v_mfma_f32_16x16x32_bf16 v[66:69], v[236:239], v[228:231], v[66:69]
	v_mfma_f32_16x16x32_bf16 v[62:65], v[240:243], v[200:203], v[62:65]
	v_mfma_f32_16x16x32_bf16 v[58:61], v[240:243], v[204:207], v[58:61]
	v_mfma_f32_16x16x32_bf16 v[54:57], v[240:243], v[208:211], v[54:57]
	v_mfma_f32_16x16x32_bf16 v[50:53], v[240:243], v[212:215], v[50:53]
	v_mfma_f32_16x16x32_bf16 v[46:49], v[240:243], v[216:219], v[46:49]
	v_mfma_f32_16x16x32_bf16 v[42:45], v[240:243], v[220:223], v[42:45]
	v_mfma_f32_16x16x32_bf16 v[38:41], v[240:243], v[224:227], v[38:41]
	v_mfma_f32_16x16x32_bf16 v[34:37], v[240:243], v[228:231], v[34:37]
	v_mfma_f32_16x16x32_bf16 v[30:33], v[244:247], v[200:203], v[30:33]
	v_mfma_f32_16x16x32_bf16 v[26:29], v[244:247], v[204:207], v[26:29]
	v_mfma_f32_16x16x32_bf16 v[22:25], v[244:247], v[208:211], v[22:25]
	v_mfma_f32_16x16x32_bf16 v[18:21], v[244:247], v[212:215], v[18:21]
	v_mfma_f32_16x16x32_bf16 v[14:17], v[244:247], v[216:219], v[14:17]
	v_mfma_f32_16x16x32_bf16 v[10:13], v[244:247], v[220:223], v[10:13]
	v_mfma_f32_16x16x32_bf16 v[6:9], v[244:247], v[224:227], v[6:9]
	v_mfma_f32_16x16x32_bf16 v[2:5], v[244:247], v[228:231], v[2:5]
	s_mov_b32 m0, s40
	s_cmp_eq_u32 s98, 0
	s_cbranch_scc1 .Lta4_first
	s_nop 7
	global_store_dwordx4 v[140:141], v[126:129], off offset:0
	global_store_dwordx4 v[140:141], v[94:97], off offset:64
	global_store_dwordx4 v[140:141], v[62:65], off offset:128
	global_store_dwordx4 v[140:141], v[30:33], off offset:192
	v_lshl_add_u64 v[140:141], v[140:141], 0, s[10:11]
	global_store_dwordx4 v[140:141], v[122:125], off offset:0
	global_store_dwordx4 v[140:141], v[90:93], off offset:64
	global_store_dwordx4 v[140:141], v[58:61], off offset:128
	global_store_dwordx4 v[140:141], v[26:29], off offset:192
	v_lshl_add_u64 v[140:141], v[140:141], 0, s[10:11]
	global_store_dwordx4 v[140:141], v[118:121], off offset:0
	global_store_dwordx4 v[140:141], v[86:89], off offset:64
	global_store_dwordx4 v[140:141], v[54:57], off offset:128
	global_store_dwordx4 v[140:141], v[22:25], off offset:192
	v_lshl_add_u64 v[140:141], v[140:141], 0, s[10:11]
	global_store_dwordx4 v[140:141], v[114:117], off offset:0
	global_store_dwordx4 v[140:141], v[82:85], off offset:64
	global_store_dwordx4 v[140:141], v[50:53], off offset:128
	global_store_dwordx4 v[140:141], v[18:21], off offset:192
	v_lshl_add_u64 v[140:141], v[140:141], 0, s[10:11]
	global_store_dwordx4 v[140:141], v[110:113], off offset:0
	global_store_dwordx4 v[140:141], v[78:81], off offset:64
	global_store_dwordx4 v[140:141], v[46:49], off offset:128
	global_store_dwordx4 v[140:141], v[14:17], off offset:192
	v_lshl_add_u64 v[140:141], v[140:141], 0, s[10:11]
	global_store_dwordx4 v[140:141], v[106:109], off offset:0
	global_store_dwordx4 v[140:141], v[74:77], off offset:64
	global_store_dwordx4 v[140:141], v[42:45], off offset:128
	global_store_dwordx4 v[140:141], v[10:13], off offset:192
	v_lshl_add_u64 v[140:141], v[140:141], 0, s[10:11]
	global_store_dwordx4 v[140:141], v[102:105], off offset:0
	global_store_dwordx4 v[140:141], v[70:73], off offset:64
	global_store_dwordx4 v[140:141], v[38:41], off offset:128
	global_store_dwordx4 v[140:141], v[6:9], off offset:192
	v_lshl_add_u64 v[140:141], v[140:141], 0, s[10:11]
	global_store_dwordx4 v[140:141], v[98:101], off offset:0
	global_store_dwordx4 v[140:141], v[66:69], off offset:64
	global_store_dwordx4 v[140:141], v[34:37], off offset:128
	global_store_dwordx4 v[140:141], v[2:5], off offset:192
	v_readlane_b32 s0, v250, 7
	s_cmpk_lg_u32 s0, 0x200
	s_cbranch_scc1 .Lta4_ar1
	s_mov_b32 s0, 1
	v_writelane_b32 v255, s0, 41
	v_readlane_b32 s1, v250, 0
	s_lshr_b32 s14, s1, 3
	s_and_b32 s1, s1, 7
	s_lshl_b32 s1, s1, 6
	s_add_i32 s1, s1, s14
	s_sub_i32 s39, s1, 0x200

; DEVI float blo(unsigned u) { return __uint_as_float(u << 16); }
; DEVI float bhi(unsigned u) { return __uint_as_float(u & 0xffff0000u); }
;     ...
;         if (EPI == EPI_RESID || EPI == EPI_RESID_ATOMIC) {
;           f32x4 x = a;
;           if (EPI == EPI_RESID || kpart == 0) {
;             const u32x2 xr = *(const u32x2*)((const u16*)(p.ws + WS_XB) + (size_t)row * 1024 + col);
;             x[0] += ALPHA * blo(xr[0]); x[1] += ALPHA * bhi(xr[0]); x[2] += ALPHA * blo(xr[1]); x[3] += ALPHA * bhi(xr[1]);
;           }
;           if (EPI == EPI_RESID) *(f32x4*)((float*)(p.ws + WS_XF) + (size_t)row * 1024 + col) = x;
;           else *(f32x4*)((float*)(p.ws + WS_SLAB) + ((size_t)kpart * 512 + (row - T_P)) * 1024 + col) = x;
.Lta4_first:
	global_load_dwordx4 v[146:149], v[138:139], off offset:0
	global_load_dwordx4 v[152:155], v[138:139], off offset:64
	v_lshl_add_u64 v[138:139], v[138:139], 0, s[4:5]
	global_load_dwordx4 v[156:159], v[138:139], off offset:0
	global_load_dwordx4 v[162:165], v[138:139], off offset:64
	v_lshl_add_u64 v[138:139], v[138:139], 0, s[4:5]
	global_load_dwordx4 v[166:169], v[138:139], off offset:0
	global_load_dwordx4 v[170:173], v[138:139], off offset:64
	v_lshl_add_u64 v[138:139], v[138:139], 0, s[4:5]
	global_load_dwordx4 v[176:179], v[138:139], off offset:0
	global_load_dwordx4 v[180:183], v[138:139], off offset:64
	v_lshl_add_u64 v[138:139], v[138:139], 0, s[4:5]
	global_load_dwordx4 v[184:187], v[138:139], off offset:0
	global_load_dwordx4 v[188:191], v[138:139], off offset:64
	v_lshl_add_u64 v[138:139], v[138:139], 0, s[4:5]
	global_load_dwordx4 v[192:195], v[138:139], off offset:0
	global_load_dwordx4 v[196:199], v[138:139], off offset:64
	v_lshl_add_u64 v[138:139], v[138:139], 0, s[4:5]
	global_load_dwordx4 v[200:203], v[138:139], off offset:0
	global_load_dwordx4 v[204:207], v[138:139], off offset:64
	v_lshl_add_u64 v[138:139], v[138:139], 0, s[4:5]
	global_load_dwordx4 v[208:211], v[138:139], off offset:0
	global_load_dwordx4 v[212:215], v[138:139], off offset:64
	v_lshl_add_u64 v[138:139], v[138:139], 0, s[4:5]
	s_nop 7
	s_waitcnt vmcnt(15)
	v_permlane16_swap_b32_e32 v146, v148
	v_permlane16_swap_b32_e32 v147, v149
	v_lshlrev_b32_e32 v216, 16, v146
	v_and_b32_e32 v146, 0xffff0000, v146
	v_lshlrev_b32_e32 v217, 16, v147
	v_and_b32_e32 v147, 0xffff0000, v147
	v_fmac_f32_e32 v126, s41, v216
	v_fmac_f32_e32 v127, s41, v146
	v_fmac_f32_e32 v128, s41, v217
	v_fmac_f32_e32 v129, s41, v147
	global_store_dwordx4 v[140:141], v[126:129], off offset:0
	v_lshlrev_b32_e32 v216, 16, v148
	v_and_b32_e32 v148, 0xffff0000, v148
	v_lshlrev_b32_e32 v217, 16, v149
	v_and_b32_e32 v149, 0xffff0000, v149
	v_fmac_f32_e32 v94, s41, v216
	v_fmac_f32_e32 v95, s41, v148
	v_fmac_f32_e32 v96, s41, v217
	v_fmac_f32_e32 v97, s41, v149
	global_store_dwordx4 v[140:141], v[94:97], off offset:64
	s_waitcnt vmcnt(16)
	v_permlane16_swap_b32_e32 v152, v154
	v_permlane16_swap_b32_e32 v153, v155
	v_lshlrev_b32_e32 v216, 16, v152
	v_and_b32_e32 v152, 0xffff0000, v152
	v_lshlrev_b32_e32 v217, 16, v153
	v_and_b32_e32 v153, 0xffff0000, v153
	v_fmac_f32_e32 v62, s41, v216
	v_fmac_f32_e32 v63, s41, v152
	v_fmac_f32_e32 v64, s41, v217
	v_fmac_f32_e32 v65, s41, v153
	global_store_dwordx4 v[140:141], v[62:65], off offset:128
	v_lshlrev_b32_e32 v216, 16, v154
	v_and_b32_e32 v154, 0xffff0000, v154
	v_lshlrev_b32_e32 v217, 16, v155
	v_and_b32_e32 v155, 0xffff0000, v155
	v_fmac_f32_e32 v30, s41, v216
	v_fmac_f32_e32 v31, s41, v154
	v_fmac_f32_e32 v32, s41, v217
	v_fmac_f32_e32 v33, s41, v155
	global_store_dwordx4 v[140:141], v[30:33], off offset:192
	v_lshl_add_u64 v[140:141], v[140:141], 0, s[10:11]
	s_waitcnt vmcnt(17)
	v_permlane16_swap_b32_e32 v156, v158
	v_permlane16_swap_b32_e32 v157, v159
	v_lshlrev_b32_e32 v216, 16, v156
	v_and_b32_e32 v156, 0xffff0000, v156
	v_lshlrev_b32_e32 v217, 16, v157
	v_and_b32_e32 v157, 0xffff0000, v157
	v_fmac_f32_e32 v122, s41, v216
	v_fmac_f32_e32 v123, s41, v156
	v_fmac_f32_e32 v124, s41, v217
	v_fmac_f32_e32 v125, s41, v157
	global_store_dwordx4 v[140:141], v[122:125], off offset:0
	v_lshlrev_b32_e32 v216, 16, v158
	v_and_b32_e32 v158, 0xffff0000, v158
	v_lshlrev_b32_e32 v217, 16, v159
	v_and_b32_e32 v159, 0xffff0000, v159
	v_fmac_f32_e32 v90, s41, v216
	v_fmac_f32_e32 v91, s41, v158
	v_fmac_f32_e32 v92, s41, v217
	v_fmac_f32_e32 v93, s41, v159
	global_store_dwordx4 v[140:141], v[90:93], off offset:64
	s_waitcnt vmcnt(18)
	v_permlane16_swap_b32_e32 v162, v164
	v_permlane16_swap_b32_e32 v163, v165
	v_lshlrev_b32_e32 v216, 16, v162
	v_and_b32_e32 v162, 0xffff0000, v162
	v_lshlrev_b32_e32 v217, 16, v163
	v_and_b32_e32 v163, 0xffff0000, v163
	v_fmac_f32_e32 v58, s41, v216
	v_fmac_f32_e32 v59, s41, v162
	v_fmac_f32_e32 v60, s41, v217
	v_fmac_f32_e32 v61, s41, v163
	global_store_dwordx4 v[140:141], v[58:61], off offset:128
	v_lshlrev_b32_e32 v216, 16, v164
	v_and_b32_e32 v164, 0xffff0000, v164
	v_lshlrev_b32_e32 v217, 16, v165
	v_and_b32_e32 v165, 0xffff0000, v165
	v_fmac_f32_e32 v26, s41, v216
	v_fmac_f32_e32 v27, s41, v164
	v_fmac_f32_e32 v28, s41, v217
	v_fmac_f32_e32 v29, s41, v165
	global_store_dwordx4 v[140:141], v[26:29], off offset:192
	v_lshl_add_u64 v[140:141], v[140:141], 0, s[10:11]
	s_waitcnt vmcnt(19)
	v_permlane16_swap_b32_e32 v166, v168
	v_permlane16_swap_b32_e32 v167, v169
	v_lshlrev_b32_e32 v216, 16, v166
	v_and_b32_e32 v166, 0xffff0000, v166
	v_lshlrev_b32_e32 v217, 16, v167
	v_and_b32_e32 v167, 0xffff0000, v167
	v_fmac_f32_e32 v118, s41, v216
	v_fmac_f32_e32 v119, s41, v166
	v_fmac_f32_e32 v120, s41, v217
	v_fmac_f32_e32 v121, s41, v167
	global_store_dwordx4 v[140:141], v[118:121], off offset:0
	v_lshlrev_b32_e32 v216, 16, v168
	v_and_b32_e32 v168, 0xffff0000, v168
	v_lshlrev_b32_e32 v217, 16, v169
	v_and_b32_e32 v169, 0xffff0000, v169
	v_fmac_f32_e32 v86, s41, v216
	v_fmac_f32_e32 v87, s41, v168
	v_fmac_f32_e32 v88, s41, v217
	v_fmac_f32_e32 v89, s41, v169
	global_store_dwordx4 v[140:141], v[86:89], off offset:64
	s_waitcnt vmcnt(20)
; DEVI float blo(unsigned u) { return __uint_as_float(u << 16); }
; DEVI float bhi(unsigned u) { return __uint_as_float(u & 0xffff0000u); }
;     ...
;         if (EPI == EPI_RESID || EPI == EPI_RESID_ATOMIC) {
;           f32x4 x = a;
;           if (EPI == EPI_RESID || kpart == 0) {
;             const u32x2 xr = *(const u32x2*)((const u16*)(p.ws + WS_XB) + (size_t)row * 1024 + col);
;             x[0] += ALPHA * blo(xr[0]); x[1] += ALPHA * bhi(xr[0]); x[2] += ALPHA * blo(xr[1]); x[3] += ALPHA * bhi(xr[1]);
;           }
;           if (EPI == EPI_RESID) *(f32x4*)((float*)(p.ws + WS_XF) + (size_t)row * 1024 + col) = x;
;           else *(f32x4*)((float*)(p.ws + WS_SLAB) + ((size_t)kpart * 512 + (row - T_P)) * 1024 + col) = x;
	v_permlane16_swap_b32_e32 v170, v172
	v_permlane16_swap_b32_e32 v171, v173
	v_lshlrev_b32_e32 v216, 16, v170
	v_and_b32_e32 v170, 0xffff0000, v170
	v_lshlrev_b32_e32 v217, 16, v171
	v_and_b32_e32 v171, 0xffff0000, v171
	v_fmac_f32_e32 v54, s41, v216
	v_fmac_f32_e32 v55, s41, v170
	v_fmac_f32_e32 v56, s41, v217
	v_fmac_f32_e32 v57, s41, v171
	global_store_dwordx4 v[140:141], v[54:57], off offset:128
	v_lshlrev_b32_e32 v216, 16, v172
	v_and_b32_e32 v172, 0xffff0000, v172
	v_lshlrev_b32_e32 v217, 16, v173
	v_and_b32_e32 v173, 0xffff0000, v173
	v_fmac_f32_e32 v22, s41, v216
	v_fmac_f32_e32 v23, s41, v172
	v_fmac_f32_e32 v24, s41, v217
	v_fmac_f32_e32 v25, s41, v173
	global_store_dwordx4 v[140:141], v[22:25], off offset:192
	v_lshl_add_u64 v[140:141], v[140:141], 0, s[10:11]
	s_waitcnt vmcnt(21)
	v_permlane16_swap_b32_e32 v176, v178
	v_permlane16_swap_b32_e32 v177, v179
	v_lshlrev_b32_e32 v216, 16, v176
	v_and_b32_e32 v176, 0xffff0000, v176
	v_lshlrev_b32_e32 v217, 16, v177
	v_and_b32_e32 v177, 0xffff0000, v177
	v_fmac_f32_e32 v114, s41, v216
	v_fmac_f32_e32 v115, s41, v176
	v_fmac_f32_e32 v116, s41, v217
	v_fmac_f32_e32 v117, s41, v177
	global_store_dwordx4 v[140:141], v[114:117], off offset:0
	v_lshlrev_b32_e32 v216, 16, v178
	v_and_b32_e32 v178, 0xffff0000, v178
	v_lshlrev_b32_e32 v217, 16, v179
	v_and_b32_e32 v179, 0xffff0000, v179
	v_fmac_f32_e32 v82, s41, v216
	v_fmac_f32_e32 v83, s41, v178
	v_fmac_f32_e32 v84, s41, v217
	v_fmac_f32_e32 v85, s41, v179
	global_store_dwordx4 v[140:141], v[82:85], off offset:64
	s_waitcnt vmcnt(22)
	v_permlane16_swap_b32_e32 v180, v182
	v_permlane16_swap_b32_e32 v181, v183
	v_lshlrev_b32_e32 v216, 16, v180
	v_and_b32_e32 v180, 0xffff0000, v180
	v_lshlrev_b32_e32 v217, 16, v181
	v_and_b32_e32 v181, 0xffff0000, v181
	v_fmac_f32_e32 v50, s41, v216
	v_fmac_f32_e32 v51, s41, v180
	v_fmac_f32_e32 v52, s41, v217
	v_fmac_f32_e32 v53, s41, v181
	global_store_dwordx4 v[140:141], v[50:53], off offset:128
	v_lshlrev_b32_e32 v216, 16, v182
	v_and_b32_e32 v182, 0xffff0000, v182
	v_lshlrev_b32_e32 v217, 16, v183
	v_and_b32_e32 v183, 0xffff0000, v183
	v_fmac_f32_e32 v18, s41, v216
	v_fmac_f32_e32 v19, s41, v182
	v_fmac_f32_e32 v20, s41, v217
	v_fmac_f32_e32 v21, s41, v183
	global_store_dwordx4 v[140:141], v[18:21], off offset:192
	v_lshl_add_u64 v[140:141], v[140:141], 0, s[10:11]
	s_waitcnt vmcnt(23)
	v_permlane16_swap_b32_e32 v184, v186
	v_permlane16_swap_b32_e32 v185, v187
	v_lshlrev_b32_e32 v216, 16, v184
	v_and_b32_e32 v184, 0xffff0000, v184
	v_lshlrev_b32_e32 v217, 16, v185
	v_and_b32_e32 v185, 0xffff0000, v185
	v_fmac_f32_e32 v110, s41, v216
	v_fmac_f32_e32 v111, s41, v184
	v_fmac_f32_e32 v112, s41, v217
	v_fmac_f32_e32 v113, s41, v185
	global_store_dwordx4 v[140:141], v[110:113], off offset:0
	v_lshlrev_b32_e32 v216, 16, v186
	v_and_b32_e32 v186, 0xffff0000, v186
	v_lshlrev_b32_e32 v217, 16, v187
	v_and_b32_e32 v187, 0xffff0000, v187
	v_fmac_f32_e32 v78, s41, v216
	v_fmac_f32_e32 v79, s41, v186
	v_fmac_f32_e32 v80, s41, v217
	v_fmac_f32_e32 v81, s41, v187
	global_store_dwordx4 v[140:141], v[78:81], off offset:64
	s_waitcnt vmcnt(24)
	v_permlane16_swap_b32_e32 v188, v190
	v_permlane16_swap_b32_e32 v189, v191
	v_lshlrev_b32_e32 v216, 16, v188
	v_and_b32_e32 v188, 0xffff0000, v188
	v_lshlrev_b32_e32 v217, 16, v189
	v_and_b32_e32 v189, 0xffff0000, v189
	v_fmac_f32_e32 v46, s41, v216
	v_fmac_f32_e32 v47, s41, v188
	v_fmac_f32_e32 v48, s41, v217
	v_fmac_f32_e32 v49, s41, v189
	global_store_dwordx4 v[140:141], v[46:49], off offset:128
	v_lshlrev_b32_e32 v216, 16, v190
	v_and_b32_e32 v190, 0xffff0000, v190
	v_lshlrev_b32_e32 v217, 16, v191
	v_and_b32_e32 v191, 0xffff0000, v191
	v_fmac_f32_e32 v14, s41, v216
	v_fmac_f32_e32 v15, s41, v190
	v_fmac_f32_e32 v16, s41, v217
	v_fmac_f32_e32 v17, s41, v191
	global_store_dwordx4 v[140:141], v[14:17], off offset:192
	v_lshl_add_u64 v[140:141], v[140:141], 0, s[10:11]
	s_waitcnt vmcnt(25)
	v_permlane16_swap_b32_e32 v192, v194
	v_permlane16_swap_b32_e32 v193, v195
	v_lshlrev_b32_e32 v216, 16, v192
	v_and_b32_e32 v192, 0xffff0000, v192
	v_lshlrev_b32_e32 v217, 16, v193
	v_and_b32_e32 v193, 0xffff0000, v193
	v_fmac_f32_e32 v106, s41, v216
	v_fmac_f32_e32 v107, s41, v192
	v_fmac_f32_e32 v108, s41, v217
	v_fmac_f32_e32 v109, s41, v193
	global_store_dwordx4 v[140:141], v[106:109], off offset:0
	v_lshlrev_b32_e32 v216, 16, v194
	v_and_b32_e32 v194, 0xffff0000, v194
	v_lshlrev_b32_e32 v217, 16, v195
	v_and_b32_e32 v195, 0xffff0000, v195
	v_fmac_f32_e32 v74, s41, v216
	v_fmac_f32_e32 v75, s41, v194
	v_fmac_f32_e32 v76, s41, v217
	v_fmac_f32_e32 v77, s41, v195
	global_store_dwordx4 v[140:141], v[74:77], off offset:64
	s_waitcnt vmcnt(26)
; DEVI float blo(unsigned u) { return __uint_as_float(u << 16); }
; DEVI float bhi(unsigned u) { return __uint_as_float(u & 0xffff0000u); }
; DEVI int xcd_first_tile() { return (blockIdx.x & 7) * (gridDim.x >> 3) + (blockIdx.x >> 3); }
;     ...
;         if (EPI == EPI_RESID || EPI == EPI_RESID_ATOMIC) {
;           f32x4 x = a;
;           if (EPI == EPI_RESID || kpart == 0) {
;             const u32x2 xr = *(const u32x2*)((const u16*)(p.ws + WS_XB) + (size_t)row * 1024 + col);
;             x[0] += ALPHA * blo(xr[0]); x[1] += ALPHA * bhi(xr[0]); x[2] += ALPHA * blo(xr[1]); x[3] += ALPHA * bhi(xr[1]);
;           }
;           if (EPI == EPI_RESID) *(f32x4*)((float*)(p.ws + WS_XF) + (size_t)row * 1024 + col) = x;
;           else *(f32x4*)((float*)(p.ws + WS_SLAB) + ((size_t)kpart * 512 + (row - T_P)) * 1024 + col) = x;
; DEVI void run_phase(const Params& p, int ph, char* smem) {
;     ...
;       for (int t = xcd_first_tile(); t < 512 + 16 * 8; t += xcd_tile_step()) {
	v_permlane16_swap_b32_e32 v196, v198
	v_permlane16_swap_b32_e32 v197, v199
	v_lshlrev_b32_e32 v216, 16, v196
	v_and_b32_e32 v196, 0xffff0000, v196
	v_lshlrev_b32_e32 v217, 16, v197
	v_and_b32_e32 v197, 0xffff0000, v197
	v_fmac_f32_e32 v42, s41, v216
	v_fmac_f32_e32 v43, s41, v196
	v_fmac_f32_e32 v44, s41, v217
	v_fmac_f32_e32 v45, s41, v197
	global_store_dwordx4 v[140:141], v[42:45], off offset:128
	v_lshlrev_b32_e32 v216, 16, v198
	v_and_b32_e32 v198, 0xffff0000, v198
	v_lshlrev_b32_e32 v217, 16, v199
	v_and_b32_e32 v199, 0xffff0000, v199
	v_fmac_f32_e32 v10, s41, v216
	v_fmac_f32_e32 v11, s41, v198
	v_fmac_f32_e32 v12, s41, v217
	v_fmac_f32_e32 v13, s41, v199
	global_store_dwordx4 v[140:141], v[10:13], off offset:192
	v_lshl_add_u64 v[140:141], v[140:141], 0, s[10:11]
	s_waitcnt vmcnt(27)
	v_permlane16_swap_b32_e32 v200, v202
	v_permlane16_swap_b32_e32 v201, v203
	v_lshlrev_b32_e32 v216, 16, v200
	v_and_b32_e32 v200, 0xffff0000, v200
	v_lshlrev_b32_e32 v217, 16, v201
	v_and_b32_e32 v201, 0xffff0000, v201
	v_fmac_f32_e32 v102, s41, v216
	v_fmac_f32_e32 v103, s41, v200
	v_fmac_f32_e32 v104, s41, v217
	v_fmac_f32_e32 v105, s41, v201
	global_store_dwordx4 v[140:141], v[102:105], off offset:0
	v_lshlrev_b32_e32 v216, 16, v202
	v_and_b32_e32 v202, 0xffff0000, v202
	v_lshlrev_b32_e32 v217, 16, v203
	v_and_b32_e32 v203, 0xffff0000, v203
	v_fmac_f32_e32 v70, s41, v216
	v_fmac_f32_e32 v71, s41, v202
	v_fmac_f32_e32 v72, s41, v217
	v_fmac_f32_e32 v73, s41, v203
	global_store_dwordx4 v[140:141], v[70:73], off offset:64
	s_waitcnt vmcnt(28)
	v_permlane16_swap_b32_e32 v204, v206
	v_permlane16_swap_b32_e32 v205, v207
	v_lshlrev_b32_e32 v216, 16, v204
	v_and_b32_e32 v204, 0xffff0000, v204
	v_lshlrev_b32_e32 v217, 16, v205
	v_and_b32_e32 v205, 0xffff0000, v205
	v_fmac_f32_e32 v38, s41, v216
	v_fmac_f32_e32 v39, s41, v204
	v_fmac_f32_e32 v40, s41, v217
	v_fmac_f32_e32 v41, s41, v205
	global_store_dwordx4 v[140:141], v[38:41], off offset:128
	v_lshlrev_b32_e32 v216, 16, v206
	v_and_b32_e32 v206, 0xffff0000, v206
	v_lshlrev_b32_e32 v217, 16, v207
	v_and_b32_e32 v207, 0xffff0000, v207
	v_fmac_f32_e32 v6, s41, v216
	v_fmac_f32_e32 v7, s41, v206
	v_fmac_f32_e32 v8, s41, v217
	v_fmac_f32_e32 v9, s41, v207
	global_store_dwordx4 v[140:141], v[6:9], off offset:192
	v_lshl_add_u64 v[140:141], v[140:141], 0, s[10:11]
	s_waitcnt vmcnt(29)
	v_permlane16_swap_b32_e32 v208, v210
	v_permlane16_swap_b32_e32 v209, v211
	v_lshlrev_b32_e32 v216, 16, v208
	v_and_b32_e32 v208, 0xffff0000, v208
	v_lshlrev_b32_e32 v217, 16, v209
	v_and_b32_e32 v209, 0xffff0000, v209
	v_fmac_f32_e32 v98, s41, v216
	v_fmac_f32_e32 v99, s41, v208
	v_fmac_f32_e32 v100, s41, v217
	v_fmac_f32_e32 v101, s41, v209
	global_store_dwordx4 v[140:141], v[98:101], off offset:0
	v_lshlrev_b32_e32 v216, 16, v210
	v_and_b32_e32 v210, 0xffff0000, v210
	v_lshlrev_b32_e32 v217, 16, v211
	v_and_b32_e32 v211, 0xffff0000, v211
	v_fmac_f32_e32 v66, s41, v216
	v_fmac_f32_e32 v67, s41, v210
	v_fmac_f32_e32 v68, s41, v217
	v_fmac_f32_e32 v69, s41, v211
	global_store_dwordx4 v[140:141], v[66:69], off offset:64
	s_waitcnt vmcnt(30)
	v_permlane16_swap_b32_e32 v212, v214
	v_permlane16_swap_b32_e32 v213, v215
	v_lshlrev_b32_e32 v216, 16, v212
	v_and_b32_e32 v212, 0xffff0000, v212
	v_lshlrev_b32_e32 v217, 16, v213
	v_and_b32_e32 v213, 0xffff0000, v213
	v_fmac_f32_e32 v34, s41, v216
	v_fmac_f32_e32 v35, s41, v212
	v_fmac_f32_e32 v36, s41, v217
	v_fmac_f32_e32 v37, s41, v213
	global_store_dwordx4 v[140:141], v[34:37], off offset:128
	v_lshlrev_b32_e32 v216, 16, v214
	v_and_b32_e32 v214, 0xffff0000, v214
	v_lshlrev_b32_e32 v217, 16, v215
	v_and_b32_e32 v215, 0xffff0000, v215
	v_fmac_f32_e32 v2, s41, v216
	v_fmac_f32_e32 v3, s41, v214
	v_fmac_f32_e32 v4, s41, v217
	v_fmac_f32_e32 v5, s41, v215
	global_store_dwordx4 v[140:141], v[2:5], off offset:192
	v_readlane_b32 s0, v250, 7
	s_cmpk_lg_u32 s0, 0x200
	s_cbranch_scc1 .Lta4_ar2
	s_mov_b32 s0, 1
	v_writelane_b32 v255, s0, 41
	v_readlane_b32 s1, v250, 0
	s_lshr_b32 s14, s1, 3
	s_and_b32 s1, s1, 7
	s_lshl_b32 s1, s1, 6
	s_add_i32 s1, s1, s14
	s_sub_i32 s39, s1, 0x200

; #define LAS __attribute__((address_space(3)))
; DEVI int xcd_first_tile() { return (blockIdx.x & 7) * (gridDim.x >> 3) + (blockIdx.x >> 3); }
;     ...
;   const int nk = (nk_part < 0) ? (K >> 5) : nk_part;
;   const int lrow = tid >> 2, lpc = tid & 3;
;   const int lch = lpc ^ ((0x78 >> (((lrow >> 2) & 3) * 2)) & 3);
;   const u16* ga = A + (size_t)(m0 + lrow) * lda + kbeg + lch * 8;
;   const u16* gb = Bt + (size_t)(n0 + lrow) * K + kbeg + lch * 8;
;   const size_t ga1 = (size_t)64 * lda, gb1 = (size_t)64 * K;
;   const unsigned lds0 = (unsigned)(uintptr_t)(LAS char*)smem + (unsigned)__builtin_amdgcn_readfirstlane(wid) * 1024u;
;     ...
;   __syncthreads();
;   G2_STAGE(0); G2_STAGE(1);
; DEVI void run_phase(const Params& p, int ph, char* smem) {
;     ...
;       for (int t = xcd_first_tile(); t < 512 + 16 * 8; t += xcd_tile_step()) {
;         if (t < 512) {
;           int mt_, nt_; tile_coords(t, 64, 8, mt_, nt_);
;           gemm_tile256<EPI_RESID>(p, mix, 1024, Bt, 1024, mt_ * 256, nt_ * 128, nullptr, 0, smem);
.LBB0_812:
	s_and_b64 vcc, exec, s[2:3]
	s_cbranch_vccz .LBB0_757
	v_readlane_b32 s40, v250, 7
	s_cmpk_lg_u32 s40, 0x200
	s_cbranch_scc1 .Lt4_go
	v_readlane_b32 s41, v255, 41
	s_cmp_lg_u32 s41, 0
	s_cbranch_scc1 .Lt4_go
	v_readlane_b32 s41, v250, 0
	s_lshr_b32 s42, s41, 3
	s_cmp_lt_u32 s42, 16
	s_cbranch_scc0 .Lt4_go
	s_and_b32 s41, s41, 7
	s_mul_i32 s41, s41, 16
	s_add_i32 s39, s41, s42
	s_branch .LBB0_757
.Lt4_go:
	s_lshr_b32 s46, s39, 6
	s_and_b32 s47, s39, 63
	s_lshr_b32 s43, s47, 3
	s_and_b32 s47, s47, 7
	s_lshl_b32 s46, s46, 3
	s_add_i32 s46, s46, s47
	v_readlane_b32 s2, v250, 5
	v_readlane_b32 s3, v250, 6
	v_readlane_b32 s47, v254, 62
	s_mul_i32 s41, s46, 0x80000
	s_add_u32 s4, s2, s41
	s_addc_u32 s5, s3, 0
	s_add_u32 s4, s4, 0xb580000
	s_addc_u32 s5, s5, 0
	s_mul_i32 s41, s47, 0x200000
	s_mul_i32 s42, s43, 0x40000
	s_add_i32 s41, s41, s42
	s_add_u32 s10, s2, s41
	s_addc_u32 s11, s3, 0
	s_add_u32 s10, s10, 0x15e00000
	s_addc_u32 s11, s11, 0
	s_movk_i32 s40, 0x78
	v_lshrrev_b32_e32 v0, 2, v145
	v_and_b32_e32 v131, 3, v145
	v_bfe_u32 v136, v145, 4, 2
	v_lshlrev_b32_e32 v136, 1, v136
	v_lshrrev_b32_e64 v136, v136, s40
	v_and_b32_e32 v136, 3, v136
	v_xor_b32_e32 v131, v131, v136
	v_lshlrev_b32_e32 v131, 4, v131
	s_movk_i32 s42, 0x800
	v_mad_u32_u24 v0, v0, s42, v131
	v_bfe_u32 v137, v145, 2, 1
	s_movk_i32 s42, 0x7c0
	v_mul_u32_u24_e32 v136, s42, v137
	v_sub_u32_e32 v136, v0, v136
	v_mov_b32_e32 v137, 0
	v_lshl_add_u64 v[134:135], s[10:11], 0, v[136:137]
	v_bfe_u32 v137, v145, 2, 1
	s_mov_b32 s12, 64
	s_mov_b32 s13, 0
	v_lshl_add_u64 v[132:133], s[4:5], 0, v[0:1]
	v_bfe_u32 v136, v145, 2, 2
	v_lshlrev_b32_e32 v136, 1, v136
	v_lshrrev_b32_e64 v136, v136, s40
	v_and_b32_e32 v136, 3, v136
	v_bfe_u32 v137, v145, 4, 2
	v_xor_b32_e32 v136, v136, v137
	v_lshlrev_b32_e32 v136, 4, v136
	v_and_b32_e32 v131, 15, v145
	v_lshl_or_b32 v136, v131, 6, v136
	v_bfe_u32 v137, v145, 6, 1
	v_lshl_or_b32 v137, v137, 12, v136
	v_lshrrev_b32_e32 v0, 7, v145
	v_lshl_or_b32 v136, v0, 13, v136
	v_and_b32_e32 v140, 1, v131
	v_lshl_or_b32 v131, v0, 7, v131
	v_bfe_u32 v0, v145, 4, 2
	v_lshlrev_b32_e32 v0, 3, v0
	v_bfe_u32 v141, v145, 6, 1
	s_lshl_b32 s41, s46, 19
	s_lshl_b32 s42, s43, 9
	s_add_i32 s41, s41, s42
	s_add_u32 s4, s2, s41
	s_addc_u32 s5, s3, 0
	s_add_u32 s4, s4, 0x4200000
	s_addc_u32 s5, s5, 0
	v_lshlrev_b32_e32 v138, 11, v131
	v_lshl_add_u32 v138, v141, 8, v138
	v_bfe_u32 v139, v145, 4, 1
	v_lshl_add_u32 v138, v139, 5, v138
	v_bfe_u32 v139, v145, 5, 1
	v_lshl_add_u32 v138, v139, 4, v138
	s_movk_i32 s42, 1984
	v_mul_u32_u24_e32 v139, s42, v140
	v_sub_u32_e32 v138, v138, v139
	v_mov_b32_e32 v139, 0
	v_lshl_add_u64 v[138:139], s[4:5], 0, v[138:139]
	s_lshl_b32 s41, s46, 20
	s_lshl_b32 s42, s43, 9
	s_add_i32 s41, s41, s42
	s_add_u32 s10, s2, s41
	s_addc_u32 s11, s3, 0
	v_lshlrev_b32_e32 v140, 12, v131
	v_lshl_add_u32 v140, v141, 8, v140
	v_lshl_add_u32 v140, v0, 1, v140
	v_mov_b32_e32 v141, 0
	v_lshl_add_u64 v[140:141], s[10:11], 0, v[140:141]
	s_mov_b32 s2, 0x20000
	s_mov_b32 s3, 0
	v_lshrrev_b32_e32 v0, 6, v145
	v_lshlrev_b32_e32 v0, 10, v0
	s_nop 0
	v_readfirstlane_b32 s47, v0
	s_mov_b32 s44, m0
	s_mov_b32 s4, 128
	s_mov_b32 s5, 0
	s_barrier
	s_add_i32 s43, s47, 0x0
	s_mov_b32 m0, s43
	v_lshl_add_u64 v[142:143], v[132:133], 0, s[2:3]
	global_load_lds_dwordx4 v[132:133], off
	s_add_i32 m0, m0, 0x1000
	s_nop 0
	global_load_lds_dwordx4 v[142:143], off
	v_lshl_add_u64 v[142:143], v[142:143], 0, s[2:3]
	s_add_i32 m0, m0, 0x1000
	s_nop 0
	global_load_lds_dwordx4 v[142:143], off
	v_lshl_add_u64 v[142:143], v[142:143], 0, s[2:3]
	s_add_i32 m0, m0, 0x1000
	s_nop 0
	global_load_lds_dwordx4 v[142:143], off
	s_add_i32 m0, m0, 0x1000
	v_lshl_add_u64 v[142:143], v[134:135], 0, s[2:3]
	s_nop 0
	global_load_lds_dwordx4 v[134:135], off
	s_add_i32 m0, m0, 0x1000
	v_lshl_add_u64 v[132:133], v[132:133], 0, s[12:13]
	s_nop 0
	global_load_lds_dwordx4 v[142:143], off
	v_lshl_add_u64 v[134:135], v[134:135], 0, s[4:5]
	s_nop 0
	s_add_i32 s43, s47, 0x6000
	s_mov_b32 m0, s43
	v_lshl_add_u64 v[142:143], v[132:133], 0, s[2:3]
	global_load_lds_dwordx4 v[132:133], off
	s_add_i32 m0, m0, 0x1000
	s_nop 0
	global_load_lds_dwordx4 v[142:143], off
	v_lshl_add_u64 v[142:143], v[142:143], 0, s[2:3]
	s_add_i32 m0, m0, 0x1000
	s_nop 0
	global_load_lds_dwordx4 v[142:143], off
	v_lshl_add_u64 v[142:143], v[142:143], 0, s[2:3]
	s_add_i32 m0, m0, 0x1000
	s_nop 0
	global_load_lds_dwordx4 v[142:143], off
	s_add_i32 m0, m0, 0x1000
	v_lshl_add_u64 v[142:143], v[134:135], 0, s[2:3]
	s_nop 0
	global_load_lds_dwordx4 v[134:135], off
	s_add_i32 m0, m0, 0x1000
	v_lshl_add_u64 v[132:133], v[132:133], 0, s[12:13]
	s_nop 0
	global_load_lds_dwordx4 v[142:143], off
	v_lshl_add_u64 v[134:135], v[134:135], 0, s[4:5]
	s_nop 0
	s_add_i32 s43, s47, 0xc000
	s_mov_b32 m0, s43
	v_lshl_add_u64 v[142:143], v[132:133], 0, s[2:3]
	global_load_lds_dwordx4 v[132:133], off
	s_add_i32 m0, m0, 0x1000
	s_nop 0
	global_load_lds_dwordx4 v[142:143], off
	v_lshl_add_u64 v[142:143], v[142:143], 0, s[2:3]
	s_add_i32 m0, m0, 0x1000
	s_nop 0
	global_load_lds_dwordx4 v[142:143], off
	v_lshl_add_u64 v[142:143], v[142:143], 0, s[2:3]
	s_add_i32 m0, m0, 0x1000
	s_nop 0
	global_load_lds_dwordx4 v[142:143], off
	s_add_i32 m0, m0, 0x1000
	v_lshl_add_u64 v[142:143], v[134:135], 0, s[2:3]
	s_nop 0
	global_load_lds_dwordx4 v[134:135], off
	s_add_i32 m0, m0, 0x1000
	v_lshl_add_u64 v[132:133], v[132:133], 0, s[12:13]
	s_nop 0
	global_load_lds_dwordx4 v[142:143], off
	v_lshl_add_u64 v[134:135], v[134:135], 0, s[4:5]
	s_nop 0
	v_mov_b32_e32 v2, 0
	v_mov_b32_e32 v3, 0
	v_mov_b32_e32 v4, 0
	v_mov_b32_e32 v5, 0
	v_mov_b32_e32 v6, 0
	v_mov_b32_e32 v7, 0
; #define LAS __attribute__((address_space(3)))
;     ...
;   f32x4 acc[4][8];
; #pragma unroll
;   for (int i = 0; i < 4; i++)
; #pragma unroll
;     for (int j = 0; j < 8; j++) acc[i][j] = (f32x4){0.f, 0.f, 0.f, 0.f};
;   const int nk = (nk_part < 0) ? (K >> 5) : nk_part;
;   const int lrow = tid >> 2, lpc = tid & 3;
;   const int lch = lpc ^ ((0x78 >> (((lrow >> 2) & 3) * 2)) & 3);
;   const u16* ga = A + (size_t)(m0 + lrow) * lda + kbeg + lch * 8;
;   const u16* gb = Bt + (size_t)(n0 + lrow) * K + kbeg + lch * 8;
;   const size_t ga1 = (size_t)64 * lda, gb1 = (size_t)64 * K;
;   const unsigned lds0 = (unsigned)(uintptr_t)(LAS char*)smem + (unsigned)__builtin_amdgcn_readfirstlane(wid) * 1024u;
;     ...
;   __syncthreads();
;   G2_STAGE(0); G2_STAGE(1);
;   const int fsw = (0x78 >> (((r16 >> 2) & 3) * 2)) & 3;
;   const int aoff = (wm * 128 + r16) * 64 + ((quad ^ fsw) << 4);
;   const int boff = 16384 + (wn * 64 + r16) * 64 + ((quad ^ fsw) << 4);
;   for (int kt = 0; kt < nk; kt++) {
;     if (kt + 1 < nk) asm volatile("s_waitcnt vmcnt(6)" ::: "memory");
;     else asm volatile("s_waitcnt vmcnt(0)" ::: "memory");
;     __builtin_amdgcn_s_barrier();
;     asm volatile("" ::: "memory");
;     if (kt + 2 < nk) G2_STAGE(kt + 2);
;     const char* cS = smem + (kt % 3) * 24576;
;     bf16x8 xa[8], wb[4];
; #pragma unroll
;     for (int f = 0; f < 8; f++) xa[f] = *(const bf16x8*)(cS + aoff + f * 1024);
; #pragma unroll
;     for (int f = 0; f < 4; f++) wb[f] = *(const bf16x8*)(cS + boff + f * 1024);
; #pragma unroll
;     for (int nf = 0; nf < 4; nf++)
; #pragma unroll
;       for (int mf = 0; mf < 8; mf++)
;         acc[nf][mf] = __builtin_amdgcn_mfma_f32_16x16x32_bf16(wb[nf], xa[mf], acc[nf][mf], 0, 0, 0);
	v_mov_b32_e32 v8, 0
	v_mov_b32_e32 v9, 0
	v_mov_b32_e32 v10, 0
	v_mov_b32_e32 v11, 0
	v_mov_b32_e32 v12, 0
	v_mov_b32_e32 v13, 0
	v_mov_b32_e32 v14, 0
	v_mov_b32_e32 v15, 0
	v_mov_b32_e32 v16, 0
	v_mov_b32_e32 v17, 0
	v_mov_b32_e32 v18, 0
	v_mov_b32_e32 v19, 0
	v_mov_b32_e32 v20, 0
	v_mov_b32_e32 v21, 0
	v_mov_b32_e32 v22, 0
	v_mov_b32_e32 v23, 0
	v_mov_b32_e32 v24, 0
	v_mov_b32_e32 v25, 0
	v_mov_b32_e32 v26, 0
	v_mov_b32_e32 v27, 0
	v_mov_b32_e32 v28, 0
	v_mov_b32_e32 v29, 0
	v_mov_b32_e32 v30, 0
	v_mov_b32_e32 v31, 0
	v_mov_b32_e32 v32, 0
	v_mov_b32_e32 v33, 0
	v_mov_b32_e32 v34, 0
	v_mov_b32_e32 v35, 0
	v_mov_b32_e32 v36, 0
	v_mov_b32_e32 v37, 0
	v_mov_b32_e32 v38, 0
	v_mov_b32_e32 v39, 0
	v_mov_b32_e32 v40, 0
	v_mov_b32_e32 v41, 0
	v_mov_b32_e32 v42, 0
	v_mov_b32_e32 v43, 0
	v_mov_b32_e32 v44, 0
	v_mov_b32_e32 v45, 0
	v_mov_b32_e32 v46, 0
	v_mov_b32_e32 v47, 0
	v_mov_b32_e32 v48, 0
	v_mov_b32_e32 v49, 0
	v_mov_b32_e32 v50, 0
	v_mov_b32_e32 v51, 0
	v_mov_b32_e32 v52, 0
	v_mov_b32_e32 v53, 0
	v_mov_b32_e32 v54, 0
	v_mov_b32_e32 v55, 0
	v_mov_b32_e32 v56, 0
	v_mov_b32_e32 v57, 0
	v_mov_b32_e32 v58, 0
	v_mov_b32_e32 v59, 0
	v_mov_b32_e32 v60, 0
	v_mov_b32_e32 v61, 0
	v_mov_b32_e32 v62, 0
	v_mov_b32_e32 v63, 0
	v_mov_b32_e32 v64, 0
	v_mov_b32_e32 v65, 0
	v_mov_b32_e32 v66, 0
	v_mov_b32_e32 v67, 0
	v_mov_b32_e32 v68, 0
	v_mov_b32_e32 v69, 0
	v_mov_b32_e32 v70, 0
	v_mov_b32_e32 v71, 0
	v_mov_b32_e32 v72, 0
	v_mov_b32_e32 v73, 0
	v_mov_b32_e32 v74, 0
	v_mov_b32_e32 v75, 0
	v_mov_b32_e32 v76, 0
	v_mov_b32_e32 v77, 0
	v_mov_b32_e32 v78, 0
	v_mov_b32_e32 v79, 0
	v_mov_b32_e32 v80, 0
	v_mov_b32_e32 v81, 0
	v_mov_b32_e32 v82, 0
	v_mov_b32_e32 v83, 0
	v_mov_b32_e32 v84, 0
	v_mov_b32_e32 v85, 0
	v_mov_b32_e32 v86, 0
	v_mov_b32_e32 v87, 0
	v_mov_b32_e32 v88, 0
	v_mov_b32_e32 v89, 0
	v_mov_b32_e32 v90, 0
	v_mov_b32_e32 v91, 0
	v_mov_b32_e32 v92, 0
	v_mov_b32_e32 v93, 0
	v_mov_b32_e32 v94, 0
	v_mov_b32_e32 v95, 0
	v_mov_b32_e32 v96, 0
	v_mov_b32_e32 v97, 0
	v_mov_b32_e32 v98, 0
	v_mov_b32_e32 v99, 0
	v_mov_b32_e32 v100, 0
	v_mov_b32_e32 v101, 0
	v_mov_b32_e32 v102, 0
	v_mov_b32_e32 v103, 0
	v_mov_b32_e32 v104, 0
	v_mov_b32_e32 v105, 0
	v_mov_b32_e32 v106, 0
	v_mov_b32_e32 v107, 0
	v_mov_b32_e32 v108, 0
	v_mov_b32_e32 v109, 0
	v_mov_b32_e32 v110, 0
	v_mov_b32_e32 v111, 0
	v_mov_b32_e32 v112, 0
	v_mov_b32_e32 v113, 0
	v_mov_b32_e32 v114, 0
	v_mov_b32_e32 v115, 0
	v_mov_b32_e32 v116, 0
	v_mov_b32_e32 v117, 0
	v_mov_b32_e32 v118, 0
	v_mov_b32_e32 v119, 0
	v_mov_b32_e32 v120, 0
	v_mov_b32_e32 v121, 0
	v_mov_b32_e32 v122, 0
	v_mov_b32_e32 v123, 0
	v_mov_b32_e32 v124, 0
	v_mov_b32_e32 v125, 0
	v_mov_b32_e32 v126, 0
	v_mov_b32_e32 v127, 0
	v_mov_b32_e32 v128, 0
	v_mov_b32_e32 v129, 0
	s_waitcnt vmcnt(12)
	s_barrier
	ds_read_b128 v[146:149], v136 offset:0
	ds_read_b128 v[152:155], v136 offset:1024
	ds_read_b128 v[156:159], v136 offset:2048
	ds_read_b128 v[162:165], v136 offset:3072
	ds_read_b128 v[166:169], v136 offset:4096
	ds_read_b128 v[170:173], v136 offset:5120
	ds_read_b128 v[176:179], v136 offset:6144
	ds_read_b128 v[180:183], v136 offset:7168
	ds_read_b128 v[184:187], v137 offset:16384
	ds_read_b128 v[188:191], v137 offset:17408
	ds_read_b128 v[192:195], v137 offset:18432
	ds_read_b128 v[196:199], v137 offset:19456
	s_movk_i32 s41, 0x6000
	s_mov_b32 s42, 0
	s_movk_i32 s40, 14
	.p2align 6
.Lt4_loop:
	.p2align 3
	s_waitcnt vmcnt(6) lgkmcnt(0)
	s_barrier
	s_setprio 1
	v_add_u32_e32 v144, s41, v136
	v_mfma_f32_16x16x32_bf16 v[126:129], v[184:187], v[146:149], v[126:129]
	ds_read_b128 v[200:203], v144 offset:0
	v_mfma_f32_16x16x32_bf16 v[122:125], v[184:187], v[152:155], v[122:125]
	ds_read_b128 v[204:207], v144 offset:1024
	v_mfma_f32_16x16x32_bf16 v[118:121], v[184:187], v[156:159], v[118:121]
	ds_read_b128 v[208:211], v144 offset:2048
	v_mfma_f32_16x16x32_bf16 v[114:117], v[184:187], v[162:165], v[114:117]
	ds_read_b128 v[212:215], v144 offset:3072
	v_mfma_f32_16x16x32_bf16 v[110:113], v[184:187], v[166:169], v[110:113]
	ds_read_b128 v[216:219], v144 offset:4096
	v_mfma_f32_16x16x32_bf16 v[106:109], v[184:187], v[170:173], v[106:109]
	ds_read_b128 v[220:223], v144 offset:5120
	v_mfma_f32_16x16x32_bf16 v[102:105], v[184:187], v[176:179], v[102:105]
	ds_read_b128 v[224:227], v144 offset:6144
	v_mfma_f32_16x16x32_bf16 v[98:101], v[184:187], v[180:183], v[98:101]
	ds_read_b128 v[228:231], v144 offset:7168
	v_mfma_f32_16x16x32_bf16 v[94:97], v[188:191], v[146:149], v[94:97]
	v_add_u32_e64 v144, s41, v137
	v_mfma_f32_16x16x32_bf16 v[90:93], v[188:191], v[152:155], v[90:93]
	v_mfma_f32_16x16x32_bf16 v[86:89], v[188:191], v[156:159], v[86:89]
	ds_read_b128 v[232:235], v144 offset:16384
	v_mfma_f32_16x16x32_bf16 v[82:85], v[188:191], v[162:165], v[82:85]
	ds_read_b128 v[236:239], v144 offset:17408
	v_mfma_f32_16x16x32_bf16 v[78:81], v[188:191], v[166:169], v[78:81]
	ds_read_b128 v[240:243], v144 offset:18432
	v_mfma_f32_16x16x32_bf16 v[74:77], v[188:191], v[170:173], v[74:77]
	ds_read_b128 v[244:247], v144 offset:19456
	v_mfma_f32_16x16x32_bf16 v[70:73], v[188:191], v[176:179], v[70:73]
	s_add_i32 s43, s47, s42
	s_mov_b32 m0, s43
	v_lshl_add_u64 v[142:143], v[132:133], 0, s[2:3]
	v_mfma_f32_16x16x32_bf16 v[66:69], v[188:191], v[180:183], v[66:69]
	global_load_lds_dwordx4 v[132:133], off
	s_add_i32 m0, m0, 0x1000
	v_mfma_f32_16x16x32_bf16 v[62:65], v[192:195], v[146:149], v[62:65]
	v_mfma_f32_16x16x32_bf16 v[58:61], v[192:195], v[152:155], v[58:61]
	v_mfma_f32_16x16x32_bf16 v[54:57], v[192:195], v[156:159], v[54:57]
	global_load_lds_dwordx4 v[142:143], off
	v_lshl_add_u64 v[142:143], v[142:143], 0, s[2:3]
	s_add_i32 m0, m0, 0x1000
;     ...
;   for (int kt = 0; kt < nk; kt++) {
;     if (kt + 1 < nk) asm volatile("s_waitcnt vmcnt(6)" ::: "memory");
;     else asm volatile("s_waitcnt vmcnt(0)" ::: "memory");
;     __builtin_amdgcn_s_barrier();
;     asm volatile("" ::: "memory");
;     if (kt + 2 < nk) G2_STAGE(kt + 2);
;     const char* cS = smem + (kt % 3) * 24576;
;     bf16x8 xa[8], wb[4];
; #pragma unroll
;     for (int f = 0; f < 8; f++) xa[f] = *(const bf16x8*)(cS + aoff + f * 1024);
; #pragma unroll
;     for (int f = 0; f < 4; f++) wb[f] = *(const bf16x8*)(cS + boff + f * 1024);
; #pragma unroll
;     for (int nf = 0; nf < 4; nf++)
; #pragma unroll
;       for (int mf = 0; mf < 8; mf++)
;         acc[nf][mf] = __builtin_amdgcn_mfma_f32_16x16x32_bf16(wb[nf], xa[mf], acc[nf][mf], 0, 0, 0);
	v_mfma_f32_16x16x32_bf16 v[50:53], v[192:195], v[162:165], v[50:53]
	v_mfma_f32_16x16x32_bf16 v[46:49], v[192:195], v[166:169], v[46:49]
	v_mfma_f32_16x16x32_bf16 v[42:45], v[192:195], v[170:173], v[42:45]
	global_load_lds_dwordx4 v[142:143], off
	v_lshl_add_u64 v[142:143], v[142:143], 0, s[2:3]
	s_add_i32 m0, m0, 0x1000
	v_mfma_f32_16x16x32_bf16 v[38:41], v[192:195], v[176:179], v[38:41]
	v_mfma_f32_16x16x32_bf16 v[34:37], v[192:195], v[180:183], v[34:37]
	v_mfma_f32_16x16x32_bf16 v[30:33], v[196:199], v[146:149], v[30:33]
	global_load_lds_dwordx4 v[142:143], off
	s_add_i32 m0, m0, 0x1000
	v_lshl_add_u64 v[142:143], v[134:135], 0, s[2:3]
	v_mfma_f32_16x16x32_bf16 v[26:29], v[196:199], v[152:155], v[26:29]
	v_mfma_f32_16x16x32_bf16 v[22:25], v[196:199], v[156:159], v[22:25]
	v_mfma_f32_16x16x32_bf16 v[18:21], v[196:199], v[162:165], v[18:21]
	global_load_lds_dwordx4 v[134:135], off
	s_add_i32 m0, m0, 0x1000
	v_lshl_add_u64 v[132:133], v[132:133], 0, s[12:13]
	v_mfma_f32_16x16x32_bf16 v[14:17], v[196:199], v[166:169], v[14:17]
	v_mfma_f32_16x16x32_bf16 v[10:13], v[196:199], v[170:173], v[10:13]
	v_mfma_f32_16x16x32_bf16 v[6:9], v[196:199], v[176:179], v[6:9]
	global_load_lds_dwordx4 v[142:143], off
	v_lshl_add_u64 v[134:135], v[134:135], 0, s[4:5]
	v_mfma_f32_16x16x32_bf16 v[2:5], v[196:199], v[180:183], v[2:5]
	s_setprio 0
	s_mov_b32 s42, s41
	s_add_i32 s41, s41, 0x6000
	s_cmp_eq_u32 s41, 0x12000
	s_cselect_b32 s41, 0, s41
	s_nop 0
	.p2align 3
	s_waitcnt vmcnt(6) lgkmcnt(0)
	s_barrier
	s_setprio 1
	v_add_u32_e32 v144, s41, v136
	v_mfma_f32_16x16x32_bf16 v[126:129], v[232:235], v[200:203], v[126:129]
	ds_read_b128 v[146:149], v144 offset:0
	v_mfma_f32_16x16x32_bf16 v[122:125], v[232:235], v[204:207], v[122:125]
	ds_read_b128 v[152:155], v144 offset:1024
	v_mfma_f32_16x16x32_bf16 v[118:121], v[232:235], v[208:211], v[118:121]
	ds_read_b128 v[156:159], v144 offset:2048
	v_mfma_f32_16x16x32_bf16 v[114:117], v[232:235], v[212:215], v[114:117]
	ds_read_b128 v[162:165], v144 offset:3072
	v_mfma_f32_16x16x32_bf16 v[110:113], v[232:235], v[216:219], v[110:113]
	ds_read_b128 v[166:169], v144 offset:4096
	v_mfma_f32_16x16x32_bf16 v[106:109], v[232:235], v[220:223], v[106:109]
	ds_read_b128 v[170:173], v144 offset:5120
	v_mfma_f32_16x16x32_bf16 v[102:105], v[232:235], v[224:227], v[102:105]
	ds_read_b128 v[176:179], v144 offset:6144
	v_mfma_f32_16x16x32_bf16 v[98:101], v[232:235], v[228:231], v[98:101]
	ds_read_b128 v[180:183], v144 offset:7168
	v_mfma_f32_16x16x32_bf16 v[94:97], v[236:239], v[200:203], v[94:97]
	v_add_u32_e64 v144, s41, v137
	v_mfma_f32_16x16x32_bf16 v[90:93], v[236:239], v[204:207], v[90:93]
	v_mfma_f32_16x16x32_bf16 v[86:89], v[236:239], v[208:211], v[86:89]
	ds_read_b128 v[184:187], v144 offset:16384
	v_mfma_f32_16x16x32_bf16 v[82:85], v[236:239], v[212:215], v[82:85]
	ds_read_b128 v[188:191], v144 offset:17408
	v_mfma_f32_16x16x32_bf16 v[78:81], v[236:239], v[216:219], v[78:81]
	ds_read_b128 v[192:195], v144 offset:18432
	v_mfma_f32_16x16x32_bf16 v[74:77], v[236:239], v[220:223], v[74:77]
	ds_read_b128 v[196:199], v144 offset:19456
	v_mfma_f32_16x16x32_bf16 v[70:73], v[236:239], v[224:227], v[70:73]
	s_add_i32 s43, s47, s42
	s_mov_b32 m0, s43
	v_lshl_add_u64 v[142:143], v[132:133], 0, s[2:3]
	v_mfma_f32_16x16x32_bf16 v[66:69], v[236:239], v[228:231], v[66:69]
	global_load_lds_dwordx4 v[132:133], off
	s_add_i32 m0, m0, 0x1000
	v_mfma_f32_16x16x32_bf16 v[62:65], v[240:243], v[200:203], v[62:65]
	v_mfma_f32_16x16x32_bf16 v[58:61], v[240:243], v[204:207], v[58:61]
	v_mfma_f32_16x16x32_bf16 v[54:57], v[240:243], v[208:211], v[54:57]
	global_load_lds_dwordx4 v[142:143], off
	v_lshl_add_u64 v[142:143], v[142:143], 0, s[2:3]
	s_add_i32 m0, m0, 0x1000
	v_mfma_f32_16x16x32_bf16 v[50:53], v[240:243], v[212:215], v[50:53]
	v_mfma_f32_16x16x32_bf16 v[46:49], v[240:243], v[216:219], v[46:49]
	v_mfma_f32_16x16x32_bf16 v[42:45], v[240:243], v[220:223], v[42:45]
	global_load_lds_dwordx4 v[142:143], off
	v_lshl_add_u64 v[142:143], v[142:143], 0, s[2:3]
	s_add_i32 m0, m0, 0x1000
	v_mfma_f32_16x16x32_bf16 v[38:41], v[240:243], v[224:227], v[38:41]
	v_mfma_f32_16x16x32_bf16 v[34:37], v[240:243], v[228:231], v[34:37]
	v_mfma_f32_16x16x32_bf16 v[30:33], v[244:247], v[200:203], v[30:33]
	global_load_lds_dwordx4 v[142:143], off
	s_add_i32 m0, m0, 0x1000
	v_lshl_add_u64 v[142:143], v[134:135], 0, s[2:3]
	v_mfma_f32_16x16x32_bf16 v[26:29], v[244:247], v[204:207], v[26:29]
	v_mfma_f32_16x16x32_bf16 v[22:25], v[244:247], v[208:211], v[22:25]
	v_mfma_f32_16x16x32_bf16 v[18:21], v[244:247], v[212:215], v[18:21]
	global_load_lds_dwordx4 v[134:135], off
	s_add_i32 m0, m0, 0x1000
	v_lshl_add_u64 v[132:133], v[132:133], 0, s[12:13]
	v_mfma_f32_16x16x32_bf16 v[14:17], v[244:247], v[216:219], v[14:17]
	v_mfma_f32_16x16x32_bf16 v[10:13], v[244:247], v[220:223], v[10:13]
	v_mfma_f32_16x16x32_bf16 v[6:9], v[244:247], v[224:227], v[6:9]
	global_load_lds_dwordx4 v[142:143], off
	v_lshl_add_u64 v[134:135], v[134:135], 0, s[4:5]
	v_mfma_f32_16x16x32_bf16 v[2:5], v[244:247], v[228:231], v[2:5]
	s_setprio 0
	s_mov_b32 s42, s41
	s_add_i32 s41, s41, 0x6000
	s_cmp_eq_u32 s41, 0x12000
	s_cselect_b32 s41, 0, s41
	s_nop 0
	s_sub_i32 s40, s40, 1
	s_cmp_lg_u32 s40, 0
	s_cbranch_scc1 .Lt4_loop
	.p2align 3
	s_waitcnt vmcnt(6) lgkmcnt(0)
	s_barrier
;     ...
;   for (int kt = 0; kt < nk; kt++) {
;     if (kt + 1 < nk) asm volatile("s_waitcnt vmcnt(6)" ::: "memory");
;     else asm volatile("s_waitcnt vmcnt(0)" ::: "memory");
;     __builtin_amdgcn_s_barrier();
;     asm volatile("" ::: "memory");
;     if (kt + 2 < nk) G2_STAGE(kt + 2);
;     const char* cS = smem + (kt % 3) * 24576;
;     bf16x8 xa[8], wb[4];
; #pragma unroll
;     for (int f = 0; f < 8; f++) xa[f] = *(const bf16x8*)(cS + aoff + f * 1024);
; #pragma unroll
;     for (int f = 0; f < 4; f++) wb[f] = *(const bf16x8*)(cS + boff + f * 1024);
; #pragma unroll
;     for (int nf = 0; nf < 4; nf++)
; #pragma unroll
;       for (int mf = 0; mf < 8; mf++)
;         acc[nf][mf] = __builtin_amdgcn_mfma_f32_16x16x32_bf16(wb[nf], xa[mf], acc[nf][mf], 0, 0, 0);
	s_setprio 1
	v_add_u32_e32 v144, s41, v136
	v_mfma_f32_16x16x32_bf16 v[126:129], v[184:187], v[146:149], v[126:129]
	ds_read_b128 v[200:203], v144 offset:0
	v_mfma_f32_16x16x32_bf16 v[122:125], v[184:187], v[152:155], v[122:125]
	ds_read_b128 v[204:207], v144 offset:1024
	v_mfma_f32_16x16x32_bf16 v[118:121], v[184:187], v[156:159], v[118:121]
	ds_read_b128 v[208:211], v144 offset:2048
	v_mfma_f32_16x16x32_bf16 v[114:117], v[184:187], v[162:165], v[114:117]
	ds_read_b128 v[212:215], v144 offset:3072
	v_mfma_f32_16x16x32_bf16 v[110:113], v[184:187], v[166:169], v[110:113]
	ds_read_b128 v[216:219], v144 offset:4096
	v_mfma_f32_16x16x32_bf16 v[106:109], v[184:187], v[170:173], v[106:109]
	ds_read_b128 v[220:223], v144 offset:5120
	v_mfma_f32_16x16x32_bf16 v[102:105], v[184:187], v[176:179], v[102:105]
	ds_read_b128 v[224:227], v144 offset:6144
	v_mfma_f32_16x16x32_bf16 v[98:101], v[184:187], v[180:183], v[98:101]
	ds_read_b128 v[228:231], v144 offset:7168
	v_mfma_f32_16x16x32_bf16 v[94:97], v[188:191], v[146:149], v[94:97]
	v_add_u32_e64 v144, s41, v137
	v_mfma_f32_16x16x32_bf16 v[90:93], v[188:191], v[152:155], v[90:93]
	v_mfma_f32_16x16x32_bf16 v[86:89], v[188:191], v[156:159], v[86:89]
	ds_read_b128 v[232:235], v144 offset:16384
	v_mfma_f32_16x16x32_bf16 v[82:85], v[188:191], v[162:165], v[82:85]
	ds_read_b128 v[236:239], v144 offset:17408
	v_mfma_f32_16x16x32_bf16 v[78:81], v[188:191], v[166:169], v[78:81]
	ds_read_b128 v[240:243], v144 offset:18432
	v_mfma_f32_16x16x32_bf16 v[74:77], v[188:191], v[170:173], v[74:77]
	ds_read_b128 v[244:247], v144 offset:19456
	v_mfma_f32_16x16x32_bf16 v[70:73], v[188:191], v[176:179], v[70:73]
	s_add_i32 s43, s47, s42
	s_mov_b32 m0, s43
	v_lshl_add_u64 v[142:143], v[132:133], 0, s[2:3]
	v_mfma_f32_16x16x32_bf16 v[66:69], v[188:191], v[180:183], v[66:69]
	global_load_lds_dwordx4 v[132:133], off
	s_add_i32 m0, m0, 0x1000
	v_mfma_f32_16x16x32_bf16 v[62:65], v[192:195], v[146:149], v[62:65]
	v_mfma_f32_16x16x32_bf16 v[58:61], v[192:195], v[152:155], v[58:61]
	v_mfma_f32_16x16x32_bf16 v[54:57], v[192:195], v[156:159], v[54:57]
	global_load_lds_dwordx4 v[142:143], off
	v_lshl_add_u64 v[142:143], v[142:143], 0, s[2:3]
	s_add_i32 m0, m0, 0x1000
	v_mfma_f32_16x16x32_bf16 v[50:53], v[192:195], v[162:165], v[50:53]
	v_mfma_f32_16x16x32_bf16 v[46:49], v[192:195], v[166:169], v[46:49]
	v_mfma_f32_16x16x32_bf16 v[42:45], v[192:195], v[170:173], v[42:45]
	global_load_lds_dwordx4 v[142:143], off
	v_lshl_add_u64 v[142:143], v[142:143], 0, s[2:3]
	s_add_i32 m0, m0, 0x1000
	v_mfma_f32_16x16x32_bf16 v[38:41], v[192:195], v[176:179], v[38:41]
	v_mfma_f32_16x16x32_bf16 v[34:37], v[192:195], v[180:183], v[34:37]
	v_mfma_f32_16x16x32_bf16 v[30:33], v[196:199], v[146:149], v[30:33]
	global_load_lds_dwordx4 v[142:143], off
	s_add_i32 m0, m0, 0x1000
	v_lshl_add_u64 v[142:143], v[134:135], 0, s[2:3]
	v_mfma_f32_16x16x32_bf16 v[26:29], v[196:199], v[152:155], v[26:29]
	v_mfma_f32_16x16x32_bf16 v[22:25], v[196:199], v[156:159], v[22:25]
	v_mfma_f32_16x16x32_bf16 v[18:21], v[196:199], v[162:165], v[18:21]
	global_load_lds_dwordx4 v[134:135], off
	s_add_i32 m0, m0, 0x1000
	v_lshl_add_u64 v[132:133], v[132:133], 0, s[12:13]
	v_mfma_f32_16x16x32_bf16 v[14:17], v[196:199], v[166:169], v[14:17]
	v_mfma_f32_16x16x32_bf16 v[10:13], v[196:199], v[170:173], v[10:13]
	v_mfma_f32_16x16x32_bf16 v[6:9], v[196:199], v[176:179], v[6:9]
	global_load_lds_dwordx4 v[142:143], off
	v_lshl_add_u64 v[134:135], v[134:135], 0, s[4:5]
	v_mfma_f32_16x16x32_bf16 v[2:5], v[196:199], v[180:183], v[2:5]
	s_setprio 0
	s_mov_b32 s42, s41
	s_add_i32 s41, s41, 0x6000
	s_cmp_eq_u32 s41, 0x12000
	s_cselect_b32 s41, 0, s41
	s_nop 0
	.p2align 3
	s_waitcnt vmcnt(6) lgkmcnt(0)
	s_barrier
	s_setprio 1
	v_add_u32_e32 v144, s41, v136
	v_mfma_f32_16x16x32_bf16 v[126:129], v[232:235], v[200:203], v[126:129]
	ds_read_b128 v[146:149], v144 offset:0
	v_mfma_f32_16x16x32_bf16 v[122:125], v[232:235], v[204:207], v[122:125]
	ds_read_b128 v[152:155], v144 offset:1024
	v_mfma_f32_16x16x32_bf16 v[118:121], v[232:235], v[208:211], v[118:121]
	ds_read_b128 v[156:159], v144 offset:2048
	v_mfma_f32_16x16x32_bf16 v[114:117], v[232:235], v[212:215], v[114:117]
	ds_read_b128 v[162:165], v144 offset:3072
	v_mfma_f32_16x16x32_bf16 v[110:113], v[232:235], v[216:219], v[110:113]
	ds_read_b128 v[166:169], v144 offset:4096
	v_mfma_f32_16x16x32_bf16 v[106:109], v[232:235], v[220:223], v[106:109]
	ds_read_b128 v[170:173], v144 offset:5120
	v_mfma_f32_16x16x32_bf16 v[102:105], v[232:235], v[224:227], v[102:105]
	ds_read_b128 v[176:179], v144 offset:6144
	v_mfma_f32_16x16x32_bf16 v[98:101], v[232:235], v[228:231], v[98:101]
	ds_read_b128 v[180:183], v144 offset:7168
	v_mfma_f32_16x16x32_bf16 v[94:97], v[236:239], v[200:203], v[94:97]
	v_add_u32_e64 v144, s41, v137
	v_mfma_f32_16x16x32_bf16 v[90:93], v[236:239], v[204:207], v[90:93]
	v_mfma_f32_16x16x32_bf16 v[86:89], v[236:239], v[208:211], v[86:89]
	ds_read_b128 v[184:187], v144 offset:16384
	v_mfma_f32_16x16x32_bf16 v[82:85], v[236:239], v[212:215], v[82:85]
	ds_read_b128 v[188:191], v144 offset:17408
	v_mfma_f32_16x16x32_bf16 v[78:81], v[236:239], v[216:219], v[78:81]
	ds_read_b128 v[192:195], v144 offset:18432
	v_mfma_f32_16x16x32_bf16 v[74:77], v[236:239], v[220:223], v[74:77]
	ds_read_b128 v[196:199], v144 offset:19456
	v_mfma_f32_16x16x32_bf16 v[70:73], v[236:239], v[224:227], v[70:73]
	v_mfma_f32_16x16x32_bf16 v[66:69], v[236:239], v[228:231], v[66:69]
	v_mfma_f32_16x16x32_bf16 v[62:65], v[240:243], v[200:203], v[62:65]
	v_mfma_f32_16x16x32_bf16 v[58:61], v[240:243], v[204:207], v[58:61]
	v_mfma_f32_16x16x32_bf16 v[54:57], v[240:243], v[208:211], v[54:57]
	v_mfma_f32_16x16x32_bf16 v[50:53], v[240:243], v[212:215], v[50:53]
	v_mfma_f32_16x16x32_bf16 v[46:49], v[240:243], v[216:219], v[46:49]
	v_mfma_f32_16x16x32_bf16 v[42:45], v[240:243], v[220:223], v[42:45]
	v_mfma_f32_16x16x32_bf16 v[38:41], v[240:243], v[224:227], v[38:41]
	v_mfma_f32_16x16x32_bf16 v[34:37], v[240:243], v[228:231], v[34:37]
	v_mfma_f32_16x16x32_bf16 v[30:33], v[244:247], v[200:203], v[30:33]
	v_mfma_f32_16x16x32_bf16 v[26:29], v[244:247], v[204:207], v[26:29]
	v_mfma_f32_16x16x32_bf16 v[22:25], v[244:247], v[208:211], v[22:25]
	v_mfma_f32_16x16x32_bf16 v[18:21], v[244:247], v[212:215], v[18:21]
	v_mfma_f32_16x16x32_bf16 v[14:17], v[244:247], v[216:219], v[14:17]
	v_mfma_f32_16x16x32_bf16 v[10:13], v[244:247], v[220:223], v[10:13]
	v_mfma_f32_16x16x32_bf16 v[6:9], v[244:247], v[224:227], v[6:9]
	v_mfma_f32_16x16x32_bf16 v[2:5], v[244:247], v[228:231], v[2:5]
	s_setprio 0
	s_mov_b32 s42, s41
	s_add_i32 s41, s41, 0x6000
	s_cmp_eq_u32 s41, 0x12000
	s_cselect_b32 s41, 0, s41
	s_nop 0
	.p2align 3
	s_waitcnt vmcnt(0) lgkmcnt(0)
	s_barrier
; DEVI unsigned pack2(float a, float b) { return __builtin_bit_cast(unsigned, __builtin_convertvector((f32x2_t){a, b}, bf16x2_t)); }
; DEVI float blo(unsigned u) { return __uint_as_float(u << 16); }
; DEVI float bhi(unsigned u) { return __uint_as_float(u & 0xffff0000u); }
; DEVI float siluf_(float x) { return x * __builtin_amdgcn_rcpf(1.f + __expf(-x)); }
;     ...
;   for (int kt = 0; kt < nk; kt++) {
;     if (kt + 1 < nk) asm volatile("s_waitcnt vmcnt(6)" ::: "memory");
;     else asm volatile("s_waitcnt vmcnt(0)" ::: "memory");
;     __builtin_amdgcn_s_barrier();
;     asm volatile("" ::: "memory");
;     if (kt + 2 < nk) G2_STAGE(kt + 2);
;     const char* cS = smem + (kt % 3) * 24576;
;     bf16x8 xa[8], wb[4];
; #pragma unroll
;     for (int f = 0; f < 8; f++) xa[f] = *(const bf16x8*)(cS + aoff + f * 1024);
; #pragma unroll
;     for (int f = 0; f < 4; f++) wb[f] = *(const bf16x8*)(cS + boff + f * 1024);
; #pragma unroll
;     for (int nf = 0; nf < 4; nf++)
; #pragma unroll
;       for (int mf = 0; mf < 8; mf++)
;         acc[nf][mf] = __builtin_amdgcn_mfma_f32_16x16x32_bf16(wb[nf], xa[mf], acc[nf][mf], 0, 0, 0);
;   }
;     ...
; #pragma unroll
;   for (int mf = 0; mf < 8; mf++) {
;     const int row = m0 + wm * 128 + mf * 16 + r16;
;     if (EPI == EPI_SWIGLU) {
; #pragma unroll
;       for (int nf = 0; nf < 2; nf++) {
;         const int hcol = (n0 >> 1) + wn * 32 + nf * 16 + quad * 4;
;         f32x4 g = acc[nf][mf], u = acc[nf + 2][mf];
;         u32x2 pk;
;         pk[0] = pack2(siluf_(g[0]) * u[0], siluf_(g[1]) * u[1]);
;         pk[1] = pack2(siluf_(g[2]) * u[2], siluf_(g[3]) * u[3]);
;         *(u32x2*)(outb + (size_t)row * DFF + hcol) = pk;
;       }
;     } else {
; #pragma unroll
;       for (int nf = 0; nf < 4; nf++) {
;         const int col = n0 + wn * 64 + nf * 16 + quad * 4;
;         f32x4 a = acc[nf][mf];
;         if (EPI == EPI_RESID || EPI == EPI_RESID_ATOMIC) {
;           f32x4 x = a;
;           if (EPI == EPI_RESID || kpart == 0) {
;             const u32x2 xr = *(const u32x2*)((const u16*)(p.ws + WS_XB) + (size_t)row * 1024 + col);
;             x[0] += ALPHA * blo(xr[0]); x[1] += ALPHA * bhi(xr[0]); x[2] += ALPHA * blo(xr[1]); x[3] += ALPHA * bhi(xr[1]);
;           }
;           if (EPI == EPI_RESID) *(f32x4*)((float*)(p.ws + WS_XF) + (size_t)row * 1024 + col) = x;
	s_setprio 1
	v_add_u32_e32 v144, s41, v136
	v_mfma_f32_16x16x32_bf16 v[126:129], v[184:187], v[146:149], v[126:129]
	ds_read_b128 v[200:203], v144 offset:0
	v_mfma_f32_16x16x32_bf16 v[122:125], v[184:187], v[152:155], v[122:125]
	ds_read_b128 v[204:207], v144 offset:1024
	v_mfma_f32_16x16x32_bf16 v[118:121], v[184:187], v[156:159], v[118:121]
	ds_read_b128 v[208:211], v144 offset:2048
	v_mfma_f32_16x16x32_bf16 v[114:117], v[184:187], v[162:165], v[114:117]
	ds_read_b128 v[212:215], v144 offset:3072
	v_mfma_f32_16x16x32_bf16 v[110:113], v[184:187], v[166:169], v[110:113]
	ds_read_b128 v[216:219], v144 offset:4096
	v_mfma_f32_16x16x32_bf16 v[106:109], v[184:187], v[170:173], v[106:109]
	ds_read_b128 v[220:223], v144 offset:5120
	v_mfma_f32_16x16x32_bf16 v[102:105], v[184:187], v[176:179], v[102:105]
	ds_read_b128 v[224:227], v144 offset:6144
	v_mfma_f32_16x16x32_bf16 v[98:101], v[184:187], v[180:183], v[98:101]
	ds_read_b128 v[228:231], v144 offset:7168
	v_mfma_f32_16x16x32_bf16 v[94:97], v[188:191], v[146:149], v[94:97]
	v_add_u32_e64 v144, s41, v137
	v_mfma_f32_16x16x32_bf16 v[90:93], v[188:191], v[152:155], v[90:93]
	v_mfma_f32_16x16x32_bf16 v[86:89], v[188:191], v[156:159], v[86:89]
	ds_read_b128 v[232:235], v144 offset:16384
	v_mfma_f32_16x16x32_bf16 v[82:85], v[188:191], v[162:165], v[82:85]
	ds_read_b128 v[236:239], v144 offset:17408
	v_mfma_f32_16x16x32_bf16 v[78:81], v[188:191], v[166:169], v[78:81]
	ds_read_b128 v[240:243], v144 offset:18432
	v_mfma_f32_16x16x32_bf16 v[74:77], v[188:191], v[170:173], v[74:77]
	ds_read_b128 v[244:247], v144 offset:19456
	v_mfma_f32_16x16x32_bf16 v[70:73], v[188:191], v[176:179], v[70:73]
	v_mfma_f32_16x16x32_bf16 v[66:69], v[188:191], v[180:183], v[66:69]
	v_mfma_f32_16x16x32_bf16 v[62:65], v[192:195], v[146:149], v[62:65]
	v_mfma_f32_16x16x32_bf16 v[58:61], v[192:195], v[152:155], v[58:61]
	v_mfma_f32_16x16x32_bf16 v[54:57], v[192:195], v[156:159], v[54:57]
	v_mfma_f32_16x16x32_bf16 v[50:53], v[192:195], v[162:165], v[50:53]
	v_mfma_f32_16x16x32_bf16 v[46:49], v[192:195], v[166:169], v[46:49]
	v_mfma_f32_16x16x32_bf16 v[42:45], v[192:195], v[170:173], v[42:45]
	v_mfma_f32_16x16x32_bf16 v[38:41], v[192:195], v[176:179], v[38:41]
	v_mfma_f32_16x16x32_bf16 v[34:37], v[192:195], v[180:183], v[34:37]
	v_mfma_f32_16x16x32_bf16 v[30:33], v[196:199], v[146:149], v[30:33]
	v_mfma_f32_16x16x32_bf16 v[26:29], v[196:199], v[152:155], v[26:29]
	v_mfma_f32_16x16x32_bf16 v[22:25], v[196:199], v[156:159], v[22:25]
	v_mfma_f32_16x16x32_bf16 v[18:21], v[196:199], v[162:165], v[18:21]
	v_mfma_f32_16x16x32_bf16 v[14:17], v[196:199], v[166:169], v[14:17]
	v_mfma_f32_16x16x32_bf16 v[10:13], v[196:199], v[170:173], v[10:13]
	v_mfma_f32_16x16x32_bf16 v[6:9], v[196:199], v[176:179], v[6:9]
	v_mfma_f32_16x16x32_bf16 v[2:5], v[196:199], v[180:183], v[2:5]
	s_setprio 0
	s_mov_b32 s42, s41
	s_add_i32 s41, s41, 0x6000
	s_cmp_eq_u32 s41, 0x12000
	s_cselect_b32 s41, 0, s41
	s_nop 0
	s_mov_b32 s4, 0x8000
	s_mov_b32 s5, 0
	s_mov_b32 s10, 0x10000
	s_mov_b32 s11, 0
	s_mov_b32 s45, 0x3fd744fd
	.p2align 3
	s_waitcnt lgkmcnt(0)
	s_nop 0
	v_mfma_f32_16x16x32_bf16 v[126:129], v[232:235], v[200:203], v[126:129]
	v_mfma_f32_16x16x32_bf16 v[122:125], v[232:235], v[204:207], v[122:125]
	v_mfma_f32_16x16x32_bf16 v[118:121], v[232:235], v[208:211], v[118:121]
	v_mfma_f32_16x16x32_bf16 v[114:117], v[232:235], v[212:215], v[114:117]
	v_mfma_f32_16x16x32_bf16 v[110:113], v[232:235], v[216:219], v[110:113]
	global_load_dwordx4 v[146:149], v[138:139], off offset:0
	v_mfma_f32_16x16x32_bf16 v[106:109], v[232:235], v[220:223], v[106:109]
	v_mfma_f32_16x16x32_bf16 v[102:105], v[232:235], v[224:227], v[102:105]
	global_load_dwordx4 v[152:155], v[138:139], off offset:128
	v_mfma_f32_16x16x32_bf16 v[98:101], v[232:235], v[228:231], v[98:101]
	v_lshl_add_u64 v[138:139], v[138:139], 0, s[4:5]
	v_mfma_f32_16x16x32_bf16 v[94:97], v[236:239], v[200:203], v[94:97]
	global_load_dwordx4 v[156:159], v[138:139], off offset:0
	v_mfma_f32_16x16x32_bf16 v[90:93], v[236:239], v[204:207], v[90:93]
	v_mfma_f32_16x16x32_bf16 v[86:89], v[236:239], v[208:211], v[86:89]
	global_load_dwordx4 v[162:165], v[138:139], off offset:128
	v_mfma_f32_16x16x32_bf16 v[82:85], v[236:239], v[212:215], v[82:85]
	v_lshl_add_u64 v[138:139], v[138:139], 0, s[4:5]
	v_mfma_f32_16x16x32_bf16 v[78:81], v[236:239], v[216:219], v[78:81]
	global_load_dwordx4 v[166:169], v[138:139], off offset:0
	v_mfma_f32_16x16x32_bf16 v[74:77], v[236:239], v[220:223], v[74:77]
	v_mfma_f32_16x16x32_bf16 v[70:73], v[236:239], v[224:227], v[70:73]
	global_load_dwordx4 v[170:173], v[138:139], off offset:128
	v_mfma_f32_16x16x32_bf16 v[66:69], v[236:239], v[228:231], v[66:69]
	v_lshl_add_u64 v[138:139], v[138:139], 0, s[4:5]
	v_mfma_f32_16x16x32_bf16 v[62:65], v[240:243], v[200:203], v[62:65]
	global_load_dwordx4 v[176:179], v[138:139], off offset:0
	v_mfma_f32_16x16x32_bf16 v[58:61], v[240:243], v[204:207], v[58:61]
	v_mfma_f32_16x16x32_bf16 v[54:57], v[240:243], v[208:211], v[54:57]
	global_load_dwordx4 v[180:183], v[138:139], off offset:128
	v_mfma_f32_16x16x32_bf16 v[50:53], v[240:243], v[212:215], v[50:53]
	v_lshl_add_u64 v[138:139], v[138:139], 0, s[4:5]
	v_mfma_f32_16x16x32_bf16 v[46:49], v[240:243], v[216:219], v[46:49]
	global_load_dwordx4 v[184:187], v[138:139], off offset:0
	v_mfma_f32_16x16x32_bf16 v[42:45], v[240:243], v[220:223], v[42:45]
	v_mfma_f32_16x16x32_bf16 v[38:41], v[240:243], v[224:227], v[38:41]
	global_load_dwordx4 v[188:191], v[138:139], off offset:128
	v_mfma_f32_16x16x32_bf16 v[34:37], v[240:243], v[228:231], v[34:37]
	v_lshl_add_u64 v[138:139], v[138:139], 0, s[4:5]
	v_mfma_f32_16x16x32_bf16 v[30:33], v[244:247], v[200:203], v[30:33]
	global_load_dwordx4 v[192:195], v[138:139], off offset:0
	v_mfma_f32_16x16x32_bf16 v[26:29], v[244:247], v[204:207], v[26:29]
	v_mfma_f32_16x16x32_bf16 v[22:25], v[244:247], v[208:211], v[22:25]
	global_load_dwordx4 v[196:199], v[138:139], off offset:128
	v_mfma_f32_16x16x32_bf16 v[18:21], v[244:247], v[212:215], v[18:21]
	v_lshl_add_u64 v[138:139], v[138:139], 0, s[4:5]
	v_mfma_f32_16x16x32_bf16 v[14:17], v[244:247], v[216:219], v[14:17]
	v_mfma_f32_16x16x32_bf16 v[10:13], v[244:247], v[220:223], v[10:13]
	v_mfma_f32_16x16x32_bf16 v[6:9], v[244:247], v[224:227], v[6:9]
	v_mfma_f32_16x16x32_bf16 v[2:5], v[244:247], v[228:231], v[2:5]
	s_mov_b32 m0, s44
	global_load_dwordx4 v[200:203], v[138:139], off offset:0
	global_load_dwordx4 v[204:207], v[138:139], off offset:128
	v_lshl_add_u64 v[138:139], v[138:139], 0, s[4:5]
	global_load_dwordx4 v[208:211], v[138:139], off offset:0
	global_load_dwordx4 v[212:215], v[138:139], off offset:128
	v_lshl_add_u64 v[138:139], v[138:139], 0, s[4:5]
	s_nop 7
	s_waitcnt vmcnt(15)
; DEVI float blo(unsigned u) { return __uint_as_float(u << 16); }
; DEVI float bhi(unsigned u) { return __uint_as_float(u & 0xffff0000u); }
;     ...
;         if (EPI == EPI_RESID || EPI == EPI_RESID_ATOMIC) {
;           f32x4 x = a;
;           if (EPI == EPI_RESID || kpart == 0) {
;             const u32x2 xr = *(const u32x2*)((const u16*)(p.ws + WS_XB) + (size_t)row * 1024 + col);
;             x[0] += ALPHA * blo(xr[0]); x[1] += ALPHA * bhi(xr[0]); x[2] += ALPHA * blo(xr[1]); x[3] += ALPHA * bhi(xr[1]);
;           }
;           if (EPI == EPI_RESID) *(f32x4*)((float*)(p.ws + WS_XF) + (size_t)row * 1024 + col) = x;
;           else *(f32x4*)((float*)(p.ws + WS_SLAB) + ((size_t)kpart * 512 + (row - T_P)) * 1024 + col) = x;
	v_permlane16_swap_b32_e32 v146, v148
	v_permlane16_swap_b32_e32 v147, v149
	v_lshlrev_b32_e32 v216, 16, v146
	v_and_b32_e32 v146, 0xffff0000, v146
	v_lshlrev_b32_e32 v217, 16, v147
	v_and_b32_e32 v147, 0xffff0000, v147
	v_fmac_f32_e32 v126, s45, v216
	v_fmac_f32_e32 v127, s45, v146
	v_fmac_f32_e32 v128, s45, v217
	v_fmac_f32_e32 v129, s45, v147
	global_store_dwordx4 v[140:141], v[126:129], off offset:0
	v_lshlrev_b32_e32 v216, 16, v148
	v_and_b32_e32 v148, 0xffff0000, v148
	v_lshlrev_b32_e32 v217, 16, v149
	v_and_b32_e32 v149, 0xffff0000, v149
	v_fmac_f32_e32 v94, s45, v216
	v_fmac_f32_e32 v95, s45, v148
	v_fmac_f32_e32 v96, s45, v217
	v_fmac_f32_e32 v97, s45, v149
	global_store_dwordx4 v[140:141], v[94:97], off offset:64
	s_waitcnt vmcnt(16)
	v_permlane16_swap_b32_e32 v152, v154
	v_permlane16_swap_b32_e32 v153, v155
	v_lshlrev_b32_e32 v216, 16, v152
	v_and_b32_e32 v152, 0xffff0000, v152
	v_lshlrev_b32_e32 v217, 16, v153
	v_and_b32_e32 v153, 0xffff0000, v153
	v_fmac_f32_e32 v62, s45, v216
	v_fmac_f32_e32 v63, s45, v152
	v_fmac_f32_e32 v64, s45, v217
	v_fmac_f32_e32 v65, s45, v153
	global_store_dwordx4 v[140:141], v[62:65], off offset:128
	v_lshlrev_b32_e32 v216, 16, v154
	v_and_b32_e32 v154, 0xffff0000, v154
	v_lshlrev_b32_e32 v217, 16, v155
	v_and_b32_e32 v155, 0xffff0000, v155
	v_fmac_f32_e32 v30, s45, v216
	v_fmac_f32_e32 v31, s45, v154
	v_fmac_f32_e32 v32, s45, v217
	v_fmac_f32_e32 v33, s45, v155
	global_store_dwordx4 v[140:141], v[30:33], off offset:192
	v_lshl_add_u64 v[140:141], v[140:141], 0, s[10:11]
	s_waitcnt vmcnt(17)
	v_permlane16_swap_b32_e32 v156, v158
	v_permlane16_swap_b32_e32 v157, v159
	v_lshlrev_b32_e32 v216, 16, v156
	v_and_b32_e32 v156, 0xffff0000, v156
	v_lshlrev_b32_e32 v217, 16, v157
	v_and_b32_e32 v157, 0xffff0000, v157
	v_fmac_f32_e32 v122, s45, v216
	v_fmac_f32_e32 v123, s45, v156
	v_fmac_f32_e32 v124, s45, v217
	v_fmac_f32_e32 v125, s45, v157
	global_store_dwordx4 v[140:141], v[122:125], off offset:0
	v_lshlrev_b32_e32 v216, 16, v158
	v_and_b32_e32 v158, 0xffff0000, v158
	v_lshlrev_b32_e32 v217, 16, v159
	v_and_b32_e32 v159, 0xffff0000, v159
	v_fmac_f32_e32 v90, s45, v216
	v_fmac_f32_e32 v91, s45, v158
	v_fmac_f32_e32 v92, s45, v217
	v_fmac_f32_e32 v93, s45, v159
	global_store_dwordx4 v[140:141], v[90:93], off offset:64
	s_waitcnt vmcnt(18)
	v_permlane16_swap_b32_e32 v162, v164
	v_permlane16_swap_b32_e32 v163, v165
	v_lshlrev_b32_e32 v216, 16, v162
	v_and_b32_e32 v162, 0xffff0000, v162
	v_lshlrev_b32_e32 v217, 16, v163
	v_and_b32_e32 v163, 0xffff0000, v163
	v_fmac_f32_e32 v58, s45, v216
	v_fmac_f32_e32 v59, s45, v162
	v_fmac_f32_e32 v60, s45, v217
	v_fmac_f32_e32 v61, s45, v163
	global_store_dwordx4 v[140:141], v[58:61], off offset:128
	v_lshlrev_b32_e32 v216, 16, v164
	v_and_b32_e32 v164, 0xffff0000, v164
	v_lshlrev_b32_e32 v217, 16, v165
	v_and_b32_e32 v165, 0xffff0000, v165
	v_fmac_f32_e32 v26, s45, v216
	v_fmac_f32_e32 v27, s45, v164
	v_fmac_f32_e32 v28, s45, v217
	v_fmac_f32_e32 v29, s45, v165
	global_store_dwordx4 v[140:141], v[26:29], off offset:192
	v_lshl_add_u64 v[140:141], v[140:141], 0, s[10:11]
	s_waitcnt vmcnt(19)
	v_permlane16_swap_b32_e32 v166, v168
	v_permlane16_swap_b32_e32 v167, v169
	v_lshlrev_b32_e32 v216, 16, v166
	v_and_b32_e32 v166, 0xffff0000, v166
	v_lshlrev_b32_e32 v217, 16, v167
	v_and_b32_e32 v167, 0xffff0000, v167
	v_fmac_f32_e32 v118, s45, v216
	v_fmac_f32_e32 v119, s45, v166
	v_fmac_f32_e32 v120, s45, v217
	v_fmac_f32_e32 v121, s45, v167
	global_store_dwordx4 v[140:141], v[118:121], off offset:0
	v_lshlrev_b32_e32 v216, 16, v168
	v_and_b32_e32 v168, 0xffff0000, v168
	v_lshlrev_b32_e32 v217, 16, v169
	v_and_b32_e32 v169, 0xffff0000, v169
	v_fmac_f32_e32 v86, s45, v216
	v_fmac_f32_e32 v87, s45, v168
	v_fmac_f32_e32 v88, s45, v217
	v_fmac_f32_e32 v89, s45, v169
	global_store_dwordx4 v[140:141], v[86:89], off offset:64
	s_waitcnt vmcnt(20)
	v_permlane16_swap_b32_e32 v170, v172
	v_permlane16_swap_b32_e32 v171, v173
	v_lshlrev_b32_e32 v216, 16, v170
	v_and_b32_e32 v170, 0xffff0000, v170
	v_lshlrev_b32_e32 v217, 16, v171
	v_and_b32_e32 v171, 0xffff0000, v171
	v_fmac_f32_e32 v54, s45, v216
	v_fmac_f32_e32 v55, s45, v170
	v_fmac_f32_e32 v56, s45, v217
	v_fmac_f32_e32 v57, s45, v171
	global_store_dwordx4 v[140:141], v[54:57], off offset:128
	v_lshlrev_b32_e32 v216, 16, v172
	v_and_b32_e32 v172, 0xffff0000, v172
	v_lshlrev_b32_e32 v217, 16, v173
	v_and_b32_e32 v173, 0xffff0000, v173
	v_fmac_f32_e32 v22, s45, v216
	v_fmac_f32_e32 v23, s45, v172
	v_fmac_f32_e32 v24, s45, v217
	v_fmac_f32_e32 v25, s45, v173
	global_store_dwordx4 v[140:141], v[22:25], off offset:192
	v_lshl_add_u64 v[140:141], v[140:141], 0, s[10:11]
	s_waitcnt vmcnt(21)
	v_permlane16_swap_b32_e32 v176, v178
	v_permlane16_swap_b32_e32 v177, v179
	v_lshlrev_b32_e32 v216, 16, v176
	v_and_b32_e32 v176, 0xffff0000, v176
	v_lshlrev_b32_e32 v217, 16, v177
	v_and_b32_e32 v177, 0xffff0000, v177
	v_fmac_f32_e32 v114, s45, v216
	v_fmac_f32_e32 v115, s45, v176
	v_fmac_f32_e32 v116, s45, v217
	v_fmac_f32_e32 v117, s45, v177
	global_store_dwordx4 v[140:141], v[114:117], off offset:0
	v_lshlrev_b32_e32 v216, 16, v178
	v_and_b32_e32 v178, 0xffff0000, v178
	v_lshlrev_b32_e32 v217, 16, v179
	v_and_b32_e32 v179, 0xffff0000, v179
	v_fmac_f32_e32 v82, s45, v216
	v_fmac_f32_e32 v83, s45, v178
	v_fmac_f32_e32 v84, s45, v217
	v_fmac_f32_e32 v85, s45, v179
	global_store_dwordx4 v[140:141], v[82:85], off offset:64
	s_waitcnt vmcnt(22)
; DEVI float blo(unsigned u) { return __uint_as_float(u << 16); }
; DEVI float bhi(unsigned u) { return __uint_as_float(u & 0xffff0000u); }
;     ...
;         if (EPI == EPI_RESID || EPI == EPI_RESID_ATOMIC) {
;           f32x4 x = a;
;           if (EPI == EPI_RESID || kpart == 0) {
;             const u32x2 xr = *(const u32x2*)((const u16*)(p.ws + WS_XB) + (size_t)row * 1024 + col);
;             x[0] += ALPHA * blo(xr[0]); x[1] += ALPHA * bhi(xr[0]); x[2] += ALPHA * blo(xr[1]); x[3] += ALPHA * bhi(xr[1]);
;           }
;           if (EPI == EPI_RESID) *(f32x4*)((float*)(p.ws + WS_XF) + (size_t)row * 1024 + col) = x;
;           else *(f32x4*)((float*)(p.ws + WS_SLAB) + ((size_t)kpart * 512 + (row - T_P)) * 1024 + col) = x;
	v_permlane16_swap_b32_e32 v180, v182
	v_permlane16_swap_b32_e32 v181, v183
	v_lshlrev_b32_e32 v216, 16, v180
	v_and_b32_e32 v180, 0xffff0000, v180
	v_lshlrev_b32_e32 v217, 16, v181
	v_and_b32_e32 v181, 0xffff0000, v181
	v_fmac_f32_e32 v50, s45, v216
	v_fmac_f32_e32 v51, s45, v180
	v_fmac_f32_e32 v52, s45, v217
	v_fmac_f32_e32 v53, s45, v181
	global_store_dwordx4 v[140:141], v[50:53], off offset:128
	v_lshlrev_b32_e32 v216, 16, v182
	v_and_b32_e32 v182, 0xffff0000, v182
	v_lshlrev_b32_e32 v217, 16, v183
	v_and_b32_e32 v183, 0xffff0000, v183
	v_fmac_f32_e32 v18, s45, v216
	v_fmac_f32_e32 v19, s45, v182
	v_fmac_f32_e32 v20, s45, v217
	v_fmac_f32_e32 v21, s45, v183
	global_store_dwordx4 v[140:141], v[18:21], off offset:192
	v_lshl_add_u64 v[140:141], v[140:141], 0, s[10:11]
	s_waitcnt vmcnt(23)
	v_permlane16_swap_b32_e32 v184, v186
	v_permlane16_swap_b32_e32 v185, v187
	v_lshlrev_b32_e32 v216, 16, v184
	v_and_b32_e32 v184, 0xffff0000, v184
	v_lshlrev_b32_e32 v217, 16, v185
	v_and_b32_e32 v185, 0xffff0000, v185
	v_fmac_f32_e32 v110, s45, v216
	v_fmac_f32_e32 v111, s45, v184
	v_fmac_f32_e32 v112, s45, v217
	v_fmac_f32_e32 v113, s45, v185
	global_store_dwordx4 v[140:141], v[110:113], off offset:0
	v_lshlrev_b32_e32 v216, 16, v186
	v_and_b32_e32 v186, 0xffff0000, v186
	v_lshlrev_b32_e32 v217, 16, v187
	v_and_b32_e32 v187, 0xffff0000, v187
	v_fmac_f32_e32 v78, s45, v216
	v_fmac_f32_e32 v79, s45, v186
	v_fmac_f32_e32 v80, s45, v217
	v_fmac_f32_e32 v81, s45, v187
	global_store_dwordx4 v[140:141], v[78:81], off offset:64
	s_waitcnt vmcnt(24)
	v_permlane16_swap_b32_e32 v188, v190
	v_permlane16_swap_b32_e32 v189, v191
	v_lshlrev_b32_e32 v216, 16, v188
	v_and_b32_e32 v188, 0xffff0000, v188
	v_lshlrev_b32_e32 v217, 16, v189
	v_and_b32_e32 v189, 0xffff0000, v189
	v_fmac_f32_e32 v46, s45, v216
	v_fmac_f32_e32 v47, s45, v188
	v_fmac_f32_e32 v48, s45, v217
	v_fmac_f32_e32 v49, s45, v189
	global_store_dwordx4 v[140:141], v[46:49], off offset:128
	v_lshlrev_b32_e32 v216, 16, v190
	v_and_b32_e32 v190, 0xffff0000, v190
	v_lshlrev_b32_e32 v217, 16, v191
	v_and_b32_e32 v191, 0xffff0000, v191
	v_fmac_f32_e32 v14, s45, v216
	v_fmac_f32_e32 v15, s45, v190
	v_fmac_f32_e32 v16, s45, v217
	v_fmac_f32_e32 v17, s45, v191
	global_store_dwordx4 v[140:141], v[14:17], off offset:192
	v_lshl_add_u64 v[140:141], v[140:141], 0, s[10:11]
	s_waitcnt vmcnt(25)
	v_permlane16_swap_b32_e32 v192, v194
	v_permlane16_swap_b32_e32 v193, v195
	v_lshlrev_b32_e32 v216, 16, v192
	v_and_b32_e32 v192, 0xffff0000, v192
	v_lshlrev_b32_e32 v217, 16, v193
	v_and_b32_e32 v193, 0xffff0000, v193
	v_fmac_f32_e32 v106, s45, v216
	v_fmac_f32_e32 v107, s45, v192
	v_fmac_f32_e32 v108, s45, v217
	v_fmac_f32_e32 v109, s45, v193
	global_store_dwordx4 v[140:141], v[106:109], off offset:0
	v_lshlrev_b32_e32 v216, 16, v194
	v_and_b32_e32 v194, 0xffff0000, v194
	v_lshlrev_b32_e32 v217, 16, v195
	v_and_b32_e32 v195, 0xffff0000, v195
	v_fmac_f32_e32 v74, s45, v216
	v_fmac_f32_e32 v75, s45, v194
	v_fmac_f32_e32 v76, s45, v217
	v_fmac_f32_e32 v77, s45, v195
	global_store_dwordx4 v[140:141], v[74:77], off offset:64
	s_waitcnt vmcnt(26)
	v_permlane16_swap_b32_e32 v196, v198
	v_permlane16_swap_b32_e32 v197, v199
	v_lshlrev_b32_e32 v216, 16, v196
	v_and_b32_e32 v196, 0xffff0000, v196
	v_lshlrev_b32_e32 v217, 16, v197
	v_and_b32_e32 v197, 0xffff0000, v197
	v_fmac_f32_e32 v42, s45, v216
	v_fmac_f32_e32 v43, s45, v196
	v_fmac_f32_e32 v44, s45, v217
	v_fmac_f32_e32 v45, s45, v197
	global_store_dwordx4 v[140:141], v[42:45], off offset:128
	v_lshlrev_b32_e32 v216, 16, v198
	v_and_b32_e32 v198, 0xffff0000, v198
	v_lshlrev_b32_e32 v217, 16, v199
	v_and_b32_e32 v199, 0xffff0000, v199
	v_fmac_f32_e32 v10, s45, v216
	v_fmac_f32_e32 v11, s45, v198
	v_fmac_f32_e32 v12, s45, v217
	v_fmac_f32_e32 v13, s45, v199
	global_store_dwordx4 v[140:141], v[10:13], off offset:192
	v_lshl_add_u64 v[140:141], v[140:141], 0, s[10:11]
	s_waitcnt vmcnt(27)
	v_permlane16_swap_b32_e32 v200, v202
	v_permlane16_swap_b32_e32 v201, v203
	v_lshlrev_b32_e32 v216, 16, v200
	v_and_b32_e32 v200, 0xffff0000, v200
	v_lshlrev_b32_e32 v217, 16, v201
	v_and_b32_e32 v201, 0xffff0000, v201
	v_fmac_f32_e32 v102, s45, v216
	v_fmac_f32_e32 v103, s45, v200
	v_fmac_f32_e32 v104, s45, v217
	v_fmac_f32_e32 v105, s45, v201
	global_store_dwordx4 v[140:141], v[102:105], off offset:0
	v_lshlrev_b32_e32 v216, 16, v202
	v_and_b32_e32 v202, 0xffff0000, v202
	v_lshlrev_b32_e32 v217, 16, v203
	v_and_b32_e32 v203, 0xffff0000, v203
	v_fmac_f32_e32 v70, s45, v216
	v_fmac_f32_e32 v71, s45, v202
	v_fmac_f32_e32 v72, s45, v217
	v_fmac_f32_e32 v73, s45, v203
	global_store_dwordx4 v[140:141], v[70:73], off offset:64
	s_waitcnt vmcnt(28)
	v_permlane16_swap_b32_e32 v204, v206
	v_permlane16_swap_b32_e32 v205, v207
	v_lshlrev_b32_e32 v216, 16, v204
	v_and_b32_e32 v204, 0xffff0000, v204
	v_lshlrev_b32_e32 v217, 16, v205
	v_and_b32_e32 v205, 0xffff0000, v205
	v_fmac_f32_e32 v38, s45, v216
	v_fmac_f32_e32 v39, s45, v204
	v_fmac_f32_e32 v40, s45, v217
	v_fmac_f32_e32 v41, s45, v205
	global_store_dwordx4 v[140:141], v[38:41], off offset:128
	v_lshlrev_b32_e32 v216, 16, v206
	v_and_b32_e32 v206, 0xffff0000, v206
	v_lshlrev_b32_e32 v217, 16, v207
	v_and_b32_e32 v207, 0xffff0000, v207
	v_fmac_f32_e32 v6, s45, v216
	v_fmac_f32_e32 v7, s45, v206
	v_fmac_f32_e32 v8, s45, v217
	v_fmac_f32_e32 v9, s45, v207
	global_store_dwordx4 v[140:141], v[6:9], off offset:192
	v_lshl_add_u64 v[140:141], v[140:141], 0, s[10:11]
	s_waitcnt vmcnt(29)
	v_permlane16_swap_b32_e32 v208, v210
	v_permlane16_swap_b32_e32 v209, v211
	v_lshlrev_b32_e32 v216, 16, v208
	v_and_b32_e32 v208, 0xffff0000, v208
	v_lshlrev_b32_e32 v217, 16, v209
	v_and_b32_e32 v209, 0xffff0000, v209
	v_fmac_f32_e32 v98, s45, v216
	v_fmac_f32_e32 v99, s45, v208
	v_fmac_f32_e32 v100, s45, v217
	v_fmac_f32_e32 v101, s45, v209
	global_store_dwordx4 v[140:141], v[98:101], off offset:0
	v_lshlrev_b32_e32 v216, 16, v210
	v_and_b32_e32 v210, 0xffff0000, v210
	v_lshlrev_b32_e32 v217, 16, v211
	v_and_b32_e32 v211, 0xffff0000, v211
	v_fmac_f32_e32 v66, s45, v216
	v_fmac_f32_e32 v67, s45, v210
	v_fmac_f32_e32 v68, s45, v217
	v_fmac_f32_e32 v69, s45, v211
	global_store_dwordx4 v[140:141], v[66:69], off offset:64
	s_waitcnt vmcnt(30)
	v_permlane16_swap_b32_e32 v212, v214
	v_permlane16_swap_b32_e32 v213, v215
	v_lshlrev_b32_e32 v216, 16, v212
	v_and_b32_e32 v212, 0xffff0000, v212
	v_lshlrev_b32_e32 v217, 16, v213
	v_and_b32_e32 v213, 0xffff0000, v213
	v_fmac_f32_e32 v34, s45, v216
	v_fmac_f32_e32 v35, s45, v212
	v_fmac_f32_e32 v36, s45, v217
	v_fmac_f32_e32 v37, s45, v213
	global_store_dwordx4 v[140:141], v[34:37], off offset:128
	v_lshlrev_b32_e32 v216, 16, v214
	v_and_b32_e32 v214, 0xffff0000, v214
	v_lshlrev_b32_e32 v217, 16, v215
	v_and_b32_e32 v215, 0xffff0000, v215
	v_fmac_f32_e32 v2, s45, v216
	v_fmac_f32_e32 v3, s45, v214
	v_fmac_f32_e32 v4, s45, v217
	v_fmac_f32_e32 v5, s45, v215
	global_store_dwordx4 v[140:141], v[2:5], off offset:192
	v_readlane_b32 s40, v250, 7
	s_cmpk_lg_u32 s40, 0x200
	s_cbranch_scc1 .LBB0_757
; DEVI int xcd_first_tile() { return (blockIdx.x & 7) * (gridDim.x >> 3) + (blockIdx.x >> 3); }
; DEVI void run_phase(const Params& p, int ph, char* smem) {
;     ...
;       for (int t = xcd_first_tile(); t < 512 + 16 * 8; t += xcd_tile_step()) {
;         if (t < 512) {
;           int mt_, nt_; tile_coords(t, 64, 8, mt_, nt_);
;           gemm_tile256<EPI_RESID>(p, mix, 1024, Bt, 1024, mt_ * 256, nt_ * 128, nullptr, 0, smem);
;         } else {
;           const int u_ = t - 512, tl_ = u_ / 8, q_ = u_ - tl_ * 8;
;           gemm_tile256<EPI_RESID_ATOMIC>(p, mix, 1024, Bt, 1024, (64 + (tl_ & 1)) * 256, (tl_ >> 1) * 128, nullptr, 0, smem, q_ * 128, 4, q_);
;         }
;       }
	v_readlane_b32 s41, v250, 0
	s_lshr_b32 s42, s41, 3
	s_and_b32 s41, s41, 7
	s_mul_i32 s41, s41, 16
	s_add_i32 s41, s41, s42
	s_cmp_lt_u32 s42, 16
	s_movk_i32 s39, 0x4000
	s_branch .LBB0_757
